# v35 = v30 + v_cvt_pk_bf16_f32 peephole and dead RNE-chain removal in the prep and scan/attention-queue phases (non-attention items)
# baseline (speedup 1.0000x reference)
.LBB0_376:
	s_sub_u32 s0, s76, 0x400
	s_cmp_lt_u32 s0, 0x200
	s_sub_i32 s0, 0x9ff, s76
	s_cselect_b32 s76, s0, s76
	s_mul_hi_i32 s0, s76, 0x38e38e39
	s_lshr_b32 s1, s0, 31
	s_ashr_i32 s0, s0, 8
	s_add_i32 s0, s0, s1
	s_mulk_i32 s0, 0x480
	s_sub_i32 s26, s76, s0
	s_add_i32 s0, s76, 0x47f
	s_lshl_b32 s18, s26, 5
	s_cmpk_gt_u32 s0, 0x8fe
	s_mov_b64 s[0:1], -1
	s_cbranch_scc0 .LBB0_421
	s_add_i32 s0, s76, 0xfffffb80
	s_cmpk_gt_u32 s0, 0x47f
	s_mov_b64 s[0:1], -1
	s_cbranch_scc0 .LBB0_387
	s_mov_b64 s[8:9], s[30:31]
	v_mov_b32_e32 v0, v65
	s_sext_i32_i16 s4, s26
	v_mbcnt_lo_u32_b32 v0, -1, v0
	v_mbcnt_hi_u32_b32 v0, -1, v0
	v_add_u32_e32 v79, s33, v0
	v_mov_b32_e32 v0, s8
	v_mov_b32_e32 v1, s9
	v_add_co_u32_e32 v0, vcc, s55, v0
	s_mulk_i32 s4, 0xe39
	s_nop 0
	v_addc_co_u32_e32 v1, vcc, 0, v1, vcc
	global_load_dwordx2 v[0:1], v[0:1], off offset:504
	s_lshr_b32 s5, s4, 31
	s_ashr_i32 s13, s4, 18
	s_add_i32 s13, s13, s5
	s_add_u32 s10, s8, 0x7157900
	s_addc_u32 s11, s9, 0
	v_ashrrev_i32_e32 v36, 3, v79
	v_lshlrev_b32_e32 v78, 4, v79
	v_mov_b64_e32 v[12:13], s[10:11]
	v_add_u32_e32 v2, s18, v36
	v_and_b32_e32 v14, 0x70, v78
	v_mad_i64_i32 v[2:3], s[4:5], v2, s34, v[12:13]
	v_lshlrev_b32_e32 v64, 1, v14
	s_mov_b64 s[0:1], 0x1100
	v_lshl_add_u64 v[2:3], v[2:3], 0, v[64:65]
	v_lshl_add_u64 v[4:5], v[2:3], 0, s[0:1]
	v_add_co_u32_e32 v2, vcc, s35, v2
	global_load_dwordx4 v[8:11], v[4:5], off offset:16
	s_nop 0
	v_addc_co_u32_e32 v3, vcc, 0, v3, vcc
	global_load_dwordx4 v[4:7], v[2:3], off offset:256
	v_mov_b32_e32 v3, v65
	v_lshlrev_b32_e32 v2, 2, v14
	s_waitcnt lgkmcnt(0)
	s_barrier
	v_ashrrev_i32_e32 v81, 5, v79
	v_add_u32_e32 v66, s18, v81
	v_and_b32_e32 v80, 31, v79
	v_cmp_gt_u32_e64 s[6:7], 16, v80
	s_waitcnt vmcnt(0)
	v_readfirstlane_b32 s1, v1
	v_readfirstlane_b32 s0, v0
	v_lshlrev_b32_e32 v15, 16, v9
	s_nop 0
	v_lshl_add_u64 v[18:19], s[0:1], 0, v[2:3]
	global_load_dwordx4 v[0:3], v[18:19], off
	global_load_dwordx4 v[20:23], v[18:19], off offset:16
	v_and_b32_e32 v27, 0xffff0000, v5
	v_and_b32_e32 v26, 0xffff0000, v4
	v_lshlrev_b32_e32 v25, 16, v5
	v_lshlrev_b32_e32 v24, 16, v4
	v_and_b32_e32 v31, 0xffff0000, v7
	v_and_b32_e32 v30, 0xffff0000, v6
	v_pk_mul_f32 v[32:33], v[26:27], v[26:27]
	v_lshlrev_b32_e32 v29, 16, v7
	v_lshlrev_b32_e32 v28, 16, v6
	v_pk_mul_f32 v[34:35], v[30:31], v[30:31]
	v_pk_fma_f32 v[32:33], v[24:25], v[24:25], v[32:33]
	v_lshlrev_b32_e32 v14, 16, v8
	v_and_b32_e32 v9, 0xffff0000, v9
	v_and_b32_e32 v8, 0xffff0000, v8
	v_pk_fma_f32 v[34:35], v[28:29], v[28:29], v[34:35]
	v_add_f32_e32 v32, v32, v33
	v_pk_mul_f32 v[4:5], v[8:9], v[8:9]
	v_add_f32_e32 v32, v34, v32
	v_lshlrev_b32_e32 v17, 16, v11
	v_lshlrev_b32_e32 v16, 16, v10
	v_and_b32_e32 v11, 0xffff0000, v11
	v_and_b32_e32 v10, 0xffff0000, v10
	v_pk_fma_f32 v[4:5], v[14:15], v[14:15], v[4:5]
	v_add_f32_e32 v32, v35, v32
	v_pk_mul_f32 v[6:7], v[10:11], v[10:11]
	v_add_f32_e32 v4, v4, v32
	v_pk_fma_f32 v[6:7], v[16:17], v[16:17], v[6:7]
	v_add_f32_e32 v4, v5, v4
	v_add_f32_e32 v4, v6, v4
	v_add_f32_e32 v4, v7, v4
	s_waitcnt vmcnt(0) lgkmcnt(0)
	v_mov_b32_e32 v32, v0
	v_add_f32_dpp v4, v4, v4 quad_perm:[1,0,3,2] row_mask:0xf bank_mask:0xf bound_ctrl:1
	v_mov_b32_e32 v33, v2
	v_mov_b32_e32 v2, v1
	v_add_f32_dpp v4, v4, v4 quad_perm:[2,3,0,1] row_mask:0xf bank_mask:0xf bound_ctrl:1
	v_mov_b32_e32 v0, v20
	v_mov_b32_e32 v1, v22
	v_add_f32_dpp v4, v4, v4 row_half_mirror row_mask:0xf bank_mask:0xf bound_ctrl:1
	v_fmamk_f32 v4, v4, 0x3c000000, v127
	v_mul_f32_e32 v5, 0x4b800000, v4
	v_cmp_gt_f32_e32 vcc, s57, v4
	v_mov_b32_e32 v22, v21
	s_nop 0
	v_cndmask_b32_e32 v4, v4, v5, vcc
	v_rsq_f32_e32 v6, v4
	v_mad_u64_u32 v[4:5], s[0:1], v36, s56, v[64:65]
	v_lshlrev_b32_e32 v64, 1, v80
	v_mul_f32_e32 v5, 0x45800000, v6
	v_cndmask_b32_e32 v6, v6, v5, vcc
	v_pk_mul_f32 v[24:25], v[6:7], v[24:25] op_sel_hi:[0,1]
	v_pk_mul_f32 v[26:27], v[6:7], v[26:27] op_sel_hi:[0,1]
	v_pk_mul_f32 v[28:29], v[6:7], v[28:29] op_sel_hi:[0,1]
	v_pk_mul_f32 v[30:31], v[6:7], v[30:31] op_sel_hi:[0,1]
	v_pk_mul_f32 v[20:21], v[32:33], v[24:25]
	v_pk_mul_f32 v[2:3], v[2:3], v[26:27]
	s_nop 0
	v_cvt_pk_bf16_f32 v208, v21, v3
	v_cvt_pk_bf16_f32 v209, v20, v2
	v_pk_mul_f32 v[0:1], v[0:1], v[28:29]
	v_pk_mul_f32 v[22:23], v[22:23], v[30:31]
	v_bfe_u32 v26, v20, 16, 1
	v_cvt_pk_bf16_f32 v3, v1, v23
	v_cvt_pk_bf16_f32 v2, v0, v22
	v_add3_u32 v7, v20, v26, s58
	v_lshrrev_b32_e32 v7, 16, v7
	v_mov_b32_e32 v1, v208
	v_mov_b32_e32 v0, v209
	ds_write_b128 v4, v[0:3]
	global_load_dwordx4 v[20:23], v[18:19], off offset:32
	global_load_dwordx4 v[24:27], v[18:19], off offset:48
	v_mad_i64_i32 v[0:1], s[0:1], v66, s34, v[12:13]
	v_pk_mul_f32 v[12:13], v[6:7], v[14:15] op_sel_hi:[0,1]
	v_pk_mul_f32 v[8:9], v[6:7], v[8:9] op_sel_hi:[0,1]
	v_pk_mul_f32 v[14:15], v[6:7], v[16:17] op_sel_hi:[0,1]
	v_pk_mul_f32 v[6:7], v[6:7], v[10:11] op_sel_hi:[0,1]
	v_lshl_add_u64 v[0:1], v[0:1], 0, s[20:21]
	v_lshl_add_u64 v[2:3], v[0:1], 0, v[64:65]
	s_mul_i32 s0, s13, 0xfffff700
	s_add_i32 s12, s0, s18
	s_cmpk_gt_i32 s12, 0xff
	s_cselect_b64 s[24:25], -1, 0
	s_cmpk_lt_i32 s12, 0x100
	s_waitcnt vmcnt(0) lgkmcnt(0)
	v_mov_b32_e32 v10, v20
	v_mov_b32_e32 v11, v22
	v_mov_b32_e32 v22, v21
	v_mov_b32_e32 v16, v24
	v_mov_b32_e32 v17, v26
	v_mov_b32_e32 v26, v25
	v_pk_mul_f32 v[10:11], v[10:11], v[12:13]
	v_pk_mul_f32 v[8:9], v[22:23], v[8:9]
	s_nop 0
	v_cvt_pk_bf16_f32 v209, v11, v9
	v_cvt_pk_bf16_f32 v210, v10, v8
	v_pk_mul_f32 v[12:13], v[16:17], v[14:15]
	v_pk_mul_f32 v[6:7], v[6:7], v[26:27]
	s_nop 0
	v_cvt_pk_bf16_f32 v208, v13, v7
	v_cvt_pk_bf16_f32 v8, v12, v6
	v_mov_b32_e32 v9, v208
	v_mov_b32_e32 v7, v209
	v_mov_b32_e32 v6, v210
	ds_write_b128 v4, v[6:9] offset:16
	global_load_ushort v2, v[2:3], off
	v_and_b32_e32 v4, 7, v79
	v_cvt_f32_ubyte0_e32 v4, v4
	v_mul_f32_e32 v6, 0xbfd49a78, v4
	v_cmp_gt_f32_e32 vcc, s59, v6
	v_and_b32_e32 v5, 8, v79
	v_bitop3_b32 v3, v79, 8, 31 bitop3:0x6c
	v_cndmask_b32_e32 v6, 0, v129, vcc
	v_fmac_f32_e32 v6, 0xbfd49a78, v4
	v_exp_f32_e32 v4, v6
	v_cmp_eq_u32_e64 s[4:5], 0, v5
	v_cndmask_b32_e32 v5, 0, v130, vcc
	v_ldexp_f32 v6, v4, v5
	s_waitcnt vmcnt(0) lgkmcnt(0)
	v_lshlrev_b32_e32 v4, 16, v2
	v_lshlrev_b32_e32 v2, 1, v3
	s_cbranch_scc1 .LBB0_380
	v_mov_b32_e32 v3, v65
	v_lshl_add_u64 v[0:1], v[0:1], 0, v[2:3]
	global_load_ushort v0, v[0:1], off
	v_add_u32_e32 v1, s12, v81
	v_add_u32_e32 v3, 0xffffff00, v1
	v_ashrrev_i32_e32 v3, 6, v3
	v_and_b32_e32 v1, 63, v1
	v_cndmask_b32_e64 v1, v1, v3, s[6:7]
	v_cvt_f32_i32_e32 v1, v1
	v_mul_f32_e32 v1, v6, v1
	v_mul_f32_e32 v1, 0.15915494, v1
	v_sin_f32_e32 v3, v1
	v_cos_f32_e32 v1, v1
	s_waitcnt vmcnt(0) lgkmcnt(0)
	v_lshlrev_b32_e32 v0, 16, v0
	v_mul_f32_e32 v0, v3, v0
	v_cndmask_b32_e64 v0, v0, -v0, s[4:5]
	v_fmac_f32_e32 v0, v1, v4
	v_mov_b32_e32 v4, v0

.LBB0_386:
	v_ashrrev_i32_e32 v73, 31, v72
	v_bfe_u32 v2, v7, 16, 1
	v_add3_u32 v4, v7, v2, s58
	v_lshlrev_b64 v[2:3], 6, v[72:73]
	v_lshl_add_u64 v[0:1], v[0:1], 0, v[2:3]
	global_store_short_d16_hi v[0:1], v4, off
	v_mov_b32_e32 v1, v65
	s_waitcnt lgkmcnt(0)
	s_barrier
	v_lshlrev_b32_e32 v0, 1, v79
	v_mbcnt_lo_u32_b32 v1, -1, v1
	v_mbcnt_hi_u32_b32 v2, -1, v1
	v_and_b32_e32 v20, 31, v2
	s_movk_i32 s0, 0xff80
	v_and_or_b32 v0, v0, s0, v20
	v_ashrrev_i32_e32 v1, 31, v0
	v_ashrrev_i32_e32 v2, 2, v2
	v_lshlrev_b64 v[0:1], 8, v[0:1]
	v_and_b32_e32 v16, -8, v2
	v_lshl_add_u64 v[0:1], s[8:9], 0, v[0:1]
	v_ashrrev_i32_e32 v17, 31, v16
	v_lshl_add_u64 v[18:19], v[16:17], 1, v[0:1]
	s_mov_b32 s0, 0x1710000
	v_add_co_u32_e32 v0, vcc, s0, v18
	s_mov_b32 s0, 0x1712000
	s_nop 0
	v_addc_co_u32_e32 v1, vcc, 0, v19, vcc
	v_add_co_u32_e32 v76, vcc, s0, v18
	s_mov_b32 s0, 0x1714000
	s_nop 0
	v_addc_co_u32_e32 v77, vcc, 0, v19, vcc
	v_add_co_u32_e32 v74, vcc, s0, v18
	s_mov_b32 s0, 0x1716000
	s_nop 0
	v_addc_co_u32_e32 v75, vcc, 0, v19, vcc
	v_add_co_u32_e32 v118, vcc, s0, v18
	global_load_dwordx4 v[0:3], v[0:1], off
	s_nop 0
	v_addc_co_u32_e32 v119, vcc, 0, v19, vcc
	global_load_dwordx4 v[4:7], v[76:77], off
	global_load_dwordx4 v[98:101], v[76:77], off offset:32
	global_load_dwordx4 v[8:11], v[74:75], off
	global_load_dwordx4 v[12:15], v[118:119], off
	v_lshlrev_b32_e32 v16, 1, v16
	s_mov_b64 s[0:1], 0x1710000
	v_mad_u32_u24 v64, v20, s56, v16
	ds_read_b128 v[86:89], v64
	ds_read_b128 v[94:97], v64 offset:32
	v_lshl_add_u64 v[120:121], v[18:19], 0, s[0:1]
	global_load_dwordx4 v[90:93], v[120:121], off offset:32
	global_load_dwordx4 v[102:105], v[74:75], off offset:32
	global_load_dwordx4 v[106:109], v[76:77], off offset:96
	global_load_dwordx4 v[110:113], v[118:119], off offset:32
	global_load_dwordx4 v[114:117], v[74:75], off offset:96
	s_waitcnt vmcnt(0) lgkmcnt(0)
	v_mfma_f32_32x32x16_bf16 v[48:63], v[86:89], v[0:3], 0
	v_mfma_f32_32x32x16_bf16 v[32:47], v[86:89], v[4:7], 0
	v_mfma_f32_32x32x16_bf16 v[16:31], v[86:89], v[8:11], 0
	v_mfma_f32_32x32x16_bf16 v[0:15], v[86:89], v[12:15], 0
	global_load_dwordx4 v[86:89], v[120:121], off offset:64
	v_mfma_f32_32x32x16_bf16 v[48:63], v[94:97], v[90:93], v[48:63]
	global_load_dwordx4 v[90:93], v[76:77], off offset:64
	v_mfma_f32_32x32x16_bf16 v[32:47], v[94:97], v[98:101], v[32:47]
	global_load_dwordx4 v[98:101], v[74:75], off offset:64
	v_mfma_f32_32x32x16_bf16 v[16:31], v[94:97], v[102:105], v[16:31]
	global_load_dwordx4 v[102:105], v[118:119], off offset:64
	v_mfma_f32_32x32x16_bf16 v[0:15], v[94:97], v[110:113], v[0:15]
	ds_read_b128 v[94:97], v64 offset:64
	ds_read_b128 v[110:113], v64 offset:96
	s_waitcnt vmcnt(0) lgkmcnt(0)
	v_mfma_f32_32x32x16_bf16 v[48:63], v[94:97], v[86:89], v[48:63]
	global_load_dwordx4 v[86:89], v[120:121], off offset:96
	v_mfma_f32_32x32x16_bf16 v[32:47], v[94:97], v[90:93], v[32:47]
	v_mfma_f32_32x32x16_bf16 v[16:31], v[94:97], v[98:101], v[16:31]
	v_mfma_f32_32x32x16_bf16 v[0:15], v[94:97], v[102:105], v[0:15]
	v_mfma_f32_32x32x16_bf16 v[32:47], v[110:113], v[106:109], v[32:47]
	s_waitcnt vmcnt(0) lgkmcnt(0)
	v_mfma_f32_32x32x16_bf16 v[48:63], v[110:113], v[86:89], v[48:63]
	global_load_dwordx4 v[86:89], v[118:119], off offset:96
	v_mfma_f32_32x32x16_bf16 v[16:31], v[110:113], v[114:117], v[16:31]
	s_waitcnt vmcnt(0) lgkmcnt(0)
	v_mfma_f32_32x32x16_bf16 v[0:15], v[110:113], v[86:89], v[0:15]
	global_load_dwordx4 v[86:89], v[120:121], off offset:128
	global_load_dwordx4 v[90:93], v[76:77], off offset:128
	global_load_dwordx4 v[94:97], v[74:75], off offset:128
	global_load_dwordx4 v[98:101], v[118:119], off offset:128
	ds_read_b128 v[102:105], v64 offset:128
	ds_read_b128 v[110:113], v64 offset:160
	global_load_dwordx4 v[106:109], v[120:121], off offset:160
	s_waitcnt vmcnt(0) lgkmcnt(0)
	v_mfma_f32_32x32x16_bf16 v[48:63], v[102:105], v[86:89], v[48:63]
	global_load_dwordx4 v[86:89], v[76:77], off offset:160
	v_mfma_f32_32x32x16_bf16 v[32:47], v[102:105], v[90:93], v[32:47]
	global_load_dwordx4 v[90:93], v[74:75], off offset:160
	v_mfma_f32_32x32x16_bf16 v[16:31], v[102:105], v[94:97], v[16:31]
	global_load_dwordx4 v[94:97], v[118:119], off offset:160
	v_mfma_f32_32x32x16_bf16 v[0:15], v[102:105], v[98:101], v[0:15]
	global_load_dwordx4 v[98:101], v[120:121], off offset:192
	global_load_dwordx4 v[102:105], v[76:77], off offset:192
	v_mfma_f32_32x32x16_bf16 v[48:63], v[110:113], v[106:109], v[48:63]
	ds_read_b128 v[106:109], v64 offset:192
	s_waitcnt vmcnt(0) lgkmcnt(0)
	v_mfma_f32_32x32x16_bf16 v[32:47], v[110:113], v[86:89], v[32:47]
	global_load_dwordx4 v[86:89], v[74:75], off offset:192
	v_mfma_f32_32x32x16_bf16 v[16:31], v[110:113], v[90:93], v[16:31]
	global_load_dwordx4 v[90:93], v[118:119], off offset:192
	v_mfma_f32_32x32x16_bf16 v[0:15], v[110:113], v[94:97], v[0:15]
	global_load_dwordx4 v[94:97], v[120:121], off offset:224
	ds_read_b128 v[110:113], v64 offset:224
	v_mfma_f32_32x32x16_bf16 v[48:63], v[106:109], v[98:101], v[48:63]
	global_load_dwordx4 v[98:101], v[76:77], off offset:224
	v_mfma_f32_32x32x16_bf16 v[32:47], v[106:109], v[102:105], v[32:47]
	s_waitcnt vmcnt(0) lgkmcnt(0)
	v_mfma_f32_32x32x16_bf16 v[16:31], v[106:109], v[86:89], v[16:31]
	global_load_dwordx4 v[86:89], v[118:119], off offset:224
	s_nop 0
	global_load_dwordx4 v[74:77], v[74:75], off offset:224
	v_mfma_f32_32x32x16_bf16 v[0:15], v[106:109], v[90:93], v[0:15]
	v_mfma_f32_32x32x16_bf16 v[48:63], v[110:113], v[94:97], v[48:63]
	v_mfma_f32_32x32x16_bf16 v[32:47], v[110:113], v[98:101], v[32:47]
	s_waitcnt vmcnt(0) lgkmcnt(0)
	v_mfma_f32_32x32x16_bf16 v[16:31], v[110:113], v[74:77], v[16:31]
	s_nop 11
	v_cvt_pk_bf16_f32 v208, v16, v17
	v_cvt_pk_bf16_f32 v209, v18, v19
	v_mfma_f32_32x32x16_bf16 v[0:15], v[110:113], v[86:89], v[0:15]
	s_nop 11
	v_cvt_pk_bf16_f32 v210, v0, v1
	v_cvt_pk_bf16_f32 v211, v2, v3
	v_lshrrev_b32_e32 v74, 3, v79
	v_and_b32_e32 v74, 4, v74
	s_nop 5
	v_bfe_u32 v76, v48, 16, 1
	v_and_b32_e32 v64, 0xffffffc0, v79
	v_add3_u32 v48, v48, v76, s58
	v_mul_u32_u24_e32 v76, 0x108, v74
	v_or_b32_e32 v75, v64, v80
	v_lshlrev_b32_e32 v76, 1, v76
	v_lshl_add_u32 v75, v75, 1, v76
	ds_write_b16_d16_hi v75, v48 offset:16896
	v_bfe_u32 v48, v49, 16, 1
	v_add3_u32 v48, v49, v48, s58
	ds_write_b16_d16_hi v75, v48 offset:17424
	v_bfe_u32 v48, v50, 16, 1
	v_add3_u32 v48, v50, v48, s58
	ds_write_b16_d16_hi v75, v48 offset:17952
	v_bfe_u32 v48, v51, 16, 1
	v_add3_u32 v48, v51, v48, s58
	ds_write_b16_d16_hi v75, v48 offset:18480
	v_bfe_u32 v48, v52, 16, 1
	v_add3_u32 v48, v52, v48, s58
	ds_write_b16_d16_hi v75, v48 offset:21120
	v_bfe_u32 v48, v53, 16, 1
	v_add3_u32 v48, v53, v48, s58
	ds_write_b16_d16_hi v75, v48 offset:21648
	v_bfe_u32 v48, v54, 16, 1
	v_add3_u32 v48, v54, v48, s58
	ds_write_b16_d16_hi v75, v48 offset:22176
	v_bfe_u32 v48, v55, 16, 1
	v_add3_u32 v48, v55, v48, s58
	ds_write_b16_d16_hi v75, v48 offset:22704
	v_bfe_u32 v48, v56, 16, 1
	v_add3_u32 v48, v56, v48, s58
	ds_write_b16_d16_hi v75, v48 offset:25344
	v_bfe_u32 v48, v57, 16, 1
	v_add3_u32 v48, v57, v48, s58
	ds_write_b16_d16_hi v75, v48 offset:25872
	v_bfe_u32 v48, v58, 16, 1
	v_add3_u32 v48, v58, v48, s58
	ds_write_b16_d16_hi v75, v48 offset:26400
	v_bfe_u32 v48, v59, 16, 1
	v_add3_u32 v48, v59, v48, s58
	ds_write_b16_d16_hi v75, v48 offset:26928
	v_bfe_u32 v48, v60, 16, 1
	v_add3_u32 v48, v60, v48, s58
	ds_write_b16_d16_hi v75, v48 offset:29568
	v_bfe_u32 v48, v61, 16, 1
	v_add3_u32 v48, v61, v48, s58
	ds_write_b16_d16_hi v75, v48 offset:30096
	v_bfe_u32 v48, v62, 16, 1
	v_add3_u32 v48, v62, v48, s58
	ds_write_b16_d16_hi v75, v48 offset:30624
	v_bfe_u32 v48, v63, 16, 1
	v_add3_u32 v48, v63, v48, s58
	ds_write_b16_d16_hi v75, v48 offset:31152
	v_bfe_u32 v48, v32, 16, 1
	v_add3_u32 v32, v32, v48, s58
	ds_write_b16_d16_hi v75, v32 offset:16960
	v_bfe_u32 v32, v33, 16, 1
	v_add3_u32 v32, v33, v32, s58
	ds_write_b16_d16_hi v75, v32 offset:17488
	v_bfe_u32 v32, v34, 16, 1
	v_add3_u32 v32, v34, v32, s58
	ds_write_b16_d16_hi v75, v32 offset:18016
	v_bfe_u32 v32, v35, 16, 1
	v_add3_u32 v32, v35, v32, s58
	ds_write_b16_d16_hi v75, v32 offset:18544
	v_bfe_u32 v32, v36, 16, 1
	v_add3_u32 v32, v36, v32, s58
	ds_write_b16_d16_hi v75, v32 offset:21184
	v_bfe_u32 v32, v37, 16, 1
	v_add3_u32 v32, v37, v32, s58
	ds_write_b16_d16_hi v75, v32 offset:21712
	v_bfe_u32 v32, v38, 16, 1
	v_add3_u32 v32, v38, v32, s58
	ds_write_b16_d16_hi v75, v32 offset:22240
	v_bfe_u32 v32, v39, 16, 1
	v_add3_u32 v32, v39, v32, s58
	ds_write_b16_d16_hi v75, v32 offset:22768
	v_bfe_u32 v32, v40, 16, 1
	v_add3_u32 v32, v40, v32, s58
	ds_write_b16_d16_hi v75, v32 offset:25408
	v_bfe_u32 v32, v41, 16, 1
	v_add3_u32 v32, v41, v32, s58
	ds_write_b16_d16_hi v75, v32 offset:25936
	v_bfe_u32 v32, v42, 16, 1
	v_add3_u32 v32, v42, v32, s58
	ds_write_b16_d16_hi v75, v32 offset:26464
	v_bfe_u32 v32, v43, 16, 1
	v_add3_u32 v32, v43, v32, s58
	ds_write_b16_d16_hi v75, v32 offset:26992
	v_bfe_u32 v32, v44, 16, 1
	v_add3_u32 v32, v44, v32, s58
	ds_write_b16_d16_hi v75, v32 offset:29632
	v_bfe_u32 v32, v45, 16, 1
	v_add3_u32 v32, v45, v32, s58
	ds_write_b16_d16_hi v75, v32 offset:30160
	v_bfe_u32 v32, v46, 16, 1
	v_add3_u32 v32, v46, v32, s58
	ds_write_b16_d16_hi v75, v32 offset:30688
	v_bfe_u32 v32, v47, 16, 1
	v_add3_u32 v32, v47, v32, s58
	ds_write_b16_d16_hi v75, v32 offset:31216
	v_lshl_add_u32 v32, s13, 8, v64
	s_ashr_i32 s13, s12, 31
	s_lshl_b64 s[0:1], s[12:13], 1
	v_bfe_u32 v37, v17, 16, 1
	s_add_u32 s0, s8, s0
	s_addc_u32 s1, s9, s1
	v_lshlrev_b32_e32 v64, 1, v74
	v_mov_b32_e32 v16, v208
	v_or_b32_e32 v36, v32, v80
	v_lshl_add_u64 v[32:33], s[0:1], 0, v[64:65]
	s_mov_b64 s[0:1], 0x144d7900
	v_lshl_add_u64 v[32:33], v[32:33], 0, s[0:1]
	v_mad_i64_i32 v[34:35], s[0:1], v36, s61, v[32:33]
	v_mov_b32_e32 v17, v209
	global_store_dwordx2 v[34:35], v[16:17], off
	v_cvt_pk_bf16_f32 v16, v20, v21
	v_cvt_pk_bf16_f32 v17, v22, v23
	global_store_dwordx2 v[34:35], v[16:17], off offset:16
	v_cvt_pk_bf16_f32 v16, v24, v25
	v_cvt_pk_bf16_f32 v17, v26, v27
	global_store_dwordx2 v[34:35], v[16:17], off offset:32
	v_cvt_pk_bf16_f32 v16, v28, v29
	v_cvt_pk_bf16_f32 v17, v30, v31
	v_bfe_u32 v18, v1, 16, 1
	v_mov_b32_e32 v0, v210
	global_store_dwordx2 v[34:35], v[16:17], off offset:48
	v_or_b32_e32 v16, 32, v36
	v_mad_i64_i32 v[16:17], s[0:1], v16, s61, v[32:33]
	v_mov_b32_e32 v1, v211
	global_store_dwordx2 v[16:17], v[0:1], off
	v_cvt_pk_bf16_f32 v0, v4, v5
	v_cvt_pk_bf16_f32 v1, v6, v7
	global_store_dwordx2 v[16:17], v[0:1], off offset:16
	v_cvt_pk_bf16_f32 v0, v8, v9
	v_cvt_pk_bf16_f32 v1, v10, v11
	global_store_dwordx2 v[16:17], v[0:1], off offset:32
	v_cvt_pk_bf16_f32 v0, v12, v13
	v_cvt_pk_bf16_f32 v1, v14, v15
	v_and_b32_e32 v64, 0x1f0, v78
	global_store_dwordx2 v[16:17], v[0:1], off offset:48
	v_mad_u64_u32 v[0:1], s[0:1], v81, s62, v[64:65]
	s_waitcnt lgkmcnt(0)
	s_barrier
	ds_read_b128 v[0:3], v0 offset:16896
	v_lshl_add_u64 v[4:5], s[8:9], 0, v[64:65]
	s_mov_b64 s[0:1], 0x13097900
	v_lshl_add_u64 v[4:5], v[4:5], 0, s[0:1]
	v_lshlrev_b64 v[6:7], 9, v[66:67]
	v_lshl_add_u64 v[6:7], v[4:5], 0, v[6:7]
	s_waitcnt lgkmcnt(0)
	global_store_dwordx4 v[6:7], v[0:3], off
	v_lshlrev_b64 v[6:7], 9, v[68:69]
	v_lshl_add_u64 v[6:7], v[4:5], 0, v[6:7]
	v_mad_u64_u32 v[0:1], s[0:1], v82, s62, v[64:65]
	ds_read_b128 v[0:3], v0 offset:16896
	s_waitcnt lgkmcnt(0)
	global_store_dwordx4 v[6:7], v[0:3], off
	s_nop 1
	v_mad_u64_u32 v[0:1], s[0:1], v83, s62, v[64:65]
	ds_read_b128 v[0:3], v0 offset:16896
	v_lshlrev_b64 v[6:7], 9, v[70:71]
	v_lshl_add_u64 v[6:7], v[4:5], 0, v[6:7]
	s_waitcnt lgkmcnt(0)
	global_store_dwordx4 v[6:7], v[0:3], off
	s_nop 1
	v_mad_u64_u32 v[0:1], s[0:1], v84, s62, v[64:65]
	ds_read_b128 v[0:3], v0 offset:16896
	v_lshlrev_b64 v[6:7], 9, v[72:73]
	v_lshl_add_u64 v[4:5], v[4:5], 0, v[6:7]
	s_mov_b64 s[0:1], 0
	s_waitcnt lgkmcnt(0)
	global_store_dwordx4 v[4:5], v[0:3], off
.LBB0_387:
	s_and_b64 vcc, exec, s[0:1]
	s_cbranch_vccz .LBB0_434
	s_mov_b64 s[0:1], s[30:31]
	v_mov_b32_e32 v0, v65
	s_nop 0
	v_mbcnt_lo_u32_b32 v0, -1, v0
	v_mbcnt_hi_u32_b32 v0, -1, v0
	v_add_u32_e32 v48, s33, v0
	v_mov_b64_e32 v[0:1], s[0:1]
	v_ashrrev_i32_e32 v49, 3, v48
	v_add_u32_e32 v2, s18, v49
	v_mad_i64_i32 v[0:1], s[4:5], v2, s34, v[0:1]
	v_mov_b32_e32 v2, s0
	v_mov_b32_e32 v3, s1
	v_add_co_u32_e32 v2, vcc, s55, v2
	v_lshlrev_b32_e32 v4, 5, v48
	s_nop 0
	v_addc_co_u32_e32 v3, vcc, 0, v3, vcc
	global_load_dwordx2 v[2:3], v[2:3], off offset:488
	v_and_b32_e32 v10, 0xe0, v4
	v_lshlrev_b32_e32 v64, 1, v10
	v_lshl_add_u64 v[0:1], v[0:1], 0, v[64:65]
	s_mov_b64 s[4:5], 0x7157f00
	v_lshl_add_u64 v[8:9], v[0:1], 0, s[4:5]
	s_mov_b32 s4, 0x7157000
	v_add_co_u32_e32 v0, vcc, s4, v0
	global_load_dwordx4 v[4:7], v[8:9], off offset:48
	global_load_dwordx4 v[12:15], v[8:9], off offset:16
	global_load_dwordx4 v[16:19], v[8:9], off offset:32
	v_addc_co_u32_e32 v1, vcc, 0, v1, vcc
	global_load_dwordx4 v[20:23], v[0:1], off offset:3840
	v_mov_b32_e32 v1, v65
	v_lshlrev_b32_e32 v0, 2, v10
	s_waitcnt lgkmcnt(0)
	s_barrier
	s_waitcnt vmcnt(0)
	v_readfirstlane_b32 s5, v3
	v_readfirstlane_b32 s4, v2
	v_and_b32_e32 v3, 0xffff0000, v5
	s_nop 0
	v_lshl_add_u64 v[10:11], s[4:5], 0, v[0:1]
	global_load_dwordx4 v[24:27], v[10:11], off
	global_load_dwordx4 v[28:31], v[10:11], off offset:16
	v_lshlrev_b32_e32 v41, 16, v17
	v_lshlrev_b32_e32 v40, 16, v16
	v_and_b32_e32 v43, 0xffff0000, v17
	v_and_b32_e32 v42, 0xffff0000, v16
	v_and_b32_e32 v17, 0xffff0000, v21
	v_and_b32_e32 v16, 0xffff0000, v20
	v_lshlrev_b32_e32 v37, 16, v15
	v_lshlrev_b32_e32 v36, 16, v14
	v_and_b32_e32 v39, 0xffff0000, v15
	v_and_b32_e32 v38, 0xffff0000, v14
	v_lshlrev_b32_e32 v15, 16, v21
	v_lshlrev_b32_e32 v14, 16, v20
	v_and_b32_e32 v21, 0xffff0000, v23
	v_and_b32_e32 v20, 0xffff0000, v22
	v_pk_mul_f32 v[56:57], v[16:17], v[16:17]
	v_lshlrev_b32_e32 v45, 16, v19
	v_lshlrev_b32_e32 v44, 16, v18
	v_and_b32_e32 v47, 0xffff0000, v19
	v_and_b32_e32 v46, 0xffff0000, v18
	v_lshlrev_b32_e32 v19, 16, v23
	v_lshlrev_b32_e32 v18, 16, v22
	v_pk_mul_f32 v[58:59], v[20:21], v[20:21]
	v_pk_fma_f32 v[56:57], v[14:15], v[14:15], v[56:57]
	v_and_b32_e32 v35, 0xffff0000, v13
	v_and_b32_e32 v34, 0xffff0000, v12
	v_pk_fma_f32 v[58:59], v[18:19], v[18:19], v[58:59]
	v_add_f32_e32 v56, v56, v57
	v_lshlrev_b32_e32 v33, 16, v13
	v_lshlrev_b32_e32 v32, 16, v12
	v_pk_mul_f32 v[22:23], v[34:35], v[34:35]
	v_add_f32_e32 v56, v58, v56
	v_pk_fma_f32 v[22:23], v[32:33], v[32:33], v[22:23]
	v_add_f32_e32 v56, v59, v56
	v_pk_mul_f32 v[50:51], v[38:39], v[38:39]
	v_add_f32_e32 v22, v22, v56
	v_pk_fma_f32 v[50:51], v[36:37], v[36:37], v[50:51]
	v_add_f32_e32 v22, v23, v22
	v_pk_mul_f32 v[52:53], v[42:43], v[42:43]
	v_add_f32_e32 v22, v50, v22
	v_pk_fma_f32 v[52:53], v[40:41], v[40:41], v[52:53]
	v_add_f32_e32 v22, v51, v22
	v_pk_mul_f32 v[54:55], v[46:47], v[46:47]
	v_add_f32_e32 v22, v52, v22
	v_and_b32_e32 v2, 0xffff0000, v4
	v_pk_fma_f32 v[54:55], v[44:45], v[44:45], v[54:55]
	v_add_f32_e32 v22, v53, v22
	v_lshlrev_b32_e32 v1, 16, v5
	v_lshlrev_b32_e32 v0, 16, v4
	v_pk_mul_f32 v[8:9], v[2:3], v[2:3]
	v_add_f32_e32 v22, v54, v22
	v_lshlrev_b32_e32 v5, 16, v7
	v_lshlrev_b32_e32 v4, 16, v6
	v_and_b32_e32 v7, 0xffff0000, v7
	v_and_b32_e32 v6, 0xffff0000, v6
	v_pk_fma_f32 v[8:9], v[0:1], v[0:1], v[8:9]
	v_add_f32_e32 v22, v55, v22
	v_pk_mul_f32 v[12:13], v[6:7], v[6:7]
	v_add_f32_e32 v8, v8, v22
	v_pk_fma_f32 v[12:13], v[4:5], v[4:5], v[12:13]
	v_add_f32_e32 v8, v9, v8
	v_add_f32_e32 v8, v12, v8
	v_add_f32_e32 v8, v13, v8
	v_and_b32_e32 v57, 31, v48
	s_waitcnt vmcnt(0) lgkmcnt(0)
	v_mov_b32_e32 v22, v24
	v_add_f32_dpp v8, v8, v8 quad_perm:[1,0,3,2] row_mask:0xf bank_mask:0xf bound_ctrl:1
	v_mov_b32_e32 v23, v26
	v_mov_b32_e32 v26, v25
	v_add_f32_dpp v8, v8, v8 quad_perm:[2,3,0,1] row_mask:0xf bank_mask:0xf bound_ctrl:1
	v_mov_b32_e32 v24, v28
	v_mov_b32_e32 v25, v30
	v_add_f32_dpp v8, v8, v8 row_half_mirror row_mask:0xf bank_mask:0xf bound_ctrl:1
	v_fmamk_f32 v8, v8, 0x3b800000, v127
	v_mul_f32_e32 v9, 0x4b800000, v8
	v_cmp_gt_f32_e32 vcc, s57, v8
	v_mov_b32_e32 v30, v29
	s_nop 0
	v_cndmask_b32_e32 v8, v8, v9, vcc
	v_rsq_f32_e32 v12, v8
	v_mad_u64_u32 v[8:9], s[4:5], v49, s62, v[64:65]
	s_movk_i32 s4, 0x60
	v_mul_f32_e32 v9, 0x45800000, v12
	v_cndmask_b32_e32 v12, v12, v9, vcc
	v_pk_mul_f32 v[14:15], v[12:13], v[14:15] op_sel_hi:[0,1]
	v_pk_mul_f32 v[16:17], v[12:13], v[16:17] op_sel_hi:[0,1]
	v_pk_mul_f32 v[18:19], v[12:13], v[18:19] op_sel_hi:[0,1]
	v_pk_mul_f32 v[20:21], v[12:13], v[20:21] op_sel_hi:[0,1]
	v_pk_mul_f32 v[14:15], v[22:23], v[14:15]
	v_pk_mul_f32 v[16:17], v[26:27], v[16:17]
	s_nop 0
	v_cvt_pk_bf16_f32 v209, v15, v17
	v_cvt_pk_bf16_f32 v210, v14, v16
	v_pk_mul_f32 v[18:19], v[24:25], v[18:19]
	v_pk_mul_f32 v[20:21], v[30:31], v[20:21]
	s_nop 0
	v_cvt_pk_bf16_f32 v208, v18, v20
	v_bfe_u32 v13, v20, 16, 1
	v_add3_u32 v13, v20, v13, s58
	v_cvt_pk_bf16_f32 v17, v19, v21
	v_mov_b32_e32 v16, v208
	v_mov_b32_e32 v15, v209
	v_mov_b32_e32 v14, v210
	ds_write_b128 v8, v[14:17]
	global_load_dwordx4 v[14:17], v[10:11], off offset:32
	global_load_dwordx4 v[18:21], v[10:11], off offset:48
	v_pk_mul_f32 v[22:23], v[12:13], v[32:33] op_sel_hi:[0,1]
	v_pk_mul_f32 v[24:25], v[12:13], v[34:35] op_sel_hi:[0,1]
	v_pk_mul_f32 v[26:27], v[12:13], v[36:37] op_sel_hi:[0,1]
	v_pk_mul_f32 v[28:29], v[12:13], v[38:39] op_sel_hi:[0,1]
	s_mov_b32 s5, 0x16e0000
	s_waitcnt vmcnt(0) lgkmcnt(0)
	v_mov_b32_e32 v30, v14
	v_mov_b32_e32 v31, v16
	v_mov_b32_e32 v16, v15
	v_mov_b32_e32 v14, v18
	v_mov_b32_e32 v15, v20
	v_mov_b32_e32 v20, v19
	v_pk_mul_f32 v[18:19], v[30:31], v[22:23]
	v_pk_mul_f32 v[16:17], v[16:17], v[24:25]
	s_nop 0
	v_cvt_pk_bf16_f32 v210, v19, v17
	v_cvt_pk_bf16_f32 v211, v18, v16
	v_pk_mul_f32 v[14:15], v[14:15], v[26:27]
	v_pk_mul_f32 v[20:21], v[20:21], v[28:29]
	s_nop 0
	v_cvt_pk_bf16_f32 v208, v15, v21
	v_cvt_pk_bf16_f32 v209, v14, v20
	v_bfe_u32 v13, v20, 16, 1
	v_add3_u32 v13, v20, v13, s58
	v_mov_b32_e32 v17, v208
	v_mov_b32_e32 v16, v209
	v_mov_b32_e32 v15, v210
	v_mov_b32_e32 v14, v211
	ds_write_b128 v8, v[14:17] offset:16
	global_load_dwordx4 v[14:17], v[10:11], off offset:64
	global_load_dwordx4 v[18:21], v[10:11], off offset:80
	v_pk_mul_f32 v[22:23], v[12:13], v[40:41] op_sel_hi:[0,1]
	v_pk_mul_f32 v[24:25], v[12:13], v[42:43] op_sel_hi:[0,1]
	v_pk_mul_f32 v[26:27], v[12:13], v[44:45] op_sel_hi:[0,1]
	v_pk_mul_f32 v[28:29], v[12:13], v[46:47] op_sel_hi:[0,1]
	s_waitcnt vmcnt(0) lgkmcnt(0)
	v_mov_b32_e32 v30, v14
	v_mov_b32_e32 v31, v16
	v_mov_b32_e32 v16, v15
	v_mov_b32_e32 v14, v18
	v_mov_b32_e32 v15, v20
	v_mov_b32_e32 v20, v19
	v_pk_mul_f32 v[18:19], v[30:31], v[22:23]
	v_pk_mul_f32 v[16:17], v[16:17], v[24:25]
	s_nop 0
	v_cvt_pk_bf16_f32 v210, v19, v17
	v_cvt_pk_bf16_f32 v211, v18, v16
	v_pk_mul_f32 v[14:15], v[26:27], v[14:15]
	v_pk_mul_f32 v[20:21], v[28:29], v[20:21]
	s_nop 0
	v_cvt_pk_bf16_f32 v208, v15, v21
	v_cvt_pk_bf16_f32 v209, v14, v20
	v_bfe_u32 v13, v20, 16, 1
	v_add3_u32 v13, v20, v13, s58
	v_mov_b32_e32 v17, v208
	v_mov_b32_e32 v16, v209
	v_mov_b32_e32 v15, v210
	v_mov_b32_e32 v14, v211
	ds_write_b128 v8, v[14:17] offset:32
	global_load_dwordx4 v[14:17], v[10:11], off offset:96
	global_load_dwordx4 v[18:21], v[10:11], off offset:112
	v_ashrrev_i32_e32 v10, 6, v48
	v_mul_lo_u32 v56, v10, s4
	v_pk_mul_f32 v[0:1], v[12:13], v[0:1] op_sel_hi:[0,1]
	v_pk_mul_f32 v[2:3], v[12:13], v[2:3] op_sel_hi:[0,1]
	v_pk_mul_f32 v[4:5], v[12:13], v[4:5] op_sel_hi:[0,1]
	v_pk_mul_f32 v[6:7], v[12:13], v[6:7] op_sel_hi:[0,1]
	v_mov_b32_e32 v9, v65
	s_mov_b32 s4, 0x16e4000
	s_waitcnt vmcnt(0) lgkmcnt(0)
	v_mov_b32_e32 v10, v14
	v_mov_b32_e32 v11, v16
	v_mov_b32_e32 v12, v18
	v_mov_b32_e32 v13, v20
	v_mov_b32_e32 v16, v15
	v_mov_b32_e32 v20, v19
	v_pk_mul_f32 v[0:1], v[0:1], v[10:11]
	v_pk_mul_f32 v[4:5], v[4:5], v[12:13]
	v_pk_mul_f32 v[2:3], v[2:3], v[16:17]
	s_nop 0
	v_cvt_pk_bf16_f32 v210, v1, v3
	v_cvt_pk_bf16_f32 v211, v0, v2
	v_pk_mul_f32 v[6:7], v[6:7], v[20:21]
	s_nop 0
	v_cvt_pk_bf16_f32 v208, v5, v7
	v_cvt_pk_bf16_f32 v209, v4, v6
	v_mov_b32_e32 v3, v208
	v_mov_b32_e32 v2, v209
	v_mov_b32_e32 v1, v210
	v_mov_b32_e32 v0, v211
	ds_write_b128 v8, v[0:3] offset:48
	s_waitcnt lgkmcnt(0)
	s_barrier
	s_nop 0
	v_mbcnt_lo_u32_b32 v0, -1, v9
	v_mbcnt_hi_u32_b32 v0, -1, v0
	v_and_b32_e32 v14, 31, v0
	v_ashrrev_i32_e32 v1, 2, v0
	v_or_b32_e32 v0, v14, v56
	v_and_b32_e32 v12, -8, v1
	v_ashrrev_i32_e32 v1, 31, v0
	v_lshlrev_b64 v[0:1], 9, v[0:1]
	v_ashrrev_i32_e32 v13, 31, v12
	v_lshl_add_u64 v[0:1], s[0:1], 0, v[0:1]
	v_lshl_add_u64 v[16:17], v[12:13], 1, v[0:1]
	v_add_co_u32_e32 v0, vcc, s5, v16
	v_lshlrev_b32_e32 v12, 1, v12
	s_nop 0
	v_addc_co_u32_e32 v1, vcc, 0, v17, vcc
	global_load_dwordx4 v[0:3], v[0:1], off
	v_add_co_u32_e32 v50, vcc, s4, v16
	s_mov_b32 s4, 0x16e8000
	s_nop 0
	v_addc_co_u32_e32 v51, vcc, 0, v17, vcc
	v_add_co_u32_e32 v52, vcc, s4, v16
	s_mov_b64 s[4:5], 0x16e0000
	v_lshl_add_u64 v[54:55], v[16:17], 0, s[4:5]
	global_load_dwordx4 v[58:61], v[54:55], off offset:32
	v_mad_u32_u24 v49, v14, s62, v12
	ds_read_b128 v[12:15], v49
	ds_read_b128 v[66:69], v49 offset:32
	global_load_dwordx4 v[4:7], v[50:51], off
	v_addc_co_u32_e32 v53, vcc, 0, v17, vcc
	global_load_dwordx4 v[8:11], v[52:53], off
	global_load_dwordx4 v[70:73], v[50:51], off offset:32
	s_waitcnt vmcnt(0) lgkmcnt(0)
	v_mfma_f32_32x32x16_bf16 v[32:47], v[12:15], v[0:3], 0
	global_load_dwordx4 v[74:77], v[52:53], off offset:32
	global_load_dwordx4 v[78:81], v[50:51], off offset:96
	global_load_dwordx4 v[82:85], v[54:55], off offset:64
	s_and_b32 s4, 0xffff, s26
	s_mul_i32 s4, s4, 0xe38f
	s_lshr_b32 s4, s4, 22
	s_mulk_i32 s4, 0xf700
	s_add_i32 s4, s4, s18
	v_mfma_f32_32x32x16_bf16 v[32:47], v[66:69], v[58:61], v[32:47]
	global_load_dwordx4 v[58:61], v[50:51], off offset:64
	v_mfma_f32_32x32x16_bf16 v[16:31], v[12:15], v[4:7], 0
	v_mfma_f32_32x32x16_bf16 v[0:15], v[12:15], v[8:11], 0
	v_mfma_f32_32x32x16_bf16 v[16:31], v[66:69], v[70:73], v[16:31]
	global_load_dwordx4 v[70:73], v[52:53], off offset:64
	s_waitcnt vmcnt(0) lgkmcnt(0)
	v_mfma_f32_32x32x16_bf16 v[0:15], v[66:69], v[74:77], v[0:15]
	ds_read_b128 v[66:69], v49 offset:64
	ds_read_b128 v[74:77], v49 offset:96
	s_waitcnt lgkmcnt(1)
	v_mfma_f32_32x32x16_bf16 v[16:31], v[66:69], v[58:61], v[16:31]
	global_load_dwordx4 v[58:61], v[54:55], off offset:96
	v_mfma_f32_32x32x16_bf16 v[32:47], v[66:69], v[82:85], v[32:47]
	s_waitcnt vmcnt(0) lgkmcnt(0)
	v_mfma_f32_32x32x16_bf16 v[32:47], v[74:77], v[58:61], v[32:47]
	global_load_dwordx4 v[58:61], v[52:53], off offset:96
	v_mfma_f32_32x32x16_bf16 v[0:15], v[66:69], v[70:73], v[0:15]
	v_mfma_f32_32x32x16_bf16 v[16:31], v[74:77], v[78:81], v[16:31]
	s_waitcnt vmcnt(0) lgkmcnt(0)
	v_mfma_f32_32x32x16_bf16 v[0:15], v[74:77], v[58:61], v[0:15]
	global_load_dwordx4 v[58:61], v[54:55], off offset:128
	global_load_dwordx4 v[66:69], v[50:51], off offset:128
	global_load_dwordx4 v[70:73], v[52:53], off offset:128
	global_load_dwordx4 v[74:77], v[54:55], off offset:160
	ds_read_b128 v[78:81], v49 offset:128
	ds_read_b128 v[82:85], v49 offset:160
	s_waitcnt vmcnt(0) lgkmcnt(0)
	v_mfma_f32_32x32x16_bf16 v[32:47], v[78:81], v[58:61], v[32:47]
	global_load_dwordx4 v[58:61], v[50:51], off offset:160
	v_mfma_f32_32x32x16_bf16 v[16:31], v[78:81], v[66:69], v[16:31]
	global_load_dwordx4 v[66:69], v[52:53], off offset:160
	v_mfma_f32_32x32x16_bf16 v[0:15], v[78:81], v[70:73], v[0:15]
	global_load_dwordx4 v[70:73], v[54:55], off offset:192
	ds_read_b128 v[78:81], v49 offset:192
	v_mfma_f32_32x32x16_bf16 v[32:47], v[82:85], v[74:77], v[32:47]
	global_load_dwordx4 v[74:77], v[50:51], off offset:192
	s_waitcnt vmcnt(0) lgkmcnt(0)
	v_mfma_f32_32x32x16_bf16 v[16:31], v[82:85], v[58:61], v[16:31]
	global_load_dwordx4 v[58:61], v[52:53], off offset:192
	v_mfma_f32_32x32x16_bf16 v[0:15], v[82:85], v[66:69], v[0:15]
	global_load_dwordx4 v[66:69], v[54:55], off offset:224
	ds_read_b128 v[82:85], v49 offset:224
	v_mfma_f32_32x32x16_bf16 v[32:47], v[78:81], v[70:73], v[32:47]
	global_load_dwordx4 v[70:73], v[50:51], off offset:224
	v_mfma_f32_32x32x16_bf16 v[16:31], v[78:81], v[74:77], v[16:31]
	global_load_dwordx4 v[74:77], v[52:53], off offset:224
	s_waitcnt vmcnt(0) lgkmcnt(0)
	v_mfma_f32_32x32x16_bf16 v[0:15], v[78:81], v[58:61], v[0:15]
	v_mfma_f32_32x32x16_bf16 v[16:31], v[82:85], v[70:73], v[16:31]
	v_mfma_f32_32x32x16_bf16 v[0:15], v[82:85], v[74:77], v[0:15]
	v_mfma_f32_32x32x16_bf16 v[32:47], v[82:85], v[66:69], v[32:47]
	global_load_dwordx4 v[58:61], v[54:55], off offset:256
	global_load_dwordx4 v[66:69], v[50:51], off offset:256
	global_load_dwordx4 v[70:73], v[52:53], off offset:256
	global_load_dwordx4 v[74:77], v[54:55], off offset:288
	ds_read_b128 v[78:81], v49 offset:256
	ds_read_b128 v[82:85], v49 offset:288
	s_waitcnt vmcnt(0) lgkmcnt(0)
	v_mfma_f32_32x32x16_bf16 v[32:47], v[78:81], v[58:61], v[32:47]
	global_load_dwordx4 v[58:61], v[50:51], off offset:288
	v_mfma_f32_32x32x16_bf16 v[16:31], v[78:81], v[66:69], v[16:31]
	global_load_dwordx4 v[66:69], v[52:53], off offset:288
	v_mfma_f32_32x32x16_bf16 v[0:15], v[78:81], v[70:73], v[0:15]
	global_load_dwordx4 v[70:73], v[54:55], off offset:320
	ds_read_b128 v[78:81], v49 offset:320
	v_mfma_f32_32x32x16_bf16 v[32:47], v[82:85], v[74:77], v[32:47]
	global_load_dwordx4 v[74:77], v[50:51], off offset:320
	s_waitcnt vmcnt(0) lgkmcnt(0)
	v_mfma_f32_32x32x16_bf16 v[16:31], v[82:85], v[58:61], v[16:31]
	global_load_dwordx4 v[58:61], v[52:53], off offset:320
	v_mfma_f32_32x32x16_bf16 v[0:15], v[82:85], v[66:69], v[0:15]
	global_load_dwordx4 v[66:69], v[54:55], off offset:352
	ds_read_b128 v[82:85], v49 offset:352
	v_mfma_f32_32x32x16_bf16 v[32:47], v[78:81], v[70:73], v[32:47]
	global_load_dwordx4 v[70:73], v[50:51], off offset:352
	v_mfma_f32_32x32x16_bf16 v[16:31], v[78:81], v[74:77], v[16:31]
	global_load_dwordx4 v[74:77], v[52:53], off offset:352
	s_waitcnt vmcnt(0) lgkmcnt(0)
	v_mfma_f32_32x32x16_bf16 v[0:15], v[78:81], v[58:61], v[0:15]
	v_mfma_f32_32x32x16_bf16 v[16:31], v[82:85], v[70:73], v[16:31]
	v_mfma_f32_32x32x16_bf16 v[0:15], v[82:85], v[74:77], v[0:15]
	v_mfma_f32_32x32x16_bf16 v[32:47], v[82:85], v[66:69], v[32:47]
	global_load_dwordx4 v[58:61], v[54:55], off offset:384
	global_load_dwordx4 v[66:69], v[50:51], off offset:384
	global_load_dwordx4 v[70:73], v[52:53], off offset:384
	global_load_dwordx4 v[74:77], v[54:55], off offset:416
	ds_read_b128 v[78:81], v49 offset:384
	ds_read_b128 v[82:85], v49 offset:416
	s_waitcnt vmcnt(0) lgkmcnt(0)
	v_mfma_f32_32x32x16_bf16 v[32:47], v[78:81], v[58:61], v[32:47]
	global_load_dwordx4 v[58:61], v[50:51], off offset:416
	v_mfma_f32_32x32x16_bf16 v[16:31], v[78:81], v[66:69], v[16:31]
	global_load_dwordx4 v[66:69], v[52:53], off offset:416
	v_mfma_f32_32x32x16_bf16 v[0:15], v[78:81], v[70:73], v[0:15]
	global_load_dwordx4 v[70:73], v[54:55], off offset:448
	ds_read_b128 v[78:81], v49 offset:448
	v_mfma_f32_32x32x16_bf16 v[32:47], v[82:85], v[74:77], v[32:47]
	global_load_dwordx4 v[74:77], v[50:51], off offset:448
	s_waitcnt vmcnt(0) lgkmcnt(0)
	v_mfma_f32_32x32x16_bf16 v[16:31], v[82:85], v[58:61], v[16:31]
	global_load_dwordx4 v[58:61], v[52:53], off offset:448
	v_mfma_f32_32x32x16_bf16 v[0:15], v[82:85], v[66:69], v[0:15]
	global_load_dwordx4 v[66:69], v[54:55], off offset:480
	ds_read_b128 v[82:85], v49 offset:480
	v_mfma_f32_32x32x16_bf16 v[32:47], v[78:81], v[70:73], v[32:47]
	global_load_dwordx4 v[70:73], v[50:51], off offset:480
	s_nop 0
	global_load_dwordx4 v[50:53], v[52:53], off offset:480
	v_mfma_f32_32x32x16_bf16 v[16:31], v[78:81], v[74:77], v[16:31]
	s_waitcnt vmcnt(0) lgkmcnt(0)
	v_mfma_f32_32x32x16_bf16 v[0:15], v[78:81], v[58:61], v[0:15]
	v_mfma_f32_32x32x16_bf16 v[16:31], v[82:85], v[70:73], v[16:31]
	v_mfma_f32_32x32x16_bf16 v[0:15], v[82:85], v[50:53], v[0:15]
	v_mfma_f32_32x32x16_bf16 v[32:47], v[82:85], v[66:69], v[32:47]
	v_lshrrev_b32_e32 v49, 3, v48
	s_nop 10
	v_mul_f32_e32 v32, 0x3e16c740, v32
	v_and_b32_e32 v49, 4, v49
	v_lshlrev_b32_e32 v50, 1, v56
	v_bfe_u32 v52, v32, 16, 1
	v_lshl_or_b32 v51, v57, 1, v50
	v_add3_u32 v32, v32, v52, s58
	v_mul_u32_u24_e32 v52, 0x188, v49
	v_lshl_add_u32 v51, v52, 1, v51
	ds_write_b16_d16_hi v51, v32 offset:16896
	v_mul_f32_e32 v32, 0x3e16c740, v33
	v_bfe_u32 v33, v32, 16, 1
	v_add3_u32 v32, v32, v33, s58
	ds_write_b16_d16_hi v51, v32 offset:17680
	v_mul_f32_e32 v32, 0x3e16c740, v34
	v_bfe_u32 v33, v32, 16, 1
	v_add3_u32 v32, v32, v33, s58
	ds_write_b16_d16_hi v51, v32 offset:18464
	v_mul_f32_e32 v32, 0x3e16c740, v35
	v_bfe_u32 v33, v32, 16, 1
	v_add3_u32 v32, v32, v33, s58
	ds_write_b16_d16_hi v51, v32 offset:19248
	v_mul_f32_e32 v32, 0x3e16c740, v36
	v_bfe_u32 v33, v32, 16, 1
	v_add3_u32 v32, v32, v33, s58
	ds_write_b16_d16_hi v51, v32 offset:23168
	v_mul_f32_e32 v32, 0x3e16c740, v37
	v_bfe_u32 v33, v32, 16, 1
	v_add3_u32 v32, v32, v33, s58
	ds_write_b16_d16_hi v51, v32 offset:23952
	v_mul_f32_e32 v32, 0x3e16c740, v38
	v_bfe_u32 v33, v32, 16, 1
	v_add3_u32 v32, v32, v33, s58
	ds_write_b16_d16_hi v51, v32 offset:24736
	v_mul_f32_e32 v32, 0x3e16c740, v39
	v_bfe_u32 v33, v32, 16, 1
	v_add3_u32 v32, v32, v33, s58
	ds_write_b16_d16_hi v51, v32 offset:25520
	v_mul_f32_e32 v32, 0x3e16c740, v40
	v_bfe_u32 v33, v32, 16, 1
	v_add3_u32 v32, v32, v33, s58
	ds_write_b16_d16_hi v51, v32 offset:29440
	v_mul_f32_e32 v32, 0x3e16c740, v41
	v_bfe_u32 v33, v32, 16, 1
	v_add3_u32 v32, v32, v33, s58
	ds_write_b16_d16_hi v51, v32 offset:30224
	v_mul_f32_e32 v32, 0x3e16c740, v42
	v_bfe_u32 v33, v32, 16, 1
	v_add3_u32 v32, v32, v33, s58
	ds_write_b16_d16_hi v51, v32 offset:31008
	v_mul_f32_e32 v32, 0x3e16c740, v43
	v_bfe_u32 v33, v32, 16, 1
	v_add3_u32 v32, v32, v33, s58
	ds_write_b16_d16_hi v51, v32 offset:31792
	v_mul_f32_e32 v32, 0x3e16c740, v44
	v_bfe_u32 v33, v32, 16, 1
	v_add3_u32 v32, v32, v33, s58
	ds_write_b16_d16_hi v51, v32 offset:35712
	v_mul_f32_e32 v32, 0x3e16c740, v45
	v_bfe_u32 v33, v32, 16, 1
	v_add3_u32 v32, v32, v33, s58
	ds_write_b16_d16_hi v51, v32 offset:36496
	v_mul_f32_e32 v32, 0x3e16c740, v46
	v_bfe_u32 v33, v32, 16, 1
	v_add3_u32 v32, v32, v33, s58
	ds_write_b16_d16_hi v51, v32 offset:37280
	v_mul_f32_e32 v32, 0x3e16c740, v47
	v_bfe_u32 v33, v32, 16, 1
	v_add3_u32 v32, v32, v33, s58
	v_mul_f32_e32 v16, 0x3e16c740, v16
	ds_write_b16_d16_hi v51, v32 offset:38064
	v_bfe_u32 v32, v16, 16, 1
	v_add3_u32 v16, v16, v32, s58
	ds_write_b16_d16_hi v51, v16 offset:16960
	v_mul_f32_e32 v16, 0x3e16c740, v17
	v_bfe_u32 v17, v16, 16, 1
	v_add3_u32 v16, v16, v17, s58
	ds_write_b16_d16_hi v51, v16 offset:17744
	v_mul_f32_e32 v16, 0x3e16c740, v18
	v_bfe_u32 v17, v16, 16, 1
	v_add3_u32 v16, v16, v17, s58
	ds_write_b16_d16_hi v51, v16 offset:18528
	v_mul_f32_e32 v16, 0x3e16c740, v19
	v_bfe_u32 v17, v16, 16, 1
	v_add3_u32 v16, v16, v17, s58
	ds_write_b16_d16_hi v51, v16 offset:19312
	v_mul_f32_e32 v16, 0x3e16c740, v20
	v_bfe_u32 v17, v16, 16, 1
	v_add3_u32 v16, v16, v17, s58
	ds_write_b16_d16_hi v51, v16 offset:23232
	v_mul_f32_e32 v16, 0x3e16c740, v21
	v_bfe_u32 v17, v16, 16, 1
	v_add3_u32 v16, v16, v17, s58
	ds_write_b16_d16_hi v51, v16 offset:24016
	v_mul_f32_e32 v16, 0x3e16c740, v22
	v_bfe_u32 v17, v16, 16, 1
	v_add3_u32 v16, v16, v17, s58
	ds_write_b16_d16_hi v51, v16 offset:24800
	v_mul_f32_e32 v16, 0x3e16c740, v23
	v_bfe_u32 v17, v16, 16, 1
	v_add3_u32 v16, v16, v17, s58
	ds_write_b16_d16_hi v51, v16 offset:25584
	v_mul_f32_e32 v16, 0x3e16c740, v24
	v_bfe_u32 v17, v16, 16, 1
	v_add3_u32 v16, v16, v17, s58
	ds_write_b16_d16_hi v51, v16 offset:29504
	v_mul_f32_e32 v16, 0x3e16c740, v25
	v_bfe_u32 v17, v16, 16, 1
	v_add3_u32 v16, v16, v17, s58
	ds_write_b16_d16_hi v51, v16 offset:30288
	v_mul_f32_e32 v16, 0x3e16c740, v26
	v_bfe_u32 v17, v16, 16, 1
	v_add3_u32 v16, v16, v17, s58
	ds_write_b16_d16_hi v51, v16 offset:31072
	v_mul_f32_e32 v16, 0x3e16c740, v27
	v_bfe_u32 v17, v16, 16, 1
	v_add3_u32 v16, v16, v17, s58
	ds_write_b16_d16_hi v51, v16 offset:31856
	v_mul_f32_e32 v16, 0x3e16c740, v28
	v_bfe_u32 v17, v16, 16, 1
	v_add3_u32 v16, v16, v17, s58
	ds_write_b16_d16_hi v51, v16 offset:35776
	v_mul_f32_e32 v16, 0x3e16c740, v29
	v_bfe_u32 v17, v16, 16, 1
	v_add3_u32 v16, v16, v17, s58
	ds_write_b16_d16_hi v51, v16 offset:36560
	v_mul_f32_e32 v16, 0x3e16c740, v30
	v_bfe_u32 v17, v16, 16, 1
	v_add3_u32 v16, v16, v17, s58
	ds_write_b16_d16_hi v51, v16 offset:37344
	v_mul_f32_e32 v16, 0x3e16c740, v31
	v_bfe_u32 v17, v16, 16, 1
	v_add3_u32 v16, v16, v17, s58
	ds_write_b16_d16_hi v51, v16 offset:38128
	v_and_b32_e32 v16, 7, v48
	v_cvt_f32_ubyte0_e32 v16, v16
	v_mul_f32_e32 v17, 0xbfd49a78, v16
	v_cmp_gt_f32_e32 vcc, s59, v17
	v_and_b32_e32 v18, 64, v131
	v_add_u32_e32 v18, 64, v18
	v_cndmask_b32_e32 v17, 0, v129, vcc
	v_fmac_f32_e32 v17, 0xbfd49a78, v16
	v_exp_f32_e32 v16, v17
	v_xor_b32_e32 v17, 8, v131
	v_cndmask_b32_e32 v19, 0, v130, vcc
	v_cmp_lt_i32_e32 vcc, v17, v18
	s_cmpk_gt_i32 s4, 0xff
	s_cselect_b64 s[10:11], -1, 0
	v_cndmask_b32_e32 v17, v131, v17, vcc
	v_lshlrev_b32_e32 v17, 2, v17
	ds_bpermute_b32 v18, v17, v0
	s_add_i32 s5, s4, 0xffffff00
	s_ashr_i32 s12, s5, 6
	s_and_b32 s13, s18, 32
	v_ldexp_f32 v16, v16, v19
	v_and_b32_e32 v19, 8, v48
	s_cmpk_lt_i32 s4, 0x100
	v_cmp_gt_u32_e64 s[6:7], 16, v57
	v_cmp_eq_u32_e64 s[4:5], 0, v19
	s_cbranch_scc1 .LBB0_390
	v_or_b32_e32 v19, s13, v49
	v_mov_b32_e32 v20, s12
	v_cndmask_b32_e64 v19, v19, v20, s[6:7]
	v_cvt_f32_i32_e32 v19, v19
	v_mul_f32_e32 v19, v16, v19
	v_mul_f32_e32 v19, 0.15915494, v19
	v_sin_f32_e32 v20, v19
	v_cos_f32_e32 v19, v19
	s_waitcnt lgkmcnt(0)
	v_mul_f32_e32 v18, v20, v18
	v_cndmask_b32_e64 v18, v18, -v18, s[4:5]
	v_fmac_f32_e32 v18, v19, v0
	v_mov_b32_e32 v0, v18

.LBB0_423:
	v_add_u32_e32 v4, s25, v135
	v_mul_hi_i32 v2, v4, s64
	v_lshrrev_b32_e32 v3, 31, v2
	v_ashrrev_i32_e32 v2, 3, v2
	v_add_u32_e32 v5, v2, v3
	v_mad_u64_u32 v[20:21], s[0:1], v5, s66, v[0:1]
	v_add_u32_e32 v6, s18, v5
	v_mov_b64_e32 v[2:3], s[52:53]
	v_add_u32_e32 v8, s27, v5
	v_mad_i64_i32 v[6:7], s[0:1], v6, s34, v[2:3]
	v_ashrrev_i32_e32 v21, 31, v20
	v_mad_u64_u32 v[18:19], s[0:1], v5, s65, v[4:5]
	v_lshl_add_u64 v[6:7], v[20:21], 1, v[6:7]
	v_cmp_lt_i32_e32 vcc, s12, v8
	v_lshl_add_u64 v[14:15], v[6:7], 0, s[22:23]
	v_add_co_u32_e64 v6, s[0:1], s67, v6
	v_cndmask_b32_e64 v11, 0, -1, vcc
	v_cndmask_b32_e32 v10, 0, v132, vcc
	v_cmp_gt_i32_e64 s[6:7], s24, v8
	v_addc_co_u32_e64 v7, s[0:1], 0, v7, s[0:1]
	v_lshl_add_u64 v[10:11], v[14:15], 0, v[10:11]
	global_load_dwordx4 v[6:9], v[6:7], off offset:1792
	v_cndmask_b32_e64 v64, 0, v133, s[6:7]
	global_load_dwordx4 v[10:13], v[10:11], off
	v_lshl_add_u64 v[14:15], v[14:15], 0, v[64:65]
	global_load_dwordx4 v[14:17], v[14:15], off
	v_cmp_gt_i32_e64 s[4:5], 32, v18
	v_cmp_gt_i32_e64 s[0:1], 16, v18
	v_lshl_add_u32 v5, v5, 4, v1
	v_add_u32_e32 v4, 0x100, v4
	s_addk_i32 s25, 0x200
	s_cmpk_eq_i32 s25, 0x600
	s_waitcnt vmcnt(0) lgkmcnt(0)
	v_lshlrev_b32_e32 v31, 16, v7
	v_and_b32_e32 v7, 0xffff0000, v7
	v_lshlrev_b32_e32 v26, 16, v12
	v_and_b32_e32 v27, 0xffff0000, v12
	v_lshlrev_b32_e32 v29, 16, v13
	v_and_b32_e32 v30, 0xffff0000, v13
	v_lshlrev_b64 v[12:13], 2, v[20:21]
	v_and_b32_e32 v19, 0xffff0000, v10
	v_lshlrev_b32_e32 v25, 16, v11
	v_and_b32_e32 v11, 0xffff0000, v11
	v_lshl_add_u64 v[20:21], s[10:11], 0, v[12:13]
	v_lshlrev_b32_e32 v10, 16, v10
	v_lshlrev_b32_e32 v32, 16, v14
	v_lshlrev_b32_e32 v33, 16, v15
	v_and_b32_e32 v36, 0xffff0000, v15
	v_and_b32_e32 v37, 0xffff0000, v14
	v_lshlrev_b32_e32 v38, 16, v16
	v_lshlrev_b32_e32 v39, 16, v17
	v_and_b32_e32 v40, 0xffff0000, v17
	v_and_b32_e32 v41, 0xffff0000, v16
	v_lshl_add_u64 v[22:23], s[8:9], 0, v[12:13]
	v_cndmask_b32_e32 v18, 0, v10, vcc
	v_cndmask_b32_e32 v24, 0, v19, vcc
	v_cndmask_b32_e32 v19, 0, v25, vcc
	v_cndmask_b32_e32 v25, 0, v11, vcc
	global_load_dwordx4 v[10:13], v[20:21], off offset:3072
	global_load_dwordx4 v[14:17], v[22:23], off offset:3072
	v_cndmask_b32_e32 v28, 0, v27, vcc
	v_cndmask_b32_e32 v27, 0, v29, vcc
	v_cndmask_b32_e32 v29, 0, v30, vcc
	v_lshlrev_b32_e32 v30, 16, v6
	v_cndmask_b32_e64 v33, 0, v33, s[6:7]
	v_cndmask_b32_e64 v32, 0, v32, s[6:7]
	v_pk_add_f32 v[18:19], v[18:19], v[30:31] neg_lo:[0,1] neg_hi:[0,1]
	v_and_b32_e32 v6, 0xffff0000, v6
	v_pk_add_f32 v[24:25], v[24:25], v[6:7] neg_lo:[0,1] neg_hi:[0,1]
	v_cndmask_b32_e32 v26, 0, v26, vcc
	s_waitcnt vmcnt(0) lgkmcnt(0)
	v_mov_b32_e32 v34, v10
	v_mov_b32_e32 v35, v12
	v_pk_fma_f32 v[18:19], v[34:35], v[18:19], v[30:31]
	v_pk_add_f32 v[30:31], v[32:33], v[30:31] neg_lo:[0,1] neg_hi:[0,1]
	v_mov_b32_e32 v32, v14
	v_mov_b32_e32 v33, v16
	v_pk_fma_f32 v[18:19], v[30:31], v[32:33], v[18:19]
	v_cndmask_b32_e64 v31, 0, v36, s[6:7]
	v_cndmask_b32_e64 v30, 0, v37, s[6:7]
	v_mov_b32_e32 v12, v11
	v_pk_fma_f32 v[12:13], v[12:13], v[24:25], v[6:7]
	v_pk_add_f32 v[6:7], v[30:31], v[6:7] neg_lo:[0,1] neg_hi:[0,1]
	v_mov_b32_e32 v16, v15
	v_pk_fma_f32 v[6:7], v[6:7], v[16:17], v[12:13]
	v_add_f32_e32 v10, v18, v18
	v_add_f32_e32 v11, v6, v6
	v_cndmask_b32_e64 v11, v11, v6, s[0:1]
	v_mul_f32_e32 v11, 0xbfb8aa3b, v11
	v_exp_f32_e32 v12, v11
	v_add_f32_e32 v11, v19, v19
	v_cndmask_b32_e64 v10, v10, v18, s[0:1]
	v_cndmask_b32_e64 v11, v11, v19, s[0:1]
	v_mul_f32_e32 v10, 0xbfb8aa3b, v10
	v_mul_f32_e32 v11, 0xbfb8aa3b, v11
	v_exp_f32_e32 v10, v10
	v_exp_f32_e32 v11, v11
	s_nop 0
	v_pk_add_f32 v[10:11], v[10:11], 1.0 op_sel_hi:[1,0]
	s_nop 0
	v_div_scale_f32 v13, s[78:79], v11, v11, 1.0
	v_rcp_f32_e32 v14, v13
	s_nop 0
	v_fma_f32 v15, -v13, v14, 1.0
	v_fmac_f32_e32 v14, v15, v14
	v_div_scale_f32 v15, vcc, 1.0, v11, 1.0
	v_mul_f32_e32 v16, v15, v14
	v_fma_f32 v17, -v13, v16, v15
	v_fmac_f32_e32 v16, v17, v14
	v_fma_f32 v13, -v13, v16, v15
	v_div_fmas_f32 v13, v13, v14, v16
	v_div_fixup_f32 v11, v13, v11, 1.0
	v_div_scale_f32 v13, s[78:79], v10, v10, 1.0
	v_rcp_f32_e32 v14, v13
	s_nop 0
	v_fma_f32 v15, -v13, v14, 1.0
	v_fmac_f32_e32 v14, v15, v14
	v_div_scale_f32 v15, vcc, 1.0, v10, 1.0
	v_mul_f32_e32 v16, v15, v14
	v_fma_f32 v17, -v13, v16, v15
	v_fmac_f32_e32 v16, v17, v14
	v_fma_f32 v13, -v13, v16, v15
	v_div_fmas_f32 v13, v13, v14, v16
	v_div_fixup_f32 v10, v13, v10, 1.0
	v_pk_fma_f32 v[14:15], v[10:11], 2.0, -1.0 op_sel_hi:[1,0,0]
	v_and_b32_e32 v17, 0xffff0000, v9
	v_cndmask_b32_e64 v13, v18, v14, s[4:5]
	v_cndmask_b32_e64 v25, v13, v10, s[0:1]
	v_add_f32_e32 v10, v7, v7
	v_cndmask_b32_e64 v10, v10, v7, s[0:1]
	v_mul_f32_e32 v10, 0xbfb8aa3b, v10
	v_exp_f32_e32 v13, v10
	v_cndmask_b32_e64 v14, v19, v15, s[4:5]
	v_cndmask_b32_e64 v24, v14, v11, s[0:1]
	v_cndmask_b32_e64 v19, 0, v39, s[6:7]
	v_pk_add_f32 v[10:11], v[12:13], 1.0 op_sel_hi:[1,0]
	v_cndmask_b32_e64 v18, 0, v38, s[6:7]
	v_div_scale_f32 v12, s[78:79], v11, v11, 1.0
	v_rcp_f32_e32 v13, v12
	s_nop 0
	v_fma_f32 v14, -v12, v13, 1.0
	v_fmac_f32_e32 v13, v14, v13
	v_div_scale_f32 v14, vcc, 1.0, v11, 1.0
	v_mul_f32_e32 v15, v14, v13
	v_fma_f32 v16, -v12, v15, v14
	v_fmac_f32_e32 v15, v16, v13
	v_fma_f32 v12, -v12, v15, v14
	v_div_fmas_f32 v12, v12, v13, v15
	v_div_fixup_f32 v11, v12, v11, 1.0
	v_div_scale_f32 v12, s[78:79], v10, v10, 1.0
	v_rcp_f32_e32 v13, v12
	s_nop 0
	v_fma_f32 v14, -v12, v13, 1.0
	v_fmac_f32_e32 v13, v14, v13
	v_div_scale_f32 v14, vcc, 1.0, v10, 1.0
	v_mul_f32_e32 v15, v14, v13
	v_fma_f32 v16, -v12, v15, v14
	v_fmac_f32_e32 v15, v16, v13
	v_fma_f32 v12, -v12, v15, v14
	v_div_fmas_f32 v12, v12, v13, v15
	v_div_fixup_f32 v10, v12, v10, 1.0
	v_pk_fma_f32 v[12:13], v[10:11], 2.0, -1.0 op_sel_hi:[1,0,0]
	v_lshlrev_b32_e32 v15, 16, v9
	v_cndmask_b32_e64 v7, v7, v13, s[4:5]
	v_cndmask_b32_e64 v6, v6, v12, s[4:5]
	v_cndmask_b32_e64 v30, v6, v10, s[0:1]
	v_cndmask_b32_e64 v31, v7, v11, s[0:1]
	v_lshlrev_b32_e32 v14, 16, v8
	v_and_b32_e32 v16, 0xffff0000, v8
	global_load_dwordx4 v[6:9], v[20:21], off offset:3088
	global_load_dwordx4 v[10:13], v[22:23], off offset:3088
	v_pk_add_f32 v[20:21], v[26:27], v[14:15] neg_lo:[0,1] neg_hi:[0,1]
	s_waitcnt vmcnt(0) lgkmcnt(0)
	v_mov_b32_e32 v22, v6
	v_mov_b32_e32 v23, v8
	v_pk_fma_f32 v[20:21], v[20:21], v[22:23], v[14:15]
	v_pk_add_f32 v[14:15], v[18:19], v[14:15] neg_lo:[0,1] neg_hi:[0,1]
	v_mov_b32_e32 v18, v10
	v_mov_b32_e32 v19, v12
	v_pk_fma_f32 v[14:15], v[14:15], v[18:19], v[20:21]
	v_cndmask_b32_e64 v19, 0, v40, s[6:7]
	v_cndmask_b32_e64 v18, 0, v41, s[6:7]
	v_pk_add_f32 v[20:21], v[28:29], v[16:17] neg_lo:[0,1] neg_hi:[0,1]
	v_mov_b32_e32 v8, v7
	v_pk_fma_f32 v[8:9], v[20:21], v[8:9], v[16:17]
	v_pk_add_f32 v[16:17], v[18:19], v[16:17] neg_lo:[0,1] neg_hi:[0,1]
	v_mov_b32_e32 v12, v11
	v_pk_fma_f32 v[8:9], v[16:17], v[12:13], v[8:9]
	v_add_f32_e32 v6, v14, v14
	v_add_f32_e32 v7, v8, v8
	v_cndmask_b32_e64 v7, v7, v8, s[0:1]
	v_mul_f32_e32 v7, 0xbfb8aa3b, v7
	v_exp_f32_e32 v10, v7
	v_add_f32_e32 v7, v15, v15
	v_cndmask_b32_e64 v6, v6, v14, s[0:1]
	v_cndmask_b32_e64 v7, v7, v15, s[0:1]
	v_mul_f32_e32 v6, 0xbfb8aa3b, v6
	v_mul_f32_e32 v7, 0xbfb8aa3b, v7
	v_exp_f32_e32 v6, v6
	v_exp_f32_e32 v7, v7
	s_nop 0
	v_pk_add_f32 v[6:7], v[6:7], 1.0 op_sel_hi:[1,0]
	s_nop 0
	v_div_scale_f32 v11, s[6:7], v7, v7, 1.0
	v_rcp_f32_e32 v12, v11
	s_nop 0
	v_fma_f32 v13, -v11, v12, 1.0
	v_fmac_f32_e32 v12, v13, v12
	v_div_scale_f32 v13, vcc, 1.0, v7, 1.0
	v_mul_f32_e32 v16, v13, v12
	v_fma_f32 v17, -v11, v16, v13
	v_fmac_f32_e32 v16, v17, v12
	v_fma_f32 v11, -v11, v16, v13
	v_div_fmas_f32 v11, v11, v12, v16
	v_div_fixup_f32 v7, v11, v7, 1.0
	v_div_scale_f32 v11, s[6:7], v6, v6, 1.0
	v_rcp_f32_e32 v12, v11
	s_nop 0
	v_fma_f32 v13, -v11, v12, 1.0
	v_fmac_f32_e32 v12, v13, v12
	v_div_scale_f32 v13, vcc, 1.0, v6, 1.0
	v_mul_f32_e32 v16, v13, v12
	v_fma_f32 v17, -v11, v16, v13
	v_fmac_f32_e32 v16, v17, v12
	v_fma_f32 v11, -v11, v16, v13
	v_div_fmas_f32 v11, v11, v12, v16
	v_div_fixup_f32 v6, v11, v6, 1.0
	v_pk_fma_f32 v[12:13], v[6:7], 2.0, -1.0 op_sel_hi:[1,0,0]
	s_nop 0
	v_cndmask_b32_e64 v11, v14, v12, s[4:5]
	v_cndmask_b32_e64 v12, v15, v13, s[4:5]
	v_cndmask_b32_e64 v13, v11, v6, s[0:1]
	v_add_f32_e32 v6, v9, v9
	v_cndmask_b32_e64 v6, v6, v9, s[0:1]
	v_mul_f32_e32 v6, 0xbfb8aa3b, v6
	v_exp_f32_e32 v11, v6
	v_cndmask_b32_e64 v12, v12, v7, s[0:1]
	v_pk_add_f32 v[6:7], v[10:11], 1.0 op_sel_hi:[1,0]
	s_nop 0
	v_div_scale_f32 v10, s[6:7], v7, v7, 1.0
	v_rcp_f32_e32 v11, v10
	s_nop 0
	v_fma_f32 v14, -v10, v11, 1.0
	v_fmac_f32_e32 v11, v14, v11
	v_div_scale_f32 v14, vcc, 1.0, v7, 1.0
	v_mul_f32_e32 v15, v14, v11
	v_fma_f32 v16, -v10, v15, v14
	v_fmac_f32_e32 v15, v16, v11
	v_fma_f32 v10, -v10, v15, v14
	v_div_fmas_f32 v10, v10, v11, v15
	v_div_fixup_f32 v7, v10, v7, 1.0
	v_div_scale_f32 v10, s[6:7], v6, v6, 1.0
	v_rcp_f32_e32 v11, v10
	s_nop 0
	v_fma_f32 v14, -v10, v11, 1.0
	v_fmac_f32_e32 v11, v14, v11
	v_div_scale_f32 v14, vcc, 1.0, v6, 1.0
	v_mul_f32_e32 v15, v14, v11
	v_fma_f32 v16, -v10, v15, v14
	v_fmac_f32_e32 v15, v16, v11
	v_fma_f32 v10, -v10, v15, v14
	v_div_fmas_f32 v10, v10, v11, v15
	v_div_fixup_f32 v6, v10, v6, 1.0
	v_pk_fma_f32 v[10:11], v[6:7], 2.0, -1.0 op_sel_hi:[1,0,0]
	v_bfe_u32 v14, v13, 16, 1
	v_cndmask_b32_e64 v9, v9, v11, s[4:5]
	v_cndmask_b32_e64 v8, v8, v10, s[4:5]
	v_cndmask_b32_e64 v6, v8, v6, s[0:1]
	v_cndmask_b32_e64 v7, v9, v7, s[0:1]
	v_cvt_pk_bf16_f32 v208, v12, v7
	v_bfe_u32 v9, v6, 16, 1
	v_add3_u32 v6, v6, v9, s58
	v_add3_u32 v13, v13, v14, s58
	v_lshrrev_b32_e32 v8, 16, v13
	v_mov_b32_e32 v9, v208
	v_and_or_b32 v8, v6, s54, v8
	v_cvt_pk_bf16_f32 v7, v24, v31
	v_cvt_pk_bf16_f32 v6, v25, v30
	ds_write_b128 v5, v[6:9]
	v_mul_hi_i32 v5, v4, s64
	v_lshrrev_b32_e32 v6, 31, v5
	v_ashrrev_i32_e32 v5, 3, v5
	v_add_u32_e32 v6, v5, v6
	v_mad_u64_u32 v[4:5], s[0:1], v6, s65, v[4:5]
	v_mul_lo_u32 v5, v6, s66
	s_movk_i32 s0, 0x800
	v_add3_u32 v20, v0, v5, s0
	v_add_u32_e32 v7, s18, v6
	v_mad_i64_i32 v[2:3], s[0:1], v7, s34, v[2:3]
	v_ashrrev_i32_e32 v21, 31, v20
	v_lshl_add_u64 v[2:3], v[20:21], 1, v[2:3]
	v_add_u32_e32 v5, s27, v6
	v_lshl_add_u64 v[16:17], v[2:3], 0, s[22:23]
	v_add_co_u32_e64 v2, s[0:1], s67, v2
	v_cmp_lt_i32_e32 vcc, s12, v5
	s_nop 0
	v_addc_co_u32_e64 v3, s[0:1], 0, v3, s[0:1]
	v_cmp_gt_i32_e64 s[6:7], s24, v5
	global_load_dwordx4 v[8:11], v[2:3], off offset:1792
	v_cndmask_b32_e64 v3, 0, -1, vcc
	v_cndmask_b32_e32 v2, 0, v132, vcc
	v_lshl_add_u64 v[2:3], v[16:17], 0, v[2:3]
	v_cndmask_b32_e64 v64, 0, v133, s[6:7]
	global_load_dwordx4 v[12:15], v[2:3], off
	v_lshl_add_u64 v[2:3], v[16:17], 0, v[64:65]
	global_load_dwordx4 v[16:19], v[2:3], off
	v_lshlrev_b64 v[2:3], 2, v[20:21]
	v_cmp_gt_i32_e64 s[4:5], 32, v4
	v_cmp_gt_i32_e64 s[0:1], 16, v4
	v_lshl_add_u32 v6, v6, 4, v1
	v_add_u32_e32 v1, 0x2000, v1
	v_add_u32_e32 v0, 0x1000, v0
	s_waitcnt vmcnt(0) lgkmcnt(0)
	v_lshlrev_b32_e32 v29, 16, v9
	v_lshlrev_b32_e32 v28, 16, v8
	v_and_b32_e32 v9, 0xffff0000, v9
	v_and_b32_e32 v8, 0xffff0000, v8
	v_and_b32_e32 v5, 0xffff0000, v12
	v_lshlrev_b32_e32 v7, 16, v13
	v_and_b32_e32 v13, 0xffff0000, v13
	v_lshlrev_b32_e32 v24, 16, v14
	v_and_b32_e32 v14, 0xffff0000, v14
	v_lshlrev_b32_e32 v25, 16, v15
	v_and_b32_e32 v15, 0xffff0000, v15
	v_lshlrev_b32_e32 v30, 16, v16
	v_lshlrev_b32_e32 v31, 16, v17
	v_and_b32_e32 v34, 0xffff0000, v17
	v_and_b32_e32 v35, 0xffff0000, v16
	v_lshlrev_b32_e32 v36, 16, v18
	v_lshlrev_b32_e32 v37, 16, v19
	v_and_b32_e32 v38, 0xffff0000, v19
	v_and_b32_e32 v39, 0xffff0000, v18
	v_lshl_add_u64 v[16:17], s[10:11], 0, v[2:3]
	v_lshl_add_u64 v[18:19], s[8:9], 0, v[2:3]
	v_lshlrev_b32_e32 v2, 16, v12
	v_cndmask_b32_e32 v20, 0, v2, vcc
	v_cndmask_b32_e32 v22, 0, v5, vcc
	v_cndmask_b32_e32 v23, 0, v13, vcc
	v_cndmask_b32_e32 v26, 0, v14, vcc
	v_cndmask_b32_e32 v27, 0, v15, vcc
	global_load_dwordx4 v[2:5], v[16:17], off offset:3072
	global_load_dwordx4 v[12:15], v[18:19], off offset:3072
	v_cndmask_b32_e32 v21, 0, v7, vcc
	v_cndmask_b32_e64 v31, 0, v31, s[6:7]
	v_cndmask_b32_e64 v30, 0, v30, s[6:7]
	v_pk_add_f32 v[20:21], v[20:21], v[28:29] neg_lo:[0,1] neg_hi:[0,1]
	v_pk_add_f32 v[22:23], v[22:23], v[8:9] neg_lo:[0,1] neg_hi:[0,1]
	v_cndmask_b32_e32 v24, 0, v24, vcc
	v_cndmask_b32_e32 v25, 0, v25, vcc
	s_waitcnt vmcnt(0) lgkmcnt(0)
	v_mov_b32_e32 v32, v2
	v_mov_b32_e32 v33, v4
	v_pk_fma_f32 v[20:21], v[32:33], v[20:21], v[28:29]
	v_pk_add_f32 v[28:29], v[30:31], v[28:29] neg_lo:[0,1] neg_hi:[0,1]
	v_mov_b32_e32 v30, v12
	v_mov_b32_e32 v31, v14
	v_pk_fma_f32 v[20:21], v[28:29], v[30:31], v[20:21]
	v_cndmask_b32_e64 v29, 0, v34, s[6:7]
	v_cndmask_b32_e64 v28, 0, v35, s[6:7]
	v_mov_b32_e32 v4, v3
	v_pk_fma_f32 v[4:5], v[4:5], v[22:23], v[8:9]
	v_pk_add_f32 v[8:9], v[28:29], v[8:9] neg_lo:[0,1] neg_hi:[0,1]
	v_mov_b32_e32 v14, v13
	v_pk_fma_f32 v[4:5], v[8:9], v[14:15], v[4:5]
	v_add_f32_e32 v2, v20, v20
	v_add_f32_e32 v3, v4, v4
	v_cndmask_b32_e64 v3, v3, v4, s[0:1]
	v_mul_f32_e32 v3, 0xbfb8aa3b, v3
	v_exp_f32_e32 v8, v3
	v_add_f32_e32 v3, v21, v21
	v_cndmask_b32_e64 v2, v2, v20, s[0:1]
	v_cndmask_b32_e64 v3, v3, v21, s[0:1]
	v_mul_f32_e32 v2, 0xbfb8aa3b, v2
	v_mul_f32_e32 v3, 0xbfb8aa3b, v3
	v_exp_f32_e32 v2, v2
	v_exp_f32_e32 v3, v3
	v_and_b32_e32 v15, 0xffff0000, v11
	v_pk_add_f32 v[2:3], v[2:3], 1.0 op_sel_hi:[1,0]
	s_nop 0
	v_div_scale_f32 v7, s[78:79], v3, v3, 1.0
	v_rcp_f32_e32 v9, v7
	s_nop 0
	v_fma_f32 v12, -v7, v9, 1.0
	v_fmac_f32_e32 v9, v12, v9
	v_div_scale_f32 v12, vcc, 1.0, v3, 1.0
	v_mul_f32_e32 v13, v12, v9
	v_fma_f32 v14, -v7, v13, v12
	v_fmac_f32_e32 v13, v14, v9
	v_fma_f32 v7, -v7, v13, v12
	v_div_fmas_f32 v7, v7, v9, v13
	v_div_fixup_f32 v3, v7, v3, 1.0
	v_div_scale_f32 v7, s[78:79], v2, v2, 1.0
	v_rcp_f32_e32 v9, v7
	s_nop 0
	v_fma_f32 v12, -v7, v9, 1.0
	v_fmac_f32_e32 v9, v12, v9
	v_div_scale_f32 v12, vcc, 1.0, v2, 1.0
	v_mul_f32_e32 v13, v12, v9
	v_fma_f32 v14, -v7, v13, v12
	v_fmac_f32_e32 v13, v14, v9
	v_fma_f32 v7, -v7, v13, v12
	v_div_fmas_f32 v7, v7, v9, v13
	v_div_fixup_f32 v2, v7, v2, 1.0
	v_pk_fma_f32 v[12:13], v[2:3], 2.0, -1.0 op_sel_hi:[1,0,0]
	s_nop 0
	v_cndmask_b32_e64 v7, v20, v12, s[4:5]
	v_cndmask_b32_e64 v7, v7, v2, s[0:1]
	v_add_f32_e32 v2, v5, v5
	v_cndmask_b32_e64 v2, v2, v5, s[0:1]
	v_cndmask_b32_e64 v9, v21, v13, s[4:5]
	v_mul_f32_e32 v2, 0xbfb8aa3b, v2
	v_cndmask_b32_e64 v22, v9, v3, s[0:1]
	v_exp_f32_e32 v9, v2
	s_nop 0
	v_pk_add_f32 v[2:3], v[8:9], 1.0 op_sel_hi:[1,0]
	s_nop 0
	v_div_scale_f32 v8, s[78:79], v3, v3, 1.0
	v_rcp_f32_e32 v9, v8
	s_nop 0
	v_fma_f32 v12, -v8, v9, 1.0
	v_fmac_f32_e32 v9, v12, v9
	v_div_scale_f32 v12, vcc, 1.0, v3, 1.0
	v_mul_f32_e32 v13, v12, v9
	v_fma_f32 v14, -v8, v13, v12
	v_fmac_f32_e32 v13, v14, v9
	v_fma_f32 v8, -v8, v13, v12
	v_div_fmas_f32 v8, v8, v9, v13
	v_div_fixup_f32 v3, v8, v3, 1.0
	v_div_scale_f32 v8, s[78:79], v2, v2, 1.0
	v_rcp_f32_e32 v9, v8
	s_nop 0
	v_fma_f32 v12, -v8, v9, 1.0
	v_fmac_f32_e32 v9, v12, v9
	v_div_scale_f32 v12, vcc, 1.0, v2, 1.0
	v_mul_f32_e32 v13, v12, v9
	v_fma_f32 v14, -v8, v13, v12
	v_fmac_f32_e32 v13, v14, v9
	v_fma_f32 v8, -v8, v13, v12
	v_div_fmas_f32 v8, v8, v9, v13
	v_div_fixup_f32 v2, v8, v2, 1.0
	v_pk_fma_f32 v[8:9], v[2:3], 2.0, -1.0 op_sel_hi:[1,0,0]
	v_lshlrev_b32_e32 v13, 16, v11
	v_cndmask_b32_e64 v5, v5, v9, s[4:5]
	v_cndmask_b32_e64 v4, v4, v8, s[4:5]
	v_cndmask_b32_e64 v23, v4, v2, s[0:1]
	v_cvt_pk_bf16_f32 v209, v7, v23
	v_cndmask_b32_e64 v28, v5, v3, s[0:1]
	v_lshlrev_b32_e32 v12, 16, v10
	v_and_b32_e32 v14, 0xffff0000, v10
	global_load_dwordx4 v[2:5], v[16:17], off offset:3088
	global_load_dwordx4 v[8:11], v[18:19], off offset:3088
	v_cndmask_b32_e64 v17, 0, v37, s[6:7]
	v_cndmask_b32_e64 v16, 0, v36, s[6:7]
	v_pk_add_f32 v[18:19], v[24:25], v[12:13] neg_lo:[0,1] neg_hi:[0,1]
	s_waitcnt vmcnt(0) lgkmcnt(0)
	v_mov_b32_e32 v20, v2
	v_mov_b32_e32 v21, v4
	v_pk_fma_f32 v[18:19], v[18:19], v[20:21], v[12:13]
	v_pk_add_f32 v[12:13], v[16:17], v[12:13] neg_lo:[0,1] neg_hi:[0,1]
	v_mov_b32_e32 v16, v8
	v_mov_b32_e32 v17, v10
	v_pk_fma_f32 v[12:13], v[12:13], v[16:17], v[18:19]
	v_cndmask_b32_e64 v17, 0, v38, s[6:7]
	v_cndmask_b32_e64 v16, 0, v39, s[6:7]
	v_pk_add_f32 v[18:19], v[26:27], v[14:15] neg_lo:[0,1] neg_hi:[0,1]
	v_mov_b32_e32 v4, v3
	v_pk_fma_f32 v[4:5], v[18:19], v[4:5], v[14:15]
	v_pk_add_f32 v[14:15], v[16:17], v[14:15] neg_lo:[0,1] neg_hi:[0,1]
	v_mov_b32_e32 v10, v9
	v_pk_fma_f32 v[4:5], v[14:15], v[10:11], v[4:5]
	v_add_f32_e32 v2, v12, v12
	v_add_f32_e32 v3, v4, v4
	v_cndmask_b32_e64 v3, v3, v4, s[0:1]
	v_mul_f32_e32 v3, 0xbfb8aa3b, v3
	v_exp_f32_e32 v8, v3
	v_add_f32_e32 v3, v13, v13
	v_cndmask_b32_e64 v2, v2, v12, s[0:1]
	v_cndmask_b32_e64 v3, v3, v13, s[0:1]
	v_mul_f32_e32 v2, 0xbfb8aa3b, v2
	v_mul_f32_e32 v3, 0xbfb8aa3b, v3
	v_exp_f32_e32 v2, v2
	v_exp_f32_e32 v3, v3
	s_nop 0
	v_pk_add_f32 v[2:3], v[2:3], 1.0 op_sel_hi:[1,0]
	s_nop 0
	v_div_scale_f32 v9, s[6:7], v3, v3, 1.0
	v_rcp_f32_e32 v10, v9
	s_nop 0
	v_fma_f32 v11, -v9, v10, 1.0
	v_fmac_f32_e32 v10, v11, v10
	v_div_scale_f32 v11, vcc, 1.0, v3, 1.0
	v_mul_f32_e32 v14, v11, v10
	v_fma_f32 v15, -v9, v14, v11
	v_fmac_f32_e32 v14, v15, v10
	v_fma_f32 v9, -v9, v14, v11
	v_div_fmas_f32 v9, v9, v10, v14
	v_div_fixup_f32 v3, v9, v3, 1.0
	v_div_scale_f32 v9, s[6:7], v2, v2, 1.0
	v_rcp_f32_e32 v10, v9
	s_nop 0
	v_fma_f32 v11, -v9, v10, 1.0
	v_fmac_f32_e32 v10, v11, v10
	v_div_scale_f32 v11, vcc, 1.0, v2, 1.0
	v_mul_f32_e32 v14, v11, v10
	v_fma_f32 v15, -v9, v14, v11
	v_fmac_f32_e32 v14, v15, v10
	v_fma_f32 v9, -v9, v14, v11
	v_div_fmas_f32 v9, v9, v10, v14
	v_div_fixup_f32 v2, v9, v2, 1.0
	v_pk_fma_f32 v[10:11], v[2:3], 2.0, -1.0 op_sel_hi:[1,0,0]
	s_nop 0
	v_cndmask_b32_e64 v9, v12, v10, s[4:5]
	v_cndmask_b32_e64 v10, v13, v11, s[4:5]
	v_cndmask_b32_e64 v11, v9, v2, s[0:1]
	v_add_f32_e32 v2, v5, v5
	v_cndmask_b32_e64 v2, v2, v5, s[0:1]
	v_mul_f32_e32 v2, 0xbfb8aa3b, v2
	v_exp_f32_e32 v9, v2
	v_cndmask_b32_e64 v10, v10, v3, s[0:1]
	v_pk_add_f32 v[2:3], v[8:9], 1.0 op_sel_hi:[1,0]
	s_nop 0
	v_div_scale_f32 v8, s[6:7], v3, v3, 1.0
	v_rcp_f32_e32 v9, v8
	s_nop 0
	v_fma_f32 v12, -v8, v9, 1.0
	v_fmac_f32_e32 v9, v12, v9
	v_div_scale_f32 v12, vcc, 1.0, v3, 1.0
	v_mul_f32_e32 v13, v12, v9
	v_fma_f32 v14, -v8, v13, v12
	v_fmac_f32_e32 v13, v14, v9
	v_fma_f32 v8, -v8, v13, v12
	v_div_fmas_f32 v8, v8, v9, v13
	v_div_fixup_f32 v3, v8, v3, 1.0
	v_div_scale_f32 v8, s[6:7], v2, v2, 1.0
	v_rcp_f32_e32 v9, v8
	s_nop 0
	v_fma_f32 v12, -v8, v9, 1.0
	v_fmac_f32_e32 v9, v12, v9
	v_div_scale_f32 v12, vcc, 1.0, v2, 1.0
	v_mul_f32_e32 v13, v12, v9
	v_fma_f32 v14, -v8, v13, v12
	v_fmac_f32_e32 v13, v14, v9
	v_fma_f32 v8, -v8, v13, v12
	v_div_fmas_f32 v8, v8, v9, v13
	v_div_fixup_f32 v2, v8, v2, 1.0
	v_pk_fma_f32 v[8:9], v[2:3], 2.0, -1.0 op_sel_hi:[1,0,0]
	v_bfe_u32 v12, v11, 16, 1
	v_cndmask_b32_e64 v5, v5, v9, s[4:5]
	v_cndmask_b32_e64 v4, v4, v8, s[4:5]
	v_cndmask_b32_e64 v2, v4, v2, s[0:1]
	v_cndmask_b32_e64 v3, v5, v3, s[0:1]
	v_cvt_pk_bf16_f32 v208, v10, v3
	v_bfe_u32 v5, v2, 16, 1
	v_add3_u32 v2, v2, v5, s58
	v_add3_u32 v11, v11, v12, s58
	v_lshrrev_b32_e32 v4, 16, v11
	v_mov_b32_e32 v5, v208
	v_and_or_b32 v4, v2, s54, v4
	v_cvt_pk_bf16_f32 v3, v22, v28
	v_mov_b32_e32 v2, v209
	ds_write_b128 v6, v[2:5] offset:4096
	s_cbranch_scc0 .LBB0_423
	v_ashrrev_i32_e32 v137, 3, v135
	v_and_b32_e32 v138, -4, v137
	v_add_u32_e32 v16, s27, v138
	v_add_u32_e32 v0, -1, v16
	v_or_b32_e32 v44, 1, v16
	v_and_b32_e32 v126, 31, v135
	v_max_i32_e32 v0, s12, v0
	v_max_i32_e32 v2, s12, v16
	v_max_i32_e32 v10, s12, v44
	v_lshlrev_b32_e32 v34, 4, v126
	v_mov_b32_e32 v35, v65
	s_mulk_i32 s26, 0x900
	v_min_i32_e32 v0, s24, v0
	v_min_i32_e32 v2, s24, v2
	v_min_i32_e32 v10, s24, v10
	v_lshl_add_u64 v[88:89], s[52:53], 0, v[34:35]
	s_mov_b64 s[0:1], 0x7158100
	v_add_u32_e32 v0, s26, v0
	v_add_u32_e32 v2, s26, v2
	v_add_u32_e32 v10, s26, v10
	v_lshl_add_u64 v[8:9], v[88:89], 0, s[0:1]
	v_mul_hi_i32_i24_e32 v29, 0x1240, v0
	v_mul_i32_i24_e32 v28, 0x1240, v0
	v_mul_hi_i32_i24_e32 v47, 0x1240, v2
	v_mul_i32_i24_e32 v46, 0x1240, v2
	v_mul_hi_i32_i24_e32 v49, 0x1240, v10
	v_mul_i32_i24_e32 v48, 0x1240, v10
	v_lshl_add_u64 v[0:1], v[8:9], 0, v[28:29]
	v_lshl_add_u64 v[4:5], v[8:9], 0, v[46:47]
	v_lshl_add_u64 v[10:11], v[8:9], 0, v[48:49]
	v_or_b32_e32 v45, 2, v16
	global_load_dwordx4 v[0:3], v[0:1], off
	s_nop 0
	global_load_dwordx4 v[4:7], v[4:5], off
	v_or_b32_e32 v66, 3, v16
	global_load_dwordx4 v[36:39], v[10:11], off
	v_max_i32_e32 v10, s12, v45
	v_min_i32_e32 v10, s24, v10
	v_add_u32_e32 v10, s26, v10
	v_mul_hi_i32_i24_e32 v51, 0x1240, v10
	v_mul_i32_i24_e32 v50, 0x1240, v10
	v_lshl_add_u64 v[10:11], v[8:9], 0, v[50:51]
	global_load_dwordx4 v[40:43], v[10:11], off
	v_max_i32_e32 v10, s12, v66
	v_min_i32_e32 v10, s24, v10
	v_add_u32_e32 v10, s26, v10
	v_mul_hi_i32_i24_e32 v53, 0x1240, v10
	v_mul_i32_i24_e32 v52, 0x1240, v10
	v_lshl_add_u64 v[10:11], v[8:9], 0, v[52:53]
	v_add_u32_e32 v67, 4, v16
	global_load_dwordx4 v[56:59], v[10:11], off
	v_max_i32_e32 v10, s12, v67
	v_min_i32_e32 v10, s24, v10
	v_add_u32_e32 v10, s26, v10
	v_mul_hi_i32_i24_e32 v55, 0x1240, v10
	v_mul_i32_i24_e32 v54, 0x1240, v10
	v_lshl_add_u64 v[8:9], v[8:9], 0, v[54:55]
	global_load_dwordx4 v[60:63], v[8:9], off
	v_mov_b32_e32 v8, s52
	v_lshlrev_b32_e32 v64, 5, v126
	v_mov_b32_e32 v9, s53
	v_add_co_u32_e32 v32, vcc, s55, v8
	v_lshl_add_u64 v[24:25], s[10:11], 0, v[64:65]
	s_nop 0
	v_addc_co_u32_e32 v33, vcc, 0, v9, vcc
	global_load_dwordx4 v[8:11], v[24:25], off
	v_lshl_add_u64 v[26:27], s[8:9], 0, v[64:65]
	global_load_dwordx2 v[30:31], v[32:33], off offset:464
	global_load_dwordx4 v[12:15], v[26:27], off
	v_cmp_lt_i32_e32 vcc, s12, v16
	v_cmp_ge_i32_e64 s[0:1], s13, v16
	v_cmp_le_i32_e64 s[4:5], s12, v16
	v_cmp_gt_i32_e64 s[6:7], s13, v16
	global_load_dwordx4 v[16:19], v[24:25], off offset:16
	global_load_dwordx4 v[20:23], v[26:27], off offset:16
	v_cmp_le_i32_e64 s[8:9], s12, v44
	v_cmp_gt_i32_e64 s[10:11], s13, v44
	s_and_b64 vcc, vcc, s[0:1]
	s_and_b64 s[4:5], s[4:5], s[6:7]
	s_and_b64 s[6:7], s[8:9], s[10:11]
	v_cmp_le_i32_e64 s[0:1], s12, v45
	v_cmp_gt_i32_e64 s[8:9], s13, v45
	s_and_b64 s[8:9], s[0:1], s[8:9]
	v_cmp_le_i32_e64 s[0:1], s12, v66
	v_cmp_gt_i32_e64 s[10:11], s13, v66
	s_and_b64 s[10:11], s[0:1], s[10:11]
	v_cmp_le_i32_e64 s[0:1], s12, v67
	v_cmp_gt_i32_e64 s[12:13], s13, v67
	s_and_b64 s[12:13], s[0:1], s[12:13]
	v_add_u32_e32 v90, s18, v138
	v_ashrrev_i32_e32 v91, 31, v90
	v_or_b32_e32 v92, 1, v90
	v_ashrrev_i32_e32 v93, 31, v92
	s_mov_b32 s24, 0
	v_lshlrev_b32_e32 v126, 3, v126
	s_waitcnt vmcnt(0) lgkmcnt(0)
	v_cndmask_b32_e32 v44, 0, v1, vcc
	v_cndmask_b32_e32 v68, 0, v0, vcc
	v_cndmask_b32_e64 v69, 0, v5, s[4:5]
	v_cndmask_b32_e64 v73, 0, v4, s[4:5]
	v_cndmask_b32_e64 v76, 0, v39, s[6:7]
	v_cndmask_b32_e64 v78, 0, v38, s[6:7]
	v_cndmask_b32_e64 v38, 0, v37, s[6:7]
	v_cndmask_b32_e64 v39, 0, v36, s[6:7]
	v_and_b32_e32 v37, 0xffff0000, v44
	v_and_b32_e32 v36, 0xffff0000, v68
	v_cndmask_b32_e32 v70, 0, v3, vcc
	v_cndmask_b32_e32 v71, 0, v2, vcc
	v_cndmask_b32_e64 v72, 0, v7, s[4:5]
	v_cndmask_b32_e64 v74, 0, v6, s[4:5]
	v_lshlrev_b32_e32 v45, 16, v69
	v_lshlrev_b32_e32 v75, 16, v76
	v_and_b32_e32 v77, 0xffff0000, v76
	v_and_b32_e32 v76, 0xffff0000, v78
	v_cndmask_b32_e64 v86, 0, v59, s[10:11]
	v_cndmask_b32_e64 v87, 0, v58, s[10:11]
	v_and_b32_e32 v59, 0xffff0000, v69
	v_and_b32_e32 v58, 0xffff0000, v73
	v_pk_add_f32 v[36:37], v[36:37], v[58:59] neg_lo:[0,1] neg_hi:[0,1]
	v_cndmask_b32_e64 v94, 0, v57, s[10:11]
	v_cndmask_b32_e64 v95, 0, v56, s[10:11]
	v_cndmask_b32_e64 v96, 0, v63, s[12:13]
	v_cndmask_b32_e64 v97, 0, v62, s[12:13]
	v_and_b32_e32 v63, 0xffff0000, v38
	v_and_b32_e32 v62, 0xffff0000, v39
	v_cndmask_b32_e64 v118, 0, v61, s[12:13]
	v_cndmask_b32_e64 v119, 0, v60, s[12:13]
	v_lshlrev_b32_e32 v61, 16, v38
	v_lshlrev_b32_e32 v60, 16, v39
	v_lshl_add_u64 v[56:57], v[88:89], 0, s[36:37]
	v_mov_b32_e32 v67, v10
	v_mov_b32_e32 v10, v9
	v_readfirstlane_b32 s1, v31
	v_readfirstlane_b32 s0, v30
	v_lshlrev_b32_e32 v31, 16, v44
	v_lshlrev_b32_e32 v30, 16, v68
	v_lshlrev_b32_e32 v44, 16, v73
	v_mov_b32_e32 v66, v8
	v_mov_b32_e32 v69, v14
	v_pk_fma_f32 v[8:9], v[10:11], v[36:37], v[58:59]
	v_pk_add_f32 v[36:37], v[62:63], v[58:59] neg_lo:[0,1] neg_hi:[0,1]
	v_mov_b32_e32 v14, v13
	v_pk_add_f32 v[30:31], v[30:31], v[44:45] neg_lo:[0,1] neg_hi:[0,1]
	v_mov_b32_e32 v68, v12
	v_pk_fma_f32 v[36:37], v[14:15], v[36:37], v[8:9]
	v_lshlrev_b32_e32 v9, 16, v70
	v_lshlrev_b32_e32 v8, 16, v71
	v_and_b32_e32 v13, 0xffff0000, v70
	v_and_b32_e32 v12, 0xffff0000, v71
	v_lshlrev_b32_e32 v71, 16, v72
	v_lshlrev_b32_e32 v70, 16, v74
	v_pk_fma_f32 v[30:31], v[66:67], v[30:31], v[44:45]
	v_pk_add_f32 v[38:39], v[60:61], v[44:45] neg_lo:[0,1] neg_hi:[0,1]
	v_and_b32_e32 v73, 0xffff0000, v72
	v_and_b32_e32 v72, 0xffff0000, v74
	v_lshlrev_b32_e32 v74, 16, v78
	v_pk_add_f32 v[8:9], v[8:9], v[70:71] neg_lo:[0,1] neg_hi:[0,1]
	v_mov_b32_e32 v78, v16
	v_mov_b32_e32 v79, v18
	v_pk_fma_f32 v[30:31], v[68:69], v[38:39], v[30:31]
	v_pk_fma_f32 v[8:9], v[78:79], v[8:9], v[70:71]
	v_pk_add_f32 v[38:39], v[74:75], v[70:71] neg_lo:[0,1] neg_hi:[0,1]
	v_mov_b32_e32 v80, v20
	v_mov_b32_e32 v81, v22
	v_pk_fma_f32 v[98:99], v[80:81], v[38:39], v[8:9]
	v_pk_add_f32 v[8:9], v[12:13], v[72:73] neg_lo:[0,1] neg_hi:[0,1]
	v_mov_b32_e32 v18, v17
	v_pk_fma_f32 v[8:9], v[18:19], v[8:9], v[72:73]
	v_pk_add_f32 v[12:13], v[76:77], v[72:73] neg_lo:[0,1] neg_hi:[0,1]
	v_mov_b32_e32 v22, v21
	v_pk_fma_f32 v[100:101], v[22:23], v[12:13], v[8:9]
	v_bfe_u32 v8, v30, 16, 1
	v_bfe_u32 v9, v31, 16, 1
	v_bfe_u32 v12, v98, 16, 1
	v_bfe_u32 v13, v99, 16, 1
	v_add3_u32 v13, v99, v13, s58
	v_add3_u32 v12, v98, v12, s58
	v_add3_u32 v9, v31, v9, s58
	v_add3_u32 v8, v30, v8, s58
	v_lshrrev_b32_e32 v8, 16, v8
	v_lshrrev_b32_e32 v9, 16, v9
	v_lshrrev_b32_e32 v12, 16, v12
	v_lshrrev_b32_e32 v13, 16, v13
	v_lshlrev_b64 v[38:39], 9, v[90:91]
	v_cndmask_b32_e64 v82, 0, v43, s[8:9]
	v_cndmask_b32_e64 v83, 0, v42, s[8:9]
	v_cndmask_b32_e64 v84, 0, v41, s[8:9]
	v_cndmask_b32_e64 v85, 0, v40, s[8:9]
	v_lshl_add_u64 v[0:1], s[0:1], 0, v[64:65]
	v_and_or_b32 v43, v101, s54, v13
	v_and_or_b32 v42, v100, s54, v12
	v_and_or_b32 v41, v37, s54, v9
	v_and_or_b32 v40, v36, s54, v8
	v_lshl_add_u64 v[8:9], v[56:57], 0, v[38:39]
	global_load_dwordx4 v[4:7], v[0:1], off
	s_nop 0
	global_load_dwordx4 v[0:3], v[0:1], off offset:16
	v_pk_add_f32 v[16:17], v[44:45], v[60:61] neg_lo:[0,1] neg_hi:[0,1]
	global_store_dwordx4 v[8:9], v[40:43], off
	v_lshlrev_b32_e32 v9, 16, v84
	v_lshlrev_b32_e32 v8, 16, v85
	v_pk_fma_f32 v[16:17], v[66:67], v[16:17], v[60:61]
	v_pk_add_f32 v[20:21], v[8:9], v[60:61] neg_lo:[0,1] neg_hi:[0,1]
	v_and_b32_e32 v13, 0xffff0000, v84
	v_and_b32_e32 v12, 0xffff0000, v85
	v_pk_fma_f32 v[102:103], v[68:69], v[20:21], v[16:17]
	v_pk_add_f32 v[16:17], v[58:59], v[62:63] neg_lo:[0,1] neg_hi:[0,1]
	v_pk_add_f32 v[20:21], v[12:13], v[62:63] neg_lo:[0,1] neg_hi:[0,1]
	v_pk_fma_f32 v[16:17], v[10:11], v[16:17], v[62:63]
	v_pk_add_f32 v[40:41], v[70:71], v[74:75] neg_lo:[0,1] neg_hi:[0,1]
	v_pk_fma_f32 v[104:105], v[14:15], v[20:21], v[16:17]
	v_lshlrev_b32_e32 v17, 16, v82
	v_lshlrev_b32_e32 v16, 16, v83
	v_pk_fma_f32 v[40:41], v[78:79], v[40:41], v[74:75]
	v_pk_add_f32 v[42:43], v[16:17], v[74:75] neg_lo:[0,1] neg_hi:[0,1]
	v_and_b32_e32 v21, 0xffff0000, v82
	v_and_b32_e32 v20, 0xffff0000, v83
	v_pk_fma_f32 v[106:107], v[80:81], v[42:43], v[40:41]
	v_pk_add_f32 v[40:41], v[72:73], v[76:77] neg_lo:[0,1] neg_hi:[0,1]
	v_pk_add_f32 v[42:43], v[20:21], v[76:77] neg_lo:[0,1] neg_hi:[0,1]
	v_pk_fma_f32 v[40:41], v[18:19], v[40:41], v[76:77]
	v_pk_add_f32 v[60:61], v[60:61], v[8:9] neg_lo:[0,1] neg_hi:[0,1]
	v_pk_fma_f32 v[108:109], v[22:23], v[42:43], v[40:41]
	v_bfe_u32 v40, v102, 16, 1
	v_bfe_u32 v41, v103, 16, 1
	v_bfe_u32 v42, v106, 16, 1
	v_bfe_u32 v43, v107, 16, 1
	v_add3_u32 v43, v107, v43, s58
	v_add3_u32 v42, v106, v42, s58
	v_add3_u32 v41, v103, v41, s58
	v_add3_u32 v40, v102, v40, s58
	v_lshrrev_b32_e32 v40, 16, v40
	v_lshrrev_b32_e32 v41, 16, v41
	v_lshrrev_b32_e32 v42, 16, v42
	v_lshrrev_b32_e32 v43, 16, v43
	v_and_or_b32 v45, v109, s54, v43
	v_and_or_b32 v44, v108, s54, v42
	v_and_or_b32 v43, v105, s54, v41
	v_and_or_b32 v42, v104, s54, v40
	v_lshlrev_b64 v[40:41], 9, v[92:93]
	v_lshl_add_u64 v[58:59], v[56:57], 0, v[40:41]
	global_store_dwordx4 v[58:59], v[42:45], off
	v_pk_fma_f32 v[60:61], v[66:67], v[60:61], v[8:9]
	v_and_b32_e32 v71, 0xffff0000, v94
	v_lshlrev_b32_e32 v45, 16, v94
	v_lshlrev_b32_e32 v44, 16, v95
	v_pk_add_f32 v[42:43], v[44:45], v[8:9] neg_lo:[0,1] neg_hi:[0,1]
	v_and_b32_e32 v70, 0xffff0000, v95
	v_pk_fma_f32 v[110:111], v[68:69], v[42:43], v[60:61]
	v_pk_add_f32 v[42:43], v[62:63], v[12:13] neg_lo:[0,1] neg_hi:[0,1]
	v_pk_add_f32 v[58:59], v[70:71], v[12:13] neg_lo:[0,1] neg_hi:[0,1]
	v_pk_fma_f32 v[42:43], v[10:11], v[42:43], v[12:13]
	v_lshlrev_b32_e32 v63, 16, v86
	v_lshlrev_b32_e32 v62, 16, v87
	v_pk_add_f32 v[60:61], v[74:75], v[16:17] neg_lo:[0,1] neg_hi:[0,1]
	v_pk_fma_f32 v[112:113], v[14:15], v[58:59], v[42:43]
	v_pk_add_f32 v[42:43], v[62:63], v[16:17] neg_lo:[0,1] neg_hi:[0,1]
	v_pk_fma_f32 v[60:61], v[78:79], v[60:61], v[16:17]
	v_and_b32_e32 v73, 0xffff0000, v86
	v_and_b32_e32 v72, 0xffff0000, v87
	v_pk_fma_f32 v[114:115], v[80:81], v[42:43], v[60:61]
	v_pk_add_f32 v[42:43], v[76:77], v[20:21] neg_lo:[0,1] neg_hi:[0,1]
	v_pk_add_f32 v[58:59], v[72:73], v[20:21] neg_lo:[0,1] neg_hi:[0,1]
	v_pk_fma_f32 v[42:43], v[18:19], v[42:43], v[20:21]
	v_or_b32_e32 v94, 2, v90
	v_pk_fma_f32 v[116:117], v[22:23], v[58:59], v[42:43]
	v_bfe_u32 v42, v110, 16, 1
	v_bfe_u32 v43, v111, 16, 1
	v_bfe_u32 v58, v114, 16, 1
	v_bfe_u32 v59, v115, 16, 1
	v_add3_u32 v59, v115, v59, s58
	v_add3_u32 v58, v114, v58, s58
	v_add3_u32 v43, v111, v43, s58
	v_add3_u32 v42, v110, v42, s58
	v_lshrrev_b32_e32 v42, 16, v42
	v_lshrrev_b32_e32 v43, 16, v43
	v_lshrrev_b32_e32 v58, 16, v58
	v_lshrrev_b32_e32 v59, 16, v59
	v_ashrrev_i32_e32 v95, 31, v94
	v_and_or_b32 v61, v117, s54, v59
	v_and_or_b32 v60, v116, s54, v58
	v_and_or_b32 v59, v113, s54, v43
	v_and_or_b32 v58, v112, s54, v42
	v_lshlrev_b64 v[42:43], 9, v[94:95]
	v_lshl_add_u64 v[74:75], v[56:57], 0, v[42:43]
	global_store_dwordx4 v[74:75], v[58:61], off
	v_pk_add_f32 v[8:9], v[8:9], v[44:45] neg_lo:[0,1] neg_hi:[0,1]
	v_pk_add_f32 v[12:13], v[12:13], v[70:71] neg_lo:[0,1] neg_hi:[0,1]
	v_lshlrev_b32_e32 v59, 16, v118
	v_lshlrev_b32_e32 v58, 16, v119
	v_and_b32_e32 v61, 0xffff0000, v118
	v_and_b32_e32 v60, 0xffff0000, v119
	v_pk_add_f32 v[58:59], v[58:59], v[44:45] neg_lo:[0,1] neg_hi:[0,1]
	v_pk_fma_f32 v[8:9], v[66:67], v[8:9], v[44:45]
	v_pk_add_f32 v[60:61], v[60:61], v[70:71] neg_lo:[0,1] neg_hi:[0,1]
	v_pk_fma_f32 v[118:119], v[68:69], v[58:59], v[8:9]
	v_pk_fma_f32 v[8:9], v[10:11], v[12:13], v[70:71]
	v_pk_add_f32 v[12:13], v[16:17], v[62:63] neg_lo:[0,1] neg_hi:[0,1]
	v_pk_fma_f32 v[120:121], v[14:15], v[60:61], v[8:9]
	v_lshlrev_b32_e32 v9, 16, v96
	v_lshlrev_b32_e32 v8, 16, v97
	v_and_b32_e32 v11, 0xffff0000, v96
	v_and_b32_e32 v10, 0xffff0000, v97
	v_pk_add_f32 v[8:9], v[8:9], v[62:63] neg_lo:[0,1] neg_hi:[0,1]
	v_pk_add_f32 v[14:15], v[20:21], v[72:73] neg_lo:[0,1] neg_hi:[0,1]
	v_pk_fma_f32 v[12:13], v[78:79], v[12:13], v[62:63]
	v_pk_add_f32 v[10:11], v[10:11], v[72:73] neg_lo:[0,1] neg_hi:[0,1]
	v_pk_fma_f32 v[122:123], v[80:81], v[8:9], v[12:13]
	v_pk_fma_f32 v[8:9], v[18:19], v[14:15], v[72:73]
	v_or_b32_e32 v96, 3, v90
	v_pk_fma_f32 v[124:125], v[22:23], v[10:11], v[8:9]
	v_bfe_u32 v8, v118, 16, 1
	v_bfe_u32 v9, v119, 16, 1
	v_bfe_u32 v10, v122, 16, 1
	v_bfe_u32 v11, v123, 16, 1
	v_add3_u32 v11, v123, v11, s58
	v_add3_u32 v10, v122, v10, s58
	v_add3_u32 v9, v119, v9, s58
	v_add3_u32 v8, v118, v8, s58
	v_ashrrev_i32_e32 v97, 31, v96
	v_lshrrev_b32_e32 v8, 16, v8
	v_lshrrev_b32_e32 v9, 16, v9
	v_lshrrev_b32_e32 v10, 16, v10
	v_lshrrev_b32_e32 v11, 16, v11
	v_lshlrev_b64 v[44:45], 9, v[96:97]
	v_and_or_b32 v11, v125, s54, v11
	v_and_or_b32 v10, v124, s54, v10
	v_and_or_b32 v9, v121, s54, v9
	v_and_or_b32 v8, v120, s54, v8
	v_lshl_add_u64 v[12:13], v[56:57], 0, v[44:45]
	global_store_dwordx4 v[12:13], v[8:11], off
	s_waitcnt vmcnt(0) lgkmcnt(0)
	v_mul_f32_e32 v159, v98, v0
	v_mul_f32_e32 v160, v100, v1
	v_lshl_add_u64 v[8:9], v[88:89], 0, s[38:39]
	v_lshl_add_u64 v[10:11], v[8:9], 0, v[28:29]
	global_load_dwordx4 v[56:59], v[10:11], off
	v_lshl_add_u64 v[10:11], v[8:9], 0, v[46:47]
	global_load_dwordx4 v[60:63], v[10:11], off
	v_lshl_add_u64 v[10:11], v[8:9], 0, v[48:49]
	global_load_dwordx4 v[66:69], v[10:11], off
	v_lshl_add_u64 v[10:11], v[8:9], 0, v[50:51]
	global_load_dwordx4 v[70:73], v[10:11], off
	v_lshl_add_u64 v[10:11], v[8:9], 0, v[52:53]
	global_load_dwordx4 v[74:77], v[10:11], off
	v_lshl_add_u64 v[8:9], v[8:9], 0, v[54:55]
	global_load_dwordx4 v[78:81], v[8:9], off
	s_nop 0
	global_load_dwordx4 v[8:11], v[24:25], off offset:2048
	global_load_dwordx4 v[12:15], v[26:27], off offset:2048
	global_load_dwordx4 v[16:19], v[24:25], off offset:2064
	global_load_dwordx4 v[20:23], v[26:27], off offset:2064
	v_mul_f32_e32 v161, v99, v2
	v_mul_f32_e32 v162, v101, v3
	v_mul_f32_e32 v163, v4, v102
	v_mul_f32_e32 v168, v5, v104
	v_mul_f32_e32 v169, v103, v6
	v_mul_f32_e32 v170, v105, v7
	v_mul_f32_e32 v171, v106, v0
	v_mul_f32_e32 v175, v114, v0
	v_mul_f32_e32 v187, v122, v0
	v_mul_f32_e32 v172, v108, v1
	v_mul_f32_e32 v176, v116, v1
	v_mul_f32_e32 v177, v115, v2
	v_mul_f32_e32 v188, v124, v1
	v_bitop3_b32 v1, v135, 31, v130 bitop3:0xe0
	v_mul_f32_e32 v173, v107, v2
	v_mul_f32_e32 v174, v109, v3
	v_mul_f32_e32 v110, v4, v110
	v_mul_f32_e32 v112, v5, v112
	v_mul_f32_e32 v111, v6, v111
	v_mul_f32_e32 v113, v113, v7
	v_mul_f32_e32 v178, v117, v3
	v_mul_f32_e32 v179, v4, v118
	v_mul_f32_e32 v184, v5, v120
	v_mul_f32_e32 v185, v6, v119
	v_mul_f32_e32 v186, v7, v121
	v_mul_f32_e32 v189, v123, v2
	v_mul_f32_e32 v190, v125, v3
	s_waitcnt vmcnt(0) lgkmcnt(0)
	v_cndmask_b32_e32 v84, 0, v57, vcc
	v_cndmask_b32_e32 v85, 0, v56, vcc
	v_cndmask_b32_e64 v136, 0, v61, s[4:5]
	v_cndmask_b32_e64 v139, 0, v60, s[4:5]
	v_cndmask_b32_e64 v142, 0, v67, s[6:7]
	v_cndmask_b32_e64 v143, 0, v66, s[6:7]
	v_and_b32_e32 v61, 0xffff0000, v84
	v_and_b32_e32 v60, 0xffff0000, v85
	v_and_b32_e32 v67, 0xffff0000, v136
	v_and_b32_e32 v66, 0xffff0000, v139
	v_cndmask_b32_e32 v82, 0, v59, vcc
	v_cndmask_b32_e32 v83, 0, v58, vcc
	v_cndmask_b32_e64 v86, 0, v63, s[4:5]
	v_cndmask_b32_e64 v87, 0, v62, s[4:5]
	v_cndmask_b32_e64 v144, 0, v73, s[8:9]
	v_cndmask_b32_e64 v146, 0, v71, s[8:9]
	v_cndmask_b32_e64 v147, 0, v70, s[8:9]
	v_lshlrev_b32_e32 v59, 16, v84
	v_lshlrev_b32_e32 v58, 16, v85
	v_lshlrev_b32_e32 v63, 16, v136
	v_lshlrev_b32_e32 v62, 16, v139
	v_and_b32_e32 v71, 0xffff0000, v142
	v_and_b32_e32 v70, 0xffff0000, v143
	v_mov_b32_e32 v73, v10
	v_pk_add_f32 v[60:61], v[60:61], v[66:67] neg_lo:[0,1] neg_hi:[0,1]
	v_mov_b32_e32 v10, v9
	v_cndmask_b32_e64 v140, 0, v69, s[6:7]
	v_cndmask_b32_e64 v141, 0, v68, s[6:7]
	v_cndmask_b32_e64 v145, 0, v72, s[8:9]
	v_cndmask_b32_e64 v148, 0, v77, s[10:11]
	v_lshlrev_b32_e32 v69, 16, v142
	v_lshlrev_b32_e32 v68, 16, v143
	v_pk_add_f32 v[58:59], v[58:59], v[62:63] neg_lo:[0,1] neg_hi:[0,1]
	v_mov_b32_e32 v72, v8
	v_mov_b32_e32 v77, v14
	v_pk_fma_f32 v[8:9], v[10:11], v[60:61], v[66:67]
	v_pk_add_f32 v[60:61], v[70:71], v[66:67] neg_lo:[0,1] neg_hi:[0,1]
	v_mov_b32_e32 v14, v13
	v_cndmask_b32_e64 v149, 0, v76, s[10:11]
	v_cndmask_b32_e64 v150, 0, v75, s[10:11]
	v_cndmask_b32_e64 v151, 0, v74, s[10:11]
	v_cndmask_b32_e64 v154, 0, v79, s[12:13]
	v_cndmask_b32_e64 v155, 0, v78, s[12:13]
	v_pk_fma_f32 v[58:59], v[72:73], v[58:59], v[62:63]
	v_pk_add_f32 v[74:75], v[68:69], v[62:63] neg_lo:[0,1] neg_hi:[0,1]
	v_mov_b32_e32 v76, v12
	v_pk_fma_f32 v[8:9], v[14:15], v[60:61], v[8:9]
	v_and_b32_e32 v61, 0xffff0000, v82
	v_and_b32_e32 v60, 0xffff0000, v83
	v_and_b32_e32 v79, 0xffff0000, v86
	v_and_b32_e32 v78, 0xffff0000, v87
	v_pk_fma_f32 v[58:59], v[76:77], v[74:75], v[58:59]
	s_nop 0
	v_cvt_pk_bf16_f32 v210, v59, v9
	v_cvt_pk_bf16_f32 v211, v58, v8
	v_lshlrev_b32_e32 v13, 16, v82
	v_lshlrev_b32_e32 v12, 16, v83
	v_lshlrev_b32_e32 v75, 16, v86
	v_lshlrev_b32_e32 v74, 16, v87
	v_and_b32_e32 v83, 0xffff0000, v140
	v_and_b32_e32 v82, 0xffff0000, v141
	v_mov_b32_e32 v85, v18
	v_pk_add_f32 v[60:61], v[60:61], v[78:79] neg_lo:[0,1] neg_hi:[0,1]
	v_mov_b32_e32 v18, v17
	v_cndmask_b32_e64 v152, 0, v81, s[12:13]
	v_cndmask_b32_e64 v153, 0, v80, s[12:13]
	v_lshlrev_b32_e32 v81, 16, v140
	v_lshlrev_b32_e32 v80, 16, v141
	v_pk_add_f32 v[12:13], v[12:13], v[74:75] neg_lo:[0,1] neg_hi:[0,1]
	v_mov_b32_e32 v84, v16
	v_mov_b32_e32 v141, v22
	v_pk_fma_f32 v[16:17], v[18:19], v[60:61], v[78:79]
	v_pk_add_f32 v[60:61], v[82:83], v[78:79] neg_lo:[0,1] neg_hi:[0,1]
	v_mov_b32_e32 v22, v21
	v_pk_fma_f32 v[12:13], v[84:85], v[12:13], v[74:75]
	v_pk_add_f32 v[86:87], v[80:81], v[74:75] neg_lo:[0,1] neg_hi:[0,1]
	v_mov_b32_e32 v140, v20
	v_pk_fma_f32 v[16:17], v[22:23], v[60:61], v[16:17]
	v_pk_fma_f32 v[12:13], v[140:141], v[86:87], v[12:13]
	s_nop 0
	v_cvt_pk_bf16_f32 v208, v13, v17
	v_cvt_pk_bf16_f32 v209, v12, v16
	v_lshl_add_u64 v[56:57], v[88:89], 0, s[40:41]
	v_mov_b32_e32 v61, v208
	v_mov_b32_e32 v60, v209
	v_mov_b32_e32 v59, v210
	v_mov_b32_e32 v58, v211
	v_lshl_add_u64 v[8:9], v[56:57], 0, v[38:39]
	global_store_dwordx4 v[8:9], v[58:61], off
	v_lshlrev_b32_e32 v9, 16, v146
	v_lshlrev_b32_e32 v8, 16, v147
	v_pk_add_f32 v[16:17], v[62:63], v[68:69] neg_lo:[0,1] neg_hi:[0,1]
	v_pk_add_f32 v[20:21], v[8:9], v[68:69] neg_lo:[0,1] neg_hi:[0,1]
	v_pk_fma_f32 v[16:17], v[72:73], v[16:17], v[68:69]
	v_and_b32_e32 v13, 0xffff0000, v146
	v_and_b32_e32 v12, 0xffff0000, v147
	v_pk_fma_f32 v[16:17], v[76:77], v[20:21], v[16:17]
	v_pk_add_f32 v[20:21], v[66:67], v[70:71] neg_lo:[0,1] neg_hi:[0,1]
	v_pk_add_f32 v[58:59], v[12:13], v[70:71] neg_lo:[0,1] neg_hi:[0,1]
	v_pk_fma_f32 v[20:21], v[10:11], v[20:21], v[70:71]
	v_lshlrev_b32_e32 v63, 16, v144
	v_pk_fma_f32 v[20:21], v[14:15], v[58:59], v[20:21]
	s_nop 0
	v_cvt_pk_bf16_f32 v210, v17, v21
	v_cvt_pk_bf16_f32 v211, v16, v20
	v_lshlrev_b32_e32 v62, 16, v145
	v_pk_add_f32 v[58:59], v[74:75], v[80:81] neg_lo:[0,1] neg_hi:[0,1]
	v_pk_add_f32 v[60:61], v[62:63], v[80:81] neg_lo:[0,1] neg_hi:[0,1]
	v_pk_fma_f32 v[58:59], v[84:85], v[58:59], v[80:81]
	v_and_b32_e32 v67, 0xffff0000, v144
	v_and_b32_e32 v66, 0xffff0000, v145
	v_pk_fma_f32 v[58:59], v[140:141], v[60:61], v[58:59]
	v_pk_add_f32 v[60:61], v[78:79], v[82:83] neg_lo:[0,1] neg_hi:[0,1]
	v_pk_add_f32 v[74:75], v[66:67], v[82:83] neg_lo:[0,1] neg_hi:[0,1]
	v_pk_fma_f32 v[60:61], v[18:19], v[60:61], v[82:83]
	s_nop 0
	v_pk_fma_f32 v[60:61], v[22:23], v[74:75], v[60:61]
	s_nop 0
	v_cvt_pk_bf16_f32 v208, v59, v61
	v_cvt_pk_bf16_f32 v209, v58, v60
	v_mov_b32_e32 v61, v208
	v_mov_b32_e32 v60, v209
	v_mov_b32_e32 v59, v210
	v_mov_b32_e32 v58, v211
	v_lshl_add_u64 v[16:17], v[56:57], 0, v[40:41]
	global_store_dwordx4 v[16:17], v[58:61], off
	v_lshlrev_b32_e32 v17, 16, v150
	v_lshlrev_b32_e32 v16, 16, v151
	v_pk_add_f32 v[68:69], v[68:69], v[8:9] neg_lo:[0,1] neg_hi:[0,1]
	v_pk_add_f32 v[58:59], v[16:17], v[8:9] neg_lo:[0,1] neg_hi:[0,1]
	v_pk_fma_f32 v[68:69], v[72:73], v[68:69], v[8:9]
	v_and_b32_e32 v21, 0xffff0000, v150
	v_and_b32_e32 v20, 0xffff0000, v151
	v_pk_fma_f32 v[58:59], v[76:77], v[58:59], v[68:69]
	v_pk_add_f32 v[68:69], v[70:71], v[12:13] neg_lo:[0,1] neg_hi:[0,1]
	v_pk_add_f32 v[60:61], v[20:21], v[12:13] neg_lo:[0,1] neg_hi:[0,1]
	v_pk_fma_f32 v[68:69], v[10:11], v[68:69], v[12:13]
	v_pk_add_f32 v[80:81], v[80:81], v[62:63] neg_lo:[0,1] neg_hi:[0,1]
	v_pk_fma_f32 v[60:61], v[14:15], v[60:61], v[68:69]
	s_nop 0
	v_cvt_pk_bf16_f32 v210, v59, v61
	v_cvt_pk_bf16_f32 v211, v58, v60
	v_lshlrev_b32_e32 v69, 16, v148
	v_lshlrev_b32_e32 v68, 16, v149
	v_pk_add_f32 v[74:75], v[68:69], v[62:63] neg_lo:[0,1] neg_hi:[0,1]
	v_pk_fma_f32 v[80:81], v[84:85], v[80:81], v[62:63]
	v_and_b32_e32 v71, 0xffff0000, v148
	v_and_b32_e32 v70, 0xffff0000, v149
	v_pk_fma_f32 v[74:75], v[140:141], v[74:75], v[80:81]
	v_pk_add_f32 v[80:81], v[82:83], v[66:67] neg_lo:[0,1] neg_hi:[0,1]
	v_pk_add_f32 v[78:79], v[70:71], v[66:67] neg_lo:[0,1] neg_hi:[0,1]
	v_pk_fma_f32 v[80:81], v[18:19], v[80:81], v[66:67]
	s_nop 0
	v_pk_fma_f32 v[78:79], v[22:23], v[78:79], v[80:81]
	s_nop 0
	v_cvt_pk_bf16_f32 v208, v75, v79
	v_cvt_pk_bf16_f32 v209, v74, v78
	v_mov_b32_e32 v61, v208
	v_mov_b32_e32 v60, v209
	v_mov_b32_e32 v59, v210
	v_mov_b32_e32 v58, v211
	v_lshl_add_u64 v[74:75], v[56:57], 0, v[42:43]
	global_store_dwordx4 v[74:75], v[58:61], off
	v_pk_add_f32 v[8:9], v[8:9], v[16:17] neg_lo:[0,1] neg_hi:[0,1]
	v_pk_add_f32 v[12:13], v[12:13], v[20:21] neg_lo:[0,1] neg_hi:[0,1]
	v_lshlrev_b32_e32 v59, 16, v154
	v_lshlrev_b32_e32 v58, 16, v155
	v_and_b32_e32 v61, 0xffff0000, v154
	v_and_b32_e32 v60, 0xffff0000, v155
	v_pk_add_f32 v[58:59], v[58:59], v[16:17] neg_lo:[0,1] neg_hi:[0,1]
	v_pk_add_f32 v[60:61], v[60:61], v[20:21] neg_lo:[0,1] neg_hi:[0,1]
	v_pk_fma_f32 v[8:9], v[72:73], v[8:9], v[16:17]
	v_pk_fma_f32 v[10:11], v[10:11], v[12:13], v[20:21]
	v_lshlrev_b32_e32 v13, 16, v152
	v_lshlrev_b32_e32 v12, 16, v153
	v_pk_add_f32 v[16:17], v[62:63], v[68:69] neg_lo:[0,1] neg_hi:[0,1]
	v_pk_fma_f32 v[10:11], v[14:15], v[60:61], v[10:11]
	v_and_b32_e32 v15, 0xffff0000, v152
	v_and_b32_e32 v14, 0xffff0000, v153
	v_pk_add_f32 v[12:13], v[12:13], v[68:69] neg_lo:[0,1] neg_hi:[0,1]
	v_pk_add_f32 v[20:21], v[66:67], v[70:71] neg_lo:[0,1] neg_hi:[0,1]
	v_pk_fma_f32 v[16:17], v[84:85], v[16:17], v[68:69]
	v_pk_add_f32 v[14:15], v[14:15], v[70:71] neg_lo:[0,1] neg_hi:[0,1]
	v_pk_fma_f32 v[12:13], v[140:141], v[12:13], v[16:17]
	v_pk_fma_f32 v[16:17], v[18:19], v[20:21], v[70:71]
	v_pk_fma_f32 v[8:9], v[76:77], v[58:59], v[8:9]
	s_nop 0
	v_cvt_pk_bf16_f32 v210, v9, v11
	v_cvt_pk_bf16_f32 v211, v8, v10
	v_pk_fma_f32 v[14:15], v[22:23], v[14:15], v[16:17]
	s_nop 0
	v_cvt_pk_bf16_f32 v208, v13, v15
	v_cvt_pk_bf16_f32 v209, v12, v14
	v_mov_b32_e32 v11, v208
	v_mov_b32_e32 v10, v209
	v_mov_b32_e32 v9, v210
	v_mov_b32_e32 v8, v211
	v_lshl_add_u64 v[12:13], v[56:57], 0, v[44:45]
	global_store_dwordx4 v[12:13], v[8:11], off
	v_lshl_add_u64 v[12:13], v[88:89], 0, s[42:43]
	v_lshl_add_u64 v[14:15], v[12:13], 0, v[46:47]
	v_lshl_add_u64 v[8:9], v[12:13], 0, v[28:29]
	global_load_dwordx4 v[8:11], v[8:9], off
	v_and_b32_e32 v136, 0xffffffc0, v135
	global_load_dwordx4 v[56:59], v[14:15], off
	v_lshl_add_u64 v[14:15], v[12:13], 0, v[48:49]
	global_load_dwordx4 v[46:49], v[14:15], off
	v_lshl_add_u64 v[14:15], v[12:13], 0, v[50:51]
	global_load_dwordx4 v[60:63], v[14:15], off
	v_lshl_add_u64 v[14:15], v[12:13], 0, v[52:53]
	v_lshl_add_u64 v[12:13], v[12:13], 0, v[54:55]
	global_load_dwordx4 v[50:53], v[14:15], off
	global_load_dwordx4 v[66:69], v[12:13], off
	s_nop 0
	global_load_dwordx2 v[12:13], v[32:33], off offset:448
	global_load_dwordx4 v[18:21], v[24:25], off offset:1024
	global_load_dwordx4 v[14:17], v[26:27], off offset:1024
	s_waitcnt vmcnt(0) lgkmcnt(0)
	v_cndmask_b32_e32 v82, 0, v9, vcc
	global_load_dwordx4 v[22:25], v[24:25], off offset:1040
	v_cndmask_b32_e32 v83, 0, v8, vcc
	global_load_dwordx4 v[26:29], v[26:27], off offset:1040
	v_cndmask_b32_e64 v54, 0, v57, s[4:5]
	v_cndmask_b32_e64 v56, 0, v56, s[4:5]
	v_cndmask_b32_e64 v55, 0, v47, s[6:7]
	v_cndmask_b32_e64 v57, 0, v46, s[6:7]
	v_cndmask_b32_e32 v139, 0, v11, vcc
	v_cndmask_b32_e32 v146, 0, v10, vcc
	v_cndmask_b32_e64 v151, 0, v63, s[8:9]
	v_cndmask_b32_e64 v152, 0, v62, s[8:9]
	v_cndmask_b32_e64 v157, 0, v67, s[12:13]
	v_cndmask_b32_e64 v158, 0, v66, s[12:13]
	v_lshlrev_b32_e32 v8, 16, v83
	v_lshlrev_b32_e32 v9, 16, v82
	v_lshlrev_b32_e32 v10, 16, v56
	v_lshlrev_b32_e32 v11, 16, v54
	v_lshlrev_b32_e32 v62, 16, v57
	v_lshlrev_b32_e32 v63, 16, v55
	v_readfirstlane_b32 s1, v13
	v_readfirstlane_b32 s0, v12
	v_and_b32_e32 v67, 0xffff0000, v55
	v_and_b32_e32 v66, 0xffff0000, v57
	v_and_b32_e32 v55, 0xffff0000, v54
	v_and_b32_e32 v54, 0xffff0000, v56
	v_and_b32_e32 v57, 0xffff0000, v82
	v_and_b32_e32 v56, 0xffff0000, v83
	v_cndmask_b32_e64 v147, 0, v59, s[4:5]
	v_cndmask_b32_e64 v148, 0, v58, s[4:5]
	v_cndmask_b32_e64 v58, 0, v61, s[8:9]
	v_cndmask_b32_e64 v59, 0, v60, s[8:9]
	v_lshl_add_u64 v[12:13], s[0:1], 0, v[64:65]
	v_pk_add_f32 v[8:9], v[8:9], v[10:11] neg_lo:[0,1] neg_hi:[0,1]
	v_pk_add_f32 v[56:57], v[56:57], v[54:55] neg_lo:[0,1] neg_hi:[0,1]
	v_mov_b32_e32 v82, v18
	v_mov_b32_e32 v83, v20
	v_mov_b32_e32 v20, v19
	v_cndmask_b32_e64 v155, 0, v69, s[12:13]
	v_cndmask_b32_e64 v156, 0, v68, s[12:13]
	v_lshlrev_b32_e32 v68, 16, v59
	v_lshlrev_b32_e32 v69, 16, v58
	v_and_b32_e32 v77, 0xffff0000, v58
	v_and_b32_e32 v76, 0xffff0000, v59
	v_pk_add_f32 v[58:59], v[10:11], v[62:63] neg_lo:[0,1] neg_hi:[0,1]
	v_pk_fma_f32 v[140:141], v[82:83], v[8:9], v[10:11]
	v_pk_fma_f32 v[18:19], v[20:21], v[56:57], v[54:55]
	v_pk_add_f32 v[56:57], v[62:63], v[10:11] neg_lo:[0,1] neg_hi:[0,1]
	global_load_dwordx4 v[8:11], v[12:13], off
	v_mov_b32_e32 v144, v14
	v_mov_b32_e32 v145, v16
	v_mov_b32_e32 v16, v15
	global_load_dwordx4 v[12:15], v[12:13], off offset:16
	v_cndmask_b32_e64 v60, 0, v51, s[10:11]
	v_cndmask_b32_e64 v61, 0, v50, s[10:11]
	v_pk_add_f32 v[142:143], v[66:67], v[54:55] neg_lo:[0,1] neg_hi:[0,1]
	v_lshlrev_b32_e32 v70, 16, v61
	v_lshlrev_b32_e32 v71, 16, v60
	v_and_b32_e32 v79, 0xffff0000, v60
	v_and_b32_e32 v78, 0xffff0000, v61
	v_pk_add_f32 v[60:61], v[54:55], v[66:67] neg_lo:[0,1] neg_hi:[0,1]
	v_pk_fma_f32 v[54:55], v[144:145], v[56:57], v[140:141]
	v_pk_fma_f32 v[56:57], v[16:17], v[142:143], v[18:19]
	v_pk_fma_f32 v[18:19], v[82:83], v[58:59], v[62:63]
	v_pk_add_f32 v[58:59], v[68:69], v[62:63] neg_lo:[0,1] neg_hi:[0,1]
	v_and_b32_e32 v141, 0xffff0000, v157
	v_pk_fma_f32 v[58:59], v[144:145], v[58:59], v[18:19]
	v_pk_fma_f32 v[18:19], v[20:21], v[60:61], v[66:67]
	v_pk_add_f32 v[60:61], v[76:77], v[66:67] neg_lo:[0,1] neg_hi:[0,1]
	v_and_b32_e32 v140, 0xffff0000, v158
	v_pk_fma_f32 v[60:61], v[16:17], v[60:61], v[18:19]
	v_pk_add_f32 v[18:19], v[62:63], v[68:69] neg_lo:[0,1] neg_hi:[0,1]
	v_pk_add_f32 v[62:63], v[70:71], v[68:69] neg_lo:[0,1] neg_hi:[0,1]
	v_pk_fma_f32 v[18:19], v[82:83], v[18:19], v[68:69]
	v_pk_add_f32 v[68:69], v[68:69], v[70:71] neg_lo:[0,1] neg_hi:[0,1]
	v_pk_fma_f32 v[62:63], v[144:145], v[62:63], v[18:19]
	v_pk_add_f32 v[18:19], v[66:67], v[76:77] neg_lo:[0,1] neg_hi:[0,1]
	v_pk_add_f32 v[66:67], v[78:79], v[76:77] neg_lo:[0,1] neg_hi:[0,1]
	v_pk_fma_f32 v[18:19], v[20:21], v[18:19], v[76:77]
	v_pk_fma_f32 v[68:69], v[82:83], v[68:69], v[70:71]
	v_pk_fma_f32 v[66:67], v[16:17], v[66:67], v[18:19]
	v_lshlrev_b32_e32 v19, 16, v157
	v_lshlrev_b32_e32 v18, 16, v158
	v_pk_add_f32 v[18:19], v[18:19], v[70:71] neg_lo:[0,1] neg_hi:[0,1]
	v_cndmask_b32_e64 v149, 0, v49, s[6:7]
	v_pk_fma_f32 v[68:69], v[144:145], v[18:19], v[68:69]
	v_pk_add_f32 v[18:19], v[76:77], v[78:79] neg_lo:[0,1] neg_hi:[0,1]
	v_cndmask_b32_e64 v150, 0, v48, s[6:7]
	v_lshlrev_b32_e32 v74, 16, v146
	v_lshlrev_b32_e32 v75, 16, v139
	v_lshlrev_b32_e32 v72, 16, v148
	v_lshlrev_b32_e32 v73, 16, v147
	v_pk_fma_f32 v[18:19], v[20:21], v[18:19], v[78:79]
	v_pk_add_f32 v[20:21], v[140:141], v[78:79] neg_lo:[0,1] neg_hi:[0,1]
	v_and_b32_e32 v77, 0xffff0000, v147
	v_and_b32_e32 v76, 0xffff0000, v148
	v_and_b32_e32 v141, 0xffff0000, v139
	v_and_b32_e32 v140, 0xffff0000, v146
	v_lshlrev_b32_e32 v80, 16, v150
	v_lshlrev_b32_e32 v81, 16, v149
	v_pk_fma_f32 v[70:71], v[16:17], v[20:21], v[18:19]
	v_and_b32_e32 v17, 0xffff0000, v149
	v_and_b32_e32 v16, 0xffff0000, v150
	v_pk_add_f32 v[74:75], v[74:75], v[72:73] neg_lo:[0,1] neg_hi:[0,1]
	v_pk_add_f32 v[140:141], v[140:141], v[76:77] neg_lo:[0,1] neg_hi:[0,1]
	s_waitcnt vmcnt(0) lgkmcnt(0)
	v_mov_b32_e32 v142, v22
	v_mov_b32_e32 v143, v24
	v_mov_b32_e32 v24, v23
	v_lshlrev_b32_e32 v86, 16, v152
	v_lshlrev_b32_e32 v87, 16, v151
	v_pk_add_f32 v[78:79], v[72:73], v[80:81] neg_lo:[0,1] neg_hi:[0,1]
	v_pk_add_f32 v[82:83], v[76:77], v[16:17] neg_lo:[0,1] neg_hi:[0,1]
	v_pk_fma_f32 v[74:75], v[142:143], v[74:75], v[72:73]
	v_pk_fma_f32 v[22:23], v[24:25], v[140:141], v[76:77]
	v_pk_add_f32 v[72:73], v[80:81], v[72:73] neg_lo:[0,1] neg_hi:[0,1]
	v_pk_add_f32 v[76:77], v[16:17], v[76:77] neg_lo:[0,1] neg_hi:[0,1]
	v_mov_b32_e32 v140, v26
	v_mov_b32_e32 v141, v28
	v_mov_b32_e32 v28, v27
	v_and_b32_e32 v19, 0xffff0000, v151
	v_and_b32_e32 v18, 0xffff0000, v152
	v_pk_fma_f32 v[72:73], v[140:141], v[72:73], v[74:75]
	v_pk_fma_f32 v[74:75], v[28:29], v[76:77], v[22:23]
	v_pk_fma_f32 v[22:23], v[142:143], v[78:79], v[80:81]
	v_pk_add_f32 v[26:27], v[86:87], v[80:81] neg_lo:[0,1] neg_hi:[0,1]
	v_cndmask_b32_e64 v153, 0, v53, s[10:11]
	v_cndmask_b32_e64 v154, 0, v52, s[10:11]
	v_pk_fma_f32 v[76:77], v[140:141], v[26:27], v[22:23]
	v_pk_fma_f32 v[22:23], v[24:25], v[82:83], v[16:17]
	v_pk_add_f32 v[26:27], v[18:19], v[16:17] neg_lo:[0,1] neg_hi:[0,1]
	v_lshlrev_b32_e32 v84, 16, v154
	v_lshlrev_b32_e32 v85, 16, v153
	v_pk_fma_f32 v[78:79], v[28:29], v[26:27], v[22:23]
	v_pk_add_f32 v[22:23], v[80:81], v[86:87] neg_lo:[0,1] neg_hi:[0,1]
	v_and_b32_e32 v21, 0xffff0000, v153
	v_and_b32_e32 v20, 0xffff0000, v154
	v_pk_fma_f32 v[22:23], v[142:143], v[22:23], v[86:87]
	v_pk_add_f32 v[26:27], v[84:85], v[86:87] neg_lo:[0,1] neg_hi:[0,1]
	v_pk_add_f32 v[16:17], v[16:17], v[18:19] neg_lo:[0,1] neg_hi:[0,1]
	v_pk_fma_f32 v[80:81], v[140:141], v[26:27], v[22:23]
	v_pk_fma_f32 v[16:17], v[24:25], v[16:17], v[18:19]
	v_pk_add_f32 v[22:23], v[20:21], v[18:19] neg_lo:[0,1] neg_hi:[0,1]
	v_and_b32_e32 v27, 0xffff0000, v155
	v_pk_fma_f32 v[82:83], v[28:29], v[22:23], v[16:17]
	v_pk_add_f32 v[16:17], v[86:87], v[84:85] neg_lo:[0,1] neg_hi:[0,1]
	v_lshlrev_b32_e32 v23, 16, v155
	v_pk_fma_f32 v[86:87], v[142:143], v[16:17], v[84:85]
	v_mov_b32_e32 v16, v8
	v_mov_b32_e32 v17, v10
	v_mov_b32_e32 v10, v9
	v_pk_mul_f32 v[142:143], v[16:17], v[54:55]
	v_pk_mul_f32 v[144:145], v[56:57], v[10:11]
	v_mov_b32_e32 v8, v143
	v_mov_b32_e32 v9, v145
	v_pk_mul_f32 v[146:147], v[8:9], v[8:9]
	v_mov_b32_e32 v8, v12
	v_mov_b32_e32 v9, v14
	v_mov_b32_e32 v14, v13
	v_mul_f32_e32 v139, v142, v142
	v_pk_mul_f32 v[148:149], v[72:73], v[8:9]
	v_pk_mul_f32 v[12:13], v[74:75], v[14:15]
	v_fmac_f32_e32 v139, v144, v144
	v_mov_b32_e32 v150, v148
	v_mov_b32_e32 v151, v12
	v_add_f32_e32 v139, v139, v146
	v_pk_mul_f32 v[150:151], v[150:151], v[150:151]
	v_add_f32_e32 v139, v139, v147
	v_mov_b32_e32 v152, v149
	v_mov_b32_e32 v153, v13
	v_add_f32_e32 v139, v139, v150
	v_pk_mul_f32 v[152:153], v[152:153], v[152:153]
	v_add_f32_e32 v139, v139, v151
	v_add_f32_e32 v139, v139, v152
	v_add_f32_e32 v139, v139, v153
	v_lshlrev_b32_e32 v22, 16, v156
	v_pk_add_f32 v[22:23], v[22:23], v[84:85] neg_lo:[0,1] neg_hi:[0,1]
	v_add_f32_dpp v139, v139, v139 quad_perm:[1,0,3,2] row_mask:0xf bank_mask:0xf bound_ctrl:1
	v_pk_fma_f32 v[84:85], v[140:141], v[22:23], v[86:87]
	v_and_b32_e32 v26, 0xffff0000, v156
	v_add_f32_dpp v139, v139, v139 quad_perm:[2,3,0,1] row_mask:0xf bank_mask:0xf bound_ctrl:1
	v_pk_add_f32 v[18:19], v[18:19], v[20:21] neg_lo:[0,1] neg_hi:[0,1]
	v_pk_mul_f32 v[140:141], v[78:79], v[14:15]
	v_add_f32_dpp v139, v139, v139 row_half_mirror row_mask:0xf bank_mask:0xf bound_ctrl:1
	v_mul_f32_e32 v146, 0x4f800000, v139
	v_cmp_gt_f32_e32 vcc, s69, v139
	v_pk_fma_f32 v[18:19], v[24:25], v[18:19], v[20:21]
	v_pk_add_f32 v[20:21], v[26:27], v[20:21] neg_lo:[0,1] neg_hi:[0,1]
	v_cndmask_b32_e32 v139, v139, v146, vcc
	v_sqrt_f32_e32 v146, v139
	v_lshl_add_u64 v[52:53], v[88:89], 0, s[44:45]
	v_lshl_add_u64 v[46:47], v[52:53], 0, v[38:39]
	v_lshl_add_u64 v[48:49], v[52:53], 0, v[40:41]
	v_add_u32_e32 v22, -1, v146
	v_fma_f32 v23, -v22, v146, v139
	v_cmp_ge_f32_e64 s[0:1], 0, v23
	v_add_u32_e32 v23, 1, v146
	v_fma_f32 v86, -v23, v146, v139
	v_cndmask_b32_e64 v22, v146, v22, s[0:1]
	v_cmp_lt_f32_e64 s[0:1], 0, v86
	v_pk_fma_f32 v[86:87], v[28:29], v[20:21], v[18:19]
	v_pk_mul_f32 v[28:29], v[76:77], v[8:9]
	v_cndmask_b32_e64 v22, v22, v23, s[0:1]
	v_mul_f32_e32 v23, 0x37800000, v22
	v_cndmask_b32_e32 v22, v22, v23, vcc
	v_cmp_class_f32_e32 vcc, v139, v128
	v_lshl_add_u64 v[50:51], v[52:53], 0, v[42:43]
	v_lshl_add_u64 v[52:53], v[52:53], 0, v[44:45]
	v_cndmask_b32_e32 v22, v22, v139, vcc
	v_max_f32_e32 v22, 0x2b8cbccc, v22
	v_div_scale_f32 v23, s[0:1], v22, v22, 1.0
	v_rcp_f32_e32 v139, v23
	v_mul_f32_e32 v156, v36, v5
	v_mul_f32_e32 v157, v31, v6
	v_mul_f32_e32 v158, v37, v7
	v_fma_f32 v18, -v23, v139, 1.0
	v_fmac_f32_e32 v139, v18, v139
	v_div_scale_f32 v18, vcc, 1.0, v22, 1.0
	v_mul_f32_e32 v19, v18, v139
	v_fma_f32 v20, -v23, v19, v18
	v_fmac_f32_e32 v19, v20, v139
	v_fma_f32 v18, -v23, v19, v18
	v_div_fmas_f32 v18, v18, v139, v19
	v_div_fixup_f32 v18, v18, v22, 1.0
	v_pk_mul_f32 v[20:21], v[142:143], v[18:19] op_sel_hi:[1,0]
	v_pk_mul_f32 v[22:23], v[148:149], v[18:19] op_sel_hi:[1,0]
	v_bfe_u32 v19, v20, 16, 1
	v_bfe_u32 v24, v21, 16, 1
	v_bfe_u32 v25, v22, 16, 1
	v_bfe_u32 v26, v23, 16, 1
	v_add3_u32 v23, v23, v26, s58
	v_add3_u32 v22, v22, v25, s58
	v_add3_u32 v21, v21, v24, s58
	v_add3_u32 v19, v20, v19, s58
	v_pk_mul_f32 v[24:25], v[58:59], v[16:17]
	v_pk_mul_f32 v[26:27], v[60:61], v[10:11]
	v_lshrrev_b32_e32 v139, 16, v19
	v_lshrrev_b32_e32 v19, 16, v21
	v_mov_b32_e32 v20, v27
	v_mov_b32_e32 v21, v25
	v_mul_f32_e32 v148, v24, v24
	v_pk_mul_f32 v[20:21], v[20:21], v[20:21]
	v_fmac_f32_e32 v148, v26, v26
	v_mov_b32_e32 v142, v140
	v_mov_b32_e32 v143, v28
	v_add_f32_e32 v21, v21, v148
	v_pk_mul_f32 v[142:143], v[142:143], v[142:143]
	v_add_f32_e32 v20, v20, v21
	v_lshrrev_b32_e32 v146, 16, v22
	v_lshrrev_b32_e32 v147, 16, v23
	v_pk_mul_f32 v[22:23], v[144:145], v[18:19] op_sel_hi:[1,0]
	v_mov_b32_e32 v144, v141
	v_mov_b32_e32 v145, v29
	v_add_f32_e32 v20, v143, v20
	v_pk_mul_f32 v[144:145], v[144:145], v[144:145]
	v_add_f32_e32 v20, v142, v20
	v_add_f32_e32 v20, v145, v20
	v_add_f32_e32 v20, v144, v20
	v_pk_mul_f32 v[12:13], v[12:13], v[18:19] op_sel_hi:[1,0]
	v_and_or_b32 v19, v23, s54, v19
	v_add_f32_dpp v20, v20, v20 quad_perm:[1,0,3,2] row_mask:0xf bank_mask:0xf bound_ctrl:1
	v_lshlrev_b64 v[36:37], 11, v[94:95]
	v_lshl_add_u64 v[36:37], s[52:53], 0, v[36:37]
	v_add_f32_dpp v20, v20, v20 quad_perm:[2,3,0,1] row_mask:0xf bank_mask:0xf bound_ctrl:1
	v_lshl_add_u64 v[180:181], v[36:37], 0, v[34:35]
	v_or_b32_e32 v36, 3, v137
	v_add_f32_dpp v20, v20, v20 row_half_mirror row_mask:0xf bank_mask:0xf bound_ctrl:1
	v_mul_f32_e32 v21, 0x4f800000, v20
	v_cmp_gt_f32_e32 vcc, s69, v20
	v_mul_lo_u32 v36, v36, s68
	v_add_u32_e32 v119, v64, v36
	v_cndmask_b32_e32 v142, v20, v21, vcc
	v_sqrt_f32_e32 v143, v142
	v_and_or_b32 v20, v12, s54, v146
	v_and_or_b32 v21, v13, s54, v147
	v_lshlrev_b64 v[36:37], 11, v[96:97]
	v_add_u32_e32 v12, -1, v143
	v_fma_f32 v13, -v12, v143, v142
	v_cmp_ge_f32_e64 s[0:1], 0, v13
	v_add_u32_e32 v13, 1, v143
	v_fma_f32 v18, -v13, v143, v142
	v_cndmask_b32_e64 v12, v143, v12, s[0:1]
	v_cmp_lt_f32_e64 s[0:1], 0, v18
	v_and_or_b32 v18, v22, s54, v139
	global_store_dwordx4 v[46:47], v[18:21], off
	v_cndmask_b32_e64 v12, v12, v13, s[0:1]
	v_mul_f32_e32 v13, 0x37800000, v12
	v_cndmask_b32_e32 v12, v12, v13, vcc
	v_cmp_class_f32_e32 vcc, v142, v128
	v_lshl_add_u64 v[36:37], s[52:53], 0, v[36:37]
	v_lshl_add_u64 v[182:183], v[36:37], 0, v[34:35]
	v_cndmask_b32_e32 v12, v12, v142, vcc
	v_max_f32_e32 v12, 0x2b8cbccc, v12
	v_div_scale_f32 v13, s[0:1], v12, v12, 1.0
	v_rcp_f32_e32 v142, v13
	v_mul_f32_e32 v121, v156, v56
	v_mul_f32_e32 v122, v157, v55
	v_mul_f32_e32 v123, v158, v57
	v_fma_f32 v18, -v13, v142, 1.0
	v_fmac_f32_e32 v142, v18, v142
	v_div_scale_f32 v18, vcc, 1.0, v12, 1.0
	v_mul_f32_e32 v19, v18, v142
	v_fma_f32 v20, -v13, v19, v18
	v_fmac_f32_e32 v19, v20, v142
	v_fma_f32 v13, -v13, v19, v18
	v_div_fmas_f32 v13, v13, v142, v19
	v_div_fixup_f32 v12, v13, v12, 1.0
	v_pk_mul_f32 v[18:19], v[24:25], v[12:13] op_sel_hi:[1,0]
	v_pk_mul_f32 v[20:21], v[28:29], v[12:13] op_sel_hi:[1,0]
	v_bfe_u32 v13, v18, 16, 1
	v_bfe_u32 v22, v19, 16, 1
	v_bfe_u32 v23, v20, 16, 1
	v_bfe_u32 v24, v21, 16, 1
	v_add3_u32 v21, v21, v24, s58
	v_add3_u32 v20, v20, v23, s58
	v_add3_u32 v19, v19, v22, s58
	v_add3_u32 v13, v18, v13, s58
	v_pk_mul_f32 v[22:23], v[16:17], v[62:63]
	v_pk_mul_f32 v[24:25], v[66:67], v[10:11]
	v_lshrrev_b32_e32 v139, 16, v13
	v_lshrrev_b32_e32 v146, 16, v19
	v_lshrrev_b32_e32 v147, 16, v20
	v_lshrrev_b32_e32 v148, 16, v21
	v_pk_mul_f32 v[18:19], v[26:27], v[12:13] op_sel_hi:[1,0]
	v_mov_b32_e32 v20, v25
	v_mov_b32_e32 v21, v23
	v_mul_f32_e32 v13, v22, v22
	v_pk_mul_f32 v[20:21], v[20:21], v[20:21]
	v_pk_mul_f32 v[26:27], v[80:81], v[8:9]
	v_pk_mul_f32 v[28:29], v[82:83], v[14:15]
	v_fmac_f32_e32 v13, v24, v24
	v_mov_b32_e32 v142, v28
	v_mov_b32_e32 v143, v26
	v_add_f32_e32 v13, v21, v13
	v_pk_mul_f32 v[142:143], v[142:143], v[142:143]
	v_add_f32_e32 v13, v20, v13
	v_mov_b32_e32 v144, v29
	v_mov_b32_e32 v145, v27
	v_add_f32_e32 v13, v143, v13
	v_pk_mul_f32 v[144:145], v[144:145], v[144:145]
	v_add_f32_e32 v13, v142, v13
	v_add_f32_e32 v13, v145, v13
	v_add_f32_e32 v13, v144, v13
	v_and_or_b32 v19, v19, s54, v146
	v_and_or_b32 v18, v18, s54, v139
	v_add_f32_dpp v13, v13, v13 quad_perm:[1,0,3,2] row_mask:0xf bank_mask:0xf bound_ctrl:1
	v_pk_mul_f32 v[16:17], v[16:17], v[68:69]
	v_pk_mul_f32 v[14:15], v[86:87], v[14:15]
	v_add_f32_dpp v13, v13, v13 quad_perm:[2,3,0,1] row_mask:0xf bank_mask:0xf bound_ctrl:1
	v_mul_f32_e32 v124, v163, v58
	v_mul_f32_e32 v125, v168, v60
	v_add_f32_dpp v13, v13, v13 row_half_mirror row_mask:0xf bank_mask:0xf bound_ctrl:1
	v_mul_f32_e32 v20, 0x4f800000, v13
	v_cmp_gt_f32_e32 vcc, s69, v13
	v_mul_f32_e32 v137, v169, v59
	v_mul_f32_e32 v156, v176, v82
	v_cndmask_b32_e32 v142, v13, v20, vcc
	v_sqrt_f32_e32 v143, v142
	v_pk_mul_f32 v[12:13], v[140:141], v[12:13] op_sel_hi:[1,0]
	v_mul_f32_e32 v157, v177, v81
	v_and_or_b32 v20, v12, s54, v147
	v_add_u32_e32 v12, -1, v143
	v_and_or_b32 v21, v13, s54, v148
	v_fma_f32 v13, -v12, v143, v142
	v_cmp_ge_f32_e64 s[0:1], 0, v13
	v_add_u32_e32 v13, 1, v143
	v_fma_f32 v140, -v13, v143, v142
	v_cndmask_b32_e64 v12, v143, v12, s[0:1]
	v_cmp_lt_f32_e64 s[0:1], 0, v140
	global_store_dwordx4 v[48:49], v[18:21], off
	v_mul_f32_e32 v158, v178, v83
	v_cndmask_b32_e64 v12, v12, v13, s[0:1]
	v_mul_f32_e32 v13, 0x37800000, v12
	v_cndmask_b32_e32 v12, v12, v13, vcc
	v_cmp_class_f32_e32 vcc, v142, v128
	s_nop 1
	v_cndmask_b32_e32 v12, v12, v142, vcc
	v_max_f32_e32 v12, 0x2b8cbccc, v12
	v_div_scale_f32 v13, s[0:1], v12, v12, 1.0
	v_rcp_f32_e32 v140, v13
	s_nop 0
	v_fma_f32 v18, -v13, v140, 1.0
	v_fmac_f32_e32 v140, v18, v140
	v_div_scale_f32 v18, vcc, 1.0, v12, 1.0
	v_mul_f32_e32 v19, v18, v140
	v_fma_f32 v20, -v13, v19, v18
	v_fmac_f32_e32 v19, v20, v140
	v_fma_f32 v13, -v13, v19, v18
	v_div_fmas_f32 v13, v13, v140, v19
	v_div_fixup_f32 v12, v13, v12, 1.0
	v_pk_mul_f32 v[20:21], v[26:27], v[12:13] op_sel_hi:[1,0]
	v_pk_mul_f32 v[18:19], v[22:23], v[12:13] op_sel_hi:[1,0]
	v_bfe_u32 v23, v20, 16, 1
	v_bfe_u32 v26, v21, 16, 1
	v_add3_u32 v21, v21, v26, s58
	v_add3_u32 v20, v20, v23, s58
	v_lshrrev_b32_e32 v27, 16, v20
	v_lshrrev_b32_e32 v139, 16, v21
	v_pk_mul_f32 v[20:21], v[10:11], v[70:71]
	v_bfe_u32 v22, v19, 16, 1
	v_mov_b32_e32 v10, v21
	v_mov_b32_e32 v11, v17
	v_mul_f32_e32 v140, v16, v16
	v_bfe_u32 v13, v18, 16, 1
	v_add3_u32 v19, v19, v22, s58
	v_pk_mul_f32 v[10:11], v[10:11], v[10:11]
	v_pk_mul_f32 v[22:23], v[84:85], v[8:9]
	v_fmac_f32_e32 v140, v20, v20
	v_add3_u32 v13, v18, v13, s58
	v_mov_b32_e32 v8, v14
	v_mov_b32_e32 v9, v22
	v_add_f32_e32 v11, v11, v140
	v_lshrrev_b32_e32 v13, 16, v13
	v_pk_mul_f32 v[8:9], v[8:9], v[8:9]
	v_add_f32_e32 v10, v10, v11
	v_lshrrev_b32_e32 v26, 16, v19
	v_pk_mul_f32 v[18:19], v[24:25], v[12:13] op_sel_hi:[1,0]
	v_mov_b32_e32 v24, v15
	v_mov_b32_e32 v25, v23
	v_add_f32_e32 v9, v9, v10
	v_pk_mul_f32 v[24:25], v[24:25], v[24:25]
	v_add_f32_e32 v8, v8, v9
	v_add_f32_e32 v8, v25, v8
	v_add_f32_e32 v8, v24, v8
	s_nop 1
	v_add_f32_dpp v8, v8, v8 quad_perm:[1,0,3,2] row_mask:0xf bank_mask:0xf bound_ctrl:1
	s_nop 1
	v_add_f32_dpp v8, v8, v8 quad_perm:[2,3,0,1] row_mask:0xf bank_mask:0xf bound_ctrl:1
	s_nop 1
	v_add_f32_dpp v8, v8, v8 row_half_mirror row_mask:0xf bank_mask:0xf bound_ctrl:1
	v_mul_f32_e32 v9, 0x4f800000, v8
	v_cmp_gt_f32_e32 vcc, s69, v8
	s_nop 1
	v_cndmask_b32_e32 v24, v8, v9, vcc
	v_sqrt_f32_e32 v25, v24
	v_pk_mul_f32 v[8:9], v[28:29], v[12:13] op_sel_hi:[1,0]
	s_nop 0
	v_and_or_b32 v10, v8, s54, v27
	v_add_u32_e32 v8, -1, v25
	v_and_or_b32 v11, v9, s54, v139
	v_fma_f32 v9, -v8, v25, v24
	v_cmp_ge_f32_e64 s[0:1], 0, v9
	v_add_u32_e32 v9, 1, v25
	v_fma_f32 v12, -v9, v25, v24
	v_cndmask_b32_e64 v8, v25, v8, s[0:1]
	v_cmp_lt_f32_e64 s[0:1], 0, v12
	v_mul_f32_e32 v139, v4, v30
	v_mul_f32_e32 v120, v139, v54
	v_cndmask_b32_e64 v8, v8, v9, s[0:1]
	v_mul_f32_e32 v9, 0x37800000, v8
	v_cndmask_b32_e32 v8, v8, v9, vcc
	v_cmp_class_f32_e32 vcc, v24, v128
	v_and_or_b32 v9, v19, s54, v26
	v_mul_f32_e32 v139, v110, v62
	v_cndmask_b32_e32 v8, v8, v24, vcc
	v_max_f32_e32 v12, 0x2b8cbccc, v8
	v_div_scale_f32 v24, s[0:1], v12, v12, 1.0
	v_rcp_f32_e32 v25, v24
	v_and_or_b32 v8, v18, s54, v13
	global_store_dwordx4 v[50:51], v[8:11], off
	s_nop 1
	v_fma_f32 v8, -v24, v25, 1.0
	v_fmac_f32_e32 v25, v8, v25
	v_div_scale_f32 v8, vcc, 1.0, v12, 1.0
	v_mul_f32_e32 v9, v8, v25
	v_fma_f32 v10, -v24, v9, v8
	v_fmac_f32_e32 v9, v10, v25
	v_fma_f32 v8, -v24, v9, v8
	v_div_fmas_f32 v8, v8, v25, v9
	v_div_fixup_f32 v8, v8, v12, 1.0
	v_pk_mul_f32 v[10:11], v[16:17], v[8:9] op_sel_hi:[1,0]
	v_pk_mul_f32 v[12:13], v[22:23], v[8:9] op_sel_hi:[1,0]
	v_bfe_u32 v9, v10, 16, 1
	v_bfe_u32 v16, v11, 16, 1
	v_bfe_u32 v17, v12, 16, 1
	v_bfe_u32 v18, v13, 16, 1
	v_add3_u32 v13, v13, v18, s58
	v_add3_u32 v12, v12, v17, s58
	v_add3_u32 v11, v11, v16, s58
	v_add3_u32 v9, v10, v9, s58
	v_lshrrev_b32_e32 v16, 16, v9
	v_lshrrev_b32_e32 v17, 16, v11
	v_lshrrev_b32_e32 v10, 16, v12
	v_lshrrev_b32_e32 v11, 16, v13
	v_pk_mul_f32 v[12:13], v[20:21], v[8:9] op_sel_hi:[1,0]
	v_pk_mul_f32 v[8:9], v[14:15], v[8:9] op_sel_hi:[1,0]
	v_lshlrev_b64 v[24:25], 11, v[90:91]
	v_and_or_b32 v11, v9, s54, v11
	v_and_or_b32 v10, v8, s54, v10
	v_and_or_b32 v9, v13, s54, v17
	v_and_or_b32 v8, v12, s54, v16
	global_store_dwordx4 v[52:53], v[8:11], off
	s_waitcnt lgkmcnt(0)
	s_barrier
	v_mov_b32_e32 v8, v65
	v_lshl_add_u64 v[24:25], s[52:53], 0, v[24:25]
	v_mbcnt_lo_u32_b32 v8, -1, v8
	v_mbcnt_hi_u32_b32 v10, -1, v8
	v_and_b32_e32 v20, 31, v10
	v_or_b32_e32 v8, v20, v136
	v_ashrrev_i32_e32 v9, 31, v8
	v_ashrrev_i32_e32 v10, 2, v10
	v_lshlrev_b64 v[8:9], 8, v[8:9]
	v_and_b32_e32 v12, -8, v10
	v_lshl_add_u64 v[8:9], s[52:53], 0, v[8:9]
	v_ashrrev_i32_e32 v13, 31, v12
	v_lshl_add_u64 v[14:15], v[12:13], 1, v[8:9]
	v_add_co_u32_e32 v8, vcc, s70, v14
	v_lshl_add_u64 v[166:167], v[14:15], 0, s[46:47]
	s_nop 0
	v_addc_co_u32_e32 v9, vcc, 0, v15, vcc
	v_add_co_u32_e32 v164, vcc, s71, v14
	global_load_dwordx4 v[8:11], v[8:9], off
	s_nop 0
	v_addc_co_u32_e32 v165, vcc, 0, v15, vcc
	global_load_dwordx4 v[16:19], v[164:165], off
	global_load_dwordx4 v[140:143], v[166:167], off offset:32
	global_load_dwordx4 v[144:147], v[164:165], off offset:32
	global_load_dwordx4 v[148:151], v[166:167], off offset:64
	global_load_dwordx4 v[98:101], v[166:167], off offset:96
	global_load_dwordx4 v[152:155], v[164:165], off offset:64
	global_load_dwordx4 v[102:105], v[164:165], off offset:96
	v_lshlrev_b32_e32 v0, 1, v12
	v_mad_u32_u24 v191, v20, s63, v0
	ds_read_b128 v[20:23], v191
	ds_read_b128 v[106:109], v191 offset:32
	v_lshrrev_b32_e32 v0, 3, v135
	v_and_b32_e32 v0, 4, v0
	v_mul_u32_u24_e32 v0, 0x410, v0
	v_lshl_add_u64 v[114:115], v[24:25], 0, v[34:35]
	v_lshlrev_b64 v[24:25], 11, v[92:93]
	v_lshl_add_u32 v192, v1, 2, v0
	v_mul_lo_u32 v0, v138, s68
	v_lshl_add_u64 v[24:25], s[52:53], 0, v[24:25]
	v_add_u32_e32 v118, v64, v0
	s_waitcnt vmcnt(0) lgkmcnt(0)
	v_mfma_f32_32x32x16_bf16 v[0:15], v[20:23], v[8:11], 0
	v_lshl_add_u64 v[116:117], v[24:25], 0, v[34:35]
	ds_read_b128 v[34:37], v191 offset:64
	v_mul_f32_e32 v138, v170, v61
	v_mfma_f32_32x32x16_bf16 v[16:31], v[20:23], v[16:19], 0
	v_mfma_f32_32x32x16_bf16 v[0:15], v[106:109], v[140:143], v[0:15]
	v_mul_f32_e32 v140, v112, v66
	v_mul_f32_e32 v141, v111, v63
	v_mul_f32_e32 v142, v113, v67
	v_mul_f32_e32 v143, v179, v68
	v_mfma_f32_32x32x16_bf16 v[16:31], v[106:109], v[144:147], v[16:31]
	ds_read_b128 v[106:109], v191 offset:96
	v_mul_f32_e32 v144, v184, v70
	v_mul_f32_e32 v145, v185, v69
	v_mul_f32_e32 v146, v186, v71
	v_mul_f32_e32 v147, v159, v72
	v_mul_f32_e32 v159, v187, v84
	s_waitcnt lgkmcnt(1)
	v_mfma_f32_32x32x16_bf16 v[0:15], v[34:37], v[148:151], v[0:15]
	v_mul_f32_e32 v148, v160, v74
	v_mul_f32_e32 v149, v161, v73
	v_mul_f32_e32 v150, v162, v75
	v_mul_f32_e32 v151, v171, v76
	v_mul_f32_e32 v160, v188, v86
	v_mul_f32_e32 v161, v189, v85
	v_mul_f32_e32 v162, v190, v87
	v_mfma_f32_32x32x16_bf16 v[16:31], v[34:37], v[152:155], v[16:31]
	v_mul_f32_e32 v152, v172, v78
	v_mul_f32_e32 v153, v173, v77
	v_mul_f32_e32 v154, v174, v79
	v_mul_f32_e32 v155, v175, v80
	s_waitcnt lgkmcnt(0)
	v_mfma_f32_32x32x16_bf16 v[0:15], v[106:109], v[98:101], v[0:15]
	v_mfma_f32_32x32x16_bf16 v[16:31], v[106:109], v[102:105], v[16:31]
	global_load_dwordx4 v[34:37], v[166:167], off offset:128
	global_load_dwordx4 v[98:101], v[164:165], off offset:128
	ds_read_b128 v[102:105], v191 offset:128
	ds_read_b128 v[110:113], v191 offset:160
	global_load_dwordx4 v[106:109], v[166:167], off offset:160
	s_waitcnt vmcnt(0) lgkmcnt(0)
	v_mfma_f32_32x32x16_bf16 v[0:15], v[102:105], v[34:37], v[0:15]
	global_load_dwordx4 v[34:37], v[164:165], off offset:160
	v_mfma_f32_32x32x16_bf16 v[16:31], v[102:105], v[98:101], v[16:31]
	global_load_dwordx4 v[98:101], v[166:167], off offset:192
	global_load_dwordx4 v[102:105], v[164:165], off offset:192
	v_mfma_f32_32x32x16_bf16 v[0:15], v[110:113], v[106:109], v[0:15]
	ds_read_b128 v[106:109], v191 offset:192
	s_waitcnt vmcnt(0) lgkmcnt(0)
	v_mfma_f32_32x32x16_bf16 v[16:31], v[110:113], v[34:37], v[16:31]
	global_load_dwordx4 v[34:37], v[166:167], off offset:224
	ds_read_b128 v[110:113], v191 offset:224
	v_mfma_f32_32x32x16_bf16 v[0:15], v[106:109], v[98:101], v[0:15]
	global_load_dwordx4 v[98:101], v[164:165], off offset:224
	v_mfma_f32_32x32x16_bf16 v[16:31], v[106:109], v[102:105], v[16:31]
	s_waitcnt vmcnt(0) lgkmcnt(0)
	v_mfma_f32_32x32x16_bf16 v[0:15], v[110:113], v[34:37], v[0:15]
	v_mfma_f32_32x32x16_bf16 v[16:31], v[110:113], v[98:101], v[16:31]
	v_add_u32_e32 v163, 0x6000, v192
	v_add_u32_e32 v164, 0x6400, v192
	v_add_u32_e32 v165, 0x6800, v192
	v_add_u32_e32 v166, 0x6c00, v192
	v_add_u32_e32 v167, 0x8000, v192
	v_add_u32_e32 v168, 0x8400, v192
	v_add_u32_e32 v169, 0x8800, v192
	v_add_u32_e32 v170, 0x8c00, v192
	v_add_u32_e32 v171, 0xa000, v192
	v_add_u32_e32 v172, 0xa400, v192
	v_add_u32_e32 v173, 0xa800, v192
	v_add_u32_e32 v174, 0xac00, v192
	v_add_u32_e32 v175, 0xc200, v192
	v_add_u32_e32 v176, 0xc600, v192
	v_add_u32_e32 v177, 0xca00, v192
	v_add_u32_e32 v178, 0xce00, v192
	ds_write2_b32 v163, v0, v16 offset0:128 offset1:160
	ds_write2_b32 v164, v1, v17 offset0:132 offset1:164
	ds_write2_b32 v165, v2, v18 offset0:136 offset1:168
	ds_write2_b32 v166, v3, v19 offset0:140 offset1:172
	ds_write2_b32 v167, v4, v20 offset0:160 offset1:192
	ds_write2_b32 v168, v5, v21 offset0:164 offset1:196
	ds_write2_b32 v169, v6, v22 offset0:168 offset1:200
	ds_write2_b32 v170, v7, v23 offset0:172 offset1:204
	ds_write2_b32 v171, v8, v24 offset0:192 offset1:224
	ds_write2_b32 v172, v9, v25 offset0:196 offset1:228
	ds_write2_b32 v173, v10, v26 offset0:200 offset1:232
	ds_write2_b32 v174, v11, v27 offset0:204 offset1:236
	ds_write2_b32 v175, v12, v28 offset0:96 offset1:128
	ds_write2_b32 v176, v13, v29 offset0:100 offset1:132
	ds_write2_b32 v177, v14, v30 offset0:104 offset1:136
	ds_write2_b32 v178, v15, v31 offset0:108 offset1:140
	s_waitcnt lgkmcnt(0)
	s_barrier
	ds_read_b128 v[0:3], v118 offset:25088
	ds_read_b128 v[4:7], v118 offset:25104
	s_add_u32 s77, s52, 0x1b0d7900
	s_addc_u32 s78, s53, 0
	s_add_u32 s79, s52, 0x1d4d7900
	s_waitcnt lgkmcnt(1)
	v_and_b32_sdwa v8, v2, v134 dst_sel:DWORD dst_unused:UNUSED_PAD src0_sel:WORD_1 src1_sel:DWORD
	v_and_b32_sdwa v9, v0, v134 dst_sel:DWORD dst_unused:UNUSED_PAD src0_sel:WORD_1 src1_sel:DWORD
	v_add3_u32 v2, v2, v8, s58
	v_and_b32_sdwa v8, v3, v134 dst_sel:DWORD dst_unused:UNUSED_PAD src0_sel:WORD_1 src1_sel:DWORD
	v_add3_u32 v0, v0, v9, s58
	v_and_b32_sdwa v9, v1, v134 dst_sel:DWORD dst_unused:UNUSED_PAD src0_sel:WORD_1 src1_sel:DWORD
	v_add3_u32 v3, v3, v8, s58
	v_add3_u32 v1, v1, v9, s58
	v_and_b32_e32 v3, 0xffff0000, v3
	v_and_b32_e32 v8, 0xffff0000, v1
	v_or_b32_sdwa v1, v3, v2 dst_sel:DWORD dst_unused:UNUSED_PAD src0_sel:DWORD src1_sel:WORD_1
	s_waitcnt lgkmcnt(0)
	v_and_b32_sdwa v2, v6, v134 dst_sel:DWORD dst_unused:UNUSED_PAD src0_sel:WORD_1 src1_sel:DWORD
	v_and_b32_sdwa v3, v4, v134 dst_sel:DWORD dst_unused:UNUSED_PAD src0_sel:WORD_1 src1_sel:DWORD
	v_add3_u32 v4, v4, v3, s58
	v_add3_u32 v2, v6, v2, s58
	v_and_b32_sdwa v3, v7, v134 dst_sel:DWORD dst_unused:UNUSED_PAD src0_sel:WORD_1 src1_sel:DWORD
	v_and_b32_sdwa v6, v5, v134 dst_sel:DWORD dst_unused:UNUSED_PAD src0_sel:WORD_1 src1_sel:DWORD
	v_add3_u32 v3, v7, v3, s58
	v_add3_u32 v5, v5, v6, s58
	v_and_b32_e32 v3, 0xffff0000, v3
	v_and_b32_e32 v5, 0xffff0000, v5
	v_or_b32_sdwa v3, v3, v2 dst_sel:DWORD dst_unused:UNUSED_PAD src0_sel:DWORD src1_sel:WORD_1
	v_or_b32_sdwa v2, v5, v4 dst_sel:DWORD dst_unused:UNUSED_PAD src0_sel:DWORD src1_sel:WORD_1
	v_add_co_u32_e32 v4, vcc, s72, v114
	v_or_b32_sdwa v0, v8, v0 dst_sel:DWORD dst_unused:UNUSED_PAD src0_sel:DWORD src1_sel:WORD_1
	s_nop 0
	v_addc_co_u32_e32 v5, vcc, 0, v115, vcc
	global_store_dwordx4 v[4:5], v[0:3], off offset:2816
	ds_read_b128 v[0:3], v118 offset:26128
	ds_read_b128 v[4:7], v118 offset:26144
	s_addc_u32 s80, s53, 0
	s_add_u32 s81, s52, 0x1738000
	s_addc_u32 s82, s53, 0
	s_waitcnt lgkmcnt(0)
	v_and_b32_sdwa v8, v2, v134 dst_sel:DWORD dst_unused:UNUSED_PAD src0_sel:WORD_1 src1_sel:DWORD
	v_and_b32_sdwa v9, v0, v134 dst_sel:DWORD dst_unused:UNUSED_PAD src0_sel:WORD_1 src1_sel:DWORD
	v_add3_u32 v2, v2, v8, s58
	v_and_b32_sdwa v8, v3, v134 dst_sel:DWORD dst_unused:UNUSED_PAD src0_sel:WORD_1 src1_sel:DWORD
	v_add3_u32 v0, v0, v9, s58
	v_and_b32_sdwa v9, v1, v134 dst_sel:DWORD dst_unused:UNUSED_PAD src0_sel:WORD_1 src1_sel:DWORD
	v_add3_u32 v3, v3, v8, s58
	v_add3_u32 v1, v1, v9, s58
	v_and_b32_e32 v3, 0xffff0000, v3
	v_and_b32_e32 v8, 0xffff0000, v1
	v_or_b32_sdwa v1, v3, v2 dst_sel:DWORD dst_unused:UNUSED_PAD src0_sel:DWORD src1_sel:WORD_1
	v_and_b32_sdwa v2, v6, v134 dst_sel:DWORD dst_unused:UNUSED_PAD src0_sel:WORD_1 src1_sel:DWORD
	v_and_b32_sdwa v3, v4, v134 dst_sel:DWORD dst_unused:UNUSED_PAD src0_sel:WORD_1 src1_sel:DWORD
	v_add3_u32 v4, v4, v3, s58
	v_add3_u32 v2, v6, v2, s58
	v_and_b32_sdwa v3, v7, v134 dst_sel:DWORD dst_unused:UNUSED_PAD src0_sel:WORD_1 src1_sel:DWORD
	v_and_b32_sdwa v6, v5, v134 dst_sel:DWORD dst_unused:UNUSED_PAD src0_sel:WORD_1 src1_sel:DWORD
	v_add3_u32 v3, v7, v3, s58
	v_add3_u32 v5, v5, v6, s58
	v_and_b32_e32 v3, 0xffff0000, v3
	v_and_b32_e32 v5, 0xffff0000, v5
	v_or_b32_sdwa v3, v3, v2 dst_sel:DWORD dst_unused:UNUSED_PAD src0_sel:DWORD src1_sel:WORD_1
	v_or_b32_sdwa v2, v5, v4 dst_sel:DWORD dst_unused:UNUSED_PAD src0_sel:DWORD src1_sel:WORD_1
	v_add_co_u32_e32 v4, vcc, s72, v116
	v_or_b32_sdwa v0, v8, v0 dst_sel:DWORD dst_unused:UNUSED_PAD src0_sel:DWORD src1_sel:WORD_1
	s_nop 0
	v_addc_co_u32_e32 v5, vcc, 0, v117, vcc
	global_store_dwordx4 v[4:5], v[0:3], off offset:2816
	ds_read_b128 v[0:3], v118 offset:27168
	ds_read_b128 v[4:7], v118 offset:27184
	v_lshl_add_u64 v[88:89], v[88:89], 0, s[48:49]
	s_mov_b64 s[8:9], -1
	s_waitcnt lgkmcnt(0)
	v_and_b32_sdwa v8, v2, v134 dst_sel:DWORD dst_unused:UNUSED_PAD src0_sel:WORD_1 src1_sel:DWORD
	v_and_b32_sdwa v9, v0, v134 dst_sel:DWORD dst_unused:UNUSED_PAD src0_sel:WORD_1 src1_sel:DWORD
	v_add3_u32 v2, v2, v8, s58
	v_and_b32_sdwa v8, v3, v134 dst_sel:DWORD dst_unused:UNUSED_PAD src0_sel:WORD_1 src1_sel:DWORD
	v_add3_u32 v0, v0, v9, s58
	v_and_b32_sdwa v9, v1, v134 dst_sel:DWORD dst_unused:UNUSED_PAD src0_sel:WORD_1 src1_sel:DWORD
	v_add3_u32 v3, v3, v8, s58
	v_add3_u32 v1, v1, v9, s58
	v_and_b32_e32 v3, 0xffff0000, v3
	v_and_b32_e32 v8, 0xffff0000, v1
	v_or_b32_sdwa v1, v3, v2 dst_sel:DWORD dst_unused:UNUSED_PAD src0_sel:DWORD src1_sel:WORD_1
	v_and_b32_sdwa v2, v6, v134 dst_sel:DWORD dst_unused:UNUSED_PAD src0_sel:WORD_1 src1_sel:DWORD
	v_and_b32_sdwa v3, v4, v134 dst_sel:DWORD dst_unused:UNUSED_PAD src0_sel:WORD_1 src1_sel:DWORD
	v_add3_u32 v4, v4, v3, s58
	v_add3_u32 v2, v6, v2, s58
	v_and_b32_sdwa v3, v7, v134 dst_sel:DWORD dst_unused:UNUSED_PAD src0_sel:WORD_1 src1_sel:DWORD
	v_and_b32_sdwa v6, v5, v134 dst_sel:DWORD dst_unused:UNUSED_PAD src0_sel:WORD_1 src1_sel:DWORD
	v_add3_u32 v3, v7, v3, s58
	v_add3_u32 v5, v5, v6, s58
	v_and_b32_e32 v3, 0xffff0000, v3
	v_and_b32_e32 v5, 0xffff0000, v5
	v_or_b32_sdwa v3, v3, v2 dst_sel:DWORD dst_unused:UNUSED_PAD src0_sel:DWORD src1_sel:WORD_1
	v_or_b32_sdwa v2, v5, v4 dst_sel:DWORD dst_unused:UNUSED_PAD src0_sel:DWORD src1_sel:WORD_1
	v_add_co_u32_e32 v4, vcc, s72, v180
	v_or_b32_sdwa v0, v8, v0 dst_sel:DWORD dst_unused:UNUSED_PAD src0_sel:DWORD src1_sel:WORD_1
	s_nop 0
	v_addc_co_u32_e32 v5, vcc, 0, v181, vcc
	global_store_dwordx4 v[4:5], v[0:3], off offset:2816
	ds_read_b128 v[0:3], v119 offset:25088
	ds_read_b128 v[4:7], v119 offset:25104
	s_waitcnt lgkmcnt(0)
	v_and_b32_sdwa v8, v2, v134 dst_sel:DWORD dst_unused:UNUSED_PAD src0_sel:WORD_1 src1_sel:DWORD
	v_and_b32_sdwa v9, v0, v134 dst_sel:DWORD dst_unused:UNUSED_PAD src0_sel:WORD_1 src1_sel:DWORD
	v_add3_u32 v2, v2, v8, s58
	v_and_b32_sdwa v8, v3, v134 dst_sel:DWORD dst_unused:UNUSED_PAD src0_sel:WORD_1 src1_sel:DWORD
	v_add3_u32 v0, v0, v9, s58
	v_and_b32_sdwa v9, v1, v134 dst_sel:DWORD dst_unused:UNUSED_PAD src0_sel:WORD_1 src1_sel:DWORD
	v_add3_u32 v3, v3, v8, s58
	v_add3_u32 v1, v1, v9, s58
	v_and_b32_e32 v3, 0xffff0000, v3
	v_and_b32_e32 v8, 0xffff0000, v1
	v_or_b32_sdwa v1, v3, v2 dst_sel:DWORD dst_unused:UNUSED_PAD src0_sel:DWORD src1_sel:WORD_1
	v_and_b32_sdwa v2, v6, v134 dst_sel:DWORD dst_unused:UNUSED_PAD src0_sel:WORD_1 src1_sel:DWORD
	v_and_b32_sdwa v3, v4, v134 dst_sel:DWORD dst_unused:UNUSED_PAD src0_sel:WORD_1 src1_sel:DWORD
	v_add3_u32 v4, v4, v3, s58
	v_add3_u32 v2, v6, v2, s58
	v_and_b32_sdwa v3, v7, v134 dst_sel:DWORD dst_unused:UNUSED_PAD src0_sel:WORD_1 src1_sel:DWORD
	v_and_b32_sdwa v6, v5, v134 dst_sel:DWORD dst_unused:UNUSED_PAD src0_sel:WORD_1 src1_sel:DWORD
	v_add3_u32 v3, v7, v3, s58
	v_add3_u32 v5, v5, v6, s58
	v_and_b32_e32 v3, 0xffff0000, v3
	v_and_b32_e32 v5, 0xffff0000, v5
	v_or_b32_sdwa v3, v3, v2 dst_sel:DWORD dst_unused:UNUSED_PAD src0_sel:DWORD src1_sel:WORD_1
	v_or_b32_sdwa v2, v5, v4 dst_sel:DWORD dst_unused:UNUSED_PAD src0_sel:DWORD src1_sel:WORD_1
	v_add_co_u32_e32 v4, vcc, s72, v182
	v_or_b32_sdwa v0, v8, v0 dst_sel:DWORD dst_unused:UNUSED_PAD src0_sel:DWORD src1_sel:WORD_1
	s_nop 0
	v_addc_co_u32_e32 v5, vcc, 0, v183, vcc
	global_store_dwordx4 v[4:5], v[0:3], off offset:2816
	s_waitcnt lgkmcnt(0)
	s_barrier
	global_load_dwordx2 v[0:1], v[32:33], off offset:456
	v_and_b32_e32 v8, 7, v135
	v_lshlrev_b64 v[2:3], 8, v[92:93]
	v_lshlrev_b64 v[4:5], 8, v[94:95]
	v_lshlrev_b64 v[6:7], 8, v[96:97]
	v_cmp_eq_u32_e64 s[4:5], 0, v8
	v_or_b32_e32 v2, v2, v126
	v_or_b32_e32 v4, v4, v126
	v_or_b32_e32 v6, v6, v126
	v_lshlrev_b64 v[92:93], 4, v[92:93]
	v_lshlrev_b64 v[94:95], 4, v[94:95]
	v_lshlrev_b64 v[96:97], 4, v[96:97]
	v_lshlrev_b64 v[104:105], 1, v[2:3]
	v_lshlrev_b64 v[106:107], 1, v[4:5]
	v_lshlrev_b64 v[108:109], 1, v[6:7]
	s_waitcnt vmcnt(0) lgkmcnt(0)
	v_readfirstlane_b32 s1, v1
	v_readfirstlane_b32 s0, v0
	s_nop 1
	v_lshl_add_u64 v[0:1], s[0:1], 0, v[64:65]
	global_load_dwordx4 v[30:33], v[0:1], off
	global_load_dwordx4 v[34:37], v[0:1], off offset:16
	s_add_u32 s0, s52, 0x2954198
	s_addc_u32 s1, s53, 0
	s_add_u32 s83, s52, 0x1748000
	v_lshlrev_b64 v[0:1], 8, v[90:91]
	s_addc_u32 s84, s53, 0
	v_bfe_u32 v64, v135, 1, 4
	v_or_b32_e32 v0, v0, v126
	s_add_u32 s6, s52, 0x29541a8
	v_lshl_add_u64 v[8:9], s[52:53], 0, v[64:65]
	v_lshlrev_b64 v[90:91], 4, v[90:91]
	s_addc_u32 s7, s53, 0
	v_lshl_add_u64 v[98:99], v[8:9], 0, s[50:51]
	v_lshlrev_b32_e32 v64, 2, v126
	s_waitcnt vmcnt(0) lgkmcnt(0)
	v_mov_b32_e32 v100, v30
	v_mov_b32_e32 v101, v32
	v_mov_b32_e32 v32, v31
	v_mov_b32_e32 v102, v34
	v_mov_b32_e32 v103, v36
	v_mov_b32_e32 v36, v35
	v_lshlrev_b64 v[34:35], 1, v[0:1]
	s_branch .LBB0_426

.LBB0_609:
	s_or_b64 exec, exec, s[6:7]
	v_cvt_pk_bf16_f32 v12, v12, v11
	v_bfe_u32 v3, v4, 16, 1
	v_add3_u32 v3, v4, v3, s59
	v_bfe_u32 v4, v0, 16, 1
	v_lshrrev_b32_e32 v3, 16, v3
	v_add3_u32 v0, v0, v4, s59
	v_and_or_b32 v13, v0, s63, v3
	v_cvt_pk_bf16_f32 v14, v5, v1
	v_cvt_pk_bf16_f32 v15, v6, v2
	v_lshl_or_b32 v0, v10, 9, v36
	ds_write_b128 v0, v[12:15]

.LBB0_628:
	s_or_b64 exec, exec, s[6:7]
	v_cvt_pk_bf16_f32 v12, v13, v12
	v_bfe_u32 v3, v4, 16, 1
	v_add3_u32 v3, v4, v3, s59
	v_bfe_u32 v4, v0, 16, 1
	v_lshrrev_b32_e32 v3, 16, v3
	v_add3_u32 v0, v0, v4, s59
	v_and_or_b32 v13, v0, s63, v3
	v_cvt_pk_bf16_f32 v14, v5, v1
	v_cvt_pk_bf16_f32 v15, v6, v2
	v_lshl_or_b32 v0, v11, 9, v36
	ds_write_b128 v0, v[12:15]

.LBB0_683:
	v_add_u32_e32 v35, s0, v24
	v_add_u32_e32 v37, s0, v25
	ds_read_b128 v[50:53], v35
	ds_read_b128 v[54:57], v37
	s_addk_i32 s0, 0x200
	s_cmpk_lg_i32 s0, 0x3e00
	s_waitcnt lgkmcnt(1)
	v_lshlrev_b32_e32 v75, 16, v51
	v_lshlrev_b32_e32 v74, 16, v50
	s_waitcnt lgkmcnt(0)
	v_lshlrev_b32_e32 v77, 16, v55
	v_lshlrev_b32_e32 v76, 16, v54
	v_and_b32_e32 v51, 0xffff0000, v51
	v_and_b32_e32 v50, 0xffff0000, v50
	v_and_b32_e32 v55, 0xffff0000, v55
	v_and_b32_e32 v54, 0xffff0000, v54
	v_lshlrev_b32_e32 v79, 16, v53
	v_lshlrev_b32_e32 v78, 16, v52
	v_lshlrev_b32_e32 v81, 16, v57
	v_lshlrev_b32_e32 v80, 16, v56
	v_and_b32_e32 v53, 0xffff0000, v53
	v_and_b32_e32 v52, 0xffff0000, v52
	v_and_b32_e32 v57, 0xffff0000, v57
	v_and_b32_e32 v56, 0xffff0000, v56
	v_pk_fma_f32 v[68:69], v[8:9], v[76:77], v[68:69]
	v_pk_fma_f32 v[64:65], v[12:13], v[54:55], v[64:65]
	v_pk_fma_f32 v[60:61], v[16:17], v[80:81], v[60:61]
	v_pk_fma_f32 v[58:59], v[22:23], v[56:57], v[58:59]
	v_pk_fma_f32 v[72:73], v[0:1], v[76:77], v[72:73]
	v_pk_fma_f32 v[70:71], v[4:5], v[54:55], v[70:71]
	v_pk_fma_f32 v[66:67], v[10:11], v[80:81], v[66:67]
	v_pk_fma_f32 v[62:63], v[18:19], v[56:57], v[62:63]
	v_pk_fma_f32 v[48:49], v[2:3], v[76:77], v[48:49]
	v_pk_fma_f32 v[46:47], v[6:7], v[54:55], v[46:47]
	v_pk_fma_f32 v[44:45], v[14:15], v[80:81], v[44:45]
	v_pk_fma_f32 v[42:43], v[20:21], v[56:57], v[42:43]
	v_pk_fma_f32 v[40:41], v[74:75], v[76:77], v[40:41]
	v_pk_fma_f32 v[30:31], v[50:51], v[54:55], v[30:31]
	v_pk_fma_f32 v[28:29], v[78:79], v[80:81], v[28:29]
	v_pk_fma_f32 v[26:27], v[52:53], v[56:57], v[26:27]
	v_mov_b64_e32 v[22:23], v[18:19]
	v_mov_b64_e32 v[18:19], v[20:21]
	v_mov_b64_e32 v[20:21], v[52:53]
	v_mov_b64_e32 v[16:17], v[10:11]
	v_mov_b64_e32 v[10:11], v[14:15]
	v_mov_b64_e32 v[14:15], v[78:79]
	v_mov_b64_e32 v[12:13], v[4:5]
	v_mov_b64_e32 v[4:5], v[6:7]
	v_mov_b64_e32 v[6:7], v[50:51]
	v_mov_b64_e32 v[8:9], v[0:1]
	v_mov_b64_e32 v[0:1], v[2:3]
	v_mov_b64_e32 v[2:3], v[74:75]
	s_cbranch_scc1 .LBB0_683
	v_mov_b32_e32 v0, s8
	v_add_co_u32_e32 v4, vcc, 0x2954000, v0
	v_mov_b32_e32 v0, s9
	s_nop 0
	v_addc_co_u32_e32 v5, vcc, 0, v0, vcc
	global_load_dwordx4 v[0:3], v[4:5], off offset:344
	s_nop 0
	global_load_dwordx2 v[4:5], v[4:5], off offset:360
	v_lshlrev_b32_e32 v116, 2, v38
	v_mov_b64_e32 v[52:53], s[20:21]
	s_waitcnt vmcnt(0) lgkmcnt(0)
	v_readfirstlane_b32 s1, v1
	v_readfirstlane_b32 s0, v0
	v_readfirstlane_b32 s5, v3
	v_readfirstlane_b32 s4, v2
	v_lshl_add_u64 v[0:1], s[0:1], 0, v[116:117]
	global_load_dwordx4 v[16:19], v[0:1], off
	v_readfirstlane_b32 s7, v5
	v_readfirstlane_b32 s6, v4
	v_lshl_add_u64 v[2:3], s[4:5], 0, v[116:117]
	global_load_dwordx4 v[8:11], v[2:3], off
	v_lshl_add_u64 v[4:5], s[6:7], 0, v[116:117]
	global_load_dwordx4 v[12:15], v[4:5], off
	global_load_dwordx4 v[20:23], v[0:1], off offset:16
	s_nop 0
	global_load_dwordx4 v[0:3], v[2:3], off offset:16
	s_nop 0
	global_load_dwordx4 v[4:7], v[4:5], off offset:16
	v_mad_u64_u32 v[24:25], s[0:1], v33, s64, v[36:37]
	s_waitcnt lgkmcnt(0)
	s_barrier
	s_waitcnt vmcnt(0)
	v_mov_b32_e32 v54, v16
	v_mov_b32_e32 v55, v18
	v_mov_b32_e32 v18, v17
	v_pk_add_f32 v[74:75], v[72:73], v[54:55]
	v_mov_b32_e32 v56, v20
	v_mov_b32_e32 v57, v22
	v_mov_b32_e32 v22, v21
	v_pk_add_f32 v[20:21], v[68:69], v[54:55]
	v_mov_b32_e32 v16, v8
	v_mov_b32_e32 v17, v10
	v_mov_b32_e32 v10, v9
	v_mov_b32_e32 v8, v0
	v_mov_b32_e32 v9, v2
	v_pk_add_f32 v[64:65], v[64:65], v[18:19]
	v_pk_add_f32 v[76:77], v[70:71], v[18:19]
	v_add_f32_e32 v0, 0, v20
	v_add_f32_e32 v2, 0, v74
	v_add_f32_e32 v0, v0, v64
	v_add_f32_e32 v2, v2, v76
	v_add_f32_e32 v0, v0, v21
	v_add_f32_e32 v2, v2, v75
	v_pk_add_f32 v[60:61], v[60:61], v[56:57]
	v_pk_add_f32 v[78:79], v[66:67], v[56:57]
	v_add_f32_e32 v0, v0, v65
	v_add_f32_e32 v2, v2, v77
	v_pk_add_f32 v[58:59], v[58:59], v[22:23]
	v_pk_add_f32 v[80:81], v[62:63], v[22:23]
	v_add_f32_e32 v0, v0, v60
	v_add_f32_e32 v2, v2, v78
	v_add_f32_e32 v0, v0, v58
	v_add_f32_e32 v2, v2, v80
	v_add_f32_e32 v0, v0, v61
	v_add_f32_e32 v2, v2, v79
	v_add_f32_e32 v0, v0, v59
	v_add_f32_e32 v2, v2, v81
	v_mov_b32_e32 v50, v12
	v_add_f32_dpp v0, v0, v0 quad_perm:[1,0,3,2] row_mask:0xf bank_mask:0xf bound_ctrl:1
	v_add_f32_dpp v2, v2, v2 quad_perm:[1,0,3,2] row_mask:0xf bank_mask:0xf bound_ctrl:1
	v_mov_b32_e32 v12, v4
	v_add_f32_dpp v0, v0, v0 quad_perm:[2,3,0,1] row_mask:0xf bank_mask:0xf bound_ctrl:1
	v_add_f32_dpp v2, v2, v2 quad_perm:[2,3,0,1] row_mask:0xf bank_mask:0xf bound_ctrl:1
	v_mov_b32_e32 v51, v14
	v_add_f32_dpp v0, v0, v0 row_half_mirror row_mask:0xf bank_mask:0xf bound_ctrl:1
	v_add_f32_dpp v2, v2, v2 row_half_mirror row_mask:0xf bank_mask:0xf bound_ctrl:1
	v_mul_f32_e32 v0, 0x3c800000, v0
	v_mul_f32_e32 v2, 0x3c800000, v2
	v_pk_add_f32 v[72:73], v[20:21], v[0:1] op_sel_hi:[1,0] neg_lo:[0,1] neg_hi:[0,1]
	v_pk_add_f32 v[70:71], v[64:65], v[0:1] op_sel_hi:[1,0] neg_lo:[0,1] neg_hi:[0,1]
	v_pk_add_f32 v[68:69], v[60:61], v[0:1] op_sel_hi:[1,0] neg_lo:[0,1] neg_hi:[0,1]
	v_pk_add_f32 v[62:63], v[74:75], v[2:3] op_sel_hi:[1,0] neg_lo:[0,1] neg_hi:[0,1]
	v_pk_add_f32 v[60:61], v[76:77], v[2:3] op_sel_hi:[1,0] neg_lo:[0,1] neg_hi:[0,1]
	v_pk_add_f32 v[20:21], v[80:81], v[2:3] op_sel_hi:[1,0] neg_lo:[0,1] neg_hi:[0,1]
	v_mov_b32_e32 v64, v72
	v_mov_b32_e32 v65, v70
	v_mov_b32_e32 v80, v62
	v_mov_b32_e32 v81, v60
	v_mov_b32_e32 v74, v71
	v_mov_b32_e32 v75, v73
	v_mov_b32_e32 v82, v61
	v_mov_b32_e32 v83, v63
	v_pk_mul_f32 v[64:65], v[64:65], v[64:65]
	v_pk_mul_f32 v[80:81], v[80:81], v[80:81]
	v_pk_add_f32 v[66:67], v[58:59], v[0:1] op_sel_hi:[1,0] neg_lo:[0,1] neg_hi:[0,1]
	v_pk_add_f32 v[58:59], v[78:79], v[2:3] op_sel_hi:[1,0] neg_lo:[0,1] neg_hi:[0,1]
	v_pk_mul_f32 v[74:75], v[74:75], v[74:75]
	v_pk_mul_f32 v[82:83], v[82:83], v[82:83]
	v_mov_b32_e32 v88, v80
	v_mov_b32_e32 v89, v64
	v_mov_b32_e32 v64, v81
	v_mov_b32_e32 v76, v66
	v_mov_b32_e32 v77, v68
	v_mov_b32_e32 v84, v20
	v_mov_b32_e32 v85, v58
	v_mov_b32_e32 v80, v83
	v_mov_b32_e32 v81, v75
	v_pk_add_f32 v[64:65], v[88:89], v[64:65]
	v_pk_mul_f32 v[76:77], v[76:77], v[76:77]
	v_pk_mul_f32 v[84:85], v[84:85], v[84:85]
	v_mov_b32_e32 v83, v74
	v_pk_add_f32 v[64:65], v[80:81], v[64:65]
	v_mov_b32_e32 v78, v67
	v_mov_b32_e32 v79, v69
	v_mov_b32_e32 v86, v21
	v_mov_b32_e32 v87, v59
	v_mov_b32_e32 v74, v85
	v_mov_b32_e32 v75, v77
	v_pk_add_f32 v[64:65], v[82:83], v[64:65]
	v_pk_mul_f32 v[78:79], v[78:79], v[78:79]
	v_pk_mul_f32 v[86:87], v[86:87], v[86:87]
	v_mov_b32_e32 v85, v76
	v_pk_add_f32 v[64:65], v[74:75], v[64:65]
	v_mov_b32_e32 v76, v87
	v_mov_b32_e32 v77, v79
	v_pk_add_f32 v[64:65], v[84:85], v[64:65]
	v_mov_b32_e32 v87, v78
	v_pk_add_f32 v[64:65], v[76:77], v[64:65]
	v_mov_b32_e32 v2, v1
	v_pk_add_f32 v[64:65], v[86:87], v[64:65]
	v_mov_b32_e32 v14, v13
	v_mov_b32_e32 v13, v6
	v_mov_b32_dpp v75, v65 quad_perm:[1,0,3,2] row_mask:0xf bank_mask:0xf bound_ctrl:1
	v_mov_b32_dpp v74, v64 quad_perm:[1,0,3,2] row_mask:0xf bank_mask:0xf bound_ctrl:1
	v_pk_add_f32 v[64:65], v[64:65], v[74:75]
	v_mov_b32_e32 v6, v5
	v_pk_add_f32 v[42:43], v[42:43], v[22:23]
	v_mov_b32_dpp v75, v65 quad_perm:[2,3,0,1] row_mask:0xf bank_mask:0xf bound_ctrl:1
	v_mov_b32_dpp v74, v64 quad_perm:[2,3,0,1] row_mask:0xf bank_mask:0xf bound_ctrl:1
	v_pk_add_f32 v[64:65], v[64:65], v[74:75]
	v_pk_add_f32 v[28:29], v[28:29], v[56:57]
	v_pk_add_f32 v[22:23], v[26:27], v[22:23]
	v_mov_b32_dpp v75, v65 row_half_mirror row_mask:0xf bank_mask:0xf bound_ctrl:1
	v_mov_b32_dpp v74, v64 row_half_mirror row_mask:0xf bank_mask:0xf bound_ctrl:1
	v_pk_add_f32 v[64:65], v[64:65], v[74:75]
	s_nop 0
	v_pk_fma_f32 v[64:65], v[64:65], s[18:19], v[52:53] op_sel_hi:[1,0,0]
	s_nop 0
	v_mul_f32_e32 v0, 0x4b800000, v65
	v_cmp_gt_f32_e32 vcc, s65, v65
	s_nop 1
	v_cndmask_b32_e32 v0, v65, v0, vcc
	v_rsq_f32_e32 v0, v0
	s_nop 0
	v_mul_f32_e32 v1, 0x45800000, v0
	v_cndmask_b32_e32 v4, v0, v1, vcc
	v_pk_mul_f32 v[0:1], v[72:73], v[4:5] op_sel_hi:[1,0]
	v_pk_mul_f32 v[70:71], v[70:71], v[4:5] op_sel_hi:[1,0]
	v_pk_fma_f32 v[72:73], v[16:17], v[0:1], v[50:51]
	v_pk_mul_f32 v[68:69], v[68:69], v[4:5] op_sel_hi:[1,0]
	v_mul_f32_e32 v5, 0xbfb8aa3b, v72
	v_mul_f32_e32 v35, 0xbfb8aa3b, v73
	v_pk_fma_f32 v[70:71], v[10:11], v[70:71], v[14:15]
	v_pk_fma_f32 v[0:1], v[8:9], v[68:69], v[12:13]
	v_exp_f32_e32 v68, v5
	v_exp_f32_e32 v69, v35
	v_mul_f32_e32 v25, 0xbfb8aa3b, v70
	v_mul_f32_e32 v37, 0xbfb8aa3b, v71
	v_exp_f32_e32 v74, v25
	v_exp_f32_e32 v75, v37
	v_pk_mul_f32 v[78:79], v[66:67], v[4:5] op_sel_hi:[1,0]
	v_pk_add_f32 v[4:5], v[68:69], 1.0 op_sel_hi:[1,0]
	v_mul_f32_e32 v65, 0xbfb8aa3b, v1
	v_div_scale_f32 v25, s[0:1], v5, v5, 1.0
	v_pk_add_f32 v[68:69], v[74:75], 1.0 op_sel_hi:[1,0]
	v_div_scale_f32 v37, s[0:1], v4, v4, 1.0
	v_rcp_f32_e32 v80, v25
	v_exp_f32_e32 v77, v65
	v_div_scale_f32 v65, s[4:5], v69, v69, 1.0
	v_rcp_f32_e32 v81, v37
	v_div_scale_f32 v75, s[6:7], v68, v68, 1.0
	v_rcp_f32_e32 v82, v65
	v_mul_f32_e32 v39, 0xbfb8aa3b, v0
	v_rcp_f32_e32 v83, v75
	v_exp_f32_e32 v76, v39
	v_fma_f32 v84, -v25, v80, 1.0
	v_div_scale_f32 v35, vcc, 1.0, v5, 1.0
	v_fma_f32 v85, -v37, v81, 1.0
	v_fmac_f32_e32 v80, v84, v80
	v_div_scale_f32 v39, s[0:1], 1.0, v4, 1.0
	v_fma_f32 v86, -v65, v82, 1.0
	v_fmac_f32_e32 v81, v85, v81
	v_mul_f32_e32 v84, v35, v80
	v_div_scale_f32 v74, s[4:5], 1.0, v69, 1.0
	v_fma_f32 v87, -v75, v83, 1.0
	v_fmac_f32_e32 v82, v86, v82
	v_mul_f32_e32 v85, v39, v81
	v_fma_f32 v88, -v25, v84, v35
	v_pk_add_f32 v[66:67], v[76:77], 1.0 op_sel_hi:[1,0]
	v_div_scale_f32 v76, s[6:7], 1.0, v68, 1.0
	v_fmac_f32_e32 v83, v87, v83
	v_mul_f32_e32 v86, v74, v82
	v_fma_f32 v89, -v37, v85, v39
	v_fmac_f32_e32 v84, v88, v80
	v_mul_f32_e32 v87, v76, v83
	v_fma_f32 v90, -v65, v86, v74
	v_fmac_f32_e32 v85, v89, v81
	v_fma_f32 v25, -v25, v84, v35
	v_fma_f32 v91, -v75, v87, v76
	v_fmac_f32_e32 v86, v90, v82
	v_fma_f32 v35, -v37, v85, v39
	v_div_fmas_f32 v25, v25, v80, v84
	s_mov_b64 vcc, s[0:1]
	v_fmac_f32_e32 v87, v91, v83
	v_fma_f32 v37, -v65, v86, v74
	v_div_fixup_f32 v5, v25, v5, 1.0
	v_div_fmas_f32 v25, v35, v81, v85
	s_mov_b64 vcc, s[4:5]
	v_fma_f32 v39, -v75, v87, v76
	v_div_fixup_f32 v4, v25, v4, 1.0
	v_div_fmas_f32 v25, v37, v82, v86
	s_mov_b64 vcc, s[6:7]
	v_div_scale_f32 v77, s[24:25], v67, v67, 1.0
	v_div_fixup_f32 v69, v25, v69, 1.0
	v_div_fmas_f32 v25, v39, v83, v87
	v_div_fixup_f32 v68, v25, v68, 1.0
	v_rcp_f32_e32 v25, v77
	v_pk_mul_f32 v[68:69], v[70:71], v[68:69]
	v_pk_fma_f32 v[70:71], v[2:3], v[78:79], v[6:7]
	v_pk_mul_f32 v[4:5], v[72:73], v[4:5]
	v_mul_f32_e32 v35, 0xbfb8aa3b, v70
	v_exp_f32_e32 v72, v35
	v_fma_f32 v35, -v77, v25, 1.0
	v_fmac_f32_e32 v25, v35, v25
	v_div_scale_f32 v35, vcc, 1.0, v67, 1.0
	v_mul_f32_e32 v37, v35, v25
	v_fma_f32 v39, -v77, v37, v35
	v_fmac_f32_e32 v37, v39, v25
	v_div_scale_f32 v39, s[0:1], v66, v66, 1.0
	v_rcp_f32_e32 v65, v39
	v_fma_f32 v35, -v77, v37, v35
	v_div_fmas_f32 v25, v35, v25, v37
	v_mul_f32_e32 v37, 0xbfb8aa3b, v71
	v_exp_f32_e32 v73, v37
	v_div_fixup_f32 v67, v25, v67, 1.0
	v_fma_f32 v25, -v39, v65, 1.0
	v_fmac_f32_e32 v65, v25, v65
	v_div_scale_f32 v25, vcc, 1.0, v66, 1.0
	v_mul_f32_e32 v35, v25, v65
	v_fma_f32 v37, -v39, v35, v25
	v_pk_add_f32 v[72:73], v[72:73], 1.0 op_sel_hi:[1,0]
	v_fmac_f32_e32 v35, v37, v65
	v_div_scale_f32 v37, s[0:1], v73, v73, 1.0
	v_fma_f32 v25, -v39, v35, v25
	v_rcp_f32_e32 v39, v37
	v_div_fmas_f32 v25, v25, v65, v35
	v_div_fixup_f32 v66, v25, v66, 1.0
	v_pk_mul_f32 v[0:1], v[0:1], v[66:67]
	v_fma_f32 v25, -v37, v39, 1.0
	v_fmac_f32_e32 v39, v25, v39
	v_div_scale_f32 v25, vcc, 1.0, v73, 1.0
	v_mul_f32_e32 v35, v25, v39
	v_fma_f32 v65, -v37, v35, v25
	v_fmac_f32_e32 v35, v65, v39
	v_fma_f32 v25, -v37, v35, v25
	v_div_scale_f32 v37, s[0:1], v72, v72, 1.0
	v_rcp_f32_e32 v65, v37
	v_div_fmas_f32 v25, v25, v39, v35
	v_div_fixup_f32 v67, v25, v73, 1.0
	v_fma_f32 v25, -v37, v65, 1.0
	v_fmac_f32_e32 v65, v25, v65
	v_div_scale_f32 v25, vcc, 1.0, v72, 1.0
	v_mul_f32_e32 v35, v25, v65
	v_fma_f32 v39, -v37, v35, v25
	v_fmac_f32_e32 v35, v39, v65
	v_fma_f32 v25, -v37, v35, v25
	v_div_fmas_f32 v25, v25, v65, v35
	v_div_fixup_f32 v66, v25, v72, 1.0
	v_pk_mul_f32 v[66:67], v[70:71], v[66:67]
	v_bfe_u32 v39, v68, 16, 1
	v_bfe_u32 v35, v66, 16, 1
	v_add3_u32 v35, v66, v35, s59
	v_bfe_u32 v65, v4, 16, 1
	v_bfe_u32 v66, v5, 16, 1
	v_add3_u32 v39, v68, v39, s59
	v_bfe_u32 v68, v1, 16, 1
	v_add3_u32 v5, v5, v66, s59
	v_add3_u32 v4, v4, v65, s59
	v_add3_u32 v1, v1, v68, s59
	v_lshrrev_b32_e32 v68, 16, v4
	v_lshrrev_b32_e32 v4, 16, v5
	v_mul_f32_e32 v5, 0x4b800000, v64
	v_cmp_gt_f32_e32 vcc, s65, v64
	v_bfe_u32 v25, v67, 16, 1
	v_add3_u32 v25, v67, v25, s59
	v_cndmask_b32_e32 v5, v64, v5, vcc
	v_rsq_f32_e32 v5, v5
	v_bfe_u32 v67, v0, 16, 1
	v_add3_u32 v0, v0, v67, s59
	v_bfe_u32 v37, v69, 16, 1
	v_lshrrev_b32_e32 v0, 16, v0
	v_add3_u32 v37, v69, v37, s59
	v_and_or_b32 v66, v35, s63, v0
	v_mul_f32_e32 v0, 0x45800000, v5
	v_lshrrev_b32_e32 v1, 16, v1
	v_and_or_b32 v65, v37, s63, v4
	v_cndmask_b32_e32 v4, v5, v0, vcc
	v_and_or_b32 v67, v25, s63, v1
	v_pk_mul_f32 v[0:1], v[62:63], v[4:5] op_sel_hi:[1,0]
	v_and_or_b32 v64, v39, s63, v68
	v_pk_fma_f32 v[0:1], v[16:17], v[0:1], v[50:51]
	ds_write_b128 v24, v[64:67]
	v_mul_f32_e32 v5, 0xbfb8aa3b, v0
	v_exp_f32_e32 v62, v5
	v_mul_f32_e32 v5, 0xbfb8aa3b, v1
	v_exp_f32_e32 v63, v5
	v_pk_mul_f32 v[60:61], v[60:61], v[4:5] op_sel_hi:[1,0]
	v_pk_add_f32 v[62:63], v[62:63], 1.0 op_sel_hi:[1,0]
	s_nop 0
	v_div_scale_f32 v5, s[0:1], v63, v63, 1.0
	v_rcp_f32_e32 v25, v5
	v_pk_fma_f32 v[60:61], v[10:11], v[60:61], v[14:15]
	s_nop 0
	v_mul_f32_e32 v35, 0xbfb8aa3b, v60
	v_exp_f32_e32 v64, v35
	v_fma_f32 v35, -v5, v25, 1.0
	v_fmac_f32_e32 v25, v35, v25
	v_div_scale_f32 v35, vcc, 1.0, v63, 1.0
	v_mul_f32_e32 v37, v35, v25
	v_fma_f32 v39, -v5, v37, v35
	v_fmac_f32_e32 v37, v39, v25
	v_fma_f32 v5, -v5, v37, v35
	v_div_scale_f32 v35, s[0:1], v62, v62, 1.0
	v_rcp_f32_e32 v39, v35
	v_div_fmas_f32 v5, v5, v25, v37
	v_mul_f32_e32 v37, 0xbfb8aa3b, v61
	v_div_fixup_f32 v63, v5, v63, 1.0
	v_fma_f32 v5, -v35, v39, 1.0
	v_exp_f32_e32 v65, v37
	v_fmac_f32_e32 v39, v5, v39
	v_div_scale_f32 v5, vcc, 1.0, v62, 1.0
	v_mul_f32_e32 v25, v5, v39
	v_fma_f32 v37, -v35, v25, v5
	v_fmac_f32_e32 v25, v37, v39
	v_pk_add_f32 v[64:65], v[64:65], 1.0 op_sel_hi:[1,0]
	v_fma_f32 v5, -v35, v25, v5
	v_div_scale_f32 v35, s[0:1], v65, v65, 1.0
	v_rcp_f32_e32 v37, v35
	v_div_fmas_f32 v5, v5, v39, v25
	v_div_fixup_f32 v62, v5, v62, 1.0
	v_pk_mul_f32 v[0:1], v[0:1], v[62:63]
	v_fma_f32 v5, -v35, v37, 1.0
	v_fmac_f32_e32 v37, v5, v37
	v_div_scale_f32 v5, vcc, 1.0, v65, 1.0
	v_mul_f32_e32 v25, v5, v37
	v_fma_f32 v39, -v35, v25, v5
	v_fmac_f32_e32 v25, v39, v37
	v_fma_f32 v5, -v35, v25, v5
	v_div_scale_f32 v35, s[0:1], v64, v64, 1.0
	v_rcp_f32_e32 v39, v35
	v_div_fmas_f32 v5, v5, v37, v25
	v_div_fixup_f32 v63, v5, v65, 1.0
	v_fma_f32 v5, -v35, v39, 1.0
	v_fmac_f32_e32 v39, v5, v39
	v_div_scale_f32 v5, vcc, 1.0, v64, 1.0
	v_mul_f32_e32 v25, v5, v39
	v_fma_f32 v37, -v35, v25, v5
	v_fmac_f32_e32 v25, v37, v39
	v_fma_f32 v5, -v35, v25, v5
	v_div_fmas_f32 v5, v5, v39, v25
	v_pk_mul_f32 v[58:59], v[58:59], v[4:5] op_sel_hi:[1,0]
	v_div_fixup_f32 v62, v5, v64, 1.0
	v_pk_fma_f32 v[58:59], v[8:9], v[58:59], v[12:13]
	v_pk_mul_f32 v[4:5], v[20:21], v[4:5] op_sel_hi:[1,0]
	v_mul_f32_e32 v25, 0xbfb8aa3b, v58
	v_exp_f32_e32 v66, v25
	v_mul_f32_e32 v25, 0xbfb8aa3b, v59
	v_exp_f32_e32 v67, v25
	v_pk_fma_f32 v[4:5], v[2:3], v[4:5], v[6:7]
	v_pk_mul_f32 v[60:61], v[60:61], v[62:63]
	v_mul_f32_e32 v37, 0xbfb8aa3b, v4
	v_pk_add_f32 v[20:21], v[66:67], 1.0 op_sel_hi:[1,0]
	v_exp_f32_e32 v62, v37
	v_div_scale_f32 v25, s[0:1], v21, v21, 1.0
	v_rcp_f32_e32 v35, v25
	s_nop 0
	v_fma_f32 v37, -v25, v35, 1.0
	v_fmac_f32_e32 v35, v37, v35
	v_div_scale_f32 v37, vcc, 1.0, v21, 1.0
	v_mul_f32_e32 v39, v37, v35
	v_fma_f32 v63, -v25, v39, v37
	v_fmac_f32_e32 v39, v63, v35
	v_fma_f32 v25, -v25, v39, v37
	v_div_scale_f32 v37, s[0:1], v20, v20, 1.0
	v_rcp_f32_e32 v64, v37
	v_div_fmas_f32 v25, v25, v35, v39
	v_mul_f32_e32 v39, 0xbfb8aa3b, v5
	v_div_fixup_f32 v21, v25, v21, 1.0
	v_fma_f32 v25, -v37, v64, 1.0
	v_exp_f32_e32 v63, v39
	v_fmac_f32_e32 v64, v25, v64
	v_div_scale_f32 v25, vcc, 1.0, v20, 1.0
	v_mul_f32_e32 v35, v25, v64
	v_fma_f32 v39, -v37, v35, v25
	v_fmac_f32_e32 v35, v39, v64
	v_pk_add_f32 v[62:63], v[62:63], 1.0 op_sel_hi:[1,0]
	v_fma_f32 v25, -v37, v35, v25
	v_div_scale_f32 v37, s[0:1], v63, v63, 1.0
	v_rcp_f32_e32 v39, v37
	v_div_fmas_f32 v25, v25, v64, v35
	v_div_fixup_f32 v20, v25, v20, 1.0
	v_pk_mul_f32 v[20:21], v[58:59], v[20:21]
	v_fma_f32 v25, -v37, v39, 1.0
	v_fmac_f32_e32 v39, v25, v39
	v_div_scale_f32 v25, vcc, 1.0, v63, 1.0
	v_mul_f32_e32 v35, v25, v39
	v_fma_f32 v58, -v37, v35, v25
	v_fmac_f32_e32 v35, v58, v39
	v_fma_f32 v25, -v37, v35, v25
	v_div_scale_f32 v37, s[0:1], v62, v62, 1.0
	v_rcp_f32_e32 v58, v37
	v_div_fmas_f32 v25, v25, v39, v35
	v_div_fixup_f32 v59, v25, v63, 1.0
	v_fma_f32 v25, -v37, v58, 1.0
	v_fmac_f32_e32 v58, v25, v58
	v_div_scale_f32 v25, vcc, 1.0, v62, 1.0
	v_mul_f32_e32 v35, v25, v58
	v_fma_f32 v39, -v37, v35, v25
	v_fmac_f32_e32 v35, v39, v58
	v_fma_f32 v25, -v37, v35, v25
	v_div_fmas_f32 v25, v25, v58, v35
	v_div_fixup_f32 v58, v25, v62, 1.0
	v_pk_mul_f32 v[4:5], v[4:5], v[58:59]
	v_bfe_u32 v58, v20, 16, 1
	v_bfe_u32 v25, v5, 16, 1
	v_bfe_u32 v35, v4, 16, 1
	v_add3_u32 v35, v4, v35, s59
	v_add3_u32 v25, v5, v25, s59
	v_bfe_u32 v4, v0, 16, 1
	v_bfe_u32 v5, v1, 16, 1
	v_add3_u32 v1, v1, v5, s59
	v_add3_u32 v0, v0, v4, s59
	v_add3_u32 v20, v20, v58, s59
	v_lshrrev_b32_e32 v64, 16, v0
	v_lshrrev_b32_e32 v65, 16, v1
	v_pk_add_f32 v[0:1], v[48:49], v[54:55]
	v_lshrrev_b32_e32 v66, 16, v20
	v_add_f32_e32 v20, 0, v0
	v_pk_add_f32 v[4:5], v[46:47], v[18:19]
	v_bfe_u32 v59, v21, 16, 1
	v_add_f32_e32 v20, v20, v4
	v_add3_u32 v21, v21, v59, s59
	v_add_f32_e32 v20, v20, v1
	v_lshrrev_b32_e32 v67, 16, v21
	v_add_f32_e32 v46, v20, v5
	v_pk_add_f32 v[20:21], v[44:45], v[56:57]
	v_bfe_u32 v37, v61, 16, 1
	v_add_f32_e32 v44, v46, v20
	v_add_f32_e32 v44, v44, v42
	v_add_f32_e32 v44, v44, v21
	v_add_f32_e32 v44, v44, v43
	v_bfe_u32 v39, v60, 16, 1
	v_add3_u32 v39, v60, v39, s59
	v_add_f32_dpp v44, v44, v44 quad_perm:[1,0,3,2] row_mask:0xf bank_mask:0xf bound_ctrl:1
	v_add3_u32 v37, v61, v37, s59
	v_pk_add_f32 v[18:19], v[30:31], v[18:19]
	v_add_f32_dpp v44, v44, v44 quad_perm:[2,3,0,1] row_mask:0xf bank_mask:0xf bound_ctrl:1
	s_nop 1
	v_add_f32_dpp v44, v44, v44 row_half_mirror row_mask:0xf bank_mask:0xf bound_ctrl:1
	v_mul_f32_e32 v46, 0x3c800000, v44
	v_pk_add_f32 v[48:49], v[0:1], v[46:47] op_sel_hi:[1,0] neg_lo:[0,1] neg_hi:[0,1]
	v_pk_add_f32 v[58:59], v[4:5], v[46:47] op_sel_hi:[1,0] neg_lo:[0,1] neg_hi:[0,1]
	v_mov_b32_e32 v5, v49
	v_mov_b32_e32 v4, v59
	v_pk_add_f32 v[44:45], v[20:21], v[46:47] op_sel_hi:[1,0] neg_lo:[0,1] neg_hi:[0,1]
	v_pk_add_f32 v[42:43], v[42:43], v[46:47] op_sel_hi:[1,0] neg_lo:[0,1] neg_hi:[0,1]
	v_pk_mul_f32 v[60:61], v[4:5], v[4:5]
	v_mov_b32_e32 v4, v42
	v_mov_b32_e32 v5, v44
	v_pk_mul_f32 v[46:47], v[4:5], v[4:5]
	v_mov_b32_e32 v4, v43
	v_mov_b32_e32 v5, v45
	v_pk_mul_f32 v[62:63], v[4:5], v[4:5]
	v_pk_add_f32 v[4:5], v[40:41], v[54:55]
	v_mov_b32_e32 v0, v48
	v_add_f32_e32 v20, 0, v4
	v_add_f32_e32 v20, v20, v18
	v_add_f32_e32 v20, v20, v5
	v_add_f32_e32 v20, v20, v19
	v_add_f32_e32 v20, v20, v28
	v_add_f32_e32 v20, v20, v22
	v_add_f32_e32 v20, v20, v29
	v_add_f32_e32 v20, v20, v23
	v_mov_b32_e32 v1, v58
	v_pk_mul_f32 v[0:1], v[0:1], v[0:1]
	v_add_f32_dpp v20, v20, v20 quad_perm:[1,0,3,2] row_mask:0xf bank_mask:0xf bound_ctrl:1
	v_mov_b32_e32 v31, v0
	s_nop 0
	v_add_f32_dpp v20, v20, v20 quad_perm:[2,3,0,1] row_mask:0xf bank_mask:0xf bound_ctrl:1
	s_nop 1
	v_add_f32_dpp v20, v20, v20 row_half_mirror row_mask:0xf bank_mask:0xf bound_ctrl:1
	v_mul_f32_e32 v26, 0x3c800000, v20
	v_pk_add_f32 v[20:21], v[4:5], v[26:27] op_sel_hi:[1,0] neg_lo:[0,1] neg_hi:[0,1]
	v_pk_add_f32 v[18:19], v[18:19], v[26:27] op_sel_hi:[1,0] neg_lo:[0,1] neg_hi:[0,1]
	v_mov_b32_e32 v4, v20
	v_mov_b32_e32 v5, v18
	v_pk_mul_f32 v[4:5], v[4:5], v[4:5]
	s_nop 0
	v_mov_b32_e32 v30, v4
	v_mov_b32_e32 v0, v5
	v_pk_add_f32 v[30:31], v[30:31], v[0:1]
	v_mov_b32_e32 v0, v19
	v_mov_b32_e32 v1, v21
	v_pk_mul_f32 v[40:41], v[0:1], v[0:1]
	v_pk_add_f32 v[4:5], v[28:29], v[26:27] op_sel_hi:[1,0] neg_lo:[0,1] neg_hi:[0,1]
	v_pk_add_f32 v[0:1], v[22:23], v[26:27] op_sel_hi:[1,0] neg_lo:[0,1] neg_hi:[0,1]
	v_mov_b32_e32 v23, v4
	v_mov_b32_e32 v22, v0
	v_mov_b32_e32 v28, v41
	v_mov_b32_e32 v29, v61
	v_pk_mul_f32 v[22:23], v[22:23], v[22:23]
	v_pk_add_f32 v[28:29], v[28:29], v[30:31]
	v_mov_b32_e32 v41, v60
	v_mov_b32_e32 v26, v1
	v_mov_b32_e32 v27, v5
	v_pk_add_f32 v[28:29], v[40:41], v[28:29]
	v_mov_b32_e32 v30, v23
	v_mov_b32_e32 v31, v47
	v_pk_mul_f32 v[26:27], v[26:27], v[26:27]
	v_pk_add_f32 v[28:29], v[30:31], v[28:29]
	v_mov_b32_e32 v23, v46
	v_pk_add_f32 v[22:23], v[22:23], v[28:29]
	v_mov_b32_e32 v28, v27
	v_mov_b32_e32 v29, v63
	v_pk_add_f32 v[22:23], v[28:29], v[22:23]
	v_mov_b32_e32 v27, v62
	v_pk_add_f32 v[22:23], v[26:27], v[22:23]
	v_and_or_b32 v29, v25, s63, v67
	v_and_or_b32 v28, v35, s63, v66
	v_mov_b32_dpp v27, v23 quad_perm:[1,0,3,2] row_mask:0xf bank_mask:0xf bound_ctrl:1
	v_mov_b32_dpp v26, v22 quad_perm:[1,0,3,2] row_mask:0xf bank_mask:0xf bound_ctrl:1
	v_pk_add_f32 v[22:23], v[22:23], v[26:27]
	s_nop 1
	v_mov_b32_dpp v27, v23 quad_perm:[2,3,0,1] row_mask:0xf bank_mask:0xf bound_ctrl:1
	v_mov_b32_dpp v26, v22 quad_perm:[2,3,0,1] row_mask:0xf bank_mask:0xf bound_ctrl:1
	v_pk_add_f32 v[22:23], v[22:23], v[26:27]
	s_nop 1
	v_mov_b32_dpp v27, v23 row_half_mirror row_mask:0xf bank_mask:0xf bound_ctrl:1
	v_mov_b32_dpp v26, v22 row_half_mirror row_mask:0xf bank_mask:0xf bound_ctrl:1
	v_pk_add_f32 v[22:23], v[22:23], v[26:27]
	v_and_or_b32 v27, v37, s63, v65
	v_pk_fma_f32 v[22:23], v[22:23], s[18:19], v[52:53] op_sel_hi:[1,0,0]
	s_nop 0
	v_mul_f32_e32 v26, 0x4b800000, v23
	v_cmp_gt_f32_e32 vcc, s65, v23
	s_nop 1
	v_cndmask_b32_e32 v23, v23, v26, vcc
	v_rsq_f32_e32 v23, v23
	v_and_or_b32 v26, v39, s63, v64
	ds_write_b128 v24, v[26:29] offset:528
	v_mul_f32_e32 v25, 0x45800000, v23
	v_cndmask_b32_e32 v30, v23, v25, vcc
	v_pk_mul_f32 v[40:41], v[48:49], v[30:31] op_sel_hi:[1,0]
	v_pk_mul_f32 v[26:27], v[58:59], v[30:31] op_sel_hi:[1,0]
	v_pk_fma_f32 v[40:41], v[16:17], v[40:41], v[50:51]
	s_nop 0
	v_mul_f32_e32 v23, 0xbfb8aa3b, v40
	v_exp_f32_e32 v46, v23
	v_mul_f32_e32 v23, 0xbfb8aa3b, v41
	v_exp_f32_e32 v47, v23
	s_nop 0
	v_pk_add_f32 v[28:29], v[46:47], 1.0 op_sel_hi:[1,0]
	s_nop 0
	v_div_scale_f32 v23, s[0:1], v29, v29, 1.0
	v_rcp_f32_e32 v25, v23
	v_pk_fma_f32 v[46:47], v[10:11], v[26:27], v[14:15]
	v_fma_f32 v27, -v23, v25, 1.0
	v_fmac_f32_e32 v25, v27, v25
	v_div_scale_f32 v27, vcc, 1.0, v29, 1.0
	v_mul_f32_e32 v31, v27, v25
	v_fma_f32 v35, -v23, v31, v27
	v_fmac_f32_e32 v31, v35, v25
	v_div_scale_f32 v35, s[0:1], v28, v28, 1.0
	v_rcp_f32_e32 v37, v35
	v_mul_f32_e32 v26, 0xbfb8aa3b, v46
	v_fma_f32 v23, -v23, v31, v27
	v_mul_f32_e32 v27, 0xbfb8aa3b, v47
	v_exp_f32_e32 v26, v26
	v_div_fmas_f32 v23, v23, v25, v31
	v_exp_f32_e32 v27, v27
	v_div_fixup_f32 v29, v23, v29, 1.0
	v_fma_f32 v23, -v35, v37, 1.0
	v_fmac_f32_e32 v37, v23, v37
	v_div_scale_f32 v23, vcc, 1.0, v28, 1.0
	v_mul_f32_e32 v25, v23, v37
	v_fma_f32 v31, -v35, v25, v23
	v_pk_add_f32 v[48:49], v[26:27], 1.0 op_sel_hi:[1,0]
	v_fmac_f32_e32 v25, v31, v37
	v_div_scale_f32 v31, s[0:1], v49, v49, 1.0
	v_fma_f32 v23, -v35, v25, v23
	v_rcp_f32_e32 v35, v31
	v_div_fmas_f32 v23, v23, v37, v25
	v_div_fixup_f32 v28, v23, v28, 1.0
	v_pk_mul_f32 v[26:27], v[40:41], v[28:29]
	v_fma_f32 v23, -v31, v35, 1.0
	v_fmac_f32_e32 v35, v23, v35
	v_div_scale_f32 v23, vcc, 1.0, v49, 1.0
	v_mul_f32_e32 v25, v23, v35
	v_fma_f32 v28, -v31, v25, v23
	v_fmac_f32_e32 v25, v28, v35
	v_div_scale_f32 v28, s[0:1], v48, v48, 1.0
	v_fma_f32 v23, -v31, v25, v23
	v_rcp_f32_e32 v31, v28
	v_div_fmas_f32 v23, v23, v35, v25
	v_div_fixup_f32 v29, v23, v49, 1.0
	v_fma_f32 v23, -v28, v31, 1.0
	v_fmac_f32_e32 v31, v23, v31
	v_div_scale_f32 v23, vcc, 1.0, v48, 1.0
	v_mul_f32_e32 v25, v23, v31
	v_fma_f32 v35, -v28, v25, v23
	v_fmac_f32_e32 v25, v35, v31
	v_pk_mul_f32 v[40:41], v[44:45], v[30:31] op_sel_hi:[1,0]
	v_fma_f32 v23, -v28, v25, v23
	v_pk_fma_f32 v[40:41], v[8:9], v[40:41], v[12:13]
	v_div_fmas_f32 v23, v23, v31, v25
	v_mul_f32_e32 v25, 0xbfb8aa3b, v40
	v_exp_f32_e32 v44, v25
	v_mul_f32_e32 v25, 0xbfb8aa3b, v41
	v_exp_f32_e32 v45, v25
	v_pk_mul_f32 v[30:31], v[42:43], v[30:31] op_sel_hi:[1,0]
	v_div_fixup_f32 v28, v23, v48, 1.0
	v_pk_fma_f32 v[30:31], v[2:3], v[30:31], v[6:7]
	v_pk_add_f32 v[42:43], v[44:45], 1.0 op_sel_hi:[1,0]
	v_mul_f32_e32 v35, 0xbfb8aa3b, v30
	v_div_scale_f32 v23, s[0:1], v43, v43, 1.0
	v_rcp_f32_e32 v25, v23
	v_exp_f32_e32 v44, v35
	v_pk_mul_f32 v[28:29], v[46:47], v[28:29]
	v_fma_f32 v35, -v23, v25, 1.0
	v_fmac_f32_e32 v25, v35, v25
	v_div_scale_f32 v35, vcc, 1.0, v43, 1.0
	v_mul_f32_e32 v37, v35, v25
	v_fma_f32 v39, -v23, v37, v35
	v_fmac_f32_e32 v37, v39, v25
	v_fma_f32 v23, -v23, v37, v35
	v_div_scale_f32 v35, s[0:1], v42, v42, 1.0
	v_rcp_f32_e32 v39, v35
	v_div_fmas_f32 v23, v23, v25, v37
	v_mul_f32_e32 v37, 0xbfb8aa3b, v31
	v_div_fixup_f32 v43, v23, v43, 1.0
	v_fma_f32 v23, -v35, v39, 1.0
	v_exp_f32_e32 v45, v37
	v_fmac_f32_e32 v39, v23, v39
	v_div_scale_f32 v23, vcc, 1.0, v42, 1.0
	v_mul_f32_e32 v25, v23, v39
	v_fma_f32 v37, -v35, v25, v23
	v_fmac_f32_e32 v25, v37, v39
	v_pk_add_f32 v[44:45], v[44:45], 1.0 op_sel_hi:[1,0]
	v_fma_f32 v23, -v35, v25, v23
	v_div_scale_f32 v35, s[0:1], v45, v45, 1.0
	v_rcp_f32_e32 v37, v35
	v_div_fmas_f32 v23, v23, v39, v25
	v_div_fixup_f32 v42, v23, v42, 1.0
	v_pk_mul_f32 v[40:41], v[40:41], v[42:43]
	v_fma_f32 v23, -v35, v37, 1.0
	v_fmac_f32_e32 v37, v23, v37
	v_div_scale_f32 v23, vcc, 1.0, v45, 1.0
	v_mul_f32_e32 v25, v23, v37
	v_fma_f32 v39, -v35, v25, v23
	v_fmac_f32_e32 v25, v39, v37
	v_fma_f32 v23, -v35, v25, v23
	v_div_scale_f32 v35, s[0:1], v44, v44, 1.0
	v_rcp_f32_e32 v39, v35
	v_div_fmas_f32 v23, v23, v37, v25
	v_div_fixup_f32 v43, v23, v45, 1.0
	v_fma_f32 v23, -v35, v39, 1.0
	v_fmac_f32_e32 v39, v23, v39
	v_div_scale_f32 v23, vcc, 1.0, v44, 1.0
	v_mul_f32_e32 v25, v23, v39
	v_fma_f32 v37, -v35, v25, v23
	v_fmac_f32_e32 v25, v37, v39
	v_fma_f32 v23, -v35, v25, v23
	v_div_fmas_f32 v23, v23, v39, v25
	v_div_fixup_f32 v42, v23, v44, 1.0
	v_pk_mul_f32 v[30:31], v[30:31], v[42:43]
	v_bfe_u32 v37, v28, 16, 1
	v_bfe_u32 v25, v30, 16, 1
	v_add3_u32 v25, v30, v25, s59
	v_bfe_u32 v30, v40, 16, 1
	v_add3_u32 v37, v28, v37, s59
	v_bfe_u32 v28, v26, 16, 1
	v_add3_u32 v30, v40, v30, s59
	v_add3_u32 v26, v26, v28, s59
	v_lshrrev_b32_e32 v28, 16, v30
	v_mul_f32_e32 v30, 0x4b800000, v22
	v_cmp_gt_f32_e32 vcc, s65, v22
	v_bfe_u32 v23, v31, 16, 1
	v_bfe_u32 v35, v29, 16, 1
	v_cndmask_b32_e32 v22, v22, v30, vcc
	v_rsq_f32_e32 v22, v22
	v_add3_u32 v23, v31, v23, s59
	v_bfe_u32 v31, v41, 16, 1
	v_add3_u32 v35, v29, v35, s59
	v_bfe_u32 v29, v27, 16, 1
	v_add3_u32 v31, v41, v31, s59
	v_add3_u32 v27, v27, v29, s59
	v_lshrrev_b32_e32 v29, 16, v31
	v_and_or_b32 v29, v23, s63, v29
	v_mul_f32_e32 v23, 0x45800000, v22
	v_cndmask_b32_e32 v22, v22, v23, vcc
	v_pk_mul_f32 v[20:21], v[20:21], v[22:23] op_sel_hi:[1,0]
	v_pk_mul_f32 v[18:19], v[18:19], v[22:23] op_sel_hi:[1,0]
	v_pk_fma_f32 v[16:17], v[16:17], v[20:21], v[50:51]
	v_and_or_b32 v28, v25, s63, v28
	v_mul_f32_e32 v20, 0xbfb8aa3b, v16
	v_mul_f32_e32 v21, 0xbfb8aa3b, v17
	v_exp_f32_e32 v20, v20
	v_exp_f32_e32 v21, v21
	v_pk_fma_f32 v[14:15], v[10:11], v[18:19], v[14:15]
	v_lshrrev_b32_e32 v26, 16, v26
	v_lshrrev_b32_e32 v27, 16, v27
	v_pk_add_f32 v[20:21], v[20:21], 1.0 op_sel_hi:[1,0]
	v_and_or_b32 v27, v35, s63, v27
	v_div_scale_f32 v23, s[0:1], v21, v21, 1.0
	v_rcp_f32_e32 v25, v23
	v_and_or_b32 v26, v37, s63, v26
	ds_write_b128 v24, v[26:29] offset:1056
	v_mul_f32_e32 v10, 0xbfb8aa3b, v14
	v_fma_f32 v11, -v23, v25, 1.0
	v_fmac_f32_e32 v25, v11, v25
	v_div_scale_f32 v11, vcc, 1.0, v21, 1.0
	v_mul_f32_e32 v18, v11, v25
	v_fma_f32 v19, -v23, v18, v11
	v_fmac_f32_e32 v18, v19, v25
	v_fma_f32 v11, -v23, v18, v11
	v_div_scale_f32 v23, s[0:1], v20, v20, 1.0
	v_rcp_f32_e32 v28, v23
	v_div_fmas_f32 v11, v11, v25, v18
	v_div_fixup_f32 v19, v11, v21, 1.0
	v_exp_f32_e32 v10, v10
	v_fma_f32 v11, -v23, v28, 1.0
	v_fmac_f32_e32 v28, v11, v28
	v_mul_f32_e32 v11, 0xbfb8aa3b, v15
	v_exp_f32_e32 v11, v11
	v_div_scale_f32 v18, vcc, 1.0, v20, 1.0
	v_mul_f32_e32 v21, v18, v28
	v_fma_f32 v25, -v23, v21, v18
	v_fmac_f32_e32 v21, v25, v28
	v_pk_add_f32 v[26:27], v[10:11], 1.0 op_sel_hi:[1,0]
	v_fma_f32 v18, -v23, v21, v18
	v_div_scale_f32 v23, s[0:1], v27, v27, 1.0
	v_rcp_f32_e32 v25, v23
	v_div_fmas_f32 v10, v18, v28, v21
	v_div_fixup_f32 v18, v10, v20, 1.0
	v_pk_mul_f32 v[10:11], v[16:17], v[18:19]
	v_fma_f32 v16, -v23, v25, 1.0
	v_fmac_f32_e32 v25, v16, v25
	v_div_scale_f32 v16, vcc, 1.0, v27, 1.0
	v_mul_f32_e32 v17, v16, v25
	v_fma_f32 v18, -v23, v17, v16
	v_fmac_f32_e32 v17, v18, v25
	v_div_scale_f32 v18, s[0:1], v26, v26, 1.0
	v_rcp_f32_e32 v19, v18
	v_fma_f32 v16, -v23, v17, v16
	v_div_fmas_f32 v16, v16, v25, v17
	v_div_fixup_f32 v17, v16, v27, 1.0
	v_fma_f32 v16, -v18, v19, 1.0
	v_pk_mul_f32 v[4:5], v[4:5], v[22:23] op_sel_hi:[1,0]
	v_fmac_f32_e32 v19, v16, v19
	v_div_scale_f32 v16, vcc, 1.0, v26, 1.0
	v_pk_fma_f32 v[4:5], v[8:9], v[4:5], v[12:13]
	v_mul_f32_e32 v20, v16, v19
	v_mul_f32_e32 v8, 0xbfb8aa3b, v4
	v_mul_f32_e32 v9, 0xbfb8aa3b, v5
	v_fma_f32 v21, -v18, v20, v16
	v_exp_f32_e32 v8, v8
	v_exp_f32_e32 v9, v9
	v_fmac_f32_e32 v20, v21, v19
	v_fma_f32 v16, -v18, v20, v16
	v_div_fmas_f32 v16, v16, v19, v20
	v_div_fixup_f32 v16, v16, v26, 1.0
	v_pk_add_f32 v[8:9], v[8:9], 1.0 op_sel_hi:[1,0]
	v_pk_mul_f32 v[12:13], v[14:15], v[16:17]
	v_div_scale_f32 v14, s[0:1], v9, v9, 1.0
	v_rcp_f32_e32 v15, v14
	v_pk_mul_f32 v[0:1], v[0:1], v[22:23] op_sel_hi:[1,0]
	s_nop 0
	v_pk_fma_f32 v[0:1], v[2:3], v[0:1], v[6:7]
	v_fma_f32 v3, -v14, v15, 1.0
	v_fmac_f32_e32 v15, v3, v15
	v_div_scale_f32 v3, vcc, 1.0, v9, 1.0
	v_mul_f32_e32 v6, v3, v15
	v_fma_f32 v7, -v14, v6, v3
	v_fmac_f32_e32 v6, v7, v15
	v_fma_f32 v3, -v14, v6, v3
	v_div_scale_f32 v14, s[0:1], v8, v8, 1.0
	v_rcp_f32_e32 v16, v14
	v_div_fmas_f32 v3, v3, v15, v6
	v_div_fixup_f32 v7, v3, v9, 1.0
	v_mul_f32_e32 v2, 0xbfb8aa3b, v0
	v_fma_f32 v3, -v14, v16, 1.0
	v_fmac_f32_e32 v16, v3, v16
	v_mul_f32_e32 v3, 0xbfb8aa3b, v1
	v_exp_f32_e32 v2, v2
	v_exp_f32_e32 v3, v3
	v_div_scale_f32 v6, vcc, 1.0, v8, 1.0
	v_mul_f32_e32 v9, v6, v16
	v_fma_f32 v15, -v14, v9, v6
	v_fmac_f32_e32 v9, v15, v16
	v_pk_add_f32 v[2:3], v[2:3], 1.0 op_sel_hi:[1,0]
	v_fma_f32 v6, -v14, v9, v6
	v_div_scale_f32 v14, s[0:1], v3, v3, 1.0
	v_rcp_f32_e32 v15, v14
	v_div_fmas_f32 v6, v6, v16, v9
	v_div_fixup_f32 v6, v6, v8, 1.0
	v_pk_mul_f32 v[4:5], v[4:5], v[6:7]
	v_fma_f32 v6, -v14, v15, 1.0
	v_fmac_f32_e32 v15, v6, v15
	v_div_scale_f32 v6, vcc, 1.0, v3, 1.0
	v_mul_f32_e32 v7, v6, v15
	v_fma_f32 v8, -v14, v7, v6
	v_fmac_f32_e32 v7, v8, v15
	v_div_scale_f32 v8, s[0:1], v2, v2, 1.0
	v_rcp_f32_e32 v9, v8
	v_fma_f32 v6, -v14, v7, v6
	v_div_fmas_f32 v6, v6, v15, v7
	v_div_fixup_f32 v3, v6, v3, 1.0
	v_fma_f32 v6, -v8, v9, 1.0
	v_fmac_f32_e32 v9, v6, v9
	v_div_scale_f32 v6, vcc, 1.0, v2, 1.0
	v_mul_f32_e32 v7, v6, v9
	v_fma_f32 v14, -v8, v7, v6
	v_fmac_f32_e32 v7, v14, v9
	v_fma_f32 v6, -v8, v7, v6
	v_div_fmas_f32 v6, v6, v9, v7
	v_div_fixup_f32 v2, v6, v2, 1.0
	v_pk_mul_f32 v[0:1], v[0:1], v[2:3]
	v_bfe_u32 v8, v4, 16, 1
	v_bfe_u32 v2, v1, 16, 1
	v_bfe_u32 v3, v0, 16, 1
	v_add3_u32 v0, v0, v3, s59
	v_add3_u32 v1, v1, v2, s59
	v_bfe_u32 v9, v5, 16, 1
	v_add3_u32 v5, v5, v9, s59
	v_add3_u32 v4, v4, v8, s59
	v_lshrrev_b32_e32 v2, 16, v4
	v_lshrrev_b32_e32 v3, 16, v5
	v_and_or_b32 v3, v1, s63, v3
	v_and_or_b32 v2, v0, s63, v2
	v_cvt_pk_bf16_f32 v1, v11, v13
	v_cvt_pk_bf16_f32 v0, v10, v12
	ds_write_b128 v24, v[0:3] offset:1584
	v_mov_b32_e32 v0, v117
	s_waitcnt lgkmcnt(0)
	s_barrier
	s_nop 0
	v_mbcnt_lo_u32_b32 v0, -1, v0
	v_mbcnt_hi_u32_b32 v2, -1, v0
	v_and_b32_e32 v12, 31, v2
	v_and_or_b32 v0, v32, s66, v12
	v_ashrrev_i32_e32 v1, 31, v0
	v_ashrrev_i32_e32 v2, 2, v2
	v_lshlrev_b64 v[0:1], 9, v[0:1]
	v_and_b32_e32 v8, -8, v2
	v_lshl_add_u64 v[0:1], s[8:9], 0, v[0:1]
	v_ashrrev_i32_e32 v9, 31, v8
	v_lshl_add_u64 v[10:11], v[8:9], 1, v[0:1]
	v_add_co_u32_e32 v0, vcc, s67, v10
	v_lshl_add_u64 v[62:63], v[10:11], 0, s[22:23]
	s_nop 0
	v_addc_co_u32_e32 v1, vcc, 0, v11, vcc
	global_load_dwordx4 v[0:3], v[0:1], off
	v_add_co_u32_e32 v60, vcc, s68, v10
	global_load_dwordx4 v[40:43], v[62:63], off offset:32
	s_nop 0
	v_addc_co_u32_e32 v61, vcc, 0, v11, vcc
	global_load_dwordx4 v[4:7], v[60:61], off
	v_lshlrev_b32_e32 v8, 1, v8
	v_mad_u32_u24 v35, v12, s60, v8
	ds_read_b128 v[8:11], v35
	ds_read_b128 v[44:47], v35 offset:32
	s_waitcnt vmcnt(0) lgkmcnt(0)
	v_mfma_f32_32x32x16_bf16 v[16:31], v[8:11], v[0:3], 0
	global_load_dwordx4 v[48:51], v[60:61], off offset:32
	global_load_dwordx4 v[52:55], v[62:63], off offset:64
	v_mfma_f32_32x32x16_bf16 v[16:31], v[44:47], v[40:43], v[16:31]
	global_load_dwordx4 v[40:43], v[60:61], off offset:64
	v_mfma_f32_32x32x16_bf16 v[0:15], v[8:11], v[4:7], 0
	s_waitcnt vmcnt(0) lgkmcnt(0)
	v_mfma_f32_32x32x16_bf16 v[0:15], v[44:47], v[48:51], v[0:15]
	ds_read_b128 v[44:47], v35 offset:64
	ds_read_b128 v[48:51], v35 offset:96
	s_waitcnt lgkmcnt(1)
	v_mfma_f32_32x32x16_bf16 v[0:15], v[44:47], v[40:43], v[0:15]
	global_load_dwordx4 v[40:43], v[62:63], off offset:96
	v_mfma_f32_32x32x16_bf16 v[16:31], v[44:47], v[52:55], v[16:31]
	s_waitcnt vmcnt(0) lgkmcnt(0)
	v_mfma_f32_32x32x16_bf16 v[16:31], v[48:51], v[40:43], v[16:31]
	global_load_dwordx4 v[40:43], v[60:61], off offset:96
	s_waitcnt vmcnt(0) lgkmcnt(0)
	v_mfma_f32_32x32x16_bf16 v[0:15], v[48:51], v[40:43], v[0:15]
	global_load_dwordx4 v[40:43], v[62:63], off offset:128
	global_load_dwordx4 v[44:47], v[60:61], off offset:128
	ds_read_b128 v[48:51], v35 offset:128
	ds_read_b128 v[56:59], v35 offset:160
	global_load_dwordx4 v[52:55], v[62:63], off offset:160
	s_waitcnt vmcnt(0) lgkmcnt(0)
	v_mfma_f32_32x32x16_bf16 v[16:31], v[48:51], v[40:43], v[16:31]
	global_load_dwordx4 v[40:43], v[60:61], off offset:160
	v_mfma_f32_32x32x16_bf16 v[0:15], v[48:51], v[44:47], v[0:15]
	global_load_dwordx4 v[44:47], v[62:63], off offset:192
	global_load_dwordx4 v[48:51], v[60:61], off offset:192
	v_mfma_f32_32x32x16_bf16 v[16:31], v[56:59], v[52:55], v[16:31]
	ds_read_b128 v[52:55], v35 offset:192
	s_waitcnt vmcnt(0) lgkmcnt(0)
	v_mfma_f32_32x32x16_bf16 v[0:15], v[56:59], v[40:43], v[0:15]
	global_load_dwordx4 v[40:43], v[62:63], off offset:224
	ds_read_b128 v[56:59], v35 offset:224
	v_mfma_f32_32x32x16_bf16 v[16:31], v[52:55], v[44:47], v[16:31]
	global_load_dwordx4 v[44:47], v[60:61], off offset:224
	v_mfma_f32_32x32x16_bf16 v[0:15], v[52:55], v[48:51], v[0:15]
	s_waitcnt vmcnt(0) lgkmcnt(0)
	v_mfma_f32_32x32x16_bf16 v[16:31], v[56:59], v[40:43], v[16:31]
	v_mfma_f32_32x32x16_bf16 v[0:15], v[56:59], v[44:47], v[0:15]
	global_load_dwordx4 v[40:43], v[62:63], off offset:256
	global_load_dwordx4 v[44:47], v[60:61], off offset:256
	ds_read_b128 v[48:51], v35 offset:256
	ds_read_b128 v[56:59], v35 offset:288
	global_load_dwordx4 v[52:55], v[62:63], off offset:288
	s_waitcnt vmcnt(0) lgkmcnt(0)
	v_mfma_f32_32x32x16_bf16 v[16:31], v[48:51], v[40:43], v[16:31]
	global_load_dwordx4 v[40:43], v[60:61], off offset:288
	v_mfma_f32_32x32x16_bf16 v[0:15], v[48:51], v[44:47], v[0:15]
	global_load_dwordx4 v[44:47], v[62:63], off offset:320
	global_load_dwordx4 v[48:51], v[60:61], off offset:320
	v_mfma_f32_32x32x16_bf16 v[16:31], v[56:59], v[52:55], v[16:31]
	ds_read_b128 v[52:55], v35 offset:320
	s_waitcnt vmcnt(0) lgkmcnt(0)
	v_mfma_f32_32x32x16_bf16 v[0:15], v[56:59], v[40:43], v[0:15]
	global_load_dwordx4 v[40:43], v[62:63], off offset:352
	ds_read_b128 v[56:59], v35 offset:352
	v_mfma_f32_32x32x16_bf16 v[16:31], v[52:55], v[44:47], v[16:31]
	global_load_dwordx4 v[44:47], v[60:61], off offset:352
	v_mfma_f32_32x32x16_bf16 v[0:15], v[52:55], v[48:51], v[0:15]
	s_waitcnt vmcnt(0) lgkmcnt(0)
	v_mfma_f32_32x32x16_bf16 v[16:31], v[56:59], v[40:43], v[16:31]
	v_mfma_f32_32x32x16_bf16 v[0:15], v[56:59], v[44:47], v[0:15]
	global_load_dwordx4 v[40:43], v[62:63], off offset:384
	global_load_dwordx4 v[44:47], v[60:61], off offset:384
	ds_read_b128 v[48:51], v35 offset:384
	ds_read_b128 v[56:59], v35 offset:416
	global_load_dwordx4 v[52:55], v[62:63], off offset:416
	s_waitcnt vmcnt(0) lgkmcnt(0)
	v_mfma_f32_32x32x16_bf16 v[16:31], v[48:51], v[40:43], v[16:31]
	global_load_dwordx4 v[40:43], v[60:61], off offset:416
	v_mfma_f32_32x32x16_bf16 v[0:15], v[48:51], v[44:47], v[0:15]
	global_load_dwordx4 v[44:47], v[62:63], off offset:448
	global_load_dwordx4 v[48:51], v[60:61], off offset:448
	v_mfma_f32_32x32x16_bf16 v[16:31], v[56:59], v[52:55], v[16:31]
	ds_read_b128 v[52:55], v35 offset:448
	s_waitcnt vmcnt(0) lgkmcnt(0)
	v_mfma_f32_32x32x16_bf16 v[0:15], v[56:59], v[40:43], v[0:15]
	global_load_dwordx4 v[40:43], v[62:63], off offset:480
	ds_read_b128 v[56:59], v35 offset:480
	v_mfma_f32_32x32x16_bf16 v[16:31], v[52:55], v[44:47], v[16:31]
	global_load_dwordx4 v[44:47], v[60:61], off offset:480
	v_mfma_f32_32x32x16_bf16 v[0:15], v[52:55], v[48:51], v[0:15]
	s_waitcnt vmcnt(0) lgkmcnt(0)
	v_mfma_f32_32x32x16_bf16 v[16:31], v[56:59], v[40:43], v[16:31]
	v_mfma_f32_32x32x16_bf16 v[0:15], v[56:59], v[44:47], v[0:15]
	v_lshrrev_b32_e32 v35, 3, v32
	v_and_b32_e32 v35, 4, v35
	v_mul_u32_u24_e32 v35, 0x108, v35
	v_and_b32_e32 v37, 0x7fffffdf, v32
	s_nop 6
	v_bfe_u32 v39, v16, 16, 1
	v_lshlrev_b32_e32 v35, 1, v35
	v_add3_u32 v16, v16, v39, s59
	v_lshl_add_u32 v35, v37, 1, v35
	ds_write_b16_d16_hi v35, v16 offset:16896
	v_bfe_u32 v16, v17, 16, 1
	v_add3_u32 v16, v17, v16, s59
	ds_write_b16_d16_hi v35, v16 offset:17424
	v_bfe_u32 v16, v18, 16, 1
	v_add3_u32 v16, v18, v16, s59
	ds_write_b16_d16_hi v35, v16 offset:17952
	v_bfe_u32 v16, v19, 16, 1
	v_add3_u32 v16, v19, v16, s59
	ds_write_b16_d16_hi v35, v16 offset:18480
	v_bfe_u32 v16, v20, 16, 1
	v_add3_u32 v16, v20, v16, s59
	ds_write_b16_d16_hi v35, v16 offset:21120
	v_bfe_u32 v16, v21, 16, 1
	v_add3_u32 v16, v21, v16, s59
	ds_write_b16_d16_hi v35, v16 offset:21648
	v_bfe_u32 v16, v22, 16, 1
	v_add3_u32 v16, v22, v16, s59
	ds_write_b16_d16_hi v35, v16 offset:22176
	v_bfe_u32 v16, v23, 16, 1
	v_add3_u32 v16, v23, v16, s59
	ds_write_b16_d16_hi v35, v16 offset:22704
	v_bfe_u32 v16, v24, 16, 1
	v_add3_u32 v16, v24, v16, s59
	ds_write_b16_d16_hi v35, v16 offset:25344
	v_bfe_u32 v16, v25, 16, 1
	v_add3_u32 v16, v25, v16, s59
	ds_write_b16_d16_hi v35, v16 offset:25872
	v_bfe_u32 v16, v26, 16, 1
	v_add3_u32 v16, v26, v16, s59
	ds_write_b16_d16_hi v35, v16 offset:26400
	v_bfe_u32 v16, v27, 16, 1
	v_add3_u32 v16, v27, v16, s59
	ds_write_b16_d16_hi v35, v16 offset:26928
	v_bfe_u32 v16, v28, 16, 1
	v_add3_u32 v16, v28, v16, s59
	ds_write_b16_d16_hi v35, v16 offset:29568
	v_bfe_u32 v16, v29, 16, 1
	v_add3_u32 v16, v29, v16, s59
	ds_write_b16_d16_hi v35, v16 offset:30096
	v_bfe_u32 v16, v30, 16, 1
	v_add3_u32 v16, v30, v16, s59
	ds_write_b16_d16_hi v35, v16 offset:30624
	v_bfe_u32 v16, v31, 16, 1
	v_add3_u32 v16, v31, v16, s59
	ds_write_b16_d16_hi v35, v16 offset:31152
	v_bfe_u32 v16, v0, 16, 1
	v_add3_u32 v0, v0, v16, s59
	ds_write_b16_d16_hi v35, v0 offset:16960
	v_bfe_u32 v0, v1, 16, 1
	v_add3_u32 v0, v1, v0, s59
	ds_write_b16_d16_hi v35, v0 offset:17488
	v_bfe_u32 v0, v2, 16, 1
	v_add3_u32 v0, v2, v0, s59
	ds_write_b16_d16_hi v35, v0 offset:18016
	v_bfe_u32 v0, v3, 16, 1
	v_add3_u32 v0, v3, v0, s59
	ds_write_b16_d16_hi v35, v0 offset:18544
	v_bfe_u32 v0, v4, 16, 1
	v_add3_u32 v0, v4, v0, s59
	ds_write_b16_d16_hi v35, v0 offset:21184
	v_bfe_u32 v0, v5, 16, 1
	v_add3_u32 v0, v5, v0, s59
	ds_write_b16_d16_hi v35, v0 offset:21712
	v_bfe_u32 v0, v6, 16, 1
	v_add3_u32 v0, v6, v0, s59
	ds_write_b16_d16_hi v35, v0 offset:22240
	v_bfe_u32 v0, v7, 16, 1
	v_add3_u32 v0, v7, v0, s59
	ds_write_b16_d16_hi v35, v0 offset:22768
	v_bfe_u32 v0, v8, 16, 1
	v_add3_u32 v0, v8, v0, s59
	ds_write_b16_d16_hi v35, v0 offset:25408
	v_bfe_u32 v0, v9, 16, 1
	v_add3_u32 v0, v9, v0, s59
	ds_write_b16_d16_hi v35, v0 offset:25936
	v_bfe_u32 v0, v10, 16, 1
	v_add3_u32 v0, v10, v0, s59
	ds_write_b16_d16_hi v35, v0 offset:26464
	v_bfe_u32 v0, v11, 16, 1
	v_add3_u32 v0, v11, v0, s59
	ds_write_b16_d16_hi v35, v0 offset:26992
	v_bfe_u32 v0, v12, 16, 1
	v_add3_u32 v0, v12, v0, s59
	ds_write_b16_d16_hi v35, v0 offset:29632
	v_bfe_u32 v0, v13, 16, 1
	v_add3_u32 v0, v13, v0, s59
	ds_write_b16_d16_hi v35, v0 offset:30160
	v_bfe_u32 v0, v14, 16, 1
	v_add3_u32 v0, v14, v0, s59
	ds_write_b16_d16_hi v35, v0 offset:30688
	v_bfe_u32 v0, v15, 16, 1
	v_add3_u32 v0, v15, v0, s59
	v_lshlrev_b32_e32 v116, 1, v38
	ds_write_b16_d16_hi v35, v0 offset:31216
	v_lshl_add_u64 v[0:1], s[8:9], 0, v[116:117]
	v_lshl_add_u64 v[4:5], v[0:1], 0, s[36:37]
	v_mad_u64_u32 v[0:1], s[0:1], v33, s60, v[36:37]
	s_waitcnt lgkmcnt(0)
	s_barrier
	ds_read_b128 v[0:3], v0 offset:16896
	v_add_u32_e32 v6, s53, v33
	v_ashrrev_i32_e32 v7, 31, v6
	v_lshlrev_b64 v[6:7], 11, v[6:7]
	v_lshl_add_u64 v[6:7], v[4:5], 0, v[6:7]
	s_waitcnt lgkmcnt(0)
	global_store_dwordx4 v[6:7], v[0:3], off
	s_nop 1
	v_add_u32_e32 v0, 0x100, v32
	v_ashrrev_i32_e32 v6, 5, v0
	v_mad_u64_u32 v[0:1], s[0:1], v6, s60, v[36:37]
	ds_read_b128 v[0:3], v0 offset:16896
	v_add_u32_e32 v6, s53, v6
	v_ashrrev_i32_e32 v7, 31, v6
	v_lshlrev_b64 v[6:7], 11, v[6:7]
	v_lshl_add_u64 v[6:7], v[4:5], 0, v[6:7]
	s_waitcnt lgkmcnt(0)
	global_store_dwordx4 v[6:7], v[0:3], off
	v_ashrrev_i32_e32 v6, 5, v34
	s_nop 0
	v_mad_u64_u32 v[0:1], s[0:1], v6, s60, v[36:37]
	ds_read_b128 v[0:3], v0 offset:16896
	v_add_u32_e32 v6, s53, v6
	v_ashrrev_i32_e32 v7, 31, v6
	v_lshlrev_b64 v[6:7], 11, v[6:7]
	v_lshl_add_u64 v[6:7], v[4:5], 0, v[6:7]
	s_waitcnt lgkmcnt(0)
	global_store_dwordx4 v[6:7], v[0:3], off
	s_nop 1
	v_add_u32_e32 v0, 0x300, v32
	v_ashrrev_i32_e32 v6, 5, v0
	v_mad_u64_u32 v[0:1], s[0:1], v6, s60, v[36:37]
	ds_read_b128 v[0:3], v0 offset:16896
	v_add_u32_e32 v6, s53, v6
	v_ashrrev_i32_e32 v7, 31, v6
	v_lshlrev_b64 v[6:7], 11, v[6:7]
	v_lshl_add_u64 v[4:5], v[4:5], 0, v[6:7]
	s_waitcnt lgkmcnt(0)
	global_store_dwordx4 v[4:5], v[0:3], off

.LBB0_1358:
	s_sub_u32 s0, s78, 0x400
	s_cmp_lt_u32 s0, 0x200
	s_sub_i32 s0, 0x9ff, s78
	s_cselect_b32 s78, s0, s78
	s_mul_hi_i32 s0, s78, 0x38e38e39
	s_lshr_b32 s1, s0, 31
	s_ashr_i32 s0, s0, 8
	s_add_i32 s0, s0, s1
	s_mulk_i32 s0, 0x480
	s_sub_i32 s26, s78, s0
	s_sext_i32_i16 s0, s26
	s_mulk_i32 s0, 0xe39
	s_lshr_b32 s1, s0, 31
	s_ashr_i32 s18, s0, 18
	s_add_i32 s18, s18, s1
	s_mul_i32 s0, s18, 0x48
	s_sub_i32 s0, s26, s0
	s_sext_i32_i16 s0, s0
	s_cmp_lt_i32 s0, 8
	s_cselect_b64 s[4:5], -1, 0
	s_add_i32 s6, s78, 0xfffffb80
	s_cmpk_gt_u32 s6, 0x47f
	s_cselect_b64 s[0:1], -1, 0
	s_cmpk_lt_u32 s6, 0x480
	s_cselect_b64 s[6:7], -1, 0
	s_and_b64 s[4:5], s[6:7], s[4:5]
	s_and_b64 vcc, exec, s[4:5]
	s_cbranch_vccnz .LBB0_1357
	s_add_i32 s4, s78, 0x47f
	s_cmpk_gt_u32 s4, 0x8fe
	s_mov_b64 s[4:5], -1
	s_cbranch_scc0 .LBB0_1404
	s_lshl_b32 s27, s26, 5
	s_and_b64 vcc, exec, s[0:1]
	s_cbranch_vccz .LBB0_1370
	s_mov_b64 s[8:9], s[30:31]
	v_mov_b32_e32 v0, v65
	s_add_u32 s10, s8, 0x7157900
	v_mbcnt_lo_u32_b32 v0, -1, v0
	v_mbcnt_hi_u32_b32 v0, -1, v0
	v_add_u32_e32 v79, s33, v0
	v_mov_b32_e32 v0, s8
	v_mov_b32_e32 v1, s9
	v_add_co_u32_e32 v0, vcc, s57, v0
	s_addc_u32 s11, s9, 0
	s_nop 0
	v_addc_co_u32_e32 v1, vcc, 0, v1, vcc
	global_load_dwordx2 v[0:1], v[0:1], off offset:504
	v_ashrrev_i32_e32 v36, 3, v79
	v_lshlrev_b32_e32 v78, 4, v79
	v_mov_b64_e32 v[12:13], s[10:11]
	v_add_u32_e32 v2, s27, v36
	v_and_b32_e32 v14, 0x70, v78
	v_mad_i64_i32 v[2:3], s[4:5], v2, s34, v[12:13]
	v_lshlrev_b32_e32 v64, 1, v14
	s_mov_b64 s[0:1], 0x1100
	v_lshl_add_u64 v[2:3], v[2:3], 0, v[64:65]
	v_lshl_add_u64 v[4:5], v[2:3], 0, s[0:1]
	v_add_co_u32_e32 v2, vcc, s35, v2
	global_load_dwordx4 v[8:11], v[4:5], off offset:16
	s_nop 0
	v_addc_co_u32_e32 v3, vcc, 0, v3, vcc
	global_load_dwordx4 v[4:7], v[2:3], off offset:256
	v_mov_b32_e32 v3, v65
	v_lshlrev_b32_e32 v2, 2, v14
	s_waitcnt lgkmcnt(0)
	s_barrier
	v_ashrrev_i32_e32 v81, 5, v79
	v_add_u32_e32 v66, s27, v81
	v_and_b32_e32 v80, 31, v79
	s_sext_i32_i16 s13, s18
	v_cmp_gt_u32_e64 s[6:7], 16, v80
	s_waitcnt vmcnt(0)
	v_readfirstlane_b32 s1, v1
	v_readfirstlane_b32 s0, v0
	v_lshlrev_b32_e32 v15, 16, v9
	s_nop 0
	v_lshl_add_u64 v[18:19], s[0:1], 0, v[2:3]
	global_load_dwordx4 v[0:3], v[18:19], off offset:512
	global_load_dwordx4 v[20:23], v[18:19], off offset:528
	v_and_b32_e32 v27, 0xffff0000, v5
	v_and_b32_e32 v26, 0xffff0000, v4
	v_lshlrev_b32_e32 v25, 16, v5
	v_lshlrev_b32_e32 v24, 16, v4
	v_and_b32_e32 v31, 0xffff0000, v7
	v_and_b32_e32 v30, 0xffff0000, v6
	v_pk_mul_f32 v[32:33], v[26:27], v[26:27]
	v_lshlrev_b32_e32 v29, 16, v7
	v_lshlrev_b32_e32 v28, 16, v6
	v_pk_mul_f32 v[34:35], v[30:31], v[30:31]
	v_pk_fma_f32 v[32:33], v[24:25], v[24:25], v[32:33]
	v_lshlrev_b32_e32 v14, 16, v8
	v_and_b32_e32 v9, 0xffff0000, v9
	v_and_b32_e32 v8, 0xffff0000, v8
	v_pk_fma_f32 v[34:35], v[28:29], v[28:29], v[34:35]
	v_add_f32_e32 v32, v32, v33
	v_pk_mul_f32 v[4:5], v[8:9], v[8:9]
	v_add_f32_e32 v32, v34, v32
	v_lshlrev_b32_e32 v17, 16, v11
	v_lshlrev_b32_e32 v16, 16, v10
	v_and_b32_e32 v11, 0xffff0000, v11
	v_and_b32_e32 v10, 0xffff0000, v10
	v_pk_fma_f32 v[4:5], v[14:15], v[14:15], v[4:5]
	v_add_f32_e32 v32, v35, v32
	v_pk_mul_f32 v[6:7], v[10:11], v[10:11]
	v_add_f32_e32 v4, v4, v32
	v_pk_fma_f32 v[6:7], v[16:17], v[16:17], v[6:7]
	v_add_f32_e32 v4, v5, v4
	v_add_f32_e32 v4, v6, v4
	v_add_f32_e32 v4, v7, v4
	s_waitcnt vmcnt(0) lgkmcnt(0)
	v_mov_b32_e32 v32, v0
	v_add_f32_dpp v4, v4, v4 quad_perm:[1,0,3,2] row_mask:0xf bank_mask:0xf bound_ctrl:1
	v_mov_b32_e32 v33, v2
	v_mov_b32_e32 v2, v1
	v_add_f32_dpp v4, v4, v4 quad_perm:[2,3,0,1] row_mask:0xf bank_mask:0xf bound_ctrl:1
	v_mov_b32_e32 v0, v20
	v_mov_b32_e32 v1, v22
	v_add_f32_dpp v4, v4, v4 row_half_mirror row_mask:0xf bank_mask:0xf bound_ctrl:1
	v_fmamk_f32 v4, v4, 0x3c000000, v127
	v_mul_f32_e32 v5, 0x4b800000, v4
	v_cmp_gt_f32_e32 vcc, s59, v4
	v_mov_b32_e32 v22, v21
	s_nop 0
	v_cndmask_b32_e32 v4, v4, v5, vcc
	v_rsq_f32_e32 v6, v4
	v_mad_u64_u32 v[4:5], s[0:1], v36, s58, v[64:65]
	v_lshlrev_b32_e32 v64, 1, v80
	v_mul_f32_e32 v5, 0x45800000, v6
	v_cndmask_b32_e32 v6, v6, v5, vcc
	v_pk_mul_f32 v[24:25], v[6:7], v[24:25] op_sel_hi:[0,1]
	v_pk_mul_f32 v[26:27], v[6:7], v[26:27] op_sel_hi:[0,1]
	v_pk_mul_f32 v[28:29], v[6:7], v[28:29] op_sel_hi:[0,1]
	v_pk_mul_f32 v[30:31], v[6:7], v[30:31] op_sel_hi:[0,1]
	v_pk_mul_f32 v[20:21], v[32:33], v[24:25]
	v_pk_mul_f32 v[2:3], v[2:3], v[26:27]
	s_nop 0
	v_cvt_pk_bf16_f32 v208, v21, v3
	v_cvt_pk_bf16_f32 v209, v20, v2
	v_pk_mul_f32 v[0:1], v[0:1], v[28:29]
	v_pk_mul_f32 v[22:23], v[22:23], v[30:31]
	v_bfe_u32 v26, v20, 16, 1
	v_cvt_pk_bf16_f32 v3, v1, v23
	v_cvt_pk_bf16_f32 v2, v0, v22
	v_add3_u32 v7, v20, v26, s60
	v_lshrrev_b32_e32 v7, 16, v7
	v_mov_b32_e32 v1, v208
	v_mov_b32_e32 v0, v209
	ds_write_b128 v4, v[0:3]
	global_load_dwordx4 v[20:23], v[18:19], off offset:544
	global_load_dwordx4 v[24:27], v[18:19], off offset:560
	v_mad_i64_i32 v[0:1], s[0:1], v66, s34, v[12:13]
	v_pk_mul_f32 v[12:13], v[6:7], v[14:15] op_sel_hi:[0,1]
	v_pk_mul_f32 v[8:9], v[6:7], v[8:9] op_sel_hi:[0,1]
	v_pk_mul_f32 v[14:15], v[6:7], v[16:17] op_sel_hi:[0,1]
	v_pk_mul_f32 v[6:7], v[6:7], v[10:11] op_sel_hi:[0,1]
	v_lshl_add_u64 v[0:1], v[0:1], 0, s[20:21]
	v_lshl_add_u64 v[2:3], v[0:1], 0, v[64:65]
	s_mul_i32 s0, s13, 0xfffff700
	s_add_i32 s12, s0, s27
	s_cmpk_gt_i32 s12, 0xff
	s_cselect_b64 s[24:25], -1, 0
	s_cmpk_lt_i32 s12, 0x100
	s_waitcnt vmcnt(0) lgkmcnt(0)
	v_mov_b32_e32 v10, v20
	v_mov_b32_e32 v11, v22
	v_mov_b32_e32 v22, v21
	v_mov_b32_e32 v16, v24
	v_mov_b32_e32 v17, v26
	v_mov_b32_e32 v26, v25
	v_pk_mul_f32 v[10:11], v[10:11], v[12:13]
	v_pk_mul_f32 v[8:9], v[22:23], v[8:9]
	s_nop 0
	v_cvt_pk_bf16_f32 v209, v11, v9
	v_cvt_pk_bf16_f32 v210, v10, v8
	v_pk_mul_f32 v[12:13], v[16:17], v[14:15]
	v_pk_mul_f32 v[6:7], v[6:7], v[26:27]
	s_nop 0
	v_cvt_pk_bf16_f32 v208, v13, v7
	v_cvt_pk_bf16_f32 v8, v12, v6
	v_mov_b32_e32 v9, v208
	v_mov_b32_e32 v7, v209
	v_mov_b32_e32 v6, v210
	ds_write_b128 v4, v[6:9] offset:16
	global_load_ushort v2, v[2:3], off
	v_and_b32_e32 v4, 7, v79
	v_cvt_f32_ubyte0_e32 v4, v4
	v_mul_f32_e32 v6, 0xbfd49a78, v4
	v_cmp_gt_f32_e32 vcc, s61, v6
	v_and_b32_e32 v5, 8, v79
	v_bitop3_b32 v3, v79, 8, 31 bitop3:0x6c
	v_cndmask_b32_e32 v6, 0, v129, vcc
	v_fmac_f32_e32 v6, 0xbfd49a78, v4
	v_exp_f32_e32 v4, v6
	v_cmp_eq_u32_e64 s[4:5], 0, v5
	v_cndmask_b32_e32 v5, 0, v130, vcc
	v_ldexp_f32 v6, v4, v5
	s_waitcnt vmcnt(0) lgkmcnt(0)
	v_lshlrev_b32_e32 v4, 16, v2
	v_lshlrev_b32_e32 v2, 1, v3
	s_cbranch_scc1 .LBB0_1363
	v_mov_b32_e32 v3, v65
	v_lshl_add_u64 v[0:1], v[0:1], 0, v[2:3]
	global_load_ushort v0, v[0:1], off
	v_add_u32_e32 v1, s12, v81
	v_add_u32_e32 v3, 0xffffff00, v1
	v_ashrrev_i32_e32 v3, 6, v3
	v_and_b32_e32 v1, 63, v1
	v_cndmask_b32_e64 v1, v1, v3, s[6:7]
	v_cvt_f32_i32_e32 v1, v1
	v_mul_f32_e32 v1, v6, v1
	v_mul_f32_e32 v1, 0.15915494, v1
	v_sin_f32_e32 v3, v1
	v_cos_f32_e32 v1, v1
	s_waitcnt vmcnt(0) lgkmcnt(0)
	v_lshlrev_b32_e32 v0, 16, v0
	v_mul_f32_e32 v0, v3, v0
	v_cndmask_b32_e64 v0, v0, -v0, s[4:5]
	v_fmac_f32_e32 v0, v1, v4
	v_mov_b32_e32 v4, v0

.LBB0_1369:
	v_ashrrev_i32_e32 v73, 31, v72
	v_bfe_u32 v2, v7, 16, 1
	v_add3_u32 v4, v7, v2, s60
	v_lshlrev_b64 v[2:3], 6, v[72:73]
	v_lshl_add_u64 v[0:1], v[0:1], 0, v[2:3]
	global_store_short_d16_hi v[0:1], v4, off
	v_mov_b32_e32 v1, v65
	s_waitcnt lgkmcnt(0)
	s_barrier
	v_lshlrev_b32_e32 v0, 1, v79
	v_mbcnt_lo_u32_b32 v1, -1, v1
	v_mbcnt_hi_u32_b32 v2, -1, v1
	v_and_b32_e32 v20, 31, v2
	s_movk_i32 s0, 0xff80
	v_and_or_b32 v0, v0, s0, v20
	v_ashrrev_i32_e32 v1, 31, v0
	v_ashrrev_i32_e32 v2, 2, v2
	v_lshlrev_b64 v[0:1], 8, v[0:1]
	v_and_b32_e32 v16, -8, v2
	v_lshl_add_u64 v[0:1], s[8:9], 0, v[0:1]
	v_ashrrev_i32_e32 v17, 31, v16
	v_lshl_add_u64 v[18:19], v[16:17], 1, v[0:1]
	s_mov_b32 s0, 0x1710000
	v_add_co_u32_e32 v0, vcc, s0, v18
	s_mov_b32 s0, 0x1712000
	s_nop 0
	v_addc_co_u32_e32 v1, vcc, 0, v19, vcc
	v_add_co_u32_e32 v76, vcc, s0, v18
	s_mov_b32 s0, 0x1714000
	s_nop 0
	v_addc_co_u32_e32 v77, vcc, 0, v19, vcc
	v_add_co_u32_e32 v74, vcc, s0, v18
	s_mov_b32 s0, 0x1716000
	s_nop 0
	v_addc_co_u32_e32 v75, vcc, 0, v19, vcc
	v_add_co_u32_e32 v118, vcc, s0, v18
	global_load_dwordx4 v[0:3], v[0:1], off
	s_nop 0
	v_addc_co_u32_e32 v119, vcc, 0, v19, vcc
	global_load_dwordx4 v[4:7], v[76:77], off
	global_load_dwordx4 v[98:101], v[76:77], off offset:32
	global_load_dwordx4 v[8:11], v[74:75], off
	global_load_dwordx4 v[12:15], v[118:119], off
	v_lshlrev_b32_e32 v16, 1, v16
	s_mov_b64 s[0:1], 0x1710000
	v_mad_u32_u24 v64, v20, s58, v16
	ds_read_b128 v[86:89], v64
	ds_read_b128 v[94:97], v64 offset:32
	v_lshl_add_u64 v[120:121], v[18:19], 0, s[0:1]
	global_load_dwordx4 v[90:93], v[120:121], off offset:32
	global_load_dwordx4 v[102:105], v[74:75], off offset:32
	global_load_dwordx4 v[106:109], v[76:77], off offset:96
	global_load_dwordx4 v[110:113], v[118:119], off offset:32
	global_load_dwordx4 v[114:117], v[74:75], off offset:96
	s_waitcnt vmcnt(0) lgkmcnt(0)
	v_mfma_f32_32x32x16_bf16 v[48:63], v[86:89], v[0:3], 0
	v_mfma_f32_32x32x16_bf16 v[32:47], v[86:89], v[4:7], 0
	v_mfma_f32_32x32x16_bf16 v[16:31], v[86:89], v[8:11], 0
	v_mfma_f32_32x32x16_bf16 v[0:15], v[86:89], v[12:15], 0
	global_load_dwordx4 v[86:89], v[120:121], off offset:64
	v_mfma_f32_32x32x16_bf16 v[48:63], v[94:97], v[90:93], v[48:63]
	global_load_dwordx4 v[90:93], v[76:77], off offset:64
	v_mfma_f32_32x32x16_bf16 v[32:47], v[94:97], v[98:101], v[32:47]
	global_load_dwordx4 v[98:101], v[74:75], off offset:64
	v_mfma_f32_32x32x16_bf16 v[16:31], v[94:97], v[102:105], v[16:31]
	global_load_dwordx4 v[102:105], v[118:119], off offset:64
	v_mfma_f32_32x32x16_bf16 v[0:15], v[94:97], v[110:113], v[0:15]
	ds_read_b128 v[94:97], v64 offset:64
	ds_read_b128 v[110:113], v64 offset:96
	s_waitcnt vmcnt(0) lgkmcnt(0)
	v_mfma_f32_32x32x16_bf16 v[48:63], v[94:97], v[86:89], v[48:63]
	global_load_dwordx4 v[86:89], v[120:121], off offset:96
	v_mfma_f32_32x32x16_bf16 v[32:47], v[94:97], v[90:93], v[32:47]
	v_mfma_f32_32x32x16_bf16 v[16:31], v[94:97], v[98:101], v[16:31]
	v_mfma_f32_32x32x16_bf16 v[0:15], v[94:97], v[102:105], v[0:15]
	v_mfma_f32_32x32x16_bf16 v[32:47], v[110:113], v[106:109], v[32:47]
	s_waitcnt vmcnt(0) lgkmcnt(0)
	v_mfma_f32_32x32x16_bf16 v[48:63], v[110:113], v[86:89], v[48:63]
	global_load_dwordx4 v[86:89], v[118:119], off offset:96
	v_mfma_f32_32x32x16_bf16 v[16:31], v[110:113], v[114:117], v[16:31]
	s_waitcnt vmcnt(0) lgkmcnt(0)
	v_mfma_f32_32x32x16_bf16 v[0:15], v[110:113], v[86:89], v[0:15]
	global_load_dwordx4 v[86:89], v[120:121], off offset:128
	global_load_dwordx4 v[90:93], v[76:77], off offset:128
	global_load_dwordx4 v[94:97], v[74:75], off offset:128
	global_load_dwordx4 v[98:101], v[118:119], off offset:128
	ds_read_b128 v[102:105], v64 offset:128
	ds_read_b128 v[110:113], v64 offset:160
	global_load_dwordx4 v[106:109], v[120:121], off offset:160
	s_waitcnt vmcnt(0) lgkmcnt(0)
	v_mfma_f32_32x32x16_bf16 v[48:63], v[102:105], v[86:89], v[48:63]
	global_load_dwordx4 v[86:89], v[76:77], off offset:160
	v_mfma_f32_32x32x16_bf16 v[32:47], v[102:105], v[90:93], v[32:47]
	global_load_dwordx4 v[90:93], v[74:75], off offset:160
	v_mfma_f32_32x32x16_bf16 v[16:31], v[102:105], v[94:97], v[16:31]
	global_load_dwordx4 v[94:97], v[118:119], off offset:160
	v_mfma_f32_32x32x16_bf16 v[0:15], v[102:105], v[98:101], v[0:15]
	global_load_dwordx4 v[98:101], v[120:121], off offset:192
	global_load_dwordx4 v[102:105], v[76:77], off offset:192
	v_mfma_f32_32x32x16_bf16 v[48:63], v[110:113], v[106:109], v[48:63]
	ds_read_b128 v[106:109], v64 offset:192
	s_waitcnt vmcnt(0) lgkmcnt(0)
	v_mfma_f32_32x32x16_bf16 v[32:47], v[110:113], v[86:89], v[32:47]
	global_load_dwordx4 v[86:89], v[74:75], off offset:192
	v_mfma_f32_32x32x16_bf16 v[16:31], v[110:113], v[90:93], v[16:31]
	global_load_dwordx4 v[90:93], v[118:119], off offset:192
	v_mfma_f32_32x32x16_bf16 v[0:15], v[110:113], v[94:97], v[0:15]
	global_load_dwordx4 v[94:97], v[120:121], off offset:224
	ds_read_b128 v[110:113], v64 offset:224
	v_mfma_f32_32x32x16_bf16 v[48:63], v[106:109], v[98:101], v[48:63]
	global_load_dwordx4 v[98:101], v[76:77], off offset:224
	v_mfma_f32_32x32x16_bf16 v[32:47], v[106:109], v[102:105], v[32:47]
	s_waitcnt vmcnt(0) lgkmcnt(0)
	v_mfma_f32_32x32x16_bf16 v[16:31], v[106:109], v[86:89], v[16:31]
	global_load_dwordx4 v[86:89], v[118:119], off offset:224
	s_nop 0
	global_load_dwordx4 v[74:77], v[74:75], off offset:224
	v_mfma_f32_32x32x16_bf16 v[0:15], v[106:109], v[90:93], v[0:15]
	v_mfma_f32_32x32x16_bf16 v[48:63], v[110:113], v[94:97], v[48:63]
	v_mfma_f32_32x32x16_bf16 v[32:47], v[110:113], v[98:101], v[32:47]
	s_waitcnt vmcnt(0) lgkmcnt(0)
	v_mfma_f32_32x32x16_bf16 v[16:31], v[110:113], v[74:77], v[16:31]
	s_nop 11
	v_cvt_pk_bf16_f32 v208, v16, v17
	v_cvt_pk_bf16_f32 v209, v18, v19
	v_mfma_f32_32x32x16_bf16 v[0:15], v[110:113], v[86:89], v[0:15]
	s_nop 11
	v_cvt_pk_bf16_f32 v210, v0, v1
	v_cvt_pk_bf16_f32 v211, v2, v3
	v_lshrrev_b32_e32 v74, 3, v79
	v_and_b32_e32 v74, 4, v74
	s_nop 5
	v_bfe_u32 v76, v48, 16, 1
	v_and_b32_e32 v64, 0xffffffc0, v79
	v_add3_u32 v48, v48, v76, s60
	v_mul_u32_u24_e32 v76, 0x108, v74
	v_or_b32_e32 v75, v64, v80
	v_lshlrev_b32_e32 v76, 1, v76
	v_lshl_add_u32 v75, v75, 1, v76
	ds_write_b16_d16_hi v75, v48 offset:16896
	v_bfe_u32 v48, v49, 16, 1
	v_add3_u32 v48, v49, v48, s60
	ds_write_b16_d16_hi v75, v48 offset:17424
	v_bfe_u32 v48, v50, 16, 1
	v_add3_u32 v48, v50, v48, s60
	ds_write_b16_d16_hi v75, v48 offset:17952
	v_bfe_u32 v48, v51, 16, 1
	v_add3_u32 v48, v51, v48, s60
	ds_write_b16_d16_hi v75, v48 offset:18480
	v_bfe_u32 v48, v52, 16, 1
	v_add3_u32 v48, v52, v48, s60
	ds_write_b16_d16_hi v75, v48 offset:21120
	v_bfe_u32 v48, v53, 16, 1
	v_add3_u32 v48, v53, v48, s60
	ds_write_b16_d16_hi v75, v48 offset:21648
	v_bfe_u32 v48, v54, 16, 1
	v_add3_u32 v48, v54, v48, s60
	ds_write_b16_d16_hi v75, v48 offset:22176
	v_bfe_u32 v48, v55, 16, 1
	v_add3_u32 v48, v55, v48, s60
	ds_write_b16_d16_hi v75, v48 offset:22704
	v_bfe_u32 v48, v56, 16, 1
	v_add3_u32 v48, v56, v48, s60
	ds_write_b16_d16_hi v75, v48 offset:25344
	v_bfe_u32 v48, v57, 16, 1
	v_add3_u32 v48, v57, v48, s60
	ds_write_b16_d16_hi v75, v48 offset:25872
	v_bfe_u32 v48, v58, 16, 1
	v_add3_u32 v48, v58, v48, s60
	ds_write_b16_d16_hi v75, v48 offset:26400
	v_bfe_u32 v48, v59, 16, 1
	v_add3_u32 v48, v59, v48, s60
	ds_write_b16_d16_hi v75, v48 offset:26928
	v_bfe_u32 v48, v60, 16, 1
	v_add3_u32 v48, v60, v48, s60
	ds_write_b16_d16_hi v75, v48 offset:29568
	v_bfe_u32 v48, v61, 16, 1
	v_add3_u32 v48, v61, v48, s60
	ds_write_b16_d16_hi v75, v48 offset:30096
	v_bfe_u32 v48, v62, 16, 1
	v_add3_u32 v48, v62, v48, s60
	ds_write_b16_d16_hi v75, v48 offset:30624
	v_bfe_u32 v48, v63, 16, 1
	v_add3_u32 v48, v63, v48, s60
	ds_write_b16_d16_hi v75, v48 offset:31152
	v_bfe_u32 v48, v32, 16, 1
	v_add3_u32 v32, v32, v48, s60
	ds_write_b16_d16_hi v75, v32 offset:16960
	v_bfe_u32 v32, v33, 16, 1
	v_add3_u32 v32, v33, v32, s60
	ds_write_b16_d16_hi v75, v32 offset:17488
	v_bfe_u32 v32, v34, 16, 1
	v_add3_u32 v32, v34, v32, s60
	ds_write_b16_d16_hi v75, v32 offset:18016
	v_bfe_u32 v32, v35, 16, 1
	v_add3_u32 v32, v35, v32, s60
	ds_write_b16_d16_hi v75, v32 offset:18544
	v_bfe_u32 v32, v36, 16, 1
	v_add3_u32 v32, v36, v32, s60
	ds_write_b16_d16_hi v75, v32 offset:21184
	v_bfe_u32 v32, v37, 16, 1
	v_add3_u32 v32, v37, v32, s60
	ds_write_b16_d16_hi v75, v32 offset:21712
	v_bfe_u32 v32, v38, 16, 1
	v_add3_u32 v32, v38, v32, s60
	ds_write_b16_d16_hi v75, v32 offset:22240
	v_bfe_u32 v32, v39, 16, 1
	v_add3_u32 v32, v39, v32, s60
	ds_write_b16_d16_hi v75, v32 offset:22768
	v_bfe_u32 v32, v40, 16, 1
	v_add3_u32 v32, v40, v32, s60
	ds_write_b16_d16_hi v75, v32 offset:25408
	v_bfe_u32 v32, v41, 16, 1
	v_add3_u32 v32, v41, v32, s60
	ds_write_b16_d16_hi v75, v32 offset:25936
	v_bfe_u32 v32, v42, 16, 1
	v_add3_u32 v32, v42, v32, s60
	ds_write_b16_d16_hi v75, v32 offset:26464
	v_bfe_u32 v32, v43, 16, 1
	v_add3_u32 v32, v43, v32, s60
	ds_write_b16_d16_hi v75, v32 offset:26992
	v_bfe_u32 v32, v44, 16, 1
	v_add3_u32 v32, v44, v32, s60
	ds_write_b16_d16_hi v75, v32 offset:29632
	v_bfe_u32 v32, v45, 16, 1
	v_add3_u32 v32, v45, v32, s60
	ds_write_b16_d16_hi v75, v32 offset:30160
	v_bfe_u32 v32, v46, 16, 1
	v_add3_u32 v32, v46, v32, s60
	ds_write_b16_d16_hi v75, v32 offset:30688
	v_bfe_u32 v32, v47, 16, 1
	v_add3_u32 v32, v47, v32, s60
	ds_write_b16_d16_hi v75, v32 offset:31216
	v_lshl_add_u32 v32, s13, 8, v64
	s_ashr_i32 s13, s12, 31
	s_lshl_b64 s[0:1], s[12:13], 1
	v_bfe_u32 v37, v17, 16, 1
	s_add_u32 s0, s8, s0
	s_addc_u32 s1, s9, s1
	v_lshlrev_b32_e32 v64, 1, v74
	v_mov_b32_e32 v16, v208
	v_or_b32_e32 v36, v32, v80
	v_lshl_add_u64 v[32:33], s[0:1], 0, v[64:65]
	s_mov_b64 s[0:1], 0x144d7900
	v_lshl_add_u64 v[32:33], v[32:33], 0, s[0:1]
	v_mad_i64_i32 v[34:35], s[0:1], v36, s63, v[32:33]
	v_mov_b32_e32 v17, v209
	global_store_dwordx2 v[34:35], v[16:17], off
	v_cvt_pk_bf16_f32 v16, v20, v21
	v_cvt_pk_bf16_f32 v17, v22, v23
	global_store_dwordx2 v[34:35], v[16:17], off offset:16
	v_cvt_pk_bf16_f32 v16, v24, v25
	v_cvt_pk_bf16_f32 v17, v26, v27
	global_store_dwordx2 v[34:35], v[16:17], off offset:32
	v_cvt_pk_bf16_f32 v16, v28, v29
	v_cvt_pk_bf16_f32 v17, v30, v31
	v_mov_b32_e32 v0, v210
	global_store_dwordx2 v[34:35], v[16:17], off offset:48
	v_or_b32_e32 v16, 32, v36
	v_mad_i64_i32 v[16:17], s[0:1], v16, s63, v[32:33]
	v_mov_b32_e32 v1, v211
	global_store_dwordx2 v[16:17], v[0:1], off
	v_cvt_pk_bf16_f32 v0, v4, v5
	v_cvt_pk_bf16_f32 v1, v6, v7
	global_store_dwordx2 v[16:17], v[0:1], off offset:16
	v_cvt_pk_bf16_f32 v0, v8, v9
	v_cvt_pk_bf16_f32 v1, v10, v11
	global_store_dwordx2 v[16:17], v[0:1], off offset:32
	v_cvt_pk_bf16_f32 v0, v12, v13
	v_cvt_pk_bf16_f32 v1, v14, v15
	v_and_b32_e32 v64, 0x1f0, v78
	global_store_dwordx2 v[16:17], v[0:1], off offset:48
	v_mad_u64_u32 v[0:1], s[0:1], v81, s64, v[64:65]
	s_waitcnt lgkmcnt(0)
	s_barrier
	ds_read_b128 v[0:3], v0 offset:16896
	v_lshl_add_u64 v[4:5], s[8:9], 0, v[64:65]
	s_mov_b64 s[0:1], 0x13097900
	v_lshl_add_u64 v[4:5], v[4:5], 0, s[0:1]
	v_lshlrev_b64 v[6:7], 9, v[66:67]
	v_lshl_add_u64 v[6:7], v[4:5], 0, v[6:7]
	s_waitcnt lgkmcnt(0)
	global_store_dwordx4 v[6:7], v[0:3], off
	v_lshlrev_b64 v[6:7], 9, v[68:69]
	v_lshl_add_u64 v[6:7], v[4:5], 0, v[6:7]
	v_mad_u64_u32 v[0:1], s[0:1], v82, s64, v[64:65]
	ds_read_b128 v[0:3], v0 offset:16896
	s_mov_b64 s[4:5], 0
	s_waitcnt lgkmcnt(0)
	global_store_dwordx4 v[6:7], v[0:3], off
	s_nop 1
	v_mad_u64_u32 v[0:1], s[0:1], v83, s64, v[64:65]
	ds_read_b128 v[0:3], v0 offset:16896
	v_lshlrev_b64 v[6:7], 9, v[70:71]
	v_lshl_add_u64 v[6:7], v[4:5], 0, v[6:7]
	s_waitcnt lgkmcnt(0)
	global_store_dwordx4 v[6:7], v[0:3], off
	s_nop 1
	v_mad_u64_u32 v[0:1], s[0:1], v84, s64, v[64:65]
	ds_read_b128 v[0:3], v0 offset:16896
	v_lshlrev_b64 v[6:7], 9, v[72:73]
	v_lshl_add_u64 v[4:5], v[4:5], 0, v[6:7]
	s_waitcnt lgkmcnt(0)
	global_store_dwordx4 v[4:5], v[0:3], off
.LBB0_1370:
	s_and_b64 vcc, exec, s[4:5]
	s_cbranch_vccz .LBB0_1417
	s_mov_b64 s[0:1], s[30:31]
	v_mov_b32_e32 v0, v65
	s_nop 0
	v_mbcnt_lo_u32_b32 v0, -1, v0
	v_mbcnt_hi_u32_b32 v0, -1, v0
	v_add_u32_e32 v48, s33, v0
	v_mov_b64_e32 v[0:1], s[0:1]
	v_ashrrev_i32_e32 v49, 3, v48
	v_add_u32_e32 v2, s27, v49
	v_mad_i64_i32 v[0:1], s[4:5], v2, s34, v[0:1]
	v_mov_b32_e32 v2, s0
	v_mov_b32_e32 v3, s1
	v_add_co_u32_e32 v2, vcc, s57, v2
	v_lshlrev_b32_e32 v4, 5, v48
	s_nop 0
	v_addc_co_u32_e32 v3, vcc, 0, v3, vcc
	global_load_dwordx2 v[2:3], v[2:3], off offset:488
	v_and_b32_e32 v10, 0xe0, v4
	v_lshlrev_b32_e32 v64, 1, v10
	v_lshl_add_u64 v[0:1], v[0:1], 0, v[64:65]
	s_mov_b64 s[4:5], 0x7157f00
	v_lshl_add_u64 v[8:9], v[0:1], 0, s[4:5]
	s_mov_b32 s4, 0x7157000
	v_add_co_u32_e32 v0, vcc, s4, v0
	global_load_dwordx4 v[4:7], v[8:9], off offset:48
	global_load_dwordx4 v[12:15], v[8:9], off offset:16
	global_load_dwordx4 v[16:19], v[8:9], off offset:32
	v_addc_co_u32_e32 v1, vcc, 0, v1, vcc
	global_load_dwordx4 v[20:23], v[0:1], off offset:3840
	v_mov_b32_e32 v1, v65
	v_lshlrev_b32_e32 v0, 2, v10
	s_waitcnt lgkmcnt(0)
	s_barrier
	s_waitcnt vmcnt(0)
	v_readfirstlane_b32 s5, v3
	v_readfirstlane_b32 s4, v2
	v_and_b32_e32 v3, 0xffff0000, v5
	s_nop 0
	v_lshl_add_u64 v[10:11], s[4:5], 0, v[0:1]
	global_load_dwordx4 v[24:27], v[10:11], off offset:1024
	global_load_dwordx4 v[28:31], v[10:11], off offset:1040
	v_lshlrev_b32_e32 v41, 16, v17
	v_lshlrev_b32_e32 v40, 16, v16
	v_and_b32_e32 v43, 0xffff0000, v17
	v_and_b32_e32 v42, 0xffff0000, v16
	v_and_b32_e32 v17, 0xffff0000, v21
	v_and_b32_e32 v16, 0xffff0000, v20
	v_lshlrev_b32_e32 v37, 16, v15
	v_lshlrev_b32_e32 v36, 16, v14
	v_and_b32_e32 v39, 0xffff0000, v15
	v_and_b32_e32 v38, 0xffff0000, v14
	v_lshlrev_b32_e32 v15, 16, v21
	v_lshlrev_b32_e32 v14, 16, v20
	v_and_b32_e32 v21, 0xffff0000, v23
	v_and_b32_e32 v20, 0xffff0000, v22
	v_pk_mul_f32 v[56:57], v[16:17], v[16:17]
	v_lshlrev_b32_e32 v45, 16, v19
	v_lshlrev_b32_e32 v44, 16, v18
	v_and_b32_e32 v47, 0xffff0000, v19
	v_and_b32_e32 v46, 0xffff0000, v18
	v_lshlrev_b32_e32 v19, 16, v23
	v_lshlrev_b32_e32 v18, 16, v22
	v_pk_mul_f32 v[58:59], v[20:21], v[20:21]
	v_pk_fma_f32 v[56:57], v[14:15], v[14:15], v[56:57]
	v_and_b32_e32 v35, 0xffff0000, v13
	v_and_b32_e32 v34, 0xffff0000, v12
	v_pk_fma_f32 v[58:59], v[18:19], v[18:19], v[58:59]
	v_add_f32_e32 v56, v56, v57
	v_lshlrev_b32_e32 v33, 16, v13
	v_lshlrev_b32_e32 v32, 16, v12
	v_pk_mul_f32 v[22:23], v[34:35], v[34:35]
	v_add_f32_e32 v56, v58, v56
	v_pk_fma_f32 v[22:23], v[32:33], v[32:33], v[22:23]
	v_add_f32_e32 v56, v59, v56
	v_pk_mul_f32 v[50:51], v[38:39], v[38:39]
	v_add_f32_e32 v22, v22, v56
	v_pk_fma_f32 v[50:51], v[36:37], v[36:37], v[50:51]
	v_add_f32_e32 v22, v23, v22
	v_pk_mul_f32 v[52:53], v[42:43], v[42:43]
	v_add_f32_e32 v22, v50, v22
	v_pk_fma_f32 v[52:53], v[40:41], v[40:41], v[52:53]
	v_add_f32_e32 v22, v51, v22
	v_pk_mul_f32 v[54:55], v[46:47], v[46:47]
	v_add_f32_e32 v22, v52, v22
	v_and_b32_e32 v2, 0xffff0000, v4
	v_pk_fma_f32 v[54:55], v[44:45], v[44:45], v[54:55]
	v_add_f32_e32 v22, v53, v22
	v_lshlrev_b32_e32 v1, 16, v5
	v_lshlrev_b32_e32 v0, 16, v4
	v_pk_mul_f32 v[8:9], v[2:3], v[2:3]
	v_add_f32_e32 v22, v54, v22
	v_lshlrev_b32_e32 v5, 16, v7
	v_lshlrev_b32_e32 v4, 16, v6
	v_and_b32_e32 v7, 0xffff0000, v7
	v_and_b32_e32 v6, 0xffff0000, v6
	v_pk_fma_f32 v[8:9], v[0:1], v[0:1], v[8:9]
	v_add_f32_e32 v22, v55, v22
	v_pk_mul_f32 v[12:13], v[6:7], v[6:7]
	v_add_f32_e32 v8, v8, v22
	v_pk_fma_f32 v[12:13], v[4:5], v[4:5], v[12:13]
	v_add_f32_e32 v8, v9, v8
	v_add_f32_e32 v8, v12, v8
	v_add_f32_e32 v8, v13, v8
	v_and_b32_e32 v57, 31, v48
	s_waitcnt vmcnt(0) lgkmcnt(0)
	v_mov_b32_e32 v22, v24
	v_add_f32_dpp v8, v8, v8 quad_perm:[1,0,3,2] row_mask:0xf bank_mask:0xf bound_ctrl:1
	v_mov_b32_e32 v23, v26
	v_mov_b32_e32 v26, v25
	v_add_f32_dpp v8, v8, v8 quad_perm:[2,3,0,1] row_mask:0xf bank_mask:0xf bound_ctrl:1
	v_mov_b32_e32 v24, v28
	v_mov_b32_e32 v25, v30
	v_add_f32_dpp v8, v8, v8 row_half_mirror row_mask:0xf bank_mask:0xf bound_ctrl:1
	v_fmamk_f32 v8, v8, 0x3b800000, v127
	v_mul_f32_e32 v9, 0x4b800000, v8
	v_cmp_gt_f32_e32 vcc, s59, v8
	v_mov_b32_e32 v30, v29
	s_nop 0
	v_cndmask_b32_e32 v8, v8, v9, vcc
	v_rsq_f32_e32 v12, v8
	v_mad_u64_u32 v[8:9], s[4:5], v49, s64, v[64:65]
	s_movk_i32 s4, 0x60
	v_mul_f32_e32 v9, 0x45800000, v12
	v_cndmask_b32_e32 v12, v12, v9, vcc
	v_pk_mul_f32 v[14:15], v[12:13], v[14:15] op_sel_hi:[0,1]
	v_pk_mul_f32 v[16:17], v[12:13], v[16:17] op_sel_hi:[0,1]
	v_pk_mul_f32 v[18:19], v[12:13], v[18:19] op_sel_hi:[0,1]
	v_pk_mul_f32 v[20:21], v[12:13], v[20:21] op_sel_hi:[0,1]
	v_pk_mul_f32 v[14:15], v[22:23], v[14:15]
	v_pk_mul_f32 v[16:17], v[26:27], v[16:17]
	s_nop 0
	v_cvt_pk_bf16_f32 v209, v15, v17
	v_cvt_pk_bf16_f32 v210, v14, v16
	v_pk_mul_f32 v[18:19], v[24:25], v[18:19]
	v_pk_mul_f32 v[20:21], v[30:31], v[20:21]
	s_nop 0
	v_cvt_pk_bf16_f32 v208, v18, v20
	v_bfe_u32 v13, v20, 16, 1
	v_add3_u32 v13, v20, v13, s60
	v_cvt_pk_bf16_f32 v17, v19, v21
	v_mov_b32_e32 v16, v208
	v_mov_b32_e32 v15, v209
	v_mov_b32_e32 v14, v210
	ds_write_b128 v8, v[14:17]
	global_load_dwordx4 v[14:17], v[10:11], off offset:1056
	global_load_dwordx4 v[18:21], v[10:11], off offset:1072
	v_pk_mul_f32 v[22:23], v[12:13], v[32:33] op_sel_hi:[0,1]
	v_pk_mul_f32 v[24:25], v[12:13], v[34:35] op_sel_hi:[0,1]
	v_pk_mul_f32 v[26:27], v[12:13], v[36:37] op_sel_hi:[0,1]
	v_pk_mul_f32 v[28:29], v[12:13], v[38:39] op_sel_hi:[0,1]
	s_mov_b32 s5, 0x16e0000
	s_waitcnt vmcnt(0) lgkmcnt(0)
	v_mov_b32_e32 v30, v14
	v_mov_b32_e32 v31, v16
	v_mov_b32_e32 v16, v15
	v_mov_b32_e32 v14, v18
	v_mov_b32_e32 v15, v20
	v_mov_b32_e32 v20, v19
	v_pk_mul_f32 v[18:19], v[30:31], v[22:23]
	v_pk_mul_f32 v[16:17], v[16:17], v[24:25]
	s_nop 0
	v_cvt_pk_bf16_f32 v210, v19, v17
	v_cvt_pk_bf16_f32 v211, v18, v16
	v_pk_mul_f32 v[14:15], v[14:15], v[26:27]
	v_pk_mul_f32 v[20:21], v[20:21], v[28:29]
	s_nop 0
	v_cvt_pk_bf16_f32 v208, v15, v21
	v_cvt_pk_bf16_f32 v209, v14, v20
	v_bfe_u32 v13, v20, 16, 1
	v_add3_u32 v13, v20, v13, s60
	v_mov_b32_e32 v17, v208
	v_mov_b32_e32 v16, v209
	v_mov_b32_e32 v15, v210
	v_mov_b32_e32 v14, v211
	ds_write_b128 v8, v[14:17] offset:16
	global_load_dwordx4 v[14:17], v[10:11], off offset:1088
	global_load_dwordx4 v[18:21], v[10:11], off offset:1104
	v_pk_mul_f32 v[22:23], v[12:13], v[40:41] op_sel_hi:[0,1]
	v_pk_mul_f32 v[24:25], v[12:13], v[42:43] op_sel_hi:[0,1]
	v_pk_mul_f32 v[26:27], v[12:13], v[44:45] op_sel_hi:[0,1]
	v_pk_mul_f32 v[28:29], v[12:13], v[46:47] op_sel_hi:[0,1]
	s_waitcnt vmcnt(0) lgkmcnt(0)
	v_mov_b32_e32 v30, v14
	v_mov_b32_e32 v31, v16
	v_mov_b32_e32 v16, v15
	v_mov_b32_e32 v14, v18
	v_mov_b32_e32 v15, v20
	v_mov_b32_e32 v20, v19
	v_pk_mul_f32 v[18:19], v[30:31], v[22:23]
	v_pk_mul_f32 v[16:17], v[16:17], v[24:25]
	s_nop 0
	v_cvt_pk_bf16_f32 v210, v19, v17
	v_cvt_pk_bf16_f32 v211, v18, v16
	v_pk_mul_f32 v[14:15], v[26:27], v[14:15]
	v_pk_mul_f32 v[20:21], v[28:29], v[20:21]
	s_nop 0
	v_cvt_pk_bf16_f32 v208, v15, v21
	v_cvt_pk_bf16_f32 v209, v14, v20
	v_bfe_u32 v13, v20, 16, 1
	v_add3_u32 v13, v20, v13, s60
	v_mov_b32_e32 v17, v208
	v_mov_b32_e32 v16, v209
	v_mov_b32_e32 v15, v210
	v_mov_b32_e32 v14, v211
	ds_write_b128 v8, v[14:17] offset:32
	global_load_dwordx4 v[14:17], v[10:11], off offset:1120
	global_load_dwordx4 v[18:21], v[10:11], off offset:1136
	v_ashrrev_i32_e32 v10, 6, v48
	v_mul_lo_u32 v56, v10, s4
	v_pk_mul_f32 v[0:1], v[12:13], v[0:1] op_sel_hi:[0,1]
	v_pk_mul_f32 v[2:3], v[12:13], v[2:3] op_sel_hi:[0,1]
	v_pk_mul_f32 v[4:5], v[12:13], v[4:5] op_sel_hi:[0,1]
	v_pk_mul_f32 v[6:7], v[12:13], v[6:7] op_sel_hi:[0,1]
	v_mov_b32_e32 v9, v65
	s_mov_b32 s4, 0x16e4000
	s_waitcnt vmcnt(0) lgkmcnt(0)
	v_mov_b32_e32 v10, v14
	v_mov_b32_e32 v11, v16
	v_mov_b32_e32 v12, v18
	v_mov_b32_e32 v13, v20
	v_mov_b32_e32 v16, v15
	v_mov_b32_e32 v20, v19
	v_pk_mul_f32 v[0:1], v[0:1], v[10:11]
	v_pk_mul_f32 v[4:5], v[4:5], v[12:13]
	v_pk_mul_f32 v[2:3], v[2:3], v[16:17]
	s_nop 0
	v_cvt_pk_bf16_f32 v210, v1, v3
	v_cvt_pk_bf16_f32 v211, v0, v2
	v_pk_mul_f32 v[6:7], v[6:7], v[20:21]
	s_nop 0
	v_cvt_pk_bf16_f32 v208, v5, v7
	v_cvt_pk_bf16_f32 v209, v4, v6
	v_mov_b32_e32 v3, v208
	v_mov_b32_e32 v2, v209
	v_mov_b32_e32 v1, v210
	v_mov_b32_e32 v0, v211
	ds_write_b128 v8, v[0:3] offset:48
	s_waitcnt lgkmcnt(0)
	s_barrier
	s_nop 0
	v_mbcnt_lo_u32_b32 v0, -1, v9
	v_mbcnt_hi_u32_b32 v0, -1, v0
	v_and_b32_e32 v14, 31, v0
	v_ashrrev_i32_e32 v1, 2, v0
	v_or_b32_e32 v0, v14, v56
	v_and_b32_e32 v12, -8, v1
	v_ashrrev_i32_e32 v1, 31, v0
	v_lshlrev_b64 v[0:1], 9, v[0:1]
	v_ashrrev_i32_e32 v13, 31, v12
	v_lshl_add_u64 v[0:1], s[0:1], 0, v[0:1]
	v_lshl_add_u64 v[16:17], v[12:13], 1, v[0:1]
	v_add_co_u32_e32 v0, vcc, s5, v16
	v_lshlrev_b32_e32 v12, 1, v12
	s_nop 0
	v_addc_co_u32_e32 v1, vcc, 0, v17, vcc
	global_load_dwordx4 v[0:3], v[0:1], off
	v_add_co_u32_e32 v50, vcc, s4, v16
	s_mov_b32 s4, 0x16e8000
	s_nop 0
	v_addc_co_u32_e32 v51, vcc, 0, v17, vcc
	v_add_co_u32_e32 v52, vcc, s4, v16
	s_mov_b64 s[4:5], 0x16e0000
	v_lshl_add_u64 v[54:55], v[16:17], 0, s[4:5]
	global_load_dwordx4 v[58:61], v[54:55], off offset:32
	v_mad_u32_u24 v49, v14, s64, v12
	ds_read_b128 v[12:15], v49
	ds_read_b128 v[66:69], v49 offset:32
	global_load_dwordx4 v[4:7], v[50:51], off
	v_addc_co_u32_e32 v53, vcc, 0, v17, vcc
	global_load_dwordx4 v[8:11], v[52:53], off
	global_load_dwordx4 v[70:73], v[50:51], off offset:32
	s_waitcnt vmcnt(0) lgkmcnt(0)
	v_mfma_f32_32x32x16_bf16 v[32:47], v[12:15], v[0:3], 0
	global_load_dwordx4 v[74:77], v[52:53], off offset:32
	global_load_dwordx4 v[78:81], v[50:51], off offset:96
	global_load_dwordx4 v[82:85], v[54:55], off offset:64
	s_and_b32 s4, 0xffff, s26
	s_mul_i32 s4, s4, 0xe38f
	s_lshr_b32 s4, s4, 22
	s_mulk_i32 s4, 0xf700
	s_add_i32 s4, s4, s27
	v_mfma_f32_32x32x16_bf16 v[32:47], v[66:69], v[58:61], v[32:47]
	global_load_dwordx4 v[58:61], v[50:51], off offset:64
	v_mfma_f32_32x32x16_bf16 v[16:31], v[12:15], v[4:7], 0
	v_mfma_f32_32x32x16_bf16 v[0:15], v[12:15], v[8:11], 0
	v_mfma_f32_32x32x16_bf16 v[16:31], v[66:69], v[70:73], v[16:31]
	global_load_dwordx4 v[70:73], v[52:53], off offset:64
	s_waitcnt vmcnt(0) lgkmcnt(0)
	v_mfma_f32_32x32x16_bf16 v[0:15], v[66:69], v[74:77], v[0:15]
	ds_read_b128 v[66:69], v49 offset:64
	ds_read_b128 v[74:77], v49 offset:96
	s_waitcnt lgkmcnt(1)
	v_mfma_f32_32x32x16_bf16 v[16:31], v[66:69], v[58:61], v[16:31]
	global_load_dwordx4 v[58:61], v[54:55], off offset:96
	v_mfma_f32_32x32x16_bf16 v[32:47], v[66:69], v[82:85], v[32:47]
	s_waitcnt vmcnt(0) lgkmcnt(0)
	v_mfma_f32_32x32x16_bf16 v[32:47], v[74:77], v[58:61], v[32:47]
	global_load_dwordx4 v[58:61], v[52:53], off offset:96
	v_mfma_f32_32x32x16_bf16 v[0:15], v[66:69], v[70:73], v[0:15]
	v_mfma_f32_32x32x16_bf16 v[16:31], v[74:77], v[78:81], v[16:31]
	s_waitcnt vmcnt(0) lgkmcnt(0)
	v_mfma_f32_32x32x16_bf16 v[0:15], v[74:77], v[58:61], v[0:15]
	global_load_dwordx4 v[58:61], v[54:55], off offset:128
	global_load_dwordx4 v[66:69], v[50:51], off offset:128
	global_load_dwordx4 v[70:73], v[52:53], off offset:128
	global_load_dwordx4 v[74:77], v[54:55], off offset:160
	ds_read_b128 v[78:81], v49 offset:128
	ds_read_b128 v[82:85], v49 offset:160
	s_waitcnt vmcnt(0) lgkmcnt(0)
	v_mfma_f32_32x32x16_bf16 v[32:47], v[78:81], v[58:61], v[32:47]
	global_load_dwordx4 v[58:61], v[50:51], off offset:160
	v_mfma_f32_32x32x16_bf16 v[16:31], v[78:81], v[66:69], v[16:31]
	global_load_dwordx4 v[66:69], v[52:53], off offset:160
	v_mfma_f32_32x32x16_bf16 v[0:15], v[78:81], v[70:73], v[0:15]
	global_load_dwordx4 v[70:73], v[54:55], off offset:192
	ds_read_b128 v[78:81], v49 offset:192
	v_mfma_f32_32x32x16_bf16 v[32:47], v[82:85], v[74:77], v[32:47]
	global_load_dwordx4 v[74:77], v[50:51], off offset:192
	s_waitcnt vmcnt(0) lgkmcnt(0)
	v_mfma_f32_32x32x16_bf16 v[16:31], v[82:85], v[58:61], v[16:31]
	global_load_dwordx4 v[58:61], v[52:53], off offset:192
	v_mfma_f32_32x32x16_bf16 v[0:15], v[82:85], v[66:69], v[0:15]
	global_load_dwordx4 v[66:69], v[54:55], off offset:224
	ds_read_b128 v[82:85], v49 offset:224
	v_mfma_f32_32x32x16_bf16 v[32:47], v[78:81], v[70:73], v[32:47]
	global_load_dwordx4 v[70:73], v[50:51], off offset:224
	v_mfma_f32_32x32x16_bf16 v[16:31], v[78:81], v[74:77], v[16:31]
	global_load_dwordx4 v[74:77], v[52:53], off offset:224
	s_waitcnt vmcnt(0) lgkmcnt(0)
	v_mfma_f32_32x32x16_bf16 v[0:15], v[78:81], v[58:61], v[0:15]
	v_mfma_f32_32x32x16_bf16 v[16:31], v[82:85], v[70:73], v[16:31]
	v_mfma_f32_32x32x16_bf16 v[0:15], v[82:85], v[74:77], v[0:15]
	v_mfma_f32_32x32x16_bf16 v[32:47], v[82:85], v[66:69], v[32:47]
	global_load_dwordx4 v[58:61], v[54:55], off offset:256
	global_load_dwordx4 v[66:69], v[50:51], off offset:256
	global_load_dwordx4 v[70:73], v[52:53], off offset:256
	global_load_dwordx4 v[74:77], v[54:55], off offset:288
	ds_read_b128 v[78:81], v49 offset:256
	ds_read_b128 v[82:85], v49 offset:288
	s_waitcnt vmcnt(0) lgkmcnt(0)
	v_mfma_f32_32x32x16_bf16 v[32:47], v[78:81], v[58:61], v[32:47]
	global_load_dwordx4 v[58:61], v[50:51], off offset:288
	v_mfma_f32_32x32x16_bf16 v[16:31], v[78:81], v[66:69], v[16:31]
	global_load_dwordx4 v[66:69], v[52:53], off offset:288
	v_mfma_f32_32x32x16_bf16 v[0:15], v[78:81], v[70:73], v[0:15]
	global_load_dwordx4 v[70:73], v[54:55], off offset:320
	ds_read_b128 v[78:81], v49 offset:320
	v_mfma_f32_32x32x16_bf16 v[32:47], v[82:85], v[74:77], v[32:47]
	global_load_dwordx4 v[74:77], v[50:51], off offset:320
	s_waitcnt vmcnt(0) lgkmcnt(0)
	v_mfma_f32_32x32x16_bf16 v[16:31], v[82:85], v[58:61], v[16:31]
	global_load_dwordx4 v[58:61], v[52:53], off offset:320
	v_mfma_f32_32x32x16_bf16 v[0:15], v[82:85], v[66:69], v[0:15]
	global_load_dwordx4 v[66:69], v[54:55], off offset:352
	ds_read_b128 v[82:85], v49 offset:352
	v_mfma_f32_32x32x16_bf16 v[32:47], v[78:81], v[70:73], v[32:47]
	global_load_dwordx4 v[70:73], v[50:51], off offset:352
	v_mfma_f32_32x32x16_bf16 v[16:31], v[78:81], v[74:77], v[16:31]
	global_load_dwordx4 v[74:77], v[52:53], off offset:352
	s_waitcnt vmcnt(0) lgkmcnt(0)
	v_mfma_f32_32x32x16_bf16 v[0:15], v[78:81], v[58:61], v[0:15]
	v_mfma_f32_32x32x16_bf16 v[16:31], v[82:85], v[70:73], v[16:31]
	v_mfma_f32_32x32x16_bf16 v[0:15], v[82:85], v[74:77], v[0:15]
	v_mfma_f32_32x32x16_bf16 v[32:47], v[82:85], v[66:69], v[32:47]
	global_load_dwordx4 v[58:61], v[54:55], off offset:384
	global_load_dwordx4 v[66:69], v[50:51], off offset:384
	global_load_dwordx4 v[70:73], v[52:53], off offset:384
	global_load_dwordx4 v[74:77], v[54:55], off offset:416
	ds_read_b128 v[78:81], v49 offset:384
	ds_read_b128 v[82:85], v49 offset:416
	s_waitcnt vmcnt(0) lgkmcnt(0)
	v_mfma_f32_32x32x16_bf16 v[32:47], v[78:81], v[58:61], v[32:47]
	global_load_dwordx4 v[58:61], v[50:51], off offset:416
	v_mfma_f32_32x32x16_bf16 v[16:31], v[78:81], v[66:69], v[16:31]
	global_load_dwordx4 v[66:69], v[52:53], off offset:416
	v_mfma_f32_32x32x16_bf16 v[0:15], v[78:81], v[70:73], v[0:15]
	global_load_dwordx4 v[70:73], v[54:55], off offset:448
	ds_read_b128 v[78:81], v49 offset:448
	v_mfma_f32_32x32x16_bf16 v[32:47], v[82:85], v[74:77], v[32:47]
	global_load_dwordx4 v[74:77], v[50:51], off offset:448
	s_waitcnt vmcnt(0) lgkmcnt(0)
	v_mfma_f32_32x32x16_bf16 v[16:31], v[82:85], v[58:61], v[16:31]
	global_load_dwordx4 v[58:61], v[52:53], off offset:448
	v_mfma_f32_32x32x16_bf16 v[0:15], v[82:85], v[66:69], v[0:15]
	global_load_dwordx4 v[66:69], v[54:55], off offset:480
	ds_read_b128 v[82:85], v49 offset:480
	v_mfma_f32_32x32x16_bf16 v[32:47], v[78:81], v[70:73], v[32:47]
	global_load_dwordx4 v[70:73], v[50:51], off offset:480
	s_nop 0
	global_load_dwordx4 v[50:53], v[52:53], off offset:480
	v_mfma_f32_32x32x16_bf16 v[16:31], v[78:81], v[74:77], v[16:31]
	s_waitcnt vmcnt(0) lgkmcnt(0)
	v_mfma_f32_32x32x16_bf16 v[0:15], v[78:81], v[58:61], v[0:15]
	v_mfma_f32_32x32x16_bf16 v[16:31], v[82:85], v[70:73], v[16:31]
	v_mfma_f32_32x32x16_bf16 v[0:15], v[82:85], v[50:53], v[0:15]
	v_mfma_f32_32x32x16_bf16 v[32:47], v[82:85], v[66:69], v[32:47]
	v_lshrrev_b32_e32 v49, 3, v48
	s_nop 10
	v_mul_f32_e32 v32, 0x3e16c740, v32
	v_and_b32_e32 v49, 4, v49
	v_lshlrev_b32_e32 v50, 1, v56
	v_bfe_u32 v52, v32, 16, 1
	v_lshl_or_b32 v51, v57, 1, v50
	v_add3_u32 v32, v32, v52, s60
	v_mul_u32_u24_e32 v52, 0x188, v49
	v_lshl_add_u32 v51, v52, 1, v51
	ds_write_b16_d16_hi v51, v32 offset:16896
	v_mul_f32_e32 v32, 0x3e16c740, v33
	v_bfe_u32 v33, v32, 16, 1
	v_add3_u32 v32, v32, v33, s60
	ds_write_b16_d16_hi v51, v32 offset:17680
	v_mul_f32_e32 v32, 0x3e16c740, v34
	v_bfe_u32 v33, v32, 16, 1
	v_add3_u32 v32, v32, v33, s60
	ds_write_b16_d16_hi v51, v32 offset:18464
	v_mul_f32_e32 v32, 0x3e16c740, v35
	v_bfe_u32 v33, v32, 16, 1
	v_add3_u32 v32, v32, v33, s60
	ds_write_b16_d16_hi v51, v32 offset:19248
	v_mul_f32_e32 v32, 0x3e16c740, v36
	v_bfe_u32 v33, v32, 16, 1
	v_add3_u32 v32, v32, v33, s60
	ds_write_b16_d16_hi v51, v32 offset:23168
	v_mul_f32_e32 v32, 0x3e16c740, v37
	v_bfe_u32 v33, v32, 16, 1
	v_add3_u32 v32, v32, v33, s60
	ds_write_b16_d16_hi v51, v32 offset:23952
	v_mul_f32_e32 v32, 0x3e16c740, v38
	v_bfe_u32 v33, v32, 16, 1
	v_add3_u32 v32, v32, v33, s60
	ds_write_b16_d16_hi v51, v32 offset:24736
	v_mul_f32_e32 v32, 0x3e16c740, v39
	v_bfe_u32 v33, v32, 16, 1
	v_add3_u32 v32, v32, v33, s60
	ds_write_b16_d16_hi v51, v32 offset:25520
	v_mul_f32_e32 v32, 0x3e16c740, v40
	v_bfe_u32 v33, v32, 16, 1
	v_add3_u32 v32, v32, v33, s60
	ds_write_b16_d16_hi v51, v32 offset:29440
	v_mul_f32_e32 v32, 0x3e16c740, v41
	v_bfe_u32 v33, v32, 16, 1
	v_add3_u32 v32, v32, v33, s60
	ds_write_b16_d16_hi v51, v32 offset:30224
	v_mul_f32_e32 v32, 0x3e16c740, v42
	v_bfe_u32 v33, v32, 16, 1
	v_add3_u32 v32, v32, v33, s60
	ds_write_b16_d16_hi v51, v32 offset:31008
	v_mul_f32_e32 v32, 0x3e16c740, v43
	v_bfe_u32 v33, v32, 16, 1
	v_add3_u32 v32, v32, v33, s60
	ds_write_b16_d16_hi v51, v32 offset:31792
	v_mul_f32_e32 v32, 0x3e16c740, v44
	v_bfe_u32 v33, v32, 16, 1
	v_add3_u32 v32, v32, v33, s60
	ds_write_b16_d16_hi v51, v32 offset:35712
	v_mul_f32_e32 v32, 0x3e16c740, v45
	v_bfe_u32 v33, v32, 16, 1
	v_add3_u32 v32, v32, v33, s60
	ds_write_b16_d16_hi v51, v32 offset:36496
	v_mul_f32_e32 v32, 0x3e16c740, v46
	v_bfe_u32 v33, v32, 16, 1
	v_add3_u32 v32, v32, v33, s60
	ds_write_b16_d16_hi v51, v32 offset:37280
	v_mul_f32_e32 v32, 0x3e16c740, v47
	v_bfe_u32 v33, v32, 16, 1
	v_add3_u32 v32, v32, v33, s60
	v_mul_f32_e32 v16, 0x3e16c740, v16
	ds_write_b16_d16_hi v51, v32 offset:38064
	v_bfe_u32 v32, v16, 16, 1
	v_add3_u32 v16, v16, v32, s60
	ds_write_b16_d16_hi v51, v16 offset:16960
	v_mul_f32_e32 v16, 0x3e16c740, v17
	v_bfe_u32 v17, v16, 16, 1
	v_add3_u32 v16, v16, v17, s60
	ds_write_b16_d16_hi v51, v16 offset:17744
	v_mul_f32_e32 v16, 0x3e16c740, v18
	v_bfe_u32 v17, v16, 16, 1
	v_add3_u32 v16, v16, v17, s60
	ds_write_b16_d16_hi v51, v16 offset:18528
	v_mul_f32_e32 v16, 0x3e16c740, v19
	v_bfe_u32 v17, v16, 16, 1
	v_add3_u32 v16, v16, v17, s60
	ds_write_b16_d16_hi v51, v16 offset:19312
	v_mul_f32_e32 v16, 0x3e16c740, v20
	v_bfe_u32 v17, v16, 16, 1
	v_add3_u32 v16, v16, v17, s60
	ds_write_b16_d16_hi v51, v16 offset:23232
	v_mul_f32_e32 v16, 0x3e16c740, v21
	v_bfe_u32 v17, v16, 16, 1
	v_add3_u32 v16, v16, v17, s60
	ds_write_b16_d16_hi v51, v16 offset:24016
	v_mul_f32_e32 v16, 0x3e16c740, v22
	v_bfe_u32 v17, v16, 16, 1
	v_add3_u32 v16, v16, v17, s60
	ds_write_b16_d16_hi v51, v16 offset:24800
	v_mul_f32_e32 v16, 0x3e16c740, v23
	v_bfe_u32 v17, v16, 16, 1
	v_add3_u32 v16, v16, v17, s60
	ds_write_b16_d16_hi v51, v16 offset:25584
	v_mul_f32_e32 v16, 0x3e16c740, v24
	v_bfe_u32 v17, v16, 16, 1
	v_add3_u32 v16, v16, v17, s60
	ds_write_b16_d16_hi v51, v16 offset:29504
	v_mul_f32_e32 v16, 0x3e16c740, v25
	v_bfe_u32 v17, v16, 16, 1
	v_add3_u32 v16, v16, v17, s60
	ds_write_b16_d16_hi v51, v16 offset:30288
	v_mul_f32_e32 v16, 0x3e16c740, v26
	v_bfe_u32 v17, v16, 16, 1
	v_add3_u32 v16, v16, v17, s60
	ds_write_b16_d16_hi v51, v16 offset:31072
	v_mul_f32_e32 v16, 0x3e16c740, v27
	v_bfe_u32 v17, v16, 16, 1
	v_add3_u32 v16, v16, v17, s60
	ds_write_b16_d16_hi v51, v16 offset:31856
	v_mul_f32_e32 v16, 0x3e16c740, v28
	v_bfe_u32 v17, v16, 16, 1
	v_add3_u32 v16, v16, v17, s60
	ds_write_b16_d16_hi v51, v16 offset:35776
	v_mul_f32_e32 v16, 0x3e16c740, v29
	v_bfe_u32 v17, v16, 16, 1
	v_add3_u32 v16, v16, v17, s60
	ds_write_b16_d16_hi v51, v16 offset:36560
	v_mul_f32_e32 v16, 0x3e16c740, v30
	v_bfe_u32 v17, v16, 16, 1
	v_add3_u32 v16, v16, v17, s60
	ds_write_b16_d16_hi v51, v16 offset:37344
	v_mul_f32_e32 v16, 0x3e16c740, v31
	v_bfe_u32 v17, v16, 16, 1
	v_add3_u32 v16, v16, v17, s60
	ds_write_b16_d16_hi v51, v16 offset:38128
	v_and_b32_e32 v16, 7, v48
	v_cvt_f32_ubyte0_e32 v16, v16
	v_mul_f32_e32 v17, 0xbfd49a78, v16
	v_cmp_gt_f32_e32 vcc, s61, v17
	v_and_b32_e32 v18, 64, v131
	v_add_u32_e32 v18, 64, v18
	v_cndmask_b32_e32 v17, 0, v129, vcc
	v_fmac_f32_e32 v17, 0xbfd49a78, v16
	v_exp_f32_e32 v16, v17
	v_xor_b32_e32 v17, 8, v131
	v_cndmask_b32_e32 v19, 0, v130, vcc
	v_cmp_lt_i32_e32 vcc, v17, v18
	s_cmpk_gt_i32 s4, 0xff
	s_cselect_b64 s[10:11], -1, 0
	v_cndmask_b32_e32 v17, v131, v17, vcc
	v_lshlrev_b32_e32 v17, 2, v17
	ds_bpermute_b32 v18, v17, v0
	s_add_i32 s5, s4, 0xffffff00
	s_ashr_i32 s12, s5, 6
	s_and_b32 s13, s27, 32
	v_ldexp_f32 v16, v16, v19
	v_and_b32_e32 v19, 8, v48
	s_cmpk_lt_i32 s4, 0x100
	v_cmp_gt_u32_e64 s[6:7], 16, v57
	v_cmp_eq_u32_e64 s[4:5], 0, v19
	s_cbranch_scc1 .LBB0_1373
	v_or_b32_e32 v19, s13, v49
	v_mov_b32_e32 v20, s12
	v_cndmask_b32_e64 v19, v19, v20, s[6:7]
	v_cvt_f32_i32_e32 v19, v19
	v_mul_f32_e32 v19, v16, v19
	v_mul_f32_e32 v19, 0.15915494, v19
	v_sin_f32_e32 v20, v19
	v_cos_f32_e32 v19, v19
	s_waitcnt lgkmcnt(0)
	v_mul_f32_e32 v18, v20, v18
	v_cndmask_b32_e64 v18, v18, -v18, s[4:5]
	v_fmac_f32_e32 v18, v19, v0
	v_mov_b32_e32 v0, v18

.LBB0_1406:
	v_add_u32_e32 v4, s82, v135
	v_mul_hi_i32 v2, v4, s66
	v_lshrrev_b32_e32 v3, 31, v2
	v_ashrrev_i32_e32 v2, 3, v2
	v_add_u32_e32 v5, v2, v3
	v_mad_u64_u32 v[20:21], s[0:1], v5, s68, v[0:1]
	v_add_u32_e32 v6, s26, v5
	v_mov_b64_e32 v[2:3], s[54:55]
	v_add_u32_e32 v8, s81, v5
	v_mad_i64_i32 v[6:7], s[0:1], v6, s34, v[2:3]
	v_ashrrev_i32_e32 v21, 31, v20
	v_mad_u64_u32 v[18:19], s[0:1], v5, s67, v[4:5]
	v_lshl_add_u64 v[6:7], v[20:21], 1, v[6:7]
	v_cmp_lt_i32_e32 vcc, s27, v8
	v_lshl_add_u64 v[14:15], v[6:7], 0, s[22:23]
	v_add_co_u32_e64 v6, s[0:1], s69, v6
	v_cndmask_b32_e64 v11, 0, -1, vcc
	v_cndmask_b32_e32 v10, 0, v132, vcc
	v_cmp_gt_i32_e64 s[6:7], s80, v8
	v_addc_co_u32_e64 v7, s[0:1], 0, v7, s[0:1]
	v_lshl_add_u64 v[10:11], v[14:15], 0, v[10:11]
	global_load_dwordx4 v[6:9], v[6:7], off offset:1792
	v_cndmask_b32_e64 v64, 0, v133, s[6:7]
	global_load_dwordx4 v[10:13], v[10:11], off
	v_lshl_add_u64 v[14:15], v[14:15], 0, v[64:65]
	global_load_dwordx4 v[14:17], v[14:15], off
	v_cmp_gt_i32_e64 s[4:5], 32, v18
	v_cmp_gt_i32_e64 s[0:1], 16, v18
	v_lshl_add_u32 v5, v5, 4, v1
	v_add_u32_e32 v4, 0x100, v4
	s_addk_i32 s82, 0x200
	s_cmpk_eq_i32 s82, 0x600
	s_waitcnt vmcnt(0) lgkmcnt(0)
	v_lshlrev_b32_e32 v31, 16, v7
	v_and_b32_e32 v7, 0xffff0000, v7
	v_lshlrev_b32_e32 v26, 16, v12
	v_and_b32_e32 v27, 0xffff0000, v12
	v_lshlrev_b32_e32 v29, 16, v13
	v_and_b32_e32 v30, 0xffff0000, v13
	v_lshlrev_b64 v[12:13], 2, v[20:21]
	v_and_b32_e32 v19, 0xffff0000, v10
	v_lshlrev_b32_e32 v25, 16, v11
	v_and_b32_e32 v11, 0xffff0000, v11
	v_lshl_add_u64 v[20:21], s[12:13], 0, v[12:13]
	v_lshlrev_b32_e32 v10, 16, v10
	v_lshlrev_b32_e32 v32, 16, v14
	v_lshlrev_b32_e32 v33, 16, v15
	v_and_b32_e32 v36, 0xffff0000, v15
	v_and_b32_e32 v37, 0xffff0000, v14
	v_lshlrev_b32_e32 v38, 16, v16
	v_lshlrev_b32_e32 v39, 16, v17
	v_and_b32_e32 v40, 0xffff0000, v17
	v_and_b32_e32 v41, 0xffff0000, v16
	v_lshl_add_u64 v[22:23], s[24:25], 0, v[12:13]
	v_cndmask_b32_e32 v18, 0, v10, vcc
	v_cndmask_b32_e32 v24, 0, v19, vcc
	v_cndmask_b32_e32 v19, 0, v25, vcc
	v_cndmask_b32_e32 v25, 0, v11, vcc
	global_load_dwordx4 v[10:13], v[20:21], off
	global_load_dwordx4 v[14:17], v[22:23], off
	v_cndmask_b32_e32 v28, 0, v27, vcc
	v_cndmask_b32_e32 v27, 0, v29, vcc
	v_cndmask_b32_e32 v29, 0, v30, vcc
	v_lshlrev_b32_e32 v30, 16, v6
	v_cndmask_b32_e64 v33, 0, v33, s[6:7]
	v_cndmask_b32_e64 v32, 0, v32, s[6:7]
	v_pk_add_f32 v[18:19], v[18:19], v[30:31] neg_lo:[0,1] neg_hi:[0,1]
	v_and_b32_e32 v6, 0xffff0000, v6
	v_pk_add_f32 v[24:25], v[24:25], v[6:7] neg_lo:[0,1] neg_hi:[0,1]
	v_cndmask_b32_e32 v26, 0, v26, vcc
	s_waitcnt vmcnt(0) lgkmcnt(0)
	v_mov_b32_e32 v34, v10
	v_mov_b32_e32 v35, v12
	v_pk_fma_f32 v[18:19], v[34:35], v[18:19], v[30:31]
	v_pk_add_f32 v[30:31], v[32:33], v[30:31] neg_lo:[0,1] neg_hi:[0,1]
	v_mov_b32_e32 v32, v14
	v_mov_b32_e32 v33, v16
	v_pk_fma_f32 v[18:19], v[30:31], v[32:33], v[18:19]
	v_cndmask_b32_e64 v31, 0, v36, s[6:7]
	v_cndmask_b32_e64 v30, 0, v37, s[6:7]
	v_mov_b32_e32 v12, v11
	v_pk_fma_f32 v[12:13], v[12:13], v[24:25], v[6:7]
	v_pk_add_f32 v[6:7], v[30:31], v[6:7] neg_lo:[0,1] neg_hi:[0,1]
	v_mov_b32_e32 v16, v15
	v_pk_fma_f32 v[6:7], v[6:7], v[16:17], v[12:13]
	v_add_f32_e32 v10, v18, v18
	v_add_f32_e32 v11, v6, v6
	v_cndmask_b32_e64 v11, v11, v6, s[0:1]
	v_mul_f32_e32 v11, 0xbfb8aa3b, v11
	v_exp_f32_e32 v12, v11
	v_add_f32_e32 v11, v19, v19
	v_cndmask_b32_e64 v10, v10, v18, s[0:1]
	v_cndmask_b32_e64 v11, v11, v19, s[0:1]
	v_mul_f32_e32 v10, 0xbfb8aa3b, v10
	v_mul_f32_e32 v11, 0xbfb8aa3b, v11
	v_exp_f32_e32 v10, v10
	v_exp_f32_e32 v11, v11
	s_nop 0
	v_pk_add_f32 v[10:11], v[10:11], 1.0 op_sel_hi:[1,0]
	s_nop 0
	v_div_scale_f32 v13, s[84:85], v11, v11, 1.0
	v_rcp_f32_e32 v14, v13
	s_nop 0
	v_fma_f32 v15, -v13, v14, 1.0
	v_fmac_f32_e32 v14, v15, v14
	v_div_scale_f32 v15, vcc, 1.0, v11, 1.0
	v_mul_f32_e32 v16, v15, v14
	v_fma_f32 v17, -v13, v16, v15
	v_fmac_f32_e32 v16, v17, v14
	v_fma_f32 v13, -v13, v16, v15
	v_div_fmas_f32 v13, v13, v14, v16
	v_div_fixup_f32 v11, v13, v11, 1.0
	v_div_scale_f32 v13, s[84:85], v10, v10, 1.0
	v_rcp_f32_e32 v14, v13
	s_nop 0
	v_fma_f32 v15, -v13, v14, 1.0
	v_fmac_f32_e32 v14, v15, v14
	v_div_scale_f32 v15, vcc, 1.0, v10, 1.0
	v_mul_f32_e32 v16, v15, v14
	v_fma_f32 v17, -v13, v16, v15
	v_fmac_f32_e32 v16, v17, v14
	v_fma_f32 v13, -v13, v16, v15
	v_div_fmas_f32 v13, v13, v14, v16
	v_div_fixup_f32 v10, v13, v10, 1.0
	v_pk_fma_f32 v[14:15], v[10:11], 2.0, -1.0 op_sel_hi:[1,0,0]
	v_and_b32_e32 v17, 0xffff0000, v9
	v_cndmask_b32_e64 v13, v18, v14, s[4:5]
	v_cndmask_b32_e64 v25, v13, v10, s[0:1]
	v_add_f32_e32 v10, v7, v7
	v_cndmask_b32_e64 v10, v10, v7, s[0:1]
	v_mul_f32_e32 v10, 0xbfb8aa3b, v10
	v_exp_f32_e32 v13, v10
	v_cndmask_b32_e64 v14, v19, v15, s[4:5]
	v_cndmask_b32_e64 v24, v14, v11, s[0:1]
	v_cndmask_b32_e64 v19, 0, v39, s[6:7]
	v_pk_add_f32 v[10:11], v[12:13], 1.0 op_sel_hi:[1,0]
	v_cndmask_b32_e64 v18, 0, v38, s[6:7]
	v_div_scale_f32 v12, s[84:85], v11, v11, 1.0
	v_rcp_f32_e32 v13, v12
	s_nop 0
	v_fma_f32 v14, -v12, v13, 1.0
	v_fmac_f32_e32 v13, v14, v13
	v_div_scale_f32 v14, vcc, 1.0, v11, 1.0
	v_mul_f32_e32 v15, v14, v13
	v_fma_f32 v16, -v12, v15, v14
	v_fmac_f32_e32 v15, v16, v13
	v_fma_f32 v12, -v12, v15, v14
	v_div_fmas_f32 v12, v12, v13, v15
	v_div_fixup_f32 v11, v12, v11, 1.0
	v_div_scale_f32 v12, s[84:85], v10, v10, 1.0
	v_rcp_f32_e32 v13, v12
	s_nop 0
	v_fma_f32 v14, -v12, v13, 1.0
	v_fmac_f32_e32 v13, v14, v13
	v_div_scale_f32 v14, vcc, 1.0, v10, 1.0
	v_mul_f32_e32 v15, v14, v13
	v_fma_f32 v16, -v12, v15, v14
	v_fmac_f32_e32 v15, v16, v13
	v_fma_f32 v12, -v12, v15, v14
	v_div_fmas_f32 v12, v12, v13, v15
	v_div_fixup_f32 v10, v12, v10, 1.0
	v_pk_fma_f32 v[12:13], v[10:11], 2.0, -1.0 op_sel_hi:[1,0,0]
	v_lshlrev_b32_e32 v15, 16, v9
	v_cndmask_b32_e64 v7, v7, v13, s[4:5]
	v_cndmask_b32_e64 v6, v6, v12, s[4:5]
	v_cndmask_b32_e64 v30, v6, v10, s[0:1]
	v_cndmask_b32_e64 v31, v7, v11, s[0:1]
	v_lshlrev_b32_e32 v14, 16, v8
	v_and_b32_e32 v16, 0xffff0000, v8
	global_load_dwordx4 v[6:9], v[20:21], off offset:16
	global_load_dwordx4 v[10:13], v[22:23], off offset:16
	v_pk_add_f32 v[20:21], v[26:27], v[14:15] neg_lo:[0,1] neg_hi:[0,1]
	s_waitcnt vmcnt(0) lgkmcnt(0)
	v_mov_b32_e32 v22, v6
	v_mov_b32_e32 v23, v8
	v_pk_fma_f32 v[20:21], v[20:21], v[22:23], v[14:15]
	v_pk_add_f32 v[14:15], v[18:19], v[14:15] neg_lo:[0,1] neg_hi:[0,1]
	v_mov_b32_e32 v18, v10
	v_mov_b32_e32 v19, v12
	v_pk_fma_f32 v[14:15], v[14:15], v[18:19], v[20:21]
	v_cndmask_b32_e64 v19, 0, v40, s[6:7]
	v_cndmask_b32_e64 v18, 0, v41, s[6:7]
	v_pk_add_f32 v[20:21], v[28:29], v[16:17] neg_lo:[0,1] neg_hi:[0,1]
	v_mov_b32_e32 v8, v7
	v_pk_fma_f32 v[8:9], v[20:21], v[8:9], v[16:17]
	v_pk_add_f32 v[16:17], v[18:19], v[16:17] neg_lo:[0,1] neg_hi:[0,1]
	v_mov_b32_e32 v12, v11
	v_pk_fma_f32 v[8:9], v[16:17], v[12:13], v[8:9]
	v_add_f32_e32 v6, v14, v14
	v_add_f32_e32 v7, v8, v8
	v_cndmask_b32_e64 v7, v7, v8, s[0:1]
	v_mul_f32_e32 v7, 0xbfb8aa3b, v7
	v_exp_f32_e32 v10, v7
	v_add_f32_e32 v7, v15, v15
	v_cndmask_b32_e64 v6, v6, v14, s[0:1]
	v_cndmask_b32_e64 v7, v7, v15, s[0:1]
	v_mul_f32_e32 v6, 0xbfb8aa3b, v6
	v_mul_f32_e32 v7, 0xbfb8aa3b, v7
	v_exp_f32_e32 v6, v6
	v_exp_f32_e32 v7, v7
	s_nop 0
	v_pk_add_f32 v[6:7], v[6:7], 1.0 op_sel_hi:[1,0]
	s_nop 0
	v_div_scale_f32 v11, s[6:7], v7, v7, 1.0
	v_rcp_f32_e32 v12, v11
	s_nop 0
	v_fma_f32 v13, -v11, v12, 1.0
	v_fmac_f32_e32 v12, v13, v12
	v_div_scale_f32 v13, vcc, 1.0, v7, 1.0
	v_mul_f32_e32 v16, v13, v12
	v_fma_f32 v17, -v11, v16, v13
	v_fmac_f32_e32 v16, v17, v12
	v_fma_f32 v11, -v11, v16, v13
	v_div_fmas_f32 v11, v11, v12, v16
	v_div_fixup_f32 v7, v11, v7, 1.0
	v_div_scale_f32 v11, s[6:7], v6, v6, 1.0
	v_rcp_f32_e32 v12, v11
	s_nop 0
	v_fma_f32 v13, -v11, v12, 1.0
	v_fmac_f32_e32 v12, v13, v12
	v_div_scale_f32 v13, vcc, 1.0, v6, 1.0
	v_mul_f32_e32 v16, v13, v12
	v_fma_f32 v17, -v11, v16, v13
	v_fmac_f32_e32 v16, v17, v12
	v_fma_f32 v11, -v11, v16, v13
	v_div_fmas_f32 v11, v11, v12, v16
	v_div_fixup_f32 v6, v11, v6, 1.0
	v_pk_fma_f32 v[12:13], v[6:7], 2.0, -1.0 op_sel_hi:[1,0,0]
	s_nop 0
	v_cndmask_b32_e64 v11, v14, v12, s[4:5]
	v_cndmask_b32_e64 v12, v15, v13, s[4:5]
	v_cndmask_b32_e64 v13, v11, v6, s[0:1]
	v_add_f32_e32 v6, v9, v9
	v_cndmask_b32_e64 v6, v6, v9, s[0:1]
	v_mul_f32_e32 v6, 0xbfb8aa3b, v6
	v_exp_f32_e32 v11, v6
	v_cndmask_b32_e64 v12, v12, v7, s[0:1]
	v_pk_add_f32 v[6:7], v[10:11], 1.0 op_sel_hi:[1,0]
	s_nop 0
	v_div_scale_f32 v10, s[6:7], v7, v7, 1.0
	v_rcp_f32_e32 v11, v10
	s_nop 0
	v_fma_f32 v14, -v10, v11, 1.0
	v_fmac_f32_e32 v11, v14, v11
	v_div_scale_f32 v14, vcc, 1.0, v7, 1.0
	v_mul_f32_e32 v15, v14, v11
	v_fma_f32 v16, -v10, v15, v14
	v_fmac_f32_e32 v15, v16, v11
	v_fma_f32 v10, -v10, v15, v14
	v_div_fmas_f32 v10, v10, v11, v15
	v_div_fixup_f32 v7, v10, v7, 1.0
	v_div_scale_f32 v10, s[6:7], v6, v6, 1.0
	v_rcp_f32_e32 v11, v10
	s_nop 0
	v_fma_f32 v14, -v10, v11, 1.0
	v_fmac_f32_e32 v11, v14, v11
	v_div_scale_f32 v14, vcc, 1.0, v6, 1.0
	v_mul_f32_e32 v15, v14, v11
	v_fma_f32 v16, -v10, v15, v14
	v_fmac_f32_e32 v15, v16, v11
	v_fma_f32 v10, -v10, v15, v14
	v_div_fmas_f32 v10, v10, v11, v15
	v_div_fixup_f32 v6, v10, v6, 1.0
	v_pk_fma_f32 v[10:11], v[6:7], 2.0, -1.0 op_sel_hi:[1,0,0]
	v_bfe_u32 v14, v13, 16, 1
	v_cndmask_b32_e64 v9, v9, v11, s[4:5]
	v_cndmask_b32_e64 v8, v8, v10, s[4:5]
	v_cndmask_b32_e64 v6, v8, v6, s[0:1]
	v_cndmask_b32_e64 v7, v9, v7, s[0:1]
	v_cvt_pk_bf16_f32 v208, v12, v7
	v_bfe_u32 v9, v6, 16, 1
	v_add3_u32 v6, v6, v9, s60
	v_add3_u32 v13, v13, v14, s60
	v_lshrrev_b32_e32 v8, 16, v13
	v_mov_b32_e32 v9, v208
	v_and_or_b32 v8, v6, s56, v8
	v_cvt_pk_bf16_f32 v7, v24, v31
	v_cvt_pk_bf16_f32 v6, v25, v30
	ds_write_b128 v5, v[6:9]
	v_mul_hi_i32 v5, v4, s66
	v_lshrrev_b32_e32 v6, 31, v5
	v_ashrrev_i32_e32 v5, 3, v5
	v_add_u32_e32 v6, v5, v6
	v_mad_u64_u32 v[4:5], s[0:1], v6, s67, v[4:5]
	v_mul_lo_u32 v5, v6, s68
	s_movk_i32 s0, 0x800
	v_add3_u32 v20, v0, v5, s0
	v_add_u32_e32 v7, s26, v6
	v_mad_i64_i32 v[2:3], s[0:1], v7, s34, v[2:3]
	v_ashrrev_i32_e32 v21, 31, v20
	v_lshl_add_u64 v[2:3], v[20:21], 1, v[2:3]
	v_add_u32_e32 v5, s81, v6
	v_lshl_add_u64 v[16:17], v[2:3], 0, s[22:23]
	v_add_co_u32_e64 v2, s[0:1], s69, v2
	v_cmp_lt_i32_e32 vcc, s27, v5
	s_nop 0
	v_addc_co_u32_e64 v3, s[0:1], 0, v3, s[0:1]
	v_cmp_gt_i32_e64 s[6:7], s80, v5
	global_load_dwordx4 v[8:11], v[2:3], off offset:1792
	v_cndmask_b32_e64 v3, 0, -1, vcc
	v_cndmask_b32_e32 v2, 0, v132, vcc
	v_lshl_add_u64 v[2:3], v[16:17], 0, v[2:3]
	v_cndmask_b32_e64 v64, 0, v133, s[6:7]
	global_load_dwordx4 v[12:15], v[2:3], off
	v_lshl_add_u64 v[2:3], v[16:17], 0, v[64:65]
	global_load_dwordx4 v[16:19], v[2:3], off
	v_lshlrev_b64 v[2:3], 2, v[20:21]
	v_cmp_gt_i32_e64 s[4:5], 32, v4
	v_cmp_gt_i32_e64 s[0:1], 16, v4
	v_lshl_add_u32 v6, v6, 4, v1
	v_add_u32_e32 v1, 0x2000, v1
	v_add_u32_e32 v0, 0x1000, v0
	s_waitcnt vmcnt(0) lgkmcnt(0)
	v_lshlrev_b32_e32 v29, 16, v9
	v_lshlrev_b32_e32 v28, 16, v8
	v_and_b32_e32 v9, 0xffff0000, v9
	v_and_b32_e32 v8, 0xffff0000, v8
	v_and_b32_e32 v5, 0xffff0000, v12
	v_lshlrev_b32_e32 v7, 16, v13
	v_and_b32_e32 v13, 0xffff0000, v13
	v_lshlrev_b32_e32 v24, 16, v14
	v_and_b32_e32 v14, 0xffff0000, v14
	v_lshlrev_b32_e32 v25, 16, v15
	v_and_b32_e32 v15, 0xffff0000, v15
	v_lshlrev_b32_e32 v30, 16, v16
	v_lshlrev_b32_e32 v31, 16, v17
	v_and_b32_e32 v34, 0xffff0000, v17
	v_and_b32_e32 v35, 0xffff0000, v16
	v_lshlrev_b32_e32 v36, 16, v18
	v_lshlrev_b32_e32 v37, 16, v19
	v_and_b32_e32 v38, 0xffff0000, v19
	v_and_b32_e32 v39, 0xffff0000, v18
	v_lshl_add_u64 v[16:17], s[12:13], 0, v[2:3]
	v_lshl_add_u64 v[18:19], s[24:25], 0, v[2:3]
	v_lshlrev_b32_e32 v2, 16, v12
	v_cndmask_b32_e32 v20, 0, v2, vcc
	v_cndmask_b32_e32 v22, 0, v5, vcc
	v_cndmask_b32_e32 v23, 0, v13, vcc
	v_cndmask_b32_e32 v26, 0, v14, vcc
	v_cndmask_b32_e32 v27, 0, v15, vcc
	global_load_dwordx4 v[2:5], v[16:17], off
	global_load_dwordx4 v[12:15], v[18:19], off
	v_cndmask_b32_e32 v21, 0, v7, vcc
	v_cndmask_b32_e64 v31, 0, v31, s[6:7]
	v_cndmask_b32_e64 v30, 0, v30, s[6:7]
	v_pk_add_f32 v[20:21], v[20:21], v[28:29] neg_lo:[0,1] neg_hi:[0,1]
	v_pk_add_f32 v[22:23], v[22:23], v[8:9] neg_lo:[0,1] neg_hi:[0,1]
	v_cndmask_b32_e32 v24, 0, v24, vcc
	v_cndmask_b32_e32 v25, 0, v25, vcc
	s_waitcnt vmcnt(0) lgkmcnt(0)
	v_mov_b32_e32 v32, v2
	v_mov_b32_e32 v33, v4
	v_pk_fma_f32 v[20:21], v[32:33], v[20:21], v[28:29]
	v_pk_add_f32 v[28:29], v[30:31], v[28:29] neg_lo:[0,1] neg_hi:[0,1]
	v_mov_b32_e32 v30, v12
	v_mov_b32_e32 v31, v14
	v_pk_fma_f32 v[20:21], v[28:29], v[30:31], v[20:21]
	v_cndmask_b32_e64 v29, 0, v34, s[6:7]
	v_cndmask_b32_e64 v28, 0, v35, s[6:7]
	v_mov_b32_e32 v4, v3
	v_pk_fma_f32 v[4:5], v[4:5], v[22:23], v[8:9]
	v_pk_add_f32 v[8:9], v[28:29], v[8:9] neg_lo:[0,1] neg_hi:[0,1]
	v_mov_b32_e32 v14, v13
	v_pk_fma_f32 v[4:5], v[8:9], v[14:15], v[4:5]
	v_add_f32_e32 v2, v20, v20
	v_add_f32_e32 v3, v4, v4
	v_cndmask_b32_e64 v3, v3, v4, s[0:1]
	v_mul_f32_e32 v3, 0xbfb8aa3b, v3
	v_exp_f32_e32 v8, v3
	v_add_f32_e32 v3, v21, v21
	v_cndmask_b32_e64 v2, v2, v20, s[0:1]
	v_cndmask_b32_e64 v3, v3, v21, s[0:1]
	v_mul_f32_e32 v2, 0xbfb8aa3b, v2
	v_mul_f32_e32 v3, 0xbfb8aa3b, v3
	v_exp_f32_e32 v2, v2
	v_exp_f32_e32 v3, v3
	v_and_b32_e32 v15, 0xffff0000, v11
	v_pk_add_f32 v[2:3], v[2:3], 1.0 op_sel_hi:[1,0]
	s_nop 0
	v_div_scale_f32 v7, s[84:85], v3, v3, 1.0
	v_rcp_f32_e32 v9, v7
	s_nop 0
	v_fma_f32 v12, -v7, v9, 1.0
	v_fmac_f32_e32 v9, v12, v9
	v_div_scale_f32 v12, vcc, 1.0, v3, 1.0
	v_mul_f32_e32 v13, v12, v9
	v_fma_f32 v14, -v7, v13, v12
	v_fmac_f32_e32 v13, v14, v9
	v_fma_f32 v7, -v7, v13, v12
	v_div_fmas_f32 v7, v7, v9, v13
	v_div_fixup_f32 v3, v7, v3, 1.0
	v_div_scale_f32 v7, s[84:85], v2, v2, 1.0
	v_rcp_f32_e32 v9, v7
	s_nop 0
	v_fma_f32 v12, -v7, v9, 1.0
	v_fmac_f32_e32 v9, v12, v9
	v_div_scale_f32 v12, vcc, 1.0, v2, 1.0
	v_mul_f32_e32 v13, v12, v9
	v_fma_f32 v14, -v7, v13, v12
	v_fmac_f32_e32 v13, v14, v9
	v_fma_f32 v7, -v7, v13, v12
	v_div_fmas_f32 v7, v7, v9, v13
	v_div_fixup_f32 v2, v7, v2, 1.0
	v_pk_fma_f32 v[12:13], v[2:3], 2.0, -1.0 op_sel_hi:[1,0,0]
	s_nop 0
	v_cndmask_b32_e64 v7, v20, v12, s[4:5]
	v_cndmask_b32_e64 v7, v7, v2, s[0:1]
	v_add_f32_e32 v2, v5, v5
	v_cndmask_b32_e64 v2, v2, v5, s[0:1]
	v_cndmask_b32_e64 v9, v21, v13, s[4:5]
	v_mul_f32_e32 v2, 0xbfb8aa3b, v2
	v_cndmask_b32_e64 v22, v9, v3, s[0:1]
	v_exp_f32_e32 v9, v2
	s_nop 0
	v_pk_add_f32 v[2:3], v[8:9], 1.0 op_sel_hi:[1,0]
	s_nop 0
	v_div_scale_f32 v8, s[84:85], v3, v3, 1.0
	v_rcp_f32_e32 v9, v8
	s_nop 0
	v_fma_f32 v12, -v8, v9, 1.0
	v_fmac_f32_e32 v9, v12, v9
	v_div_scale_f32 v12, vcc, 1.0, v3, 1.0
	v_mul_f32_e32 v13, v12, v9
	v_fma_f32 v14, -v8, v13, v12
	v_fmac_f32_e32 v13, v14, v9
	v_fma_f32 v8, -v8, v13, v12
	v_div_fmas_f32 v8, v8, v9, v13
	v_div_fixup_f32 v3, v8, v3, 1.0
	v_div_scale_f32 v8, s[84:85], v2, v2, 1.0
	v_rcp_f32_e32 v9, v8
	s_nop 0
	v_fma_f32 v12, -v8, v9, 1.0
	v_fmac_f32_e32 v9, v12, v9
	v_div_scale_f32 v12, vcc, 1.0, v2, 1.0
	v_mul_f32_e32 v13, v12, v9
	v_fma_f32 v14, -v8, v13, v12
	v_fmac_f32_e32 v13, v14, v9
	v_fma_f32 v8, -v8, v13, v12
	v_div_fmas_f32 v8, v8, v9, v13
	v_div_fixup_f32 v2, v8, v2, 1.0
	v_pk_fma_f32 v[8:9], v[2:3], 2.0, -1.0 op_sel_hi:[1,0,0]
	v_lshlrev_b32_e32 v13, 16, v11
	v_cndmask_b32_e64 v5, v5, v9, s[4:5]
	v_cndmask_b32_e64 v4, v4, v8, s[4:5]
	v_cndmask_b32_e64 v23, v4, v2, s[0:1]
	v_cvt_pk_bf16_f32 v209, v7, v23
	v_cndmask_b32_e64 v28, v5, v3, s[0:1]
	v_lshlrev_b32_e32 v12, 16, v10
	v_and_b32_e32 v14, 0xffff0000, v10
	global_load_dwordx4 v[2:5], v[16:17], off offset:16
	global_load_dwordx4 v[8:11], v[18:19], off offset:16
	v_cndmask_b32_e64 v17, 0, v37, s[6:7]
	v_cndmask_b32_e64 v16, 0, v36, s[6:7]
	v_pk_add_f32 v[18:19], v[24:25], v[12:13] neg_lo:[0,1] neg_hi:[0,1]
	s_waitcnt vmcnt(0) lgkmcnt(0)
	v_mov_b32_e32 v20, v2
	v_mov_b32_e32 v21, v4
	v_pk_fma_f32 v[18:19], v[18:19], v[20:21], v[12:13]
	v_pk_add_f32 v[12:13], v[16:17], v[12:13] neg_lo:[0,1] neg_hi:[0,1]
	v_mov_b32_e32 v16, v8
	v_mov_b32_e32 v17, v10
	v_pk_fma_f32 v[12:13], v[12:13], v[16:17], v[18:19]
	v_cndmask_b32_e64 v17, 0, v38, s[6:7]
	v_cndmask_b32_e64 v16, 0, v39, s[6:7]
	v_pk_add_f32 v[18:19], v[26:27], v[14:15] neg_lo:[0,1] neg_hi:[0,1]
	v_mov_b32_e32 v4, v3
	v_pk_fma_f32 v[4:5], v[18:19], v[4:5], v[14:15]
	v_pk_add_f32 v[14:15], v[16:17], v[14:15] neg_lo:[0,1] neg_hi:[0,1]
	v_mov_b32_e32 v10, v9
	v_pk_fma_f32 v[4:5], v[14:15], v[10:11], v[4:5]
	v_add_f32_e32 v2, v12, v12
	v_add_f32_e32 v3, v4, v4
	v_cndmask_b32_e64 v3, v3, v4, s[0:1]
	v_mul_f32_e32 v3, 0xbfb8aa3b, v3
	v_exp_f32_e32 v8, v3
	v_add_f32_e32 v3, v13, v13
	v_cndmask_b32_e64 v2, v2, v12, s[0:1]
	v_cndmask_b32_e64 v3, v3, v13, s[0:1]
	v_mul_f32_e32 v2, 0xbfb8aa3b, v2
	v_mul_f32_e32 v3, 0xbfb8aa3b, v3
	v_exp_f32_e32 v2, v2
	v_exp_f32_e32 v3, v3
	s_nop 0
	v_pk_add_f32 v[2:3], v[2:3], 1.0 op_sel_hi:[1,0]
	s_nop 0
	v_div_scale_f32 v9, s[6:7], v3, v3, 1.0
	v_rcp_f32_e32 v10, v9
	s_nop 0
	v_fma_f32 v11, -v9, v10, 1.0
	v_fmac_f32_e32 v10, v11, v10
	v_div_scale_f32 v11, vcc, 1.0, v3, 1.0
	v_mul_f32_e32 v14, v11, v10
	v_fma_f32 v15, -v9, v14, v11
	v_fmac_f32_e32 v14, v15, v10
	v_fma_f32 v9, -v9, v14, v11
	v_div_fmas_f32 v9, v9, v10, v14
	v_div_fixup_f32 v3, v9, v3, 1.0
	v_div_scale_f32 v9, s[6:7], v2, v2, 1.0
	v_rcp_f32_e32 v10, v9
	s_nop 0
	v_fma_f32 v11, -v9, v10, 1.0
	v_fmac_f32_e32 v10, v11, v10
	v_div_scale_f32 v11, vcc, 1.0, v2, 1.0
	v_mul_f32_e32 v14, v11, v10
	v_fma_f32 v15, -v9, v14, v11
	v_fmac_f32_e32 v14, v15, v10
	v_fma_f32 v9, -v9, v14, v11
	v_div_fmas_f32 v9, v9, v10, v14
	v_div_fixup_f32 v2, v9, v2, 1.0
	v_pk_fma_f32 v[10:11], v[2:3], 2.0, -1.0 op_sel_hi:[1,0,0]
	s_nop 0
	v_cndmask_b32_e64 v9, v12, v10, s[4:5]
	v_cndmask_b32_e64 v10, v13, v11, s[4:5]
	v_cndmask_b32_e64 v11, v9, v2, s[0:1]
	v_add_f32_e32 v2, v5, v5
	v_cndmask_b32_e64 v2, v2, v5, s[0:1]
	v_mul_f32_e32 v2, 0xbfb8aa3b, v2
	v_exp_f32_e32 v9, v2
	v_cndmask_b32_e64 v10, v10, v3, s[0:1]
	v_pk_add_f32 v[2:3], v[8:9], 1.0 op_sel_hi:[1,0]
	s_nop 0
	v_div_scale_f32 v8, s[6:7], v3, v3, 1.0
	v_rcp_f32_e32 v9, v8
	s_nop 0
	v_fma_f32 v12, -v8, v9, 1.0
	v_fmac_f32_e32 v9, v12, v9
	v_div_scale_f32 v12, vcc, 1.0, v3, 1.0
	v_mul_f32_e32 v13, v12, v9
	v_fma_f32 v14, -v8, v13, v12
	v_fmac_f32_e32 v13, v14, v9
	v_fma_f32 v8, -v8, v13, v12
	v_div_fmas_f32 v8, v8, v9, v13
	v_div_fixup_f32 v3, v8, v3, 1.0
	v_div_scale_f32 v8, s[6:7], v2, v2, 1.0
	v_rcp_f32_e32 v9, v8
	s_nop 0
	v_fma_f32 v12, -v8, v9, 1.0
	v_fmac_f32_e32 v9, v12, v9
	v_div_scale_f32 v12, vcc, 1.0, v2, 1.0
	v_mul_f32_e32 v13, v12, v9
	v_fma_f32 v14, -v8, v13, v12
	v_fmac_f32_e32 v13, v14, v9
	v_fma_f32 v8, -v8, v13, v12
	v_div_fmas_f32 v8, v8, v9, v13
	v_div_fixup_f32 v2, v8, v2, 1.0
	v_pk_fma_f32 v[8:9], v[2:3], 2.0, -1.0 op_sel_hi:[1,0,0]
	v_bfe_u32 v12, v11, 16, 1
	v_cndmask_b32_e64 v5, v5, v9, s[4:5]
	v_cndmask_b32_e64 v4, v4, v8, s[4:5]
	v_cndmask_b32_e64 v2, v4, v2, s[0:1]
	v_cndmask_b32_e64 v3, v5, v3, s[0:1]
	v_cvt_pk_bf16_f32 v208, v10, v3
	v_bfe_u32 v5, v2, 16, 1
	v_add3_u32 v2, v2, v5, s60
	v_add3_u32 v11, v11, v12, s60
	v_lshrrev_b32_e32 v4, 16, v11
	v_mov_b32_e32 v5, v208
	v_and_or_b32 v4, v2, s56, v4
	v_cvt_pk_bf16_f32 v3, v22, v28
	v_mov_b32_e32 v2, v209
	ds_write_b128 v6, v[2:5] offset:4096
	s_cbranch_scc0 .LBB0_1406
	v_ashrrev_i32_e32 v137, 3, v135
	v_and_b32_e32 v138, -4, v137
	v_add_u32_e32 v18, s81, v138
	v_add_u32_e32 v0, -1, v18
	v_or_b32_e32 v44, 1, v18
	v_and_b32_e32 v126, 31, v135
	v_max_i32_e32 v0, s27, v0
	v_max_i32_e32 v2, s27, v18
	v_max_i32_e32 v10, s27, v44
	v_lshlrev_b32_e32 v34, 4, v126
	v_mov_b32_e32 v35, v65
	s_mulk_i32 s18, 0x900
	v_min_i32_e32 v0, s80, v0
	v_min_i32_e32 v2, s80, v2
	v_min_i32_e32 v10, s80, v10
	v_lshl_add_u64 v[88:89], s[54:55], 0, v[34:35]
	s_mov_b64 s[0:1], 0x7158100
	v_add_u32_e32 v0, s18, v0
	v_add_u32_e32 v2, s18, v2
	v_add_u32_e32 v10, s18, v10
	v_lshl_add_u64 v[8:9], v[88:89], 0, s[0:1]
	v_mul_hi_i32_i24_e32 v25, 0x1240, v0
	v_mul_i32_i24_e32 v24, 0x1240, v0
	v_mul_hi_i32_i24_e32 v27, 0x1240, v2
	v_mul_i32_i24_e32 v26, 0x1240, v2
	v_mul_hi_i32_i24_e32 v49, 0x1240, v10
	v_mul_i32_i24_e32 v48, 0x1240, v10
	v_lshl_add_u64 v[0:1], v[8:9], 0, v[24:25]
	v_lshl_add_u64 v[4:5], v[8:9], 0, v[26:27]
	v_lshl_add_u64 v[10:11], v[8:9], 0, v[48:49]
	v_or_b32_e32 v45, 2, v18
	global_load_dwordx4 v[0:3], v[0:1], off
	s_nop 0
	global_load_dwordx4 v[4:7], v[4:5], off
	v_or_b32_e32 v70, 3, v18
	global_load_dwordx4 v[36:39], v[10:11], off
	v_max_i32_e32 v10, s27, v45
	v_min_i32_e32 v10, s80, v10
	v_add_u32_e32 v10, s18, v10
	v_mul_hi_i32_i24_e32 v55, 0x1240, v10
	v_mul_i32_i24_e32 v54, 0x1240, v10
	v_lshl_add_u64 v[10:11], v[8:9], 0, v[54:55]
	global_load_dwordx4 v[40:43], v[10:11], off
	v_max_i32_e32 v10, s27, v70
	v_min_i32_e32 v10, s80, v10
	v_add_u32_e32 v10, s18, v10
	v_mul_hi_i32_i24_e32 v57, 0x1240, v10
	v_mul_i32_i24_e32 v56, 0x1240, v10
	v_lshl_add_u64 v[10:11], v[8:9], 0, v[56:57]
	v_add_u32_e32 v71, 4, v18
	global_load_dwordx4 v[60:63], v[10:11], off
	v_max_i32_e32 v10, s27, v71
	v_min_i32_e32 v10, s80, v10
	v_add_u32_e32 v10, s18, v10
	v_mul_hi_i32_i24_e32 v59, 0x1240, v10
	v_mul_i32_i24_e32 v58, 0x1240, v10
	v_lshl_add_u64 v[8:9], v[8:9], 0, v[58:59]
	global_load_dwordx4 v[66:69], v[8:9], off
	v_mov_b32_e32 v8, s54
	v_mov_b32_e32 v9, s55
	v_add_co_u32_e32 v32, vcc, s57, v8
	v_lshlrev_b32_e32 v64, 5, v126
	s_nop 0
	v_addc_co_u32_e32 v33, vcc, 0, v9, vcc
	v_lshl_add_u64 v[28:29], s[8:9], 0, v[64:65]
	v_add_co_u32_e32 v50, vcc, s35, v28
	v_lshl_add_u64 v[46:47], s[10:11], 0, v[64:65]
	s_nop 0
	v_addc_co_u32_e32 v51, vcc, 0, v29, vcc
	v_add_co_u32_e32 v52, vcc, s35, v46
	global_load_dwordx4 v[8:11], v[50:51], off offset:512
	s_nop 0
	v_addc_co_u32_e32 v53, vcc, 0, v47, vcc
	global_load_dwordx2 v[30:31], v[32:33], off offset:464
	global_load_dwordx4 v[12:15], v[52:53], off offset:512
	v_lshl_add_u64 v[16:17], v[28:29], 0, s[20:21]
	v_lshl_add_u64 v[20:21], v[46:47], 0, s[20:21]
	v_cmp_lt_i32_e32 vcc, s27, v18
	v_cmp_ge_i32_e64 s[0:1], s79, v18
	v_cmp_le_i32_e64 s[4:5], s27, v18
	v_cmp_gt_i32_e64 s[6:7], s79, v18
	global_load_dwordx4 v[16:19], v[16:17], off offset:16
	s_and_b64 vcc, vcc, s[0:1]
	global_load_dwordx4 v[20:23], v[20:21], off offset:16
	s_and_b64 s[4:5], s[4:5], s[6:7]
	v_cmp_le_i32_e64 s[0:1], s27, v44
	v_cmp_gt_i32_e64 s[6:7], s79, v44
	s_and_b64 s[6:7], s[0:1], s[6:7]
	v_cmp_le_i32_e64 s[0:1], s27, v45
	v_cmp_gt_i32_e64 s[8:9], s79, v45
	s_and_b64 s[8:9], s[0:1], s[8:9]
	v_cmp_le_i32_e64 s[0:1], s27, v70
	v_cmp_gt_i32_e64 s[10:11], s79, v70
	s_and_b64 s[10:11], s[0:1], s[10:11]
	v_cmp_le_i32_e64 s[0:1], s27, v71
	v_cmp_gt_i32_e64 s[12:13], s79, v71
	s_and_b64 s[12:13], s[0:1], s[12:13]
	v_add_u32_e32 v90, s26, v138
	v_ashrrev_i32_e32 v91, 31, v90
	s_mov_b32 s24, 0
	v_lshlrev_b32_e32 v126, 3, v126
	s_waitcnt vmcnt(0) lgkmcnt(0)
	v_cndmask_b32_e32 v72, 0, v1, vcc
	v_cndmask_b32_e32 v73, 0, v0, vcc
	v_cndmask_b32_e64 v77, 0, v5, s[4:5]
	v_cndmask_b32_e64 v79, 0, v4, s[4:5]
	v_cndmask_b32_e64 v80, 0, v39, s[6:7]
	v_cndmask_b32_e64 v82, 0, v38, s[6:7]
	v_cndmask_b32_e64 v38, 0, v37, s[6:7]
	v_cndmask_b32_e64 v39, 0, v36, s[6:7]
	v_and_b32_e32 v37, 0xffff0000, v72
	v_and_b32_e32 v36, 0xffff0000, v73
	v_cndmask_b32_e32 v74, 0, v3, vcc
	v_cndmask_b32_e32 v75, 0, v2, vcc
	v_cndmask_b32_e64 v76, 0, v7, s[4:5]
	v_cndmask_b32_e64 v78, 0, v6, s[4:5]
	v_lshlrev_b32_e32 v45, 16, v77
	v_lshlrev_b32_e32 v44, 16, v79
	v_and_b32_e32 v81, 0xffff0000, v80
	v_cndmask_b32_e64 v86, 0, v43, s[8:9]
	v_cndmask_b32_e64 v94, 0, v63, s[10:11]
	v_cndmask_b32_e64 v95, 0, v62, s[10:11]
	v_and_b32_e32 v63, 0xffff0000, v77
	v_and_b32_e32 v62, 0xffff0000, v79
	v_pk_add_f32 v[36:37], v[36:37], v[62:63] neg_lo:[0,1] neg_hi:[0,1]
	v_and_b32_e32 v77, 0xffff0000, v76
	v_lshlrev_b32_e32 v79, 16, v80
	v_cndmask_b32_e64 v122, 0, v69, s[12:13]
	v_cndmask_b32_e64 v123, 0, v68, s[12:13]
	v_and_b32_e32 v69, 0xffff0000, v38
	v_and_b32_e32 v68, 0xffff0000, v39
	v_cndmask_b32_e64 v118, 0, v67, s[12:13]
	v_cndmask_b32_e64 v119, 0, v66, s[12:13]
	v_lshlrev_b32_e32 v67, 16, v38
	v_lshlrev_b32_e32 v66, 16, v39
	v_pk_add_f32 v[38:39], v[66:67], v[44:45] neg_lo:[0,1] neg_hi:[0,1]
	v_and_b32_e32 v80, 0xffff0000, v82
	v_cndmask_b32_e64 v96, 0, v61, s[10:11]
	v_cndmask_b32_e64 v97, 0, v60, s[10:11]
	v_cndmask_b32_e64 v87, 0, v42, s[8:9]
	v_cndmask_b32_e64 v92, 0, v41, s[8:9]
	v_cndmask_b32_e64 v93, 0, v40, s[8:9]
	v_mov_b32_e32 v71, v10
	v_mov_b32_e32 v10, v9
	v_mov_b32_e32 v70, v8
	v_readfirstlane_b32 s1, v31
	v_readfirstlane_b32 s0, v30
	v_lshlrev_b32_e32 v31, 16, v72
	v_lshlrev_b32_e32 v30, 16, v73
	v_mov_b32_e32 v73, v14
	v_pk_fma_f32 v[8:9], v[10:11], v[36:37], v[62:63]
	v_pk_add_f32 v[36:37], v[68:69], v[62:63] neg_lo:[0,1] neg_hi:[0,1]
	v_mov_b32_e32 v14, v13
	v_pk_add_f32 v[30:31], v[30:31], v[44:45] neg_lo:[0,1] neg_hi:[0,1]
	v_mov_b32_e32 v72, v12
	v_pk_fma_f32 v[36:37], v[14:15], v[36:37], v[8:9]
	v_lshlrev_b32_e32 v9, 16, v74
	v_lshlrev_b32_e32 v8, 16, v75
	v_and_b32_e32 v13, 0xffff0000, v74
	v_and_b32_e32 v12, 0xffff0000, v75
	v_lshlrev_b32_e32 v75, 16, v76
	v_lshlrev_b32_e32 v74, 16, v78
	v_pk_fma_f32 v[30:31], v[70:71], v[30:31], v[44:45]
	v_and_b32_e32 v76, 0xffff0000, v78
	v_lshlrev_b32_e32 v78, 16, v82
	v_pk_add_f32 v[8:9], v[8:9], v[74:75] neg_lo:[0,1] neg_hi:[0,1]
	v_mov_b32_e32 v82, v16
	v_mov_b32_e32 v83, v18
	v_pk_fma_f32 v[30:31], v[72:73], v[38:39], v[30:31]
	v_pk_fma_f32 v[8:9], v[82:83], v[8:9], v[74:75]
	v_pk_add_f32 v[38:39], v[78:79], v[74:75] neg_lo:[0,1] neg_hi:[0,1]
	v_mov_b32_e32 v84, v20
	v_mov_b32_e32 v85, v22
	v_pk_fma_f32 v[98:99], v[84:85], v[38:39], v[8:9]
	v_pk_add_f32 v[8:9], v[12:13], v[76:77] neg_lo:[0,1] neg_hi:[0,1]
	v_mov_b32_e32 v18, v17
	v_pk_fma_f32 v[8:9], v[18:19], v[8:9], v[76:77]
	v_pk_add_f32 v[12:13], v[80:81], v[76:77] neg_lo:[0,1] neg_hi:[0,1]
	v_mov_b32_e32 v22, v21
	v_pk_fma_f32 v[100:101], v[22:23], v[12:13], v[8:9]
	v_bfe_u32 v8, v30, 16, 1
	v_bfe_u32 v9, v31, 16, 1
	v_bfe_u32 v12, v98, 16, 1
	v_bfe_u32 v13, v99, 16, 1
	v_lshl_add_u64 v[0:1], s[0:1], 0, v[64:65]
	s_mov_b64 s[0:1], 0x156d7900
	v_add3_u32 v13, v99, v13, s60
	v_add3_u32 v12, v98, v12, s60
	v_add3_u32 v9, v31, v9, s60
	v_add3_u32 v8, v30, v8, s60
	v_lshl_add_u64 v[60:61], v[88:89], 0, s[0:1]
	v_lshrrev_b32_e32 v8, 16, v8
	v_lshrrev_b32_e32 v9, 16, v9
	v_lshrrev_b32_e32 v12, 16, v12
	v_lshrrev_b32_e32 v13, 16, v13
	v_lshlrev_b64 v[38:39], 9, v[90:91]
	v_and_or_b32 v43, v101, s56, v13
	v_and_or_b32 v42, v100, s56, v12
	v_and_or_b32 v41, v37, s56, v9
	v_and_or_b32 v40, v36, s56, v8
	v_lshl_add_u64 v[8:9], v[60:61], 0, v[38:39]
	global_load_dwordx4 v[4:7], v[0:1], off offset:1024
	s_nop 0
	global_load_dwordx4 v[0:3], v[0:1], off offset:1040
	v_pk_add_f32 v[16:17], v[44:45], v[66:67] neg_lo:[0,1] neg_hi:[0,1]
	global_store_dwordx4 v[8:9], v[40:43], off
	v_lshlrev_b32_e32 v9, 16, v92
	v_lshlrev_b32_e32 v8, 16, v93
	v_pk_fma_f32 v[16:17], v[70:71], v[16:17], v[66:67]
	v_pk_add_f32 v[20:21], v[8:9], v[66:67] neg_lo:[0,1] neg_hi:[0,1]
	v_and_b32_e32 v13, 0xffff0000, v92
	v_and_b32_e32 v12, 0xffff0000, v93
	v_pk_fma_f32 v[102:103], v[72:73], v[20:21], v[16:17]
	v_pk_add_f32 v[16:17], v[62:63], v[68:69] neg_lo:[0,1] neg_hi:[0,1]
	v_pk_add_f32 v[20:21], v[12:13], v[68:69] neg_lo:[0,1] neg_hi:[0,1]
	v_pk_fma_f32 v[16:17], v[10:11], v[16:17], v[68:69]
	v_pk_add_f32 v[40:41], v[74:75], v[78:79] neg_lo:[0,1] neg_hi:[0,1]
	v_pk_fma_f32 v[104:105], v[14:15], v[20:21], v[16:17]
	v_lshlrev_b32_e32 v17, 16, v86
	v_lshlrev_b32_e32 v16, 16, v87
	v_pk_fma_f32 v[40:41], v[82:83], v[40:41], v[78:79]
	v_pk_add_f32 v[42:43], v[16:17], v[78:79] neg_lo:[0,1] neg_hi:[0,1]
	v_and_b32_e32 v21, 0xffff0000, v86
	v_and_b32_e32 v20, 0xffff0000, v87
	v_pk_fma_f32 v[106:107], v[84:85], v[42:43], v[40:41]
	v_pk_add_f32 v[40:41], v[76:77], v[80:81] neg_lo:[0,1] neg_hi:[0,1]
	v_pk_add_f32 v[42:43], v[20:21], v[80:81] neg_lo:[0,1] neg_hi:[0,1]
	v_pk_fma_f32 v[40:41], v[18:19], v[40:41], v[80:81]
	v_or_b32_e32 v92, 1, v90
	v_pk_fma_f32 v[108:109], v[22:23], v[42:43], v[40:41]
	v_bfe_u32 v40, v102, 16, 1
	v_bfe_u32 v41, v103, 16, 1
	v_bfe_u32 v42, v106, 16, 1
	v_bfe_u32 v43, v107, 16, 1
	v_add3_u32 v43, v107, v43, s60
	v_add3_u32 v42, v106, v42, s60
	v_add3_u32 v41, v103, v41, s60
	v_add3_u32 v40, v102, v40, s60
	v_lshrrev_b32_e32 v40, 16, v40
	v_lshrrev_b32_e32 v41, 16, v41
	v_lshrrev_b32_e32 v42, 16, v42
	v_lshrrev_b32_e32 v43, 16, v43
	v_ashrrev_i32_e32 v93, 31, v92
	v_and_or_b32 v45, v109, s56, v43
	v_and_or_b32 v44, v108, s56, v42
	v_and_or_b32 v43, v105, s56, v41
	v_and_or_b32 v42, v104, s56, v40
	v_lshlrev_b64 v[40:41], 9, v[92:93]
	v_lshl_add_u64 v[62:63], v[60:61], 0, v[40:41]
	global_store_dwordx4 v[62:63], v[42:45], off
	v_pk_add_f32 v[66:67], v[66:67], v[8:9] neg_lo:[0,1] neg_hi:[0,1]
	v_and_b32_e32 v63, 0xffff0000, v96
	v_lshlrev_b32_e32 v45, 16, v96
	v_lshlrev_b32_e32 v44, 16, v97
	v_pk_add_f32 v[42:43], v[44:45], v[8:9] neg_lo:[0,1] neg_hi:[0,1]
	v_pk_fma_f32 v[66:67], v[70:71], v[66:67], v[8:9]
	v_and_b32_e32 v62, 0xffff0000, v97
	v_pk_fma_f32 v[110:111], v[72:73], v[42:43], v[66:67]
	v_pk_add_f32 v[42:43], v[68:69], v[12:13] neg_lo:[0,1] neg_hi:[0,1]
	v_pk_add_f32 v[74:75], v[62:63], v[12:13] neg_lo:[0,1] neg_hi:[0,1]
	v_pk_fma_f32 v[42:43], v[10:11], v[42:43], v[12:13]
	v_pk_add_f32 v[68:69], v[78:79], v[16:17] neg_lo:[0,1] neg_hi:[0,1]
	v_pk_fma_f32 v[112:113], v[14:15], v[74:75], v[42:43]
	v_lshlrev_b32_e32 v75, 16, v94
	v_lshlrev_b32_e32 v74, 16, v95
	v_pk_add_f32 v[42:43], v[74:75], v[16:17] neg_lo:[0,1] neg_hi:[0,1]
	v_pk_fma_f32 v[68:69], v[82:83], v[68:69], v[16:17]
	v_and_b32_e32 v77, 0xffff0000, v94
	v_and_b32_e32 v76, 0xffff0000, v95
	v_pk_fma_f32 v[114:115], v[84:85], v[42:43], v[68:69]
	v_pk_add_f32 v[42:43], v[80:81], v[20:21] neg_lo:[0,1] neg_hi:[0,1]
	v_pk_add_f32 v[66:67], v[76:77], v[20:21] neg_lo:[0,1] neg_hi:[0,1]
	v_pk_fma_f32 v[42:43], v[18:19], v[42:43], v[20:21]
	v_or_b32_e32 v94, 2, v90
	v_pk_fma_f32 v[116:117], v[22:23], v[66:67], v[42:43]
	v_bfe_u32 v42, v110, 16, 1
	v_bfe_u32 v43, v111, 16, 1
	v_bfe_u32 v66, v114, 16, 1
	v_bfe_u32 v67, v115, 16, 1
	v_add3_u32 v67, v115, v67, s60
	v_add3_u32 v66, v114, v66, s60
	v_add3_u32 v43, v111, v43, s60
	v_add3_u32 v42, v110, v42, s60
	v_lshrrev_b32_e32 v42, 16, v42
	v_lshrrev_b32_e32 v43, 16, v43
	v_lshrrev_b32_e32 v66, 16, v66
	v_lshrrev_b32_e32 v67, 16, v67
	v_ashrrev_i32_e32 v95, 31, v94
	v_and_or_b32 v69, v117, s56, v67
	v_and_or_b32 v68, v116, s56, v66
	v_and_or_b32 v67, v113, s56, v43
	v_and_or_b32 v66, v112, s56, v42
	v_lshlrev_b64 v[42:43], 9, v[94:95]
	v_lshl_add_u64 v[78:79], v[60:61], 0, v[42:43]
	global_store_dwordx4 v[78:79], v[66:69], off
	v_pk_add_f32 v[8:9], v[8:9], v[44:45] neg_lo:[0,1] neg_hi:[0,1]
	v_pk_add_f32 v[12:13], v[12:13], v[62:63] neg_lo:[0,1] neg_hi:[0,1]
	v_lshlrev_b32_e32 v67, 16, v118
	v_lshlrev_b32_e32 v66, 16, v119
	v_and_b32_e32 v69, 0xffff0000, v118
	v_and_b32_e32 v68, 0xffff0000, v119
	v_pk_add_f32 v[66:67], v[66:67], v[44:45] neg_lo:[0,1] neg_hi:[0,1]
	v_pk_fma_f32 v[8:9], v[70:71], v[8:9], v[44:45]
	v_pk_add_f32 v[68:69], v[68:69], v[62:63] neg_lo:[0,1] neg_hi:[0,1]
	v_pk_fma_f32 v[118:119], v[72:73], v[66:67], v[8:9]
	v_pk_fma_f32 v[8:9], v[10:11], v[12:13], v[62:63]
	v_pk_add_f32 v[12:13], v[16:17], v[74:75] neg_lo:[0,1] neg_hi:[0,1]
	v_pk_fma_f32 v[120:121], v[14:15], v[68:69], v[8:9]
	v_lshlrev_b32_e32 v9, 16, v122
	v_lshlrev_b32_e32 v8, 16, v123
	v_and_b32_e32 v11, 0xffff0000, v122
	v_and_b32_e32 v10, 0xffff0000, v123
	v_pk_add_f32 v[8:9], v[8:9], v[74:75] neg_lo:[0,1] neg_hi:[0,1]
	v_pk_add_f32 v[14:15], v[20:21], v[76:77] neg_lo:[0,1] neg_hi:[0,1]
	v_pk_fma_f32 v[12:13], v[82:83], v[12:13], v[74:75]
	v_pk_add_f32 v[10:11], v[10:11], v[76:77] neg_lo:[0,1] neg_hi:[0,1]
	v_pk_fma_f32 v[122:123], v[84:85], v[8:9], v[12:13]
	v_pk_fma_f32 v[8:9], v[18:19], v[14:15], v[76:77]
	v_or_b32_e32 v96, 3, v90
	v_pk_fma_f32 v[124:125], v[22:23], v[10:11], v[8:9]
	v_bfe_u32 v8, v118, 16, 1
	v_bfe_u32 v9, v119, 16, 1
	v_bfe_u32 v10, v122, 16, 1
	v_bfe_u32 v11, v123, 16, 1
	v_add3_u32 v11, v123, v11, s60
	v_add3_u32 v10, v122, v10, s60
	v_add3_u32 v9, v119, v9, s60
	v_add3_u32 v8, v118, v8, s60
	v_ashrrev_i32_e32 v97, 31, v96
	v_lshrrev_b32_e32 v8, 16, v8
	v_lshrrev_b32_e32 v9, 16, v9
	v_lshrrev_b32_e32 v10, 16, v10
	v_lshrrev_b32_e32 v11, 16, v11
	v_lshlrev_b64 v[44:45], 9, v[96:97]
	v_and_or_b32 v11, v125, s56, v11
	v_and_or_b32 v10, v124, s56, v10
	v_and_or_b32 v9, v121, s56, v9
	v_and_or_b32 v8, v120, s56, v8
	v_lshl_add_u64 v[12:13], v[60:61], 0, v[44:45]
	global_store_dwordx4 v[12:13], v[8:11], off
	v_lshl_add_u64 v[16:17], v[28:29], 0, s[36:37]
	v_lshl_add_u64 v[20:21], v[46:47], 0, s[36:37]
	v_lshl_add_u64 v[8:9], v[88:89], 0, s[38:39]
	v_lshl_add_u64 v[10:11], v[8:9], 0, v[24:25]
	global_load_dwordx4 v[60:63], v[10:11], off
	v_lshl_add_u64 v[10:11], v[8:9], 0, v[26:27]
	global_load_dwordx4 v[66:69], v[10:11], off
	v_lshl_add_u64 v[10:11], v[8:9], 0, v[48:49]
	global_load_dwordx4 v[70:73], v[10:11], off
	v_lshl_add_u64 v[10:11], v[8:9], 0, v[54:55]
	global_load_dwordx4 v[74:77], v[10:11], off
	v_lshl_add_u64 v[10:11], v[8:9], 0, v[56:57]
	global_load_dwordx4 v[78:81], v[10:11], off
	v_lshl_add_u64 v[8:9], v[8:9], 0, v[58:59]
	global_load_dwordx4 v[82:85], v[8:9], off
	s_nop 0
	global_load_dwordx4 v[8:11], v[50:51], off offset:2560
	global_load_dwordx4 v[12:15], v[52:53], off offset:2560
	s_waitcnt vmcnt(0) lgkmcnt(0)
	v_mul_f32_e32 v159, v98, v0
	global_load_dwordx4 v[16:19], v[16:17], off offset:16
	v_mul_f32_e32 v160, v100, v1
	global_load_dwordx4 v[20:23], v[20:21], off offset:16
	v_mul_f32_e32 v161, v99, v2
	v_mul_f32_e32 v162, v101, v3
	v_mul_f32_e32 v163, v4, v102
	v_mul_f32_e32 v168, v5, v104
	v_mul_f32_e32 v169, v103, v6
	v_mul_f32_e32 v170, v105, v7
	v_mul_f32_e32 v171, v106, v0
	v_mul_f32_e32 v114, v114, v0
	v_mul_f32_e32 v187, v122, v0
	v_mul_f32_e32 v172, v108, v1
	v_mul_f32_e32 v116, v116, v1
	v_mul_f32_e32 v188, v124, v1
	v_bitop3_b32 v1, v135, 31, v130 bitop3:0xe0
	v_mul_f32_e32 v173, v107, v2
	v_mul_f32_e32 v174, v109, v3
	v_mul_f32_e32 v175, v4, v110
	v_mul_f32_e32 v176, v5, v112
	v_mul_f32_e32 v177, v6, v111
	v_mul_f32_e32 v178, v113, v7
	v_mul_f32_e32 v115, v115, v2
	v_mul_f32_e32 v117, v117, v3
	v_mul_f32_e32 v179, v4, v118
	v_mul_f32_e32 v184, v5, v120
	v_mul_f32_e32 v185, v6, v119
	v_mul_f32_e32 v186, v7, v121
	v_mul_f32_e32 v189, v123, v2
	v_mul_f32_e32 v190, v125, v3
	v_or_b32_e32 v110, 3, v137
	v_mul_lo_u32 v110, v110, s70
	v_add_u32_e32 v119, v64, v110
	v_lshlrev_b64 v[110:111], 11, v[96:97]
	v_lshl_add_u64 v[110:111], s[54:55], 0, v[110:111]
	v_cndmask_b32_e32 v136, 0, v61, vcc
	v_cndmask_b32_e32 v139, 0, v60, vcc
	v_cndmask_b32_e64 v140, 0, v69, s[4:5]
	v_cndmask_b32_e64 v141, 0, v68, s[4:5]
	v_cndmask_b32_e64 v68, 0, v67, s[4:5]
	v_cndmask_b32_e64 v69, 0, v66, s[4:5]
	v_cndmask_b32_e64 v142, 0, v73, s[6:7]
	v_cndmask_b32_e64 v143, 0, v72, s[6:7]
	v_cndmask_b32_e64 v144, 0, v71, s[6:7]
	v_cndmask_b32_e64 v145, 0, v70, s[6:7]
	v_and_b32_e32 v67, 0xffff0000, v136
	v_and_b32_e32 v66, 0xffff0000, v139
	v_and_b32_e32 v73, 0xffff0000, v68
	v_and_b32_e32 v72, 0xffff0000, v69
	v_cndmask_b32_e64 v146, 0, v77, s[8:9]
	v_cndmask_b32_e64 v147, 0, v76, s[8:9]
	v_cndmask_b32_e64 v152, 0, v79, s[10:11]
	v_and_b32_e32 v77, 0xffff0000, v144
	v_and_b32_e32 v76, 0xffff0000, v145
	v_mov_b32_e32 v79, v10
	v_pk_add_f32 v[66:67], v[66:67], v[72:73] neg_lo:[0,1] neg_hi:[0,1]
	v_mov_b32_e32 v10, v9
	v_cndmask_b32_e32 v86, 0, v63, vcc
	v_cndmask_b32_e32 v87, 0, v62, vcc
	v_cndmask_b32_e64 v150, 0, v81, s[10:11]
	v_cndmask_b32_e64 v153, 0, v78, s[10:11]
	v_mov_b32_e32 v78, v8
	v_mov_b32_e32 v81, v14
	v_pk_fma_f32 v[8:9], v[10:11], v[66:67], v[72:73]
	v_pk_add_f32 v[66:67], v[76:77], v[72:73] neg_lo:[0,1] neg_hi:[0,1]
	v_mov_b32_e32 v14, v13
	v_cndmask_b32_e64 v154, 0, v85, s[12:13]
	v_cndmask_b32_e64 v155, 0, v84, s[12:13]
	v_lshlrev_b32_e32 v63, 16, v136
	v_lshlrev_b32_e32 v62, 16, v139
	v_lshlrev_b32_e32 v71, 16, v68
	v_lshlrev_b32_e32 v70, 16, v69
	v_pk_fma_f32 v[8:9], v[14:15], v[66:67], v[8:9]
	v_and_b32_e32 v67, 0xffff0000, v86
	v_and_b32_e32 v66, 0xffff0000, v87
	v_and_b32_e32 v85, 0xffff0000, v140
	v_and_b32_e32 v84, 0xffff0000, v141
	v_cndmask_b32_e64 v148, 0, v75, s[8:9]
	v_cndmask_b32_e64 v149, 0, v74, s[8:9]
	v_cndmask_b32_e64 v151, 0, v80, s[10:11]
	v_cndmask_b32_e64 v156, 0, v83, s[12:13]
	v_cndmask_b32_e64 v157, 0, v82, s[12:13]
	v_lshlrev_b32_e32 v75, 16, v144
	v_lshlrev_b32_e32 v74, 16, v145
	v_pk_add_f32 v[62:63], v[62:63], v[70:71] neg_lo:[0,1] neg_hi:[0,1]
	v_mov_b32_e32 v80, v12
	v_lshlrev_b32_e32 v13, 16, v86
	v_lshlrev_b32_e32 v12, 16, v87
	v_lshlrev_b32_e32 v83, 16, v140
	v_lshlrev_b32_e32 v82, 16, v141
	v_lshlrev_b32_e32 v86, 16, v143
	v_and_b32_e32 v141, 0xffff0000, v142
	v_and_b32_e32 v140, 0xffff0000, v143
	s_waitcnt vmcnt(0) lgkmcnt(0)
	v_mov_b32_e32 v143, v18
	v_pk_add_f32 v[66:67], v[66:67], v[84:85] neg_lo:[0,1] neg_hi:[0,1]
	v_mov_b32_e32 v18, v17
	v_pk_fma_f32 v[62:63], v[78:79], v[62:63], v[70:71]
	v_pk_add_f32 v[68:69], v[74:75], v[70:71] neg_lo:[0,1] neg_hi:[0,1]
	v_lshlrev_b32_e32 v87, 16, v142
	v_pk_add_f32 v[12:13], v[12:13], v[82:83] neg_lo:[0,1] neg_hi:[0,1]
	v_mov_b32_e32 v142, v16
	v_mov_b32_e32 v145, v22
	v_pk_fma_f32 v[16:17], v[18:19], v[66:67], v[84:85]
	v_pk_add_f32 v[66:67], v[140:141], v[84:85] neg_lo:[0,1] neg_hi:[0,1]
	v_mov_b32_e32 v22, v21
	v_pk_fma_f32 v[62:63], v[80:81], v[68:69], v[62:63]
	s_nop 0
	v_cvt_pk_bf16_f32 v210, v63, v9
	v_cvt_pk_bf16_f32 v211, v62, v8
	v_pk_fma_f32 v[12:13], v[142:143], v[12:13], v[82:83]
	v_pk_add_f32 v[68:69], v[86:87], v[82:83] neg_lo:[0,1] neg_hi:[0,1]
	v_mov_b32_e32 v144, v20
	v_pk_fma_f32 v[16:17], v[22:23], v[66:67], v[16:17]
	v_pk_fma_f32 v[12:13], v[144:145], v[68:69], v[12:13]
	s_nop 0
	v_cvt_pk_bf16_f32 v208, v13, v17
	v_cvt_pk_bf16_f32 v209, v12, v16
	v_lshl_add_u64 v[60:61], v[88:89], 0, s[40:41]
	v_mov_b32_e32 v69, v208
	v_mov_b32_e32 v68, v209
	v_mov_b32_e32 v67, v210
	v_mov_b32_e32 v66, v211
	v_lshl_add_u64 v[8:9], v[60:61], 0, v[38:39]
	global_store_dwordx4 v[8:9], v[66:69], off
	v_lshlrev_b32_e32 v9, 16, v148
	v_lshlrev_b32_e32 v8, 16, v149
	v_pk_add_f32 v[16:17], v[70:71], v[74:75] neg_lo:[0,1] neg_hi:[0,1]
	v_pk_add_f32 v[20:21], v[8:9], v[74:75] neg_lo:[0,1] neg_hi:[0,1]
	v_pk_fma_f32 v[16:17], v[78:79], v[16:17], v[74:75]
	v_and_b32_e32 v13, 0xffff0000, v148
	v_and_b32_e32 v12, 0xffff0000, v149
	v_pk_fma_f32 v[16:17], v[80:81], v[20:21], v[16:17]
	v_pk_add_f32 v[20:21], v[72:73], v[76:77] neg_lo:[0,1] neg_hi:[0,1]
	v_pk_add_f32 v[62:63], v[12:13], v[76:77] neg_lo:[0,1] neg_hi:[0,1]
	v_pk_fma_f32 v[20:21], v[10:11], v[20:21], v[76:77]
	v_pk_add_f32 v[66:67], v[82:83], v[86:87] neg_lo:[0,1] neg_hi:[0,1]
	v_pk_fma_f32 v[20:21], v[14:15], v[62:63], v[20:21]
	s_nop 0
	v_cvt_pk_bf16_f32 v210, v17, v21
	v_cvt_pk_bf16_f32 v211, v16, v20
	v_lshlrev_b32_e32 v63, 16, v146
	v_lshlrev_b32_e32 v62, 16, v147
	v_pk_fma_f32 v[66:67], v[142:143], v[66:67], v[86:87]
	v_pk_add_f32 v[68:69], v[62:63], v[86:87] neg_lo:[0,1] neg_hi:[0,1]
	v_and_b32_e32 v71, 0xffff0000, v146
	v_and_b32_e32 v70, 0xffff0000, v147
	v_pk_fma_f32 v[66:67], v[144:145], v[68:69], v[66:67]
	v_pk_add_f32 v[68:69], v[84:85], v[140:141] neg_lo:[0,1] neg_hi:[0,1]
	v_pk_add_f32 v[72:73], v[70:71], v[140:141] neg_lo:[0,1] neg_hi:[0,1]
	v_pk_fma_f32 v[68:69], v[18:19], v[68:69], v[140:141]
	s_nop 0
	v_pk_fma_f32 v[68:69], v[22:23], v[72:73], v[68:69]
	s_nop 0
	v_cvt_pk_bf16_f32 v208, v67, v69
	v_cvt_pk_bf16_f32 v209, v66, v68
	v_mov_b32_e32 v69, v208
	v_mov_b32_e32 v68, v209
	v_mov_b32_e32 v67, v210
	v_mov_b32_e32 v66, v211
	v_lshl_add_u64 v[16:17], v[60:61], 0, v[40:41]
	global_store_dwordx4 v[16:17], v[66:69], off
	v_lshlrev_b32_e32 v17, 16, v152
	v_lshlrev_b32_e32 v16, 16, v153
	v_pk_add_f32 v[72:73], v[74:75], v[8:9] neg_lo:[0,1] neg_hi:[0,1]
	v_pk_add_f32 v[66:67], v[16:17], v[8:9] neg_lo:[0,1] neg_hi:[0,1]
	v_pk_fma_f32 v[72:73], v[78:79], v[72:73], v[8:9]
	v_and_b32_e32 v21, 0xffff0000, v152
	v_and_b32_e32 v20, 0xffff0000, v153
	v_pk_fma_f32 v[66:67], v[80:81], v[66:67], v[72:73]
	v_pk_add_f32 v[72:73], v[76:77], v[12:13] neg_lo:[0,1] neg_hi:[0,1]
	v_pk_add_f32 v[68:69], v[20:21], v[12:13] neg_lo:[0,1] neg_hi:[0,1]
	v_pk_fma_f32 v[72:73], v[10:11], v[72:73], v[12:13]
	v_pk_add_f32 v[84:85], v[86:87], v[62:63] neg_lo:[0,1] neg_hi:[0,1]
	v_pk_fma_f32 v[68:69], v[14:15], v[68:69], v[72:73]
	s_nop 0
	v_cvt_pk_bf16_f32 v210, v67, v69
	v_cvt_pk_bf16_f32 v211, v66, v68
	v_lshlrev_b32_e32 v73, 16, v150
	v_lshlrev_b32_e32 v72, 16, v151
	v_pk_add_f32 v[76:77], v[72:73], v[62:63] neg_lo:[0,1] neg_hi:[0,1]
	v_pk_fma_f32 v[84:85], v[142:143], v[84:85], v[62:63]
	v_and_b32_e32 v75, 0xffff0000, v150
	v_and_b32_e32 v74, 0xffff0000, v151
	v_pk_fma_f32 v[76:77], v[144:145], v[76:77], v[84:85]
	v_pk_add_f32 v[84:85], v[140:141], v[70:71] neg_lo:[0,1] neg_hi:[0,1]
	v_pk_add_f32 v[82:83], v[74:75], v[70:71] neg_lo:[0,1] neg_hi:[0,1]
	v_pk_fma_f32 v[84:85], v[18:19], v[84:85], v[70:71]
	s_nop 0
	v_pk_fma_f32 v[82:83], v[22:23], v[82:83], v[84:85]
	s_nop 0
	v_cvt_pk_bf16_f32 v208, v77, v83
	v_cvt_pk_bf16_f32 v209, v76, v82
	v_mov_b32_e32 v69, v208
	v_mov_b32_e32 v68, v209
	v_mov_b32_e32 v67, v210
	v_mov_b32_e32 v66, v211
	v_lshl_add_u64 v[76:77], v[60:61], 0, v[42:43]
	global_store_dwordx4 v[76:77], v[66:69], off
	v_pk_add_f32 v[8:9], v[8:9], v[16:17] neg_lo:[0,1] neg_hi:[0,1]
	v_pk_add_f32 v[12:13], v[12:13], v[20:21] neg_lo:[0,1] neg_hi:[0,1]
	v_lshlrev_b32_e32 v67, 16, v156
	v_lshlrev_b32_e32 v66, 16, v157
	v_and_b32_e32 v69, 0xffff0000, v156
	v_and_b32_e32 v68, 0xffff0000, v157
	v_pk_add_f32 v[66:67], v[66:67], v[16:17] neg_lo:[0,1] neg_hi:[0,1]
	v_pk_add_f32 v[68:69], v[68:69], v[20:21] neg_lo:[0,1] neg_hi:[0,1]
	v_pk_fma_f32 v[8:9], v[78:79], v[8:9], v[16:17]
	v_pk_fma_f32 v[10:11], v[10:11], v[12:13], v[20:21]
	v_lshlrev_b32_e32 v13, 16, v154
	v_lshlrev_b32_e32 v12, 16, v155
	v_pk_add_f32 v[16:17], v[62:63], v[72:73] neg_lo:[0,1] neg_hi:[0,1]
	v_pk_fma_f32 v[10:11], v[14:15], v[68:69], v[10:11]
	v_and_b32_e32 v15, 0xffff0000, v154
	v_and_b32_e32 v14, 0xffff0000, v155
	v_pk_add_f32 v[12:13], v[12:13], v[72:73] neg_lo:[0,1] neg_hi:[0,1]
	v_pk_add_f32 v[20:21], v[70:71], v[74:75] neg_lo:[0,1] neg_hi:[0,1]
	v_pk_fma_f32 v[16:17], v[142:143], v[16:17], v[72:73]
	v_pk_add_f32 v[14:15], v[14:15], v[74:75] neg_lo:[0,1] neg_hi:[0,1]
	v_pk_fma_f32 v[12:13], v[144:145], v[12:13], v[16:17]
	v_pk_fma_f32 v[16:17], v[18:19], v[20:21], v[74:75]
	v_pk_fma_f32 v[8:9], v[80:81], v[66:67], v[8:9]
	s_nop 0
	v_cvt_pk_bf16_f32 v210, v9, v11
	v_cvt_pk_bf16_f32 v211, v8, v10
	v_pk_fma_f32 v[14:15], v[22:23], v[14:15], v[16:17]
	s_nop 0
	v_cvt_pk_bf16_f32 v208, v13, v15
	v_cvt_pk_bf16_f32 v209, v12, v14
	v_mov_b32_e32 v11, v208
	v_mov_b32_e32 v10, v209
	v_mov_b32_e32 v9, v210
	v_mov_b32_e32 v8, v211
	v_lshl_add_u64 v[12:13], v[60:61], 0, v[44:45]
	global_store_dwordx4 v[12:13], v[8:11], off
	v_lshl_add_u64 v[12:13], v[88:89], 0, s[44:45]
	v_lshl_add_u64 v[14:15], v[12:13], 0, v[26:27]
	v_lshl_add_u64 v[8:9], v[12:13], 0, v[24:25]
	global_load_dwordx4 v[8:11], v[8:9], off
	v_lshl_add_u64 v[26:27], v[28:29], 0, s[42:43]
	global_load_dwordx4 v[22:25], v[14:15], off
	v_lshl_add_u64 v[14:15], v[12:13], 0, v[48:49]
	global_load_dwordx4 v[60:63], v[14:15], off
	v_lshl_add_u64 v[14:15], v[12:13], 0, v[54:55]
	global_load_dwordx4 v[66:69], v[14:15], off
	v_lshl_add_u64 v[14:15], v[12:13], 0, v[56:57]
	global_load_dwordx4 v[54:57], v[14:15], off
	v_lshl_add_u64 v[12:13], v[12:13], 0, v[58:59]
	global_load_dwordx4 v[70:73], v[12:13], off
	s_nop 0
	global_load_dwordx2 v[12:13], v[32:33], off offset:448
	global_load_dwordx4 v[18:21], v[50:51], off offset:1536
	global_load_dwordx4 v[14:17], v[52:53], off offset:1536
	v_lshl_add_u64 v[28:29], v[46:47], 0, s[42:43]
	v_lshl_add_u64 v[52:53], v[88:89], 0, s[46:47]
	v_lshl_add_u64 v[46:47], v[52:53], 0, v[38:39]
	v_lshl_add_u64 v[48:49], v[52:53], 0, v[40:41]
	v_lshl_add_u64 v[50:51], v[52:53], 0, v[42:43]
	v_lshl_add_u64 v[52:53], v[52:53], 0, v[44:45]
	v_and_b32_e32 v136, 0xffffffc0, v135
	s_waitcnt vmcnt(0) lgkmcnt(0)
	v_cndmask_b32_e32 v82, 0, v9, vcc
	v_cndmask_b32_e32 v83, 0, v8, vcc
	v_cndmask_b32_e64 v147, 0, v25, s[4:5]
	v_cndmask_b32_e64 v148, 0, v24, s[4:5]
	v_cndmask_b32_e64 v58, 0, v23, s[4:5]
	v_cndmask_b32_e64 v59, 0, v22, s[4:5]
	global_load_dwordx4 v[22:25], v[26:27], off offset:16
	v_cndmask_b32_e32 v139, 0, v11, vcc
	global_load_dwordx4 v[26:29], v[28:29], off offset:16
	v_cndmask_b32_e64 v55, 0, v55, s[10:11]
	v_cndmask_b32_e64 v54, 0, v54, s[10:11]
	v_cndmask_b32_e32 v146, 0, v10, vcc
	v_cndmask_b32_e64 v61, 0, v61, s[6:7]
	v_cndmask_b32_e64 v60, 0, v60, s[6:7]
	v_cndmask_b32_e64 v153, 0, v57, s[10:11]
	v_cndmask_b32_e64 v154, 0, v56, s[10:11]
	v_cndmask_b32_e64 v157, 0, v71, s[12:13]
	v_cndmask_b32_e64 v158, 0, v70, s[12:13]
	v_lshlrev_b32_e32 v8, 16, v83
	v_lshlrev_b32_e32 v9, 16, v82
	v_lshlrev_b32_e32 v10, 16, v59
	v_lshlrev_b32_e32 v11, 16, v58
	v_lshlrev_b32_e32 v70, 16, v54
	v_lshlrev_b32_e32 v71, 16, v55
	v_readfirstlane_b32 s1, v13
	v_readfirstlane_b32 s0, v12
	v_and_b32_e32 v79, 0xffff0000, v55
	v_and_b32_e32 v78, 0xffff0000, v54
	v_and_b32_e32 v55, 0xffff0000, v58
	v_and_b32_e32 v54, 0xffff0000, v59
	v_and_b32_e32 v57, 0xffff0000, v82
	v_and_b32_e32 v56, 0xffff0000, v83
	v_cndmask_b32_e64 v149, 0, v63, s[6:7]
	v_cndmask_b32_e64 v150, 0, v62, s[6:7]
	v_lshlrev_b32_e32 v62, 16, v60
	v_lshlrev_b32_e32 v63, 16, v61
	v_lshl_add_u64 v[12:13], s[0:1], 0, v[64:65]
	v_pk_add_f32 v[8:9], v[8:9], v[10:11] neg_lo:[0,1] neg_hi:[0,1]
	v_pk_add_f32 v[56:57], v[56:57], v[54:55] neg_lo:[0,1] neg_hi:[0,1]
	v_mov_b32_e32 v82, v18
	v_mov_b32_e32 v83, v20
	v_mov_b32_e32 v20, v19
	v_pk_add_f32 v[58:59], v[10:11], v[62:63] neg_lo:[0,1] neg_hi:[0,1]
	v_pk_fma_f32 v[140:141], v[82:83], v[8:9], v[10:11]
	v_pk_fma_f32 v[18:19], v[20:21], v[56:57], v[54:55]
	v_pk_add_f32 v[56:57], v[62:63], v[10:11] neg_lo:[0,1] neg_hi:[0,1]
	global_load_dwordx4 v[8:11], v[12:13], off offset:1024
	v_mov_b32_e32 v144, v14
	v_mov_b32_e32 v145, v16
	v_mov_b32_e32 v16, v15
	global_load_dwordx4 v[12:15], v[12:13], off offset:1040
	v_cndmask_b32_e64 v67, 0, v67, s[8:9]
	v_cndmask_b32_e64 v66, 0, v66, s[8:9]
	v_cndmask_b32_e64 v151, 0, v69, s[8:9]
	v_cndmask_b32_e64 v152, 0, v68, s[8:9]
	v_lshlrev_b32_e32 v68, 16, v66
	v_lshlrev_b32_e32 v69, 16, v67
	v_and_b32_e32 v77, 0xffff0000, v67
	v_and_b32_e32 v76, 0xffff0000, v66
	v_and_b32_e32 v67, 0xffff0000, v61
	v_and_b32_e32 v66, 0xffff0000, v60
	v_pk_add_f32 v[142:143], v[66:67], v[54:55] neg_lo:[0,1] neg_hi:[0,1]
	v_pk_add_f32 v[60:61], v[54:55], v[66:67] neg_lo:[0,1] neg_hi:[0,1]
	v_pk_fma_f32 v[54:55], v[144:145], v[56:57], v[140:141]
	v_pk_fma_f32 v[56:57], v[16:17], v[142:143], v[18:19]
	v_pk_fma_f32 v[18:19], v[82:83], v[58:59], v[62:63]
	v_pk_add_f32 v[58:59], v[68:69], v[62:63] neg_lo:[0,1] neg_hi:[0,1]
	v_and_b32_e32 v141, 0xffff0000, v157
	v_pk_fma_f32 v[58:59], v[144:145], v[58:59], v[18:19]
	v_pk_fma_f32 v[18:19], v[20:21], v[60:61], v[66:67]
	v_pk_add_f32 v[60:61], v[76:77], v[66:67] neg_lo:[0,1] neg_hi:[0,1]
	v_and_b32_e32 v140, 0xffff0000, v158
	v_pk_fma_f32 v[60:61], v[16:17], v[60:61], v[18:19]
	v_pk_add_f32 v[18:19], v[62:63], v[68:69] neg_lo:[0,1] neg_hi:[0,1]
	v_pk_add_f32 v[62:63], v[70:71], v[68:69] neg_lo:[0,1] neg_hi:[0,1]
	v_pk_fma_f32 v[18:19], v[82:83], v[18:19], v[68:69]
	v_pk_add_f32 v[68:69], v[68:69], v[70:71] neg_lo:[0,1] neg_hi:[0,1]
	v_pk_fma_f32 v[62:63], v[144:145], v[62:63], v[18:19]
	v_pk_add_f32 v[18:19], v[66:67], v[76:77] neg_lo:[0,1] neg_hi:[0,1]
	v_pk_add_f32 v[66:67], v[78:79], v[76:77] neg_lo:[0,1] neg_hi:[0,1]
	v_pk_fma_f32 v[18:19], v[20:21], v[18:19], v[76:77]
	v_pk_fma_f32 v[68:69], v[82:83], v[68:69], v[70:71]
	v_pk_fma_f32 v[66:67], v[16:17], v[66:67], v[18:19]
	v_lshlrev_b32_e32 v19, 16, v157
	v_lshlrev_b32_e32 v18, 16, v158
	v_pk_add_f32 v[18:19], v[18:19], v[70:71] neg_lo:[0,1] neg_hi:[0,1]
	v_cndmask_b32_e64 v155, 0, v73, s[12:13]
	v_pk_fma_f32 v[68:69], v[144:145], v[18:19], v[68:69]
	v_pk_add_f32 v[18:19], v[76:77], v[78:79] neg_lo:[0,1] neg_hi:[0,1]
	v_cndmask_b32_e64 v156, 0, v72, s[12:13]
	v_lshlrev_b32_e32 v74, 16, v146
	v_lshlrev_b32_e32 v75, 16, v139
	v_lshlrev_b32_e32 v72, 16, v148
	v_lshlrev_b32_e32 v73, 16, v147
	v_pk_fma_f32 v[18:19], v[20:21], v[18:19], v[78:79]
	v_pk_add_f32 v[20:21], v[140:141], v[78:79] neg_lo:[0,1] neg_hi:[0,1]
	v_and_b32_e32 v77, 0xffff0000, v147
	v_and_b32_e32 v76, 0xffff0000, v148
	v_and_b32_e32 v141, 0xffff0000, v139
	v_and_b32_e32 v140, 0xffff0000, v146
	v_lshlrev_b32_e32 v80, 16, v150
	v_lshlrev_b32_e32 v81, 16, v149
	v_pk_fma_f32 v[70:71], v[16:17], v[20:21], v[18:19]
	v_and_b32_e32 v17, 0xffff0000, v149
	v_and_b32_e32 v16, 0xffff0000, v150
	v_pk_add_f32 v[74:75], v[74:75], v[72:73] neg_lo:[0,1] neg_hi:[0,1]
	v_pk_add_f32 v[140:141], v[140:141], v[76:77] neg_lo:[0,1] neg_hi:[0,1]
	s_waitcnt vmcnt(0) lgkmcnt(0)
	v_mov_b32_e32 v142, v22
	v_mov_b32_e32 v143, v24
	v_mov_b32_e32 v24, v23
	v_lshlrev_b32_e32 v86, 16, v152
	v_lshlrev_b32_e32 v87, 16, v151
	v_pk_add_f32 v[78:79], v[72:73], v[80:81] neg_lo:[0,1] neg_hi:[0,1]
	v_pk_add_f32 v[82:83], v[76:77], v[16:17] neg_lo:[0,1] neg_hi:[0,1]
	v_pk_fma_f32 v[74:75], v[142:143], v[74:75], v[72:73]
	v_pk_fma_f32 v[22:23], v[24:25], v[140:141], v[76:77]
	v_pk_add_f32 v[72:73], v[80:81], v[72:73] neg_lo:[0,1] neg_hi:[0,1]
	v_pk_add_f32 v[76:77], v[16:17], v[76:77] neg_lo:[0,1] neg_hi:[0,1]
	v_mov_b32_e32 v140, v26
	v_mov_b32_e32 v141, v28
	v_mov_b32_e32 v28, v27
	v_and_b32_e32 v19, 0xffff0000, v151
	v_and_b32_e32 v18, 0xffff0000, v152
	v_pk_fma_f32 v[72:73], v[140:141], v[72:73], v[74:75]
	v_pk_fma_f32 v[74:75], v[28:29], v[76:77], v[22:23]
	v_pk_fma_f32 v[22:23], v[142:143], v[78:79], v[80:81]
	v_pk_add_f32 v[26:27], v[86:87], v[80:81] neg_lo:[0,1] neg_hi:[0,1]
	v_lshlrev_b32_e32 v84, 16, v154
	v_pk_fma_f32 v[76:77], v[140:141], v[26:27], v[22:23]
	v_pk_fma_f32 v[22:23], v[24:25], v[82:83], v[16:17]
	v_pk_add_f32 v[26:27], v[18:19], v[16:17] neg_lo:[0,1] neg_hi:[0,1]
	v_lshlrev_b32_e32 v85, 16, v153
	v_pk_fma_f32 v[78:79], v[28:29], v[26:27], v[22:23]
	v_pk_add_f32 v[22:23], v[80:81], v[86:87] neg_lo:[0,1] neg_hi:[0,1]
	v_and_b32_e32 v21, 0xffff0000, v153
	v_and_b32_e32 v20, 0xffff0000, v154
	v_pk_fma_f32 v[22:23], v[142:143], v[22:23], v[86:87]
	v_pk_add_f32 v[26:27], v[84:85], v[86:87] neg_lo:[0,1] neg_hi:[0,1]
	v_pk_add_f32 v[16:17], v[16:17], v[18:19] neg_lo:[0,1] neg_hi:[0,1]
	v_pk_fma_f32 v[80:81], v[140:141], v[26:27], v[22:23]
	v_pk_fma_f32 v[16:17], v[24:25], v[16:17], v[18:19]
	v_pk_add_f32 v[22:23], v[20:21], v[18:19] neg_lo:[0,1] neg_hi:[0,1]
	v_and_b32_e32 v27, 0xffff0000, v155
	v_pk_fma_f32 v[82:83], v[28:29], v[22:23], v[16:17]
	v_pk_add_f32 v[16:17], v[86:87], v[84:85] neg_lo:[0,1] neg_hi:[0,1]
	v_lshlrev_b32_e32 v23, 16, v155
	v_pk_fma_f32 v[86:87], v[142:143], v[16:17], v[84:85]
	v_mov_b32_e32 v16, v8
	v_mov_b32_e32 v17, v10
	v_mov_b32_e32 v10, v9
	v_pk_mul_f32 v[142:143], v[16:17], v[54:55]
	v_pk_mul_f32 v[144:145], v[56:57], v[10:11]
	v_mov_b32_e32 v8, v143
	v_mov_b32_e32 v9, v145
	v_pk_mul_f32 v[146:147], v[8:9], v[8:9]
	v_mov_b32_e32 v8, v12
	v_mov_b32_e32 v9, v14
	v_mov_b32_e32 v14, v13
	v_mul_f32_e32 v139, v142, v142
	v_pk_mul_f32 v[148:149], v[72:73], v[8:9]
	v_pk_mul_f32 v[12:13], v[74:75], v[14:15]
	v_fmac_f32_e32 v139, v144, v144
	v_mov_b32_e32 v150, v148
	v_mov_b32_e32 v151, v12
	v_add_f32_e32 v139, v139, v146
	v_pk_mul_f32 v[150:151], v[150:151], v[150:151]
	v_add_f32_e32 v139, v139, v147
	v_mov_b32_e32 v152, v149
	v_mov_b32_e32 v153, v13
	v_add_f32_e32 v139, v139, v150
	v_pk_mul_f32 v[152:153], v[152:153], v[152:153]
	v_add_f32_e32 v139, v139, v151
	v_add_f32_e32 v139, v139, v152
	v_add_f32_e32 v139, v139, v153
	v_lshlrev_b32_e32 v22, 16, v156
	v_pk_add_f32 v[22:23], v[22:23], v[84:85] neg_lo:[0,1] neg_hi:[0,1]
	v_add_f32_dpp v139, v139, v139 quad_perm:[1,0,3,2] row_mask:0xf bank_mask:0xf bound_ctrl:1
	v_pk_fma_f32 v[84:85], v[140:141], v[22:23], v[86:87]
	v_and_b32_e32 v26, 0xffff0000, v156
	v_add_f32_dpp v139, v139, v139 quad_perm:[2,3,0,1] row_mask:0xf bank_mask:0xf bound_ctrl:1
	v_pk_add_f32 v[18:19], v[18:19], v[20:21] neg_lo:[0,1] neg_hi:[0,1]
	v_pk_mul_f32 v[140:141], v[78:79], v[14:15]
	v_add_f32_dpp v139, v139, v139 row_half_mirror row_mask:0xf bank_mask:0xf bound_ctrl:1
	v_mul_f32_e32 v146, 0x4f800000, v139
	v_cmp_gt_f32_e32 vcc, s71, v139
	v_pk_fma_f32 v[18:19], v[24:25], v[18:19], v[20:21]
	v_pk_add_f32 v[20:21], v[26:27], v[20:21] neg_lo:[0,1] neg_hi:[0,1]
	v_cndmask_b32_e32 v139, v139, v146, vcc
	v_sqrt_f32_e32 v146, v139
	v_mul_f32_e32 v156, v36, v5
	v_mul_f32_e32 v157, v31, v6
	v_mul_f32_e32 v158, v37, v7
	v_add_u32_e32 v22, -1, v146
	v_fma_f32 v23, -v22, v146, v139
	v_cmp_ge_f32_e64 s[0:1], 0, v23
	v_add_u32_e32 v23, 1, v146
	v_fma_f32 v86, -v23, v146, v139
	v_cndmask_b32_e64 v22, v146, v22, s[0:1]
	v_cmp_lt_f32_e64 s[0:1], 0, v86
	v_pk_fma_f32 v[86:87], v[28:29], v[20:21], v[18:19]
	v_pk_mul_f32 v[28:29], v[76:77], v[8:9]
	v_cndmask_b32_e64 v22, v22, v23, s[0:1]
	v_mul_f32_e32 v23, 0x37800000, v22
	v_cndmask_b32_e32 v22, v22, v23, vcc
	v_cmp_class_f32_e32 vcc, v139, v128
	v_lshlrev_b64 v[36:37], 11, v[94:95]
	v_lshl_add_u64 v[36:37], s[54:55], 0, v[36:37]
	v_cndmask_b32_e32 v22, v22, v139, vcc
	v_max_f32_e32 v22, 0x2b8cbccc, v22
	v_div_scale_f32 v23, s[0:1], v22, v22, 1.0
	v_rcp_f32_e32 v139, v23
	v_lshl_add_u64 v[36:37], v[36:37], 0, v[34:35]
	v_mul_f32_e32 v121, v156, v56
	v_mul_f32_e32 v122, v157, v55
	v_fma_f32 v18, -v23, v139, 1.0
	v_fmac_f32_e32 v139, v18, v139
	v_div_scale_f32 v18, vcc, 1.0, v22, 1.0
	v_mul_f32_e32 v19, v18, v139
	v_fma_f32 v20, -v23, v19, v18
	v_fmac_f32_e32 v19, v20, v139
	v_fma_f32 v18, -v23, v19, v18
	v_div_fmas_f32 v18, v18, v139, v19
	v_div_fixup_f32 v18, v18, v22, 1.0
	v_pk_mul_f32 v[20:21], v[142:143], v[18:19] op_sel_hi:[1,0]
	v_pk_mul_f32 v[22:23], v[148:149], v[18:19] op_sel_hi:[1,0]
	v_bfe_u32 v19, v20, 16, 1
	v_bfe_u32 v24, v21, 16, 1
	v_bfe_u32 v25, v22, 16, 1
	v_bfe_u32 v26, v23, 16, 1
	v_add3_u32 v23, v23, v26, s60
	v_add3_u32 v22, v22, v25, s60
	v_add3_u32 v21, v21, v24, s60
	v_add3_u32 v19, v20, v19, s60
	v_pk_mul_f32 v[24:25], v[58:59], v[16:17]
	v_pk_mul_f32 v[26:27], v[60:61], v[10:11]
	v_lshrrev_b32_e32 v139, 16, v19
	v_lshrrev_b32_e32 v19, 16, v21
	v_mov_b32_e32 v20, v27
	v_mov_b32_e32 v21, v25
	v_mul_f32_e32 v148, v24, v24
	v_pk_mul_f32 v[20:21], v[20:21], v[20:21]
	v_fmac_f32_e32 v148, v26, v26
	v_mov_b32_e32 v142, v140
	v_mov_b32_e32 v143, v28
	v_add_f32_e32 v21, v21, v148
	v_pk_mul_f32 v[142:143], v[142:143], v[142:143]
	v_add_f32_e32 v20, v20, v21
	v_lshrrev_b32_e32 v146, 16, v22
	v_lshrrev_b32_e32 v147, 16, v23
	v_pk_mul_f32 v[22:23], v[144:145], v[18:19] op_sel_hi:[1,0]
	v_mov_b32_e32 v144, v141
	v_mov_b32_e32 v145, v29
	v_add_f32_e32 v20, v143, v20
	v_pk_mul_f32 v[144:145], v[144:145], v[144:145]
	v_add_f32_e32 v20, v142, v20
	v_add_f32_e32 v20, v145, v20
	v_add_f32_e32 v20, v144, v20
	v_pk_mul_f32 v[12:13], v[12:13], v[18:19] op_sel_hi:[1,0]
	v_and_or_b32 v19, v23, s56, v19
	v_add_f32_dpp v20, v20, v20 quad_perm:[1,0,3,2] row_mask:0xf bank_mask:0xf bound_ctrl:1
	v_mul_f32_e32 v123, v158, v57
	v_mul_f32_e32 v124, v163, v58
	v_add_f32_dpp v20, v20, v20 quad_perm:[2,3,0,1] row_mask:0xf bank_mask:0xf bound_ctrl:1
	v_mul_f32_e32 v125, v168, v60
	v_mul_f32_e32 v137, v169, v59
	v_add_f32_dpp v20, v20, v20 row_half_mirror row_mask:0xf bank_mask:0xf bound_ctrl:1
	v_mul_f32_e32 v21, 0x4f800000, v20
	v_cmp_gt_f32_e32 vcc, s71, v20
	v_mul_f32_e32 v156, v116, v82
	v_mul_f32_e32 v157, v115, v81
	v_cndmask_b32_e32 v142, v20, v21, vcc
	v_sqrt_f32_e32 v143, v142
	v_and_or_b32 v20, v12, s56, v146
	v_and_or_b32 v21, v13, s56, v147
	v_mul_f32_e32 v158, v117, v83
	v_add_u32_e32 v12, -1, v143
	v_fma_f32 v13, -v12, v143, v142
	v_cmp_ge_f32_e64 s[0:1], 0, v13
	v_add_u32_e32 v13, 1, v143
	v_fma_f32 v18, -v13, v143, v142
	v_cndmask_b32_e64 v12, v143, v12, s[0:1]
	v_cmp_lt_f32_e64 s[0:1], 0, v18
	v_and_or_b32 v18, v22, s56, v139
	global_store_dwordx4 v[46:47], v[18:21], off
	v_cndmask_b32_e64 v12, v12, v13, s[0:1]
	v_mul_f32_e32 v13, 0x37800000, v12
	v_cndmask_b32_e32 v12, v12, v13, vcc
	v_cmp_class_f32_e32 vcc, v142, v128
	s_nop 1
	v_cndmask_b32_e32 v12, v12, v142, vcc
	v_max_f32_e32 v12, 0x2b8cbccc, v12
	v_div_scale_f32 v13, s[0:1], v12, v12, 1.0
	v_rcp_f32_e32 v142, v13
	s_nop 0
	v_fma_f32 v18, -v13, v142, 1.0
	v_fmac_f32_e32 v142, v18, v142
	v_div_scale_f32 v18, vcc, 1.0, v12, 1.0
	v_mul_f32_e32 v19, v18, v142
	v_fma_f32 v20, -v13, v19, v18
	v_fmac_f32_e32 v19, v20, v142
	v_fma_f32 v13, -v13, v19, v18
	v_div_fmas_f32 v13, v13, v142, v19
	v_div_fixup_f32 v12, v13, v12, 1.0
	v_pk_mul_f32 v[18:19], v[24:25], v[12:13] op_sel_hi:[1,0]
	v_pk_mul_f32 v[20:21], v[28:29], v[12:13] op_sel_hi:[1,0]
	v_bfe_u32 v13, v18, 16, 1
	v_bfe_u32 v22, v19, 16, 1
	v_bfe_u32 v23, v20, 16, 1
	v_bfe_u32 v24, v21, 16, 1
	v_add3_u32 v21, v21, v24, s60
	v_add3_u32 v20, v20, v23, s60
	v_add3_u32 v19, v19, v22, s60
	v_add3_u32 v13, v18, v13, s60
	v_pk_mul_f32 v[22:23], v[16:17], v[62:63]
	v_pk_mul_f32 v[24:25], v[66:67], v[10:11]
	v_lshrrev_b32_e32 v139, 16, v13
	v_lshrrev_b32_e32 v146, 16, v19
	v_lshrrev_b32_e32 v147, 16, v20
	v_lshrrev_b32_e32 v148, 16, v21
	v_pk_mul_f32 v[18:19], v[26:27], v[12:13] op_sel_hi:[1,0]
	v_mov_b32_e32 v20, v25
	v_mov_b32_e32 v21, v23
	v_mul_f32_e32 v13, v22, v22
	v_pk_mul_f32 v[20:21], v[20:21], v[20:21]
	v_pk_mul_f32 v[26:27], v[80:81], v[8:9]
	v_pk_mul_f32 v[28:29], v[82:83], v[14:15]
	v_fmac_f32_e32 v13, v24, v24
	v_mov_b32_e32 v142, v28
	v_mov_b32_e32 v143, v26
	v_add_f32_e32 v13, v21, v13
	v_pk_mul_f32 v[142:143], v[142:143], v[142:143]
	v_add_f32_e32 v13, v20, v13
	v_mov_b32_e32 v144, v29
	v_mov_b32_e32 v145, v27
	v_add_f32_e32 v13, v143, v13
	v_pk_mul_f32 v[144:145], v[144:145], v[144:145]
	v_add_f32_e32 v13, v142, v13
	v_add_f32_e32 v13, v145, v13
	v_add_f32_e32 v13, v144, v13
	v_and_or_b32 v19, v19, s56, v146
	v_and_or_b32 v18, v18, s56, v139
	v_add_f32_dpp v13, v13, v13 quad_perm:[1,0,3,2] row_mask:0xf bank_mask:0xf bound_ctrl:1
	v_pk_mul_f32 v[16:17], v[16:17], v[68:69]
	v_pk_mul_f32 v[14:15], v[86:87], v[14:15]
	v_add_f32_dpp v13, v13, v13 quad_perm:[2,3,0,1] row_mask:0xf bank_mask:0xf bound_ctrl:1
	s_nop 1
	v_add_f32_dpp v13, v13, v13 row_half_mirror row_mask:0xf bank_mask:0xf bound_ctrl:1
	v_mul_f32_e32 v20, 0x4f800000, v13
	v_cmp_gt_f32_e32 vcc, s71, v13
	s_nop 1
	v_cndmask_b32_e32 v142, v13, v20, vcc
	v_sqrt_f32_e32 v143, v142
	v_pk_mul_f32 v[12:13], v[140:141], v[12:13] op_sel_hi:[1,0]
	s_nop 0
	v_and_or_b32 v20, v12, s56, v147
	v_add_u32_e32 v12, -1, v143
	v_and_or_b32 v21, v13, s56, v148
	v_fma_f32 v13, -v12, v143, v142
	v_cmp_ge_f32_e64 s[0:1], 0, v13
	v_add_u32_e32 v13, 1, v143
	v_fma_f32 v140, -v13, v143, v142
	v_cndmask_b32_e64 v12, v143, v12, s[0:1]
	v_cmp_lt_f32_e64 s[0:1], 0, v140
	global_store_dwordx4 v[48:49], v[18:21], off
	s_nop 0
	v_cndmask_b32_e64 v12, v12, v13, s[0:1]
	v_mul_f32_e32 v13, 0x37800000, v12
	v_cndmask_b32_e32 v12, v12, v13, vcc
	v_cmp_class_f32_e32 vcc, v142, v128
	s_nop 1
	v_cndmask_b32_e32 v12, v12, v142, vcc
	v_max_f32_e32 v12, 0x2b8cbccc, v12
	v_div_scale_f32 v13, s[0:1], v12, v12, 1.0
	v_rcp_f32_e32 v140, v13
	s_nop 0
	v_fma_f32 v18, -v13, v140, 1.0
	v_fmac_f32_e32 v140, v18, v140
	v_div_scale_f32 v18, vcc, 1.0, v12, 1.0
	v_mul_f32_e32 v19, v18, v140
	v_fma_f32 v20, -v13, v19, v18
	v_fmac_f32_e32 v19, v20, v140
	v_fma_f32 v13, -v13, v19, v18
	v_div_fmas_f32 v13, v13, v140, v19
	v_div_fixup_f32 v12, v13, v12, 1.0
	v_pk_mul_f32 v[20:21], v[26:27], v[12:13] op_sel_hi:[1,0]
	v_pk_mul_f32 v[18:19], v[22:23], v[12:13] op_sel_hi:[1,0]
	v_bfe_u32 v23, v20, 16, 1
	v_bfe_u32 v26, v21, 16, 1
	v_add3_u32 v21, v21, v26, s60
	v_add3_u32 v20, v20, v23, s60
	v_lshrrev_b32_e32 v27, 16, v20
	v_lshrrev_b32_e32 v139, 16, v21
	v_pk_mul_f32 v[20:21], v[10:11], v[70:71]
	v_bfe_u32 v22, v19, 16, 1
	v_mov_b32_e32 v10, v21
	v_mov_b32_e32 v11, v17
	v_mul_f32_e32 v140, v16, v16
	v_bfe_u32 v13, v18, 16, 1
	v_add3_u32 v19, v19, v22, s60
	v_pk_mul_f32 v[10:11], v[10:11], v[10:11]
	v_pk_mul_f32 v[22:23], v[84:85], v[8:9]
	v_fmac_f32_e32 v140, v20, v20
	v_add3_u32 v13, v18, v13, s60
	v_mov_b32_e32 v8, v14
	v_mov_b32_e32 v9, v22
	v_add_f32_e32 v11, v11, v140
	v_lshrrev_b32_e32 v13, 16, v13
	v_pk_mul_f32 v[8:9], v[8:9], v[8:9]
	v_add_f32_e32 v10, v10, v11
	v_lshrrev_b32_e32 v26, 16, v19
	v_pk_mul_f32 v[18:19], v[24:25], v[12:13] op_sel_hi:[1,0]
	v_mov_b32_e32 v24, v15
	v_mov_b32_e32 v25, v23
	v_add_f32_e32 v9, v9, v10
	v_pk_mul_f32 v[24:25], v[24:25], v[24:25]
	v_add_f32_e32 v8, v8, v9
	v_add_f32_e32 v8, v25, v8
	v_add_f32_e32 v8, v24, v8
	s_nop 1
	v_add_f32_dpp v8, v8, v8 quad_perm:[1,0,3,2] row_mask:0xf bank_mask:0xf bound_ctrl:1
	s_nop 1
	v_add_f32_dpp v8, v8, v8 quad_perm:[2,3,0,1] row_mask:0xf bank_mask:0xf bound_ctrl:1
	s_nop 1
	v_add_f32_dpp v8, v8, v8 row_half_mirror row_mask:0xf bank_mask:0xf bound_ctrl:1
	v_mul_f32_e32 v9, 0x4f800000, v8
	v_cmp_gt_f32_e32 vcc, s71, v8
	s_nop 1
	v_cndmask_b32_e32 v24, v8, v9, vcc
	v_sqrt_f32_e32 v25, v24
	v_pk_mul_f32 v[8:9], v[28:29], v[12:13] op_sel_hi:[1,0]
	s_nop 0
	v_and_or_b32 v10, v8, s56, v27
	v_add_u32_e32 v8, -1, v25
	v_and_or_b32 v11, v9, s56, v139
	v_fma_f32 v9, -v8, v25, v24
	v_cmp_ge_f32_e64 s[0:1], 0, v9
	v_add_u32_e32 v9, 1, v25
	v_fma_f32 v12, -v9, v25, v24
	v_cndmask_b32_e64 v8, v25, v8, s[0:1]
	v_cmp_lt_f32_e64 s[0:1], 0, v12
	v_mul_f32_e32 v139, v4, v30
	v_mul_f32_e32 v120, v139, v54
	v_cndmask_b32_e64 v8, v8, v9, s[0:1]
	v_mul_f32_e32 v9, 0x37800000, v8
	v_cndmask_b32_e32 v8, v8, v9, vcc
	v_cmp_class_f32_e32 vcc, v24, v128
	v_and_or_b32 v9, v19, s56, v26
	v_mul_f32_e32 v139, v175, v62
	v_cndmask_b32_e32 v8, v8, v24, vcc
	v_max_f32_e32 v12, 0x2b8cbccc, v8
	v_div_scale_f32 v24, s[0:1], v12, v12, 1.0
	v_rcp_f32_e32 v25, v24
	v_and_or_b32 v8, v18, s56, v13
	global_store_dwordx4 v[50:51], v[8:11], off
	s_nop 1
	v_fma_f32 v8, -v24, v25, 1.0
	v_fmac_f32_e32 v25, v8, v25
	v_div_scale_f32 v8, vcc, 1.0, v12, 1.0
	v_mul_f32_e32 v9, v8, v25
	v_fma_f32 v10, -v24, v9, v8
	v_fmac_f32_e32 v9, v10, v25
	v_fma_f32 v8, -v24, v9, v8
	v_div_fmas_f32 v8, v8, v25, v9
	v_div_fixup_f32 v8, v8, v12, 1.0
	v_pk_mul_f32 v[10:11], v[16:17], v[8:9] op_sel_hi:[1,0]
	v_pk_mul_f32 v[12:13], v[22:23], v[8:9] op_sel_hi:[1,0]
	v_bfe_u32 v9, v10, 16, 1
	v_bfe_u32 v16, v11, 16, 1
	v_bfe_u32 v17, v12, 16, 1
	v_bfe_u32 v18, v13, 16, 1
	v_add3_u32 v13, v13, v18, s60
	v_add3_u32 v12, v12, v17, s60
	v_add3_u32 v11, v11, v16, s60
	v_add3_u32 v9, v10, v9, s60
	v_lshrrev_b32_e32 v16, 16, v9
	v_lshrrev_b32_e32 v17, 16, v11
	v_lshrrev_b32_e32 v10, 16, v12
	v_lshrrev_b32_e32 v11, 16, v13
	v_pk_mul_f32 v[12:13], v[20:21], v[8:9] op_sel_hi:[1,0]
	v_pk_mul_f32 v[8:9], v[14:15], v[8:9] op_sel_hi:[1,0]
	v_lshlrev_b64 v[24:25], 11, v[90:91]
	v_and_or_b32 v11, v9, s56, v11
	v_and_or_b32 v10, v8, s56, v10
	v_and_or_b32 v9, v13, s56, v17
	v_and_or_b32 v8, v12, s56, v16
	global_store_dwordx4 v[52:53], v[8:11], off
	s_waitcnt lgkmcnt(0)
	s_barrier
	v_mov_b32_e32 v8, v65
	v_lshl_add_u64 v[24:25], s[54:55], 0, v[24:25]
	v_mbcnt_lo_u32_b32 v8, -1, v8
	v_mbcnt_hi_u32_b32 v10, -1, v8
	v_and_b32_e32 v20, 31, v10
	v_or_b32_e32 v8, v20, v136
	v_ashrrev_i32_e32 v9, 31, v8
	v_ashrrev_i32_e32 v10, 2, v10
	v_lshlrev_b64 v[8:9], 8, v[8:9]
	v_and_b32_e32 v12, -8, v10
	v_lshl_add_u64 v[8:9], s[54:55], 0, v[8:9]
	v_ashrrev_i32_e32 v13, 31, v12
	v_lshl_add_u64 v[14:15], v[12:13], 1, v[8:9]
	v_add_co_u32_e32 v8, vcc, s72, v14
	v_lshl_add_u64 v[166:167], v[14:15], 0, s[48:49]
	s_nop 0
	v_addc_co_u32_e32 v9, vcc, 0, v15, vcc
	v_add_co_u32_e32 v164, vcc, s73, v14
	global_load_dwordx4 v[8:11], v[8:9], off
	s_nop 0
	v_addc_co_u32_e32 v165, vcc, 0, v15, vcc
	global_load_dwordx4 v[16:19], v[164:165], off
	global_load_dwordx4 v[140:143], v[166:167], off offset:32
	global_load_dwordx4 v[144:147], v[164:165], off offset:32
	global_load_dwordx4 v[148:151], v[166:167], off offset:64
	global_load_dwordx4 v[98:101], v[166:167], off offset:96
	global_load_dwordx4 v[152:155], v[164:165], off offset:64
	global_load_dwordx4 v[102:105], v[164:165], off offset:96
	v_lshlrev_b32_e32 v0, 1, v12
	v_mad_u32_u24 v191, v20, s65, v0
	ds_read_b128 v[20:23], v191
	ds_read_b128 v[106:109], v191 offset:32
	v_lshrrev_b32_e32 v0, 3, v135
	v_and_b32_e32 v0, 4, v0
	v_mul_u32_u24_e32 v0, 0x410, v0
	v_lshl_add_u64 v[180:181], v[24:25], 0, v[34:35]
	v_lshlrev_b64 v[24:25], 11, v[92:93]
	v_lshl_add_u32 v192, v1, 2, v0
	v_mul_lo_u32 v0, v138, s70
	v_lshl_add_u64 v[24:25], s[54:55], 0, v[24:25]
	v_add_u32_e32 v118, v64, v0
	s_waitcnt vmcnt(0) lgkmcnt(0)
	v_mfma_f32_32x32x16_bf16 v[0:15], v[20:23], v[8:11], 0
	v_lshl_add_u64 v[182:183], v[24:25], 0, v[34:35]
	v_lshl_add_u64 v[34:35], v[110:111], 0, v[34:35]
	ds_read_b128 v[110:113], v191 offset:64
	v_mul_f32_e32 v138, v170, v61
	v_mfma_f32_32x32x16_bf16 v[16:31], v[20:23], v[16:19], 0
	v_mfma_f32_32x32x16_bf16 v[0:15], v[106:109], v[140:143], v[0:15]
	v_mul_f32_e32 v140, v176, v66
	v_mul_f32_e32 v141, v177, v63
	v_mul_f32_e32 v142, v178, v67
	v_mul_f32_e32 v143, v179, v68
	v_mfma_f32_32x32x16_bf16 v[16:31], v[106:109], v[144:147], v[16:31]
	ds_read_b128 v[106:109], v191 offset:96
	v_mul_f32_e32 v144, v184, v70
	v_mul_f32_e32 v145, v185, v69
	v_mul_f32_e32 v146, v186, v71
	v_mul_f32_e32 v147, v159, v72
	v_mul_f32_e32 v159, v187, v84
	s_waitcnt lgkmcnt(1)
	v_mfma_f32_32x32x16_bf16 v[0:15], v[110:113], v[148:151], v[0:15]
	v_mul_f32_e32 v148, v160, v74
	v_mul_f32_e32 v149, v161, v73
	v_mul_f32_e32 v150, v162, v75
	v_mul_f32_e32 v151, v171, v76
	v_mul_f32_e32 v160, v188, v86
	v_mul_f32_e32 v161, v189, v85
	v_mul_f32_e32 v162, v190, v87
	v_mfma_f32_32x32x16_bf16 v[16:31], v[110:113], v[152:155], v[16:31]
	v_mul_f32_e32 v152, v172, v78
	v_mul_f32_e32 v153, v173, v77
	v_mul_f32_e32 v154, v174, v79
	v_mul_f32_e32 v155, v114, v80
	s_waitcnt lgkmcnt(0)
	v_mfma_f32_32x32x16_bf16 v[0:15], v[106:109], v[98:101], v[0:15]
	v_mfma_f32_32x32x16_bf16 v[16:31], v[106:109], v[102:105], v[16:31]
	global_load_dwordx4 v[98:101], v[166:167], off offset:128
	global_load_dwordx4 v[102:105], v[164:165], off offset:128
	ds_read_b128 v[106:109], v191 offset:128
	ds_read_b128 v[114:117], v191 offset:160
	global_load_dwordx4 v[110:113], v[166:167], off offset:160
	s_waitcnt vmcnt(0) lgkmcnt(0)
	v_mfma_f32_32x32x16_bf16 v[0:15], v[106:109], v[98:101], v[0:15]
	global_load_dwordx4 v[98:101], v[164:165], off offset:160
	v_mfma_f32_32x32x16_bf16 v[16:31], v[106:109], v[102:105], v[16:31]
	global_load_dwordx4 v[102:105], v[166:167], off offset:192
	global_load_dwordx4 v[106:109], v[164:165], off offset:192
	v_mfma_f32_32x32x16_bf16 v[0:15], v[114:117], v[110:113], v[0:15]
	ds_read_b128 v[110:113], v191 offset:192
	s_waitcnt vmcnt(0) lgkmcnt(0)
	v_mfma_f32_32x32x16_bf16 v[16:31], v[114:117], v[98:101], v[16:31]
	global_load_dwordx4 v[98:101], v[166:167], off offset:224
	ds_read_b128 v[114:117], v191 offset:224
	v_mfma_f32_32x32x16_bf16 v[0:15], v[110:113], v[102:105], v[0:15]
	global_load_dwordx4 v[102:105], v[164:165], off offset:224
	v_mfma_f32_32x32x16_bf16 v[16:31], v[110:113], v[106:109], v[16:31]
	s_waitcnt vmcnt(0) lgkmcnt(0)
	v_mfma_f32_32x32x16_bf16 v[0:15], v[114:117], v[98:101], v[0:15]
	v_mfma_f32_32x32x16_bf16 v[16:31], v[114:117], v[102:105], v[16:31]
	v_add_u32_e32 v163, 0x6000, v192
	v_add_u32_e32 v164, 0x6400, v192
	v_add_u32_e32 v165, 0x6800, v192
	v_add_u32_e32 v166, 0x6c00, v192
	v_add_u32_e32 v167, 0x8000, v192
	v_add_u32_e32 v168, 0x8400, v192
	v_add_u32_e32 v169, 0x8800, v192
	v_add_u32_e32 v170, 0x8c00, v192
	v_add_u32_e32 v171, 0xa000, v192
	v_add_u32_e32 v172, 0xa400, v192
	v_add_u32_e32 v173, 0xa800, v192
	v_add_u32_e32 v174, 0xac00, v192
	v_add_u32_e32 v175, 0xc200, v192
	v_add_u32_e32 v176, 0xc600, v192
	v_add_u32_e32 v177, 0xca00, v192
	v_add_u32_e32 v178, 0xce00, v192
	ds_write2_b32 v163, v0, v16 offset0:128 offset1:160
	ds_write2_b32 v164, v1, v17 offset0:132 offset1:164
	ds_write2_b32 v165, v2, v18 offset0:136 offset1:168
	ds_write2_b32 v166, v3, v19 offset0:140 offset1:172
	ds_write2_b32 v167, v4, v20 offset0:160 offset1:192
	ds_write2_b32 v168, v5, v21 offset0:164 offset1:196
	ds_write2_b32 v169, v6, v22 offset0:168 offset1:200
	ds_write2_b32 v170, v7, v23 offset0:172 offset1:204
	ds_write2_b32 v171, v8, v24 offset0:192 offset1:224
	ds_write2_b32 v172, v9, v25 offset0:196 offset1:228
	ds_write2_b32 v173, v10, v26 offset0:200 offset1:232
	ds_write2_b32 v174, v11, v27 offset0:204 offset1:236
	ds_write2_b32 v175, v12, v28 offset0:96 offset1:128
	ds_write2_b32 v176, v13, v29 offset0:100 offset1:132
	ds_write2_b32 v177, v14, v30 offset0:104 offset1:136
	ds_write2_b32 v178, v15, v31 offset0:108 offset1:140
	s_waitcnt lgkmcnt(0)
	s_barrier
	ds_read_b128 v[0:3], v118 offset:25088
	ds_read_b128 v[4:7], v118 offset:25104
	s_add_u32 s79, s54, 0x1b0d7900
	s_addc_u32 s80, s55, 0
	s_add_u32 s81, s54, 0x1d4d7900
	s_waitcnt lgkmcnt(1)
	v_and_b32_sdwa v8, v2, v134 dst_sel:DWORD dst_unused:UNUSED_PAD src0_sel:WORD_1 src1_sel:DWORD
	v_and_b32_sdwa v9, v0, v134 dst_sel:DWORD dst_unused:UNUSED_PAD src0_sel:WORD_1 src1_sel:DWORD
	v_add3_u32 v2, v2, v8, s60
	v_and_b32_sdwa v8, v3, v134 dst_sel:DWORD dst_unused:UNUSED_PAD src0_sel:WORD_1 src1_sel:DWORD
	v_add3_u32 v0, v0, v9, s60
	v_and_b32_sdwa v9, v1, v134 dst_sel:DWORD dst_unused:UNUSED_PAD src0_sel:WORD_1 src1_sel:DWORD
	v_add3_u32 v3, v3, v8, s60
	v_add3_u32 v1, v1, v9, s60
	v_and_b32_e32 v3, 0xffff0000, v3
	v_and_b32_e32 v8, 0xffff0000, v1
	v_or_b32_sdwa v1, v3, v2 dst_sel:DWORD dst_unused:UNUSED_PAD src0_sel:DWORD src1_sel:WORD_1
	s_waitcnt lgkmcnt(0)
	v_and_b32_sdwa v2, v6, v134 dst_sel:DWORD dst_unused:UNUSED_PAD src0_sel:WORD_1 src1_sel:DWORD
	v_and_b32_sdwa v3, v4, v134 dst_sel:DWORD dst_unused:UNUSED_PAD src0_sel:WORD_1 src1_sel:DWORD
	v_add3_u32 v4, v4, v3, s60
	v_add3_u32 v2, v6, v2, s60
	v_and_b32_sdwa v3, v7, v134 dst_sel:DWORD dst_unused:UNUSED_PAD src0_sel:WORD_1 src1_sel:DWORD
	v_and_b32_sdwa v6, v5, v134 dst_sel:DWORD dst_unused:UNUSED_PAD src0_sel:WORD_1 src1_sel:DWORD
	v_add3_u32 v3, v7, v3, s60
	v_add3_u32 v5, v5, v6, s60
	v_and_b32_e32 v3, 0xffff0000, v3
	v_and_b32_e32 v5, 0xffff0000, v5
	v_or_b32_sdwa v3, v3, v2 dst_sel:DWORD dst_unused:UNUSED_PAD src0_sel:DWORD src1_sel:WORD_1
	v_or_b32_sdwa v2, v5, v4 dst_sel:DWORD dst_unused:UNUSED_PAD src0_sel:DWORD src1_sel:WORD_1
	v_add_co_u32_e32 v4, vcc, s75, v180
	v_or_b32_sdwa v0, v8, v0 dst_sel:DWORD dst_unused:UNUSED_PAD src0_sel:DWORD src1_sel:WORD_1
	s_nop 0
	v_addc_co_u32_e32 v5, vcc, 0, v181, vcc
	global_store_dwordx4 v[4:5], v[0:3], off offset:2816
	ds_read_b128 v[0:3], v118 offset:26128
	ds_read_b128 v[4:7], v118 offset:26144
	s_addc_u32 s82, s55, 0
	s_add_u32 s83, s54, 0x1738000
	s_addc_u32 s84, s55, 0
	s_waitcnt lgkmcnt(0)
	v_and_b32_sdwa v8, v2, v134 dst_sel:DWORD dst_unused:UNUSED_PAD src0_sel:WORD_1 src1_sel:DWORD
	v_and_b32_sdwa v9, v0, v134 dst_sel:DWORD dst_unused:UNUSED_PAD src0_sel:WORD_1 src1_sel:DWORD
	v_add3_u32 v2, v2, v8, s60
	v_and_b32_sdwa v8, v3, v134 dst_sel:DWORD dst_unused:UNUSED_PAD src0_sel:WORD_1 src1_sel:DWORD
	v_add3_u32 v0, v0, v9, s60
	v_and_b32_sdwa v9, v1, v134 dst_sel:DWORD dst_unused:UNUSED_PAD src0_sel:WORD_1 src1_sel:DWORD
	v_add3_u32 v3, v3, v8, s60
	v_add3_u32 v1, v1, v9, s60
	v_and_b32_e32 v3, 0xffff0000, v3
	v_and_b32_e32 v8, 0xffff0000, v1
	v_or_b32_sdwa v1, v3, v2 dst_sel:DWORD dst_unused:UNUSED_PAD src0_sel:DWORD src1_sel:WORD_1
	v_and_b32_sdwa v2, v6, v134 dst_sel:DWORD dst_unused:UNUSED_PAD src0_sel:WORD_1 src1_sel:DWORD
	v_and_b32_sdwa v3, v4, v134 dst_sel:DWORD dst_unused:UNUSED_PAD src0_sel:WORD_1 src1_sel:DWORD
	v_add3_u32 v4, v4, v3, s60
	v_add3_u32 v2, v6, v2, s60
	v_and_b32_sdwa v3, v7, v134 dst_sel:DWORD dst_unused:UNUSED_PAD src0_sel:WORD_1 src1_sel:DWORD
	v_and_b32_sdwa v6, v5, v134 dst_sel:DWORD dst_unused:UNUSED_PAD src0_sel:WORD_1 src1_sel:DWORD
	v_add3_u32 v3, v7, v3, s60
	v_add3_u32 v5, v5, v6, s60
	v_and_b32_e32 v3, 0xffff0000, v3
	v_and_b32_e32 v5, 0xffff0000, v5
	v_or_b32_sdwa v3, v3, v2 dst_sel:DWORD dst_unused:UNUSED_PAD src0_sel:DWORD src1_sel:WORD_1
	v_or_b32_sdwa v2, v5, v4 dst_sel:DWORD dst_unused:UNUSED_PAD src0_sel:DWORD src1_sel:WORD_1
	v_add_co_u32_e32 v4, vcc, s75, v182
	v_or_b32_sdwa v0, v8, v0 dst_sel:DWORD dst_unused:UNUSED_PAD src0_sel:DWORD src1_sel:WORD_1
	s_nop 0
	v_addc_co_u32_e32 v5, vcc, 0, v183, vcc
	global_store_dwordx4 v[4:5], v[0:3], off offset:2816
	ds_read_b128 v[0:3], v118 offset:27168
	ds_read_b128 v[4:7], v118 offset:27184
	v_lshl_add_u64 v[88:89], v[88:89], 0, s[50:51]
	s_mov_b64 s[8:9], -1
	s_waitcnt lgkmcnt(0)
	v_and_b32_sdwa v8, v2, v134 dst_sel:DWORD dst_unused:UNUSED_PAD src0_sel:WORD_1 src1_sel:DWORD
	v_and_b32_sdwa v9, v0, v134 dst_sel:DWORD dst_unused:UNUSED_PAD src0_sel:WORD_1 src1_sel:DWORD
	v_add3_u32 v2, v2, v8, s60
	v_and_b32_sdwa v8, v3, v134 dst_sel:DWORD dst_unused:UNUSED_PAD src0_sel:WORD_1 src1_sel:DWORD
	v_add3_u32 v0, v0, v9, s60
	v_and_b32_sdwa v9, v1, v134 dst_sel:DWORD dst_unused:UNUSED_PAD src0_sel:WORD_1 src1_sel:DWORD
	v_add3_u32 v3, v3, v8, s60
	v_add3_u32 v1, v1, v9, s60
	v_and_b32_e32 v3, 0xffff0000, v3
	v_and_b32_e32 v8, 0xffff0000, v1
	v_or_b32_sdwa v1, v3, v2 dst_sel:DWORD dst_unused:UNUSED_PAD src0_sel:DWORD src1_sel:WORD_1
	v_and_b32_sdwa v2, v6, v134 dst_sel:DWORD dst_unused:UNUSED_PAD src0_sel:WORD_1 src1_sel:DWORD
	v_and_b32_sdwa v3, v4, v134 dst_sel:DWORD dst_unused:UNUSED_PAD src0_sel:WORD_1 src1_sel:DWORD
	v_add3_u32 v4, v4, v3, s60
	v_add3_u32 v2, v6, v2, s60
	v_and_b32_sdwa v3, v7, v134 dst_sel:DWORD dst_unused:UNUSED_PAD src0_sel:WORD_1 src1_sel:DWORD
	v_and_b32_sdwa v6, v5, v134 dst_sel:DWORD dst_unused:UNUSED_PAD src0_sel:WORD_1 src1_sel:DWORD
	v_add3_u32 v3, v7, v3, s60
	v_add3_u32 v5, v5, v6, s60
	v_and_b32_e32 v3, 0xffff0000, v3
	v_and_b32_e32 v5, 0xffff0000, v5
	v_or_b32_sdwa v3, v3, v2 dst_sel:DWORD dst_unused:UNUSED_PAD src0_sel:DWORD src1_sel:WORD_1
	v_or_b32_sdwa v2, v5, v4 dst_sel:DWORD dst_unused:UNUSED_PAD src0_sel:DWORD src1_sel:WORD_1
	v_add_co_u32_e32 v4, vcc, s75, v36
	v_or_b32_sdwa v0, v8, v0 dst_sel:DWORD dst_unused:UNUSED_PAD src0_sel:DWORD src1_sel:WORD_1
	s_nop 0
	v_addc_co_u32_e32 v5, vcc, 0, v37, vcc
	global_store_dwordx4 v[4:5], v[0:3], off offset:2816
	ds_read_b128 v[0:3], v119 offset:25088
	ds_read_b128 v[4:7], v119 offset:25104
	s_waitcnt lgkmcnt(0)
	v_and_b32_sdwa v8, v2, v134 dst_sel:DWORD dst_unused:UNUSED_PAD src0_sel:WORD_1 src1_sel:DWORD
	v_and_b32_sdwa v9, v0, v134 dst_sel:DWORD dst_unused:UNUSED_PAD src0_sel:WORD_1 src1_sel:DWORD
	v_add3_u32 v2, v2, v8, s60
	v_and_b32_sdwa v8, v3, v134 dst_sel:DWORD dst_unused:UNUSED_PAD src0_sel:WORD_1 src1_sel:DWORD
	v_add3_u32 v0, v0, v9, s60
	v_and_b32_sdwa v9, v1, v134 dst_sel:DWORD dst_unused:UNUSED_PAD src0_sel:WORD_1 src1_sel:DWORD
	v_add3_u32 v3, v3, v8, s60
	v_add3_u32 v1, v1, v9, s60
	v_and_b32_e32 v3, 0xffff0000, v3
	v_and_b32_e32 v8, 0xffff0000, v1
	v_or_b32_sdwa v1, v3, v2 dst_sel:DWORD dst_unused:UNUSED_PAD src0_sel:DWORD src1_sel:WORD_1
	v_and_b32_sdwa v2, v6, v134 dst_sel:DWORD dst_unused:UNUSED_PAD src0_sel:WORD_1 src1_sel:DWORD
	v_and_b32_sdwa v3, v4, v134 dst_sel:DWORD dst_unused:UNUSED_PAD src0_sel:WORD_1 src1_sel:DWORD
	v_add3_u32 v4, v4, v3, s60
	v_add3_u32 v2, v6, v2, s60
	v_and_b32_sdwa v3, v7, v134 dst_sel:DWORD dst_unused:UNUSED_PAD src0_sel:WORD_1 src1_sel:DWORD
	v_and_b32_sdwa v6, v5, v134 dst_sel:DWORD dst_unused:UNUSED_PAD src0_sel:WORD_1 src1_sel:DWORD
	v_add3_u32 v3, v7, v3, s60
	v_add3_u32 v5, v5, v6, s60
	v_and_b32_e32 v3, 0xffff0000, v3
	v_and_b32_e32 v5, 0xffff0000, v5
	v_or_b32_sdwa v3, v3, v2 dst_sel:DWORD dst_unused:UNUSED_PAD src0_sel:DWORD src1_sel:WORD_1
	v_or_b32_sdwa v2, v5, v4 dst_sel:DWORD dst_unused:UNUSED_PAD src0_sel:DWORD src1_sel:WORD_1
	v_add_co_u32_e32 v4, vcc, s75, v34
	v_or_b32_sdwa v0, v8, v0 dst_sel:DWORD dst_unused:UNUSED_PAD src0_sel:DWORD src1_sel:WORD_1
	s_nop 0
	v_addc_co_u32_e32 v5, vcc, 0, v35, vcc
	global_store_dwordx4 v[4:5], v[0:3], off offset:2816
	s_waitcnt lgkmcnt(0)
	s_barrier
	global_load_dwordx2 v[0:1], v[32:33], off offset:456
	v_and_b32_e32 v8, 7, v135
	v_lshlrev_b64 v[2:3], 8, v[92:93]
	v_lshlrev_b64 v[4:5], 8, v[94:95]
	v_lshlrev_b64 v[6:7], 8, v[96:97]
	v_cmp_eq_u32_e64 s[4:5], 0, v8
	v_or_b32_e32 v2, v2, v126
	v_or_b32_e32 v4, v4, v126
	v_or_b32_e32 v6, v6, v126
	v_lshlrev_b64 v[92:93], 4, v[92:93]
	v_lshlrev_b64 v[94:95], 4, v[94:95]
	v_lshlrev_b64 v[96:97], 4, v[96:97]
	v_lshlrev_b64 v[104:105], 1, v[2:3]
	v_lshlrev_b64 v[106:107], 1, v[4:5]
	v_lshlrev_b64 v[108:109], 1, v[6:7]
	s_waitcnt vmcnt(0) lgkmcnt(0)
	v_readfirstlane_b32 s1, v1
	v_readfirstlane_b32 s0, v0
	s_nop 1
	v_lshl_add_u64 v[0:1], s[0:1], 0, v[64:65]
	global_load_dwordx4 v[30:33], v[0:1], off offset:1024
	global_load_dwordx4 v[34:37], v[0:1], off offset:1040
	s_add_u32 s0, s54, 0x2954198
	s_addc_u32 s1, s55, 0
	s_add_u32 s85, s54, 0x1748000
	v_lshlrev_b64 v[0:1], 8, v[90:91]
	s_addc_u32 s86, s55, 0
	v_bfe_u32 v64, v135, 1, 4
	v_or_b32_e32 v0, v0, v126
	s_add_u32 s6, s54, 0x29541a8
	v_lshl_add_u64 v[8:9], s[54:55], 0, v[64:65]
	v_lshlrev_b64 v[90:91], 4, v[90:91]
	s_addc_u32 s7, s55, 0
	v_lshl_add_u64 v[98:99], v[8:9], 0, s[52:53]
	v_lshlrev_b32_e32 v64, 2, v126
	s_waitcnt vmcnt(0) lgkmcnt(0)
	v_mov_b32_e32 v100, v30
	v_mov_b32_e32 v101, v32
	v_mov_b32_e32 v32, v31
	v_mov_b32_e32 v102, v34
	v_mov_b32_e32 v103, v36
	v_mov_b32_e32 v36, v35
	v_lshlrev_b64 v[34:35], 1, v[0:1]
	s_branch .LBB0_1409

.LBB0_1593:
	s_or_b64 exec, exec, s[6:7]
	v_cvt_pk_bf16_f32 v12, v12, v11
	v_bfe_u32 v3, v4, 16, 1
	v_add3_u32 v3, v4, v3, s61
	v_bfe_u32 v4, v0, 16, 1
	v_lshrrev_b32_e32 v3, 16, v3
	v_add3_u32 v0, v0, v4, s61
	v_and_or_b32 v13, v0, s65, v3
	v_cvt_pk_bf16_f32 v14, v5, v1
	v_cvt_pk_bf16_f32 v15, v6, v2
	v_lshl_or_b32 v0, v10, 9, v36
	ds_write_b128 v0, v[12:15]

.LBB0_1612:
	s_or_b64 exec, exec, s[6:7]
	v_cvt_pk_bf16_f32 v12, v13, v12
	v_bfe_u32 v3, v4, 16, 1
	v_add3_u32 v3, v4, v3, s61
	v_bfe_u32 v4, v0, 16, 1
	v_lshrrev_b32_e32 v3, 16, v3
	v_add3_u32 v0, v0, v4, s61
	v_and_or_b32 v13, v0, s65, v3
	v_cvt_pk_bf16_f32 v14, v5, v1
	v_cvt_pk_bf16_f32 v15, v6, v2
	v_lshl_or_b32 v0, v11, 9, v36
	ds_write_b128 v0, v[12:15]

.LBB0_1667:
	v_add_u32_e32 v35, s0, v24
	v_add_u32_e32 v37, s0, v25
	ds_read_b128 v[50:53], v35
	ds_read_b128 v[54:57], v37
	s_addk_i32 s0, 0x200
	s_cmpk_lg_i32 s0, 0x3e00
	s_waitcnt lgkmcnt(1)
	v_lshlrev_b32_e32 v75, 16, v51
	v_lshlrev_b32_e32 v74, 16, v50
	s_waitcnt lgkmcnt(0)
	v_lshlrev_b32_e32 v77, 16, v55
	v_lshlrev_b32_e32 v76, 16, v54
	v_and_b32_e32 v51, 0xffff0000, v51
	v_and_b32_e32 v50, 0xffff0000, v50
	v_and_b32_e32 v55, 0xffff0000, v55
	v_and_b32_e32 v54, 0xffff0000, v54
	v_lshlrev_b32_e32 v79, 16, v53
	v_lshlrev_b32_e32 v78, 16, v52
	v_lshlrev_b32_e32 v81, 16, v57
	v_lshlrev_b32_e32 v80, 16, v56
	v_and_b32_e32 v53, 0xffff0000, v53
	v_and_b32_e32 v52, 0xffff0000, v52
	v_and_b32_e32 v57, 0xffff0000, v57
	v_and_b32_e32 v56, 0xffff0000, v56
	v_pk_fma_f32 v[68:69], v[8:9], v[76:77], v[68:69]
	v_pk_fma_f32 v[64:65], v[12:13], v[54:55], v[64:65]
	v_pk_fma_f32 v[60:61], v[16:17], v[80:81], v[60:61]
	v_pk_fma_f32 v[58:59], v[22:23], v[56:57], v[58:59]
	v_pk_fma_f32 v[72:73], v[0:1], v[76:77], v[72:73]
	v_pk_fma_f32 v[70:71], v[4:5], v[54:55], v[70:71]
	v_pk_fma_f32 v[66:67], v[10:11], v[80:81], v[66:67]
	v_pk_fma_f32 v[62:63], v[18:19], v[56:57], v[62:63]
	v_pk_fma_f32 v[48:49], v[2:3], v[76:77], v[48:49]
	v_pk_fma_f32 v[46:47], v[6:7], v[54:55], v[46:47]
	v_pk_fma_f32 v[44:45], v[14:15], v[80:81], v[44:45]
	v_pk_fma_f32 v[42:43], v[20:21], v[56:57], v[42:43]
	v_pk_fma_f32 v[40:41], v[74:75], v[76:77], v[40:41]
	v_pk_fma_f32 v[30:31], v[50:51], v[54:55], v[30:31]
	v_pk_fma_f32 v[28:29], v[78:79], v[80:81], v[28:29]
	v_pk_fma_f32 v[26:27], v[52:53], v[56:57], v[26:27]
	v_mov_b64_e32 v[22:23], v[18:19]
	v_mov_b64_e32 v[18:19], v[20:21]
	v_mov_b64_e32 v[20:21], v[52:53]
	v_mov_b64_e32 v[16:17], v[10:11]
	v_mov_b64_e32 v[10:11], v[14:15]
	v_mov_b64_e32 v[14:15], v[78:79]
	v_mov_b64_e32 v[12:13], v[4:5]
	v_mov_b64_e32 v[4:5], v[6:7]
	v_mov_b64_e32 v[6:7], v[50:51]
	v_mov_b64_e32 v[8:9], v[0:1]
	v_mov_b64_e32 v[0:1], v[2:3]
	v_mov_b64_e32 v[2:3], v[74:75]
	s_cbranch_scc1 .LBB0_1667
	v_mov_b32_e32 v0, s8
	v_add_co_u32_e32 v4, vcc, 0x2954000, v0
	v_mov_b32_e32 v0, s9
	s_nop 0
	v_addc_co_u32_e32 v5, vcc, 0, v0, vcc
	global_load_dwordx4 v[0:3], v[4:5], off offset:344
	s_nop 0
	global_load_dwordx2 v[4:5], v[4:5], off offset:360
	v_lshlrev_b32_e32 v116, 2, v38
	v_mov_b64_e32 v[52:53], s[22:23]
	s_waitcnt vmcnt(0) lgkmcnt(0)
	v_readfirstlane_b32 s1, v1
	v_readfirstlane_b32 s0, v0
	v_readfirstlane_b32 s5, v3
	v_readfirstlane_b32 s4, v2
	v_lshl_add_u64 v[0:1], s[0:1], 0, v[116:117]
	global_load_dwordx4 v[16:19], v[0:1], off offset:1024
	v_readfirstlane_b32 s7, v5
	v_readfirstlane_b32 s6, v4
	v_lshl_add_u64 v[2:3], s[4:5], 0, v[116:117]
	global_load_dwordx4 v[8:11], v[2:3], off offset:1024
	v_lshl_add_u64 v[4:5], s[6:7], 0, v[116:117]
	global_load_dwordx4 v[12:15], v[4:5], off offset:1024
	global_load_dwordx4 v[20:23], v[0:1], off offset:1040
	s_nop 0
	global_load_dwordx4 v[0:3], v[2:3], off offset:1040
	s_nop 0
	global_load_dwordx4 v[4:7], v[4:5], off offset:1040
	v_mad_u64_u32 v[24:25], s[0:1], v33, s66, v[36:37]
	s_waitcnt lgkmcnt(0)
	s_barrier
	s_waitcnt vmcnt(0)
	v_mov_b32_e32 v54, v16
	v_mov_b32_e32 v55, v18
	v_mov_b32_e32 v18, v17
	v_pk_add_f32 v[74:75], v[72:73], v[54:55]
	v_mov_b32_e32 v56, v20
	v_mov_b32_e32 v57, v22
	v_mov_b32_e32 v22, v21
	v_pk_add_f32 v[20:21], v[68:69], v[54:55]
	v_mov_b32_e32 v16, v8
	v_mov_b32_e32 v17, v10
	v_mov_b32_e32 v10, v9
	v_mov_b32_e32 v8, v0
	v_mov_b32_e32 v9, v2
	v_pk_add_f32 v[64:65], v[64:65], v[18:19]
	v_pk_add_f32 v[76:77], v[70:71], v[18:19]
	v_add_f32_e32 v0, 0, v20
	v_add_f32_e32 v2, 0, v74
	v_add_f32_e32 v0, v0, v64
	v_add_f32_e32 v2, v2, v76
	v_add_f32_e32 v0, v0, v21
	v_add_f32_e32 v2, v2, v75
	v_pk_add_f32 v[60:61], v[60:61], v[56:57]
	v_pk_add_f32 v[78:79], v[66:67], v[56:57]
	v_add_f32_e32 v0, v0, v65
	v_add_f32_e32 v2, v2, v77
	v_pk_add_f32 v[58:59], v[58:59], v[22:23]
	v_pk_add_f32 v[80:81], v[62:63], v[22:23]
	v_add_f32_e32 v0, v0, v60
	v_add_f32_e32 v2, v2, v78
	v_add_f32_e32 v0, v0, v58
	v_add_f32_e32 v2, v2, v80
	v_add_f32_e32 v0, v0, v61
	v_add_f32_e32 v2, v2, v79
	v_add_f32_e32 v0, v0, v59
	v_add_f32_e32 v2, v2, v81
	v_mov_b32_e32 v50, v12
	v_add_f32_dpp v0, v0, v0 quad_perm:[1,0,3,2] row_mask:0xf bank_mask:0xf bound_ctrl:1
	v_add_f32_dpp v2, v2, v2 quad_perm:[1,0,3,2] row_mask:0xf bank_mask:0xf bound_ctrl:1
	v_mov_b32_e32 v12, v4
	v_add_f32_dpp v0, v0, v0 quad_perm:[2,3,0,1] row_mask:0xf bank_mask:0xf bound_ctrl:1
	v_add_f32_dpp v2, v2, v2 quad_perm:[2,3,0,1] row_mask:0xf bank_mask:0xf bound_ctrl:1
	v_mov_b32_e32 v51, v14
	v_add_f32_dpp v0, v0, v0 row_half_mirror row_mask:0xf bank_mask:0xf bound_ctrl:1
	v_add_f32_dpp v2, v2, v2 row_half_mirror row_mask:0xf bank_mask:0xf bound_ctrl:1
	v_mul_f32_e32 v0, 0x3c800000, v0
	v_mul_f32_e32 v2, 0x3c800000, v2
	v_pk_add_f32 v[72:73], v[20:21], v[0:1] op_sel_hi:[1,0] neg_lo:[0,1] neg_hi:[0,1]
	v_pk_add_f32 v[70:71], v[64:65], v[0:1] op_sel_hi:[1,0] neg_lo:[0,1] neg_hi:[0,1]
	v_pk_add_f32 v[68:69], v[60:61], v[0:1] op_sel_hi:[1,0] neg_lo:[0,1] neg_hi:[0,1]
	v_pk_add_f32 v[62:63], v[74:75], v[2:3] op_sel_hi:[1,0] neg_lo:[0,1] neg_hi:[0,1]
	v_pk_add_f32 v[60:61], v[76:77], v[2:3] op_sel_hi:[1,0] neg_lo:[0,1] neg_hi:[0,1]
	v_pk_add_f32 v[20:21], v[80:81], v[2:3] op_sel_hi:[1,0] neg_lo:[0,1] neg_hi:[0,1]
	v_mov_b32_e32 v64, v72
	v_mov_b32_e32 v65, v70
	v_mov_b32_e32 v80, v62
	v_mov_b32_e32 v81, v60
	v_mov_b32_e32 v74, v71
	v_mov_b32_e32 v75, v73
	v_mov_b32_e32 v82, v61
	v_mov_b32_e32 v83, v63
	v_pk_mul_f32 v[64:65], v[64:65], v[64:65]
	v_pk_mul_f32 v[80:81], v[80:81], v[80:81]
	v_pk_add_f32 v[66:67], v[58:59], v[0:1] op_sel_hi:[1,0] neg_lo:[0,1] neg_hi:[0,1]
	v_pk_add_f32 v[58:59], v[78:79], v[2:3] op_sel_hi:[1,0] neg_lo:[0,1] neg_hi:[0,1]
	v_pk_mul_f32 v[74:75], v[74:75], v[74:75]
	v_pk_mul_f32 v[82:83], v[82:83], v[82:83]
	v_mov_b32_e32 v88, v80
	v_mov_b32_e32 v89, v64
	v_mov_b32_e32 v64, v81
	v_mov_b32_e32 v76, v66
	v_mov_b32_e32 v77, v68
	v_mov_b32_e32 v84, v20
	v_mov_b32_e32 v85, v58
	v_mov_b32_e32 v80, v83
	v_mov_b32_e32 v81, v75
	v_pk_add_f32 v[64:65], v[88:89], v[64:65]
	v_pk_mul_f32 v[76:77], v[76:77], v[76:77]
	v_pk_mul_f32 v[84:85], v[84:85], v[84:85]
	v_mov_b32_e32 v83, v74
	v_pk_add_f32 v[64:65], v[80:81], v[64:65]
	v_mov_b32_e32 v78, v67
	v_mov_b32_e32 v79, v69
	v_mov_b32_e32 v86, v21
	v_mov_b32_e32 v87, v59
	v_mov_b32_e32 v74, v85
	v_mov_b32_e32 v75, v77
	v_pk_add_f32 v[64:65], v[82:83], v[64:65]
	v_pk_mul_f32 v[78:79], v[78:79], v[78:79]
	v_pk_mul_f32 v[86:87], v[86:87], v[86:87]
	v_mov_b32_e32 v85, v76
	v_pk_add_f32 v[64:65], v[74:75], v[64:65]
	v_mov_b32_e32 v76, v87
	v_mov_b32_e32 v77, v79
	v_pk_add_f32 v[64:65], v[84:85], v[64:65]
	v_mov_b32_e32 v87, v78
	v_pk_add_f32 v[64:65], v[76:77], v[64:65]
	v_mov_b32_e32 v2, v1
	v_pk_add_f32 v[64:65], v[86:87], v[64:65]
	v_mov_b32_e32 v14, v13
	v_mov_b32_e32 v13, v6
	v_mov_b32_dpp v75, v65 quad_perm:[1,0,3,2] row_mask:0xf bank_mask:0xf bound_ctrl:1
	v_mov_b32_dpp v74, v64 quad_perm:[1,0,3,2] row_mask:0xf bank_mask:0xf bound_ctrl:1
	v_pk_add_f32 v[64:65], v[64:65], v[74:75]
	v_mov_b32_e32 v6, v5
	v_pk_add_f32 v[42:43], v[42:43], v[22:23]
	v_mov_b32_dpp v75, v65 quad_perm:[2,3,0,1] row_mask:0xf bank_mask:0xf bound_ctrl:1
	v_mov_b32_dpp v74, v64 quad_perm:[2,3,0,1] row_mask:0xf bank_mask:0xf bound_ctrl:1
	v_pk_add_f32 v[64:65], v[64:65], v[74:75]
	v_pk_add_f32 v[28:29], v[28:29], v[56:57]
	v_pk_add_f32 v[22:23], v[26:27], v[22:23]
	v_mov_b32_dpp v75, v65 row_half_mirror row_mask:0xf bank_mask:0xf bound_ctrl:1
	v_mov_b32_dpp v74, v64 row_half_mirror row_mask:0xf bank_mask:0xf bound_ctrl:1
	v_pk_add_f32 v[64:65], v[64:65], v[74:75]
	s_nop 0
	v_pk_fma_f32 v[64:65], v[64:65], s[20:21], v[52:53] op_sel_hi:[1,0,0]
	s_nop 0
	v_mul_f32_e32 v0, 0x4b800000, v65
	v_cmp_gt_f32_e32 vcc, s67, v65
	s_nop 1
	v_cndmask_b32_e32 v0, v65, v0, vcc
	v_rsq_f32_e32 v0, v0
	s_nop 0
	v_mul_f32_e32 v1, 0x45800000, v0
	v_cndmask_b32_e32 v4, v0, v1, vcc
	v_pk_mul_f32 v[0:1], v[72:73], v[4:5] op_sel_hi:[1,0]
	v_pk_mul_f32 v[70:71], v[70:71], v[4:5] op_sel_hi:[1,0]
	v_pk_fma_f32 v[72:73], v[16:17], v[0:1], v[50:51]
	v_pk_mul_f32 v[68:69], v[68:69], v[4:5] op_sel_hi:[1,0]
	v_mul_f32_e32 v5, 0xbfb8aa3b, v72
	v_mul_f32_e32 v35, 0xbfb8aa3b, v73
	v_pk_fma_f32 v[70:71], v[10:11], v[70:71], v[14:15]
	v_pk_fma_f32 v[0:1], v[8:9], v[68:69], v[12:13]
	v_exp_f32_e32 v68, v5
	v_exp_f32_e32 v69, v35
	v_mul_f32_e32 v25, 0xbfb8aa3b, v70
	v_mul_f32_e32 v37, 0xbfb8aa3b, v71
	v_exp_f32_e32 v74, v25
	v_exp_f32_e32 v75, v37
	v_pk_mul_f32 v[78:79], v[66:67], v[4:5] op_sel_hi:[1,0]
	v_pk_add_f32 v[4:5], v[68:69], 1.0 op_sel_hi:[1,0]
	v_mul_f32_e32 v65, 0xbfb8aa3b, v1
	v_div_scale_f32 v25, s[0:1], v5, v5, 1.0
	v_pk_add_f32 v[68:69], v[74:75], 1.0 op_sel_hi:[1,0]
	v_div_scale_f32 v37, s[0:1], v4, v4, 1.0
	v_rcp_f32_e32 v80, v25
	v_exp_f32_e32 v77, v65
	v_div_scale_f32 v65, s[4:5], v69, v69, 1.0
	v_rcp_f32_e32 v81, v37
	v_div_scale_f32 v75, s[6:7], v68, v68, 1.0
	v_rcp_f32_e32 v82, v65
	v_mul_f32_e32 v39, 0xbfb8aa3b, v0
	v_rcp_f32_e32 v83, v75
	v_exp_f32_e32 v76, v39
	v_fma_f32 v84, -v25, v80, 1.0
	v_div_scale_f32 v35, vcc, 1.0, v5, 1.0
	v_fma_f32 v85, -v37, v81, 1.0
	v_fmac_f32_e32 v80, v84, v80
	v_div_scale_f32 v39, s[0:1], 1.0, v4, 1.0
	v_fma_f32 v86, -v65, v82, 1.0
	v_fmac_f32_e32 v81, v85, v81
	v_mul_f32_e32 v84, v35, v80
	v_div_scale_f32 v74, s[4:5], 1.0, v69, 1.0
	v_fma_f32 v87, -v75, v83, 1.0
	v_fmac_f32_e32 v82, v86, v82
	v_mul_f32_e32 v85, v39, v81
	v_fma_f32 v88, -v25, v84, v35
	v_pk_add_f32 v[66:67], v[76:77], 1.0 op_sel_hi:[1,0]
	v_div_scale_f32 v76, s[6:7], 1.0, v68, 1.0
	v_fmac_f32_e32 v83, v87, v83
	v_mul_f32_e32 v86, v74, v82
	v_fma_f32 v89, -v37, v85, v39
	v_fmac_f32_e32 v84, v88, v80
	v_mul_f32_e32 v87, v76, v83
	v_fma_f32 v90, -v65, v86, v74
	v_fmac_f32_e32 v85, v89, v81
	v_fma_f32 v25, -v25, v84, v35
	v_fma_f32 v91, -v75, v87, v76
	v_fmac_f32_e32 v86, v90, v82
	v_fma_f32 v35, -v37, v85, v39
	v_div_fmas_f32 v25, v25, v80, v84
	s_mov_b64 vcc, s[0:1]
	v_fmac_f32_e32 v87, v91, v83
	v_fma_f32 v37, -v65, v86, v74
	v_div_fixup_f32 v5, v25, v5, 1.0
	v_div_fmas_f32 v25, v35, v81, v85
	s_mov_b64 vcc, s[4:5]
	v_fma_f32 v39, -v75, v87, v76
	v_div_fixup_f32 v4, v25, v4, 1.0
	v_div_fmas_f32 v25, v37, v82, v86
	s_mov_b64 vcc, s[6:7]
	v_div_scale_f32 v77, s[24:25], v67, v67, 1.0
	v_div_fixup_f32 v69, v25, v69, 1.0
	v_div_fmas_f32 v25, v39, v83, v87
	v_div_fixup_f32 v68, v25, v68, 1.0
	v_rcp_f32_e32 v25, v77
	v_pk_mul_f32 v[68:69], v[70:71], v[68:69]
	v_pk_fma_f32 v[70:71], v[2:3], v[78:79], v[6:7]
	v_pk_mul_f32 v[4:5], v[72:73], v[4:5]
	v_mul_f32_e32 v35, 0xbfb8aa3b, v70
	v_exp_f32_e32 v72, v35
	v_fma_f32 v35, -v77, v25, 1.0
	v_fmac_f32_e32 v25, v35, v25
	v_div_scale_f32 v35, vcc, 1.0, v67, 1.0
	v_mul_f32_e32 v37, v35, v25
	v_fma_f32 v39, -v77, v37, v35
	v_fmac_f32_e32 v37, v39, v25
	v_div_scale_f32 v39, s[0:1], v66, v66, 1.0
	v_rcp_f32_e32 v65, v39
	v_fma_f32 v35, -v77, v37, v35
	v_div_fmas_f32 v25, v35, v25, v37
	v_mul_f32_e32 v37, 0xbfb8aa3b, v71
	v_exp_f32_e32 v73, v37
	v_div_fixup_f32 v67, v25, v67, 1.0
	v_fma_f32 v25, -v39, v65, 1.0
	v_fmac_f32_e32 v65, v25, v65
	v_div_scale_f32 v25, vcc, 1.0, v66, 1.0
	v_mul_f32_e32 v35, v25, v65
	v_fma_f32 v37, -v39, v35, v25
	v_pk_add_f32 v[72:73], v[72:73], 1.0 op_sel_hi:[1,0]
	v_fmac_f32_e32 v35, v37, v65
	v_div_scale_f32 v37, s[0:1], v73, v73, 1.0
	v_fma_f32 v25, -v39, v35, v25
	v_rcp_f32_e32 v39, v37
	v_div_fmas_f32 v25, v25, v65, v35
	v_div_fixup_f32 v66, v25, v66, 1.0
	v_pk_mul_f32 v[0:1], v[0:1], v[66:67]
	v_fma_f32 v25, -v37, v39, 1.0
	v_fmac_f32_e32 v39, v25, v39
	v_div_scale_f32 v25, vcc, 1.0, v73, 1.0
	v_mul_f32_e32 v35, v25, v39
	v_fma_f32 v65, -v37, v35, v25
	v_fmac_f32_e32 v35, v65, v39
	v_fma_f32 v25, -v37, v35, v25
	v_div_scale_f32 v37, s[0:1], v72, v72, 1.0
	v_rcp_f32_e32 v65, v37
	v_div_fmas_f32 v25, v25, v39, v35
	v_div_fixup_f32 v67, v25, v73, 1.0
	v_fma_f32 v25, -v37, v65, 1.0
	v_fmac_f32_e32 v65, v25, v65
	v_div_scale_f32 v25, vcc, 1.0, v72, 1.0
	v_mul_f32_e32 v35, v25, v65
	v_fma_f32 v39, -v37, v35, v25
	v_fmac_f32_e32 v35, v39, v65
	v_fma_f32 v25, -v37, v35, v25
	v_div_fmas_f32 v25, v25, v65, v35
	v_div_fixup_f32 v66, v25, v72, 1.0
	v_pk_mul_f32 v[66:67], v[70:71], v[66:67]
	v_bfe_u32 v39, v68, 16, 1
	v_bfe_u32 v35, v66, 16, 1
	v_add3_u32 v35, v66, v35, s61
	v_bfe_u32 v65, v4, 16, 1
	v_bfe_u32 v66, v5, 16, 1
	v_add3_u32 v39, v68, v39, s61
	v_bfe_u32 v68, v1, 16, 1
	v_add3_u32 v5, v5, v66, s61
	v_add3_u32 v4, v4, v65, s61
	v_add3_u32 v1, v1, v68, s61
	v_lshrrev_b32_e32 v68, 16, v4
	v_lshrrev_b32_e32 v4, 16, v5
	v_mul_f32_e32 v5, 0x4b800000, v64
	v_cmp_gt_f32_e32 vcc, s67, v64
	v_bfe_u32 v25, v67, 16, 1
	v_add3_u32 v25, v67, v25, s61
	v_cndmask_b32_e32 v5, v64, v5, vcc
	v_rsq_f32_e32 v5, v5
	v_bfe_u32 v67, v0, 16, 1
	v_add3_u32 v0, v0, v67, s61
	v_bfe_u32 v37, v69, 16, 1
	v_lshrrev_b32_e32 v0, 16, v0
	v_add3_u32 v37, v69, v37, s61
	v_and_or_b32 v66, v35, s65, v0
	v_mul_f32_e32 v0, 0x45800000, v5
	v_lshrrev_b32_e32 v1, 16, v1
	v_and_or_b32 v65, v37, s65, v4
	v_cndmask_b32_e32 v4, v5, v0, vcc
	v_and_or_b32 v67, v25, s65, v1
	v_pk_mul_f32 v[0:1], v[62:63], v[4:5] op_sel_hi:[1,0]
	v_and_or_b32 v64, v39, s65, v68
	v_pk_fma_f32 v[0:1], v[16:17], v[0:1], v[50:51]
	ds_write_b128 v24, v[64:67]
	v_mul_f32_e32 v5, 0xbfb8aa3b, v0
	v_exp_f32_e32 v62, v5
	v_mul_f32_e32 v5, 0xbfb8aa3b, v1
	v_exp_f32_e32 v63, v5
	v_pk_mul_f32 v[60:61], v[60:61], v[4:5] op_sel_hi:[1,0]
	v_pk_add_f32 v[62:63], v[62:63], 1.0 op_sel_hi:[1,0]
	s_nop 0
	v_div_scale_f32 v5, s[0:1], v63, v63, 1.0
	v_rcp_f32_e32 v25, v5
	v_pk_fma_f32 v[60:61], v[10:11], v[60:61], v[14:15]
	s_nop 0
	v_mul_f32_e32 v35, 0xbfb8aa3b, v60
	v_exp_f32_e32 v64, v35
	v_fma_f32 v35, -v5, v25, 1.0
	v_fmac_f32_e32 v25, v35, v25
	v_div_scale_f32 v35, vcc, 1.0, v63, 1.0
	v_mul_f32_e32 v37, v35, v25
	v_fma_f32 v39, -v5, v37, v35
	v_fmac_f32_e32 v37, v39, v25
	v_fma_f32 v5, -v5, v37, v35
	v_div_scale_f32 v35, s[0:1], v62, v62, 1.0
	v_rcp_f32_e32 v39, v35
	v_div_fmas_f32 v5, v5, v25, v37
	v_mul_f32_e32 v37, 0xbfb8aa3b, v61
	v_div_fixup_f32 v63, v5, v63, 1.0
	v_fma_f32 v5, -v35, v39, 1.0
	v_exp_f32_e32 v65, v37
	v_fmac_f32_e32 v39, v5, v39
	v_div_scale_f32 v5, vcc, 1.0, v62, 1.0
	v_mul_f32_e32 v25, v5, v39
	v_fma_f32 v37, -v35, v25, v5
	v_fmac_f32_e32 v25, v37, v39
	v_pk_add_f32 v[64:65], v[64:65], 1.0 op_sel_hi:[1,0]
	v_fma_f32 v5, -v35, v25, v5
	v_div_scale_f32 v35, s[0:1], v65, v65, 1.0
	v_rcp_f32_e32 v37, v35
	v_div_fmas_f32 v5, v5, v39, v25
	v_div_fixup_f32 v62, v5, v62, 1.0
	v_pk_mul_f32 v[0:1], v[0:1], v[62:63]
	v_fma_f32 v5, -v35, v37, 1.0
	v_fmac_f32_e32 v37, v5, v37
	v_div_scale_f32 v5, vcc, 1.0, v65, 1.0
	v_mul_f32_e32 v25, v5, v37
	v_fma_f32 v39, -v35, v25, v5
	v_fmac_f32_e32 v25, v39, v37
	v_fma_f32 v5, -v35, v25, v5
	v_div_scale_f32 v35, s[0:1], v64, v64, 1.0
	v_rcp_f32_e32 v39, v35
	v_div_fmas_f32 v5, v5, v37, v25
	v_div_fixup_f32 v63, v5, v65, 1.0
	v_fma_f32 v5, -v35, v39, 1.0
	v_fmac_f32_e32 v39, v5, v39
	v_div_scale_f32 v5, vcc, 1.0, v64, 1.0
	v_mul_f32_e32 v25, v5, v39
	v_fma_f32 v37, -v35, v25, v5
	v_fmac_f32_e32 v25, v37, v39
	v_fma_f32 v5, -v35, v25, v5
	v_div_fmas_f32 v5, v5, v39, v25
	v_pk_mul_f32 v[58:59], v[58:59], v[4:5] op_sel_hi:[1,0]
	v_div_fixup_f32 v62, v5, v64, 1.0
	v_pk_fma_f32 v[58:59], v[8:9], v[58:59], v[12:13]
	v_pk_mul_f32 v[4:5], v[20:21], v[4:5] op_sel_hi:[1,0]
	v_mul_f32_e32 v25, 0xbfb8aa3b, v58
	v_exp_f32_e32 v66, v25
	v_mul_f32_e32 v25, 0xbfb8aa3b, v59
	v_exp_f32_e32 v67, v25
	v_pk_fma_f32 v[4:5], v[2:3], v[4:5], v[6:7]
	v_pk_mul_f32 v[60:61], v[60:61], v[62:63]
	v_mul_f32_e32 v37, 0xbfb8aa3b, v4
	v_pk_add_f32 v[20:21], v[66:67], 1.0 op_sel_hi:[1,0]
	v_exp_f32_e32 v62, v37
	v_div_scale_f32 v25, s[0:1], v21, v21, 1.0
	v_rcp_f32_e32 v35, v25
	s_nop 0
	v_fma_f32 v37, -v25, v35, 1.0
	v_fmac_f32_e32 v35, v37, v35
	v_div_scale_f32 v37, vcc, 1.0, v21, 1.0
	v_mul_f32_e32 v39, v37, v35
	v_fma_f32 v63, -v25, v39, v37
	v_fmac_f32_e32 v39, v63, v35
	v_fma_f32 v25, -v25, v39, v37
	v_div_scale_f32 v37, s[0:1], v20, v20, 1.0
	v_rcp_f32_e32 v64, v37
	v_div_fmas_f32 v25, v25, v35, v39
	v_mul_f32_e32 v39, 0xbfb8aa3b, v5
	v_div_fixup_f32 v21, v25, v21, 1.0
	v_fma_f32 v25, -v37, v64, 1.0
	v_exp_f32_e32 v63, v39
	v_fmac_f32_e32 v64, v25, v64
	v_div_scale_f32 v25, vcc, 1.0, v20, 1.0
	v_mul_f32_e32 v35, v25, v64
	v_fma_f32 v39, -v37, v35, v25
	v_fmac_f32_e32 v35, v39, v64
	v_pk_add_f32 v[62:63], v[62:63], 1.0 op_sel_hi:[1,0]
	v_fma_f32 v25, -v37, v35, v25
	v_div_scale_f32 v37, s[0:1], v63, v63, 1.0
	v_rcp_f32_e32 v39, v37
	v_div_fmas_f32 v25, v25, v64, v35
	v_div_fixup_f32 v20, v25, v20, 1.0
	v_pk_mul_f32 v[20:21], v[58:59], v[20:21]
	v_fma_f32 v25, -v37, v39, 1.0
	v_fmac_f32_e32 v39, v25, v39
	v_div_scale_f32 v25, vcc, 1.0, v63, 1.0
	v_mul_f32_e32 v35, v25, v39
	v_fma_f32 v58, -v37, v35, v25
	v_fmac_f32_e32 v35, v58, v39
	v_fma_f32 v25, -v37, v35, v25
	v_div_scale_f32 v37, s[0:1], v62, v62, 1.0
	v_rcp_f32_e32 v58, v37
	v_div_fmas_f32 v25, v25, v39, v35
	v_div_fixup_f32 v59, v25, v63, 1.0
	v_fma_f32 v25, -v37, v58, 1.0
	v_fmac_f32_e32 v58, v25, v58
	v_div_scale_f32 v25, vcc, 1.0, v62, 1.0
	v_mul_f32_e32 v35, v25, v58
	v_fma_f32 v39, -v37, v35, v25
	v_fmac_f32_e32 v35, v39, v58
	v_fma_f32 v25, -v37, v35, v25
	v_div_fmas_f32 v25, v25, v58, v35
	v_div_fixup_f32 v58, v25, v62, 1.0
	v_pk_mul_f32 v[4:5], v[4:5], v[58:59]
	v_bfe_u32 v58, v20, 16, 1
	v_bfe_u32 v25, v5, 16, 1
	v_bfe_u32 v35, v4, 16, 1
	v_add3_u32 v35, v4, v35, s61
	v_add3_u32 v25, v5, v25, s61
	v_bfe_u32 v4, v0, 16, 1
	v_bfe_u32 v5, v1, 16, 1
	v_add3_u32 v1, v1, v5, s61
	v_add3_u32 v0, v0, v4, s61
	v_add3_u32 v20, v20, v58, s61
	v_lshrrev_b32_e32 v64, 16, v0
	v_lshrrev_b32_e32 v65, 16, v1
	v_pk_add_f32 v[0:1], v[48:49], v[54:55]
	v_lshrrev_b32_e32 v66, 16, v20
	v_add_f32_e32 v20, 0, v0
	v_pk_add_f32 v[4:5], v[46:47], v[18:19]
	v_bfe_u32 v59, v21, 16, 1
	v_add_f32_e32 v20, v20, v4
	v_add3_u32 v21, v21, v59, s61
	v_add_f32_e32 v20, v20, v1
	v_lshrrev_b32_e32 v67, 16, v21
	v_add_f32_e32 v46, v20, v5
	v_pk_add_f32 v[20:21], v[44:45], v[56:57]
	v_bfe_u32 v37, v61, 16, 1
	v_add_f32_e32 v44, v46, v20
	v_add_f32_e32 v44, v44, v42
	v_add_f32_e32 v44, v44, v21
	v_add_f32_e32 v44, v44, v43
	v_bfe_u32 v39, v60, 16, 1
	v_add3_u32 v39, v60, v39, s61
	v_add_f32_dpp v44, v44, v44 quad_perm:[1,0,3,2] row_mask:0xf bank_mask:0xf bound_ctrl:1
	v_add3_u32 v37, v61, v37, s61
	v_pk_add_f32 v[18:19], v[30:31], v[18:19]
	v_add_f32_dpp v44, v44, v44 quad_perm:[2,3,0,1] row_mask:0xf bank_mask:0xf bound_ctrl:1
	s_nop 1
	v_add_f32_dpp v44, v44, v44 row_half_mirror row_mask:0xf bank_mask:0xf bound_ctrl:1
	v_mul_f32_e32 v46, 0x3c800000, v44
	v_pk_add_f32 v[48:49], v[0:1], v[46:47] op_sel_hi:[1,0] neg_lo:[0,1] neg_hi:[0,1]
	v_pk_add_f32 v[58:59], v[4:5], v[46:47] op_sel_hi:[1,0] neg_lo:[0,1] neg_hi:[0,1]
	v_mov_b32_e32 v5, v49
	v_mov_b32_e32 v4, v59
	v_pk_add_f32 v[44:45], v[20:21], v[46:47] op_sel_hi:[1,0] neg_lo:[0,1] neg_hi:[0,1]
	v_pk_add_f32 v[42:43], v[42:43], v[46:47] op_sel_hi:[1,0] neg_lo:[0,1] neg_hi:[0,1]
	v_pk_mul_f32 v[60:61], v[4:5], v[4:5]
	v_mov_b32_e32 v4, v42
	v_mov_b32_e32 v5, v44
	v_pk_mul_f32 v[46:47], v[4:5], v[4:5]
	v_mov_b32_e32 v4, v43
	v_mov_b32_e32 v5, v45
	v_pk_mul_f32 v[62:63], v[4:5], v[4:5]
	v_pk_add_f32 v[4:5], v[40:41], v[54:55]
	v_mov_b32_e32 v0, v48
	v_add_f32_e32 v20, 0, v4
	v_add_f32_e32 v20, v20, v18
	v_add_f32_e32 v20, v20, v5
	v_add_f32_e32 v20, v20, v19
	v_add_f32_e32 v20, v20, v28
	v_add_f32_e32 v20, v20, v22
	v_add_f32_e32 v20, v20, v29
	v_add_f32_e32 v20, v20, v23
	v_mov_b32_e32 v1, v58
	v_pk_mul_f32 v[0:1], v[0:1], v[0:1]
	v_add_f32_dpp v20, v20, v20 quad_perm:[1,0,3,2] row_mask:0xf bank_mask:0xf bound_ctrl:1
	v_mov_b32_e32 v31, v0
	s_nop 0
	v_add_f32_dpp v20, v20, v20 quad_perm:[2,3,0,1] row_mask:0xf bank_mask:0xf bound_ctrl:1
	s_nop 1
	v_add_f32_dpp v20, v20, v20 row_half_mirror row_mask:0xf bank_mask:0xf bound_ctrl:1
	v_mul_f32_e32 v26, 0x3c800000, v20
	v_pk_add_f32 v[20:21], v[4:5], v[26:27] op_sel_hi:[1,0] neg_lo:[0,1] neg_hi:[0,1]
	v_pk_add_f32 v[18:19], v[18:19], v[26:27] op_sel_hi:[1,0] neg_lo:[0,1] neg_hi:[0,1]
	v_mov_b32_e32 v4, v20
	v_mov_b32_e32 v5, v18
	v_pk_mul_f32 v[4:5], v[4:5], v[4:5]
	s_nop 0
	v_mov_b32_e32 v30, v4
	v_mov_b32_e32 v0, v5
	v_pk_add_f32 v[30:31], v[30:31], v[0:1]
	v_mov_b32_e32 v0, v19
	v_mov_b32_e32 v1, v21
	v_pk_mul_f32 v[40:41], v[0:1], v[0:1]
	v_pk_add_f32 v[4:5], v[28:29], v[26:27] op_sel_hi:[1,0] neg_lo:[0,1] neg_hi:[0,1]
	v_pk_add_f32 v[0:1], v[22:23], v[26:27] op_sel_hi:[1,0] neg_lo:[0,1] neg_hi:[0,1]
	v_mov_b32_e32 v23, v4
	v_mov_b32_e32 v22, v0
	v_mov_b32_e32 v28, v41
	v_mov_b32_e32 v29, v61
	v_pk_mul_f32 v[22:23], v[22:23], v[22:23]
	v_pk_add_f32 v[28:29], v[28:29], v[30:31]
	v_mov_b32_e32 v41, v60
	v_mov_b32_e32 v26, v1
	v_mov_b32_e32 v27, v5
	v_pk_add_f32 v[28:29], v[40:41], v[28:29]
	v_mov_b32_e32 v30, v23
	v_mov_b32_e32 v31, v47
	v_pk_mul_f32 v[26:27], v[26:27], v[26:27]
	v_pk_add_f32 v[28:29], v[30:31], v[28:29]
	v_mov_b32_e32 v23, v46
	v_pk_add_f32 v[22:23], v[22:23], v[28:29]
	v_mov_b32_e32 v28, v27
	v_mov_b32_e32 v29, v63
	v_pk_add_f32 v[22:23], v[28:29], v[22:23]
	v_mov_b32_e32 v27, v62
	v_pk_add_f32 v[22:23], v[26:27], v[22:23]
	v_and_or_b32 v29, v25, s65, v67
	v_and_or_b32 v28, v35, s65, v66
	v_mov_b32_dpp v27, v23 quad_perm:[1,0,3,2] row_mask:0xf bank_mask:0xf bound_ctrl:1
	v_mov_b32_dpp v26, v22 quad_perm:[1,0,3,2] row_mask:0xf bank_mask:0xf bound_ctrl:1
	v_pk_add_f32 v[22:23], v[22:23], v[26:27]
	s_nop 1
	v_mov_b32_dpp v27, v23 quad_perm:[2,3,0,1] row_mask:0xf bank_mask:0xf bound_ctrl:1
	v_mov_b32_dpp v26, v22 quad_perm:[2,3,0,1] row_mask:0xf bank_mask:0xf bound_ctrl:1
	v_pk_add_f32 v[22:23], v[22:23], v[26:27]
	s_nop 1
	v_mov_b32_dpp v27, v23 row_half_mirror row_mask:0xf bank_mask:0xf bound_ctrl:1
	v_mov_b32_dpp v26, v22 row_half_mirror row_mask:0xf bank_mask:0xf bound_ctrl:1
	v_pk_add_f32 v[22:23], v[22:23], v[26:27]
	v_and_or_b32 v27, v37, s65, v65
	v_pk_fma_f32 v[22:23], v[22:23], s[20:21], v[52:53] op_sel_hi:[1,0,0]
	s_nop 0
	v_mul_f32_e32 v26, 0x4b800000, v23
	v_cmp_gt_f32_e32 vcc, s67, v23
	s_nop 1
	v_cndmask_b32_e32 v23, v23, v26, vcc
	v_rsq_f32_e32 v23, v23
	v_and_or_b32 v26, v39, s65, v64
	ds_write_b128 v24, v[26:29] offset:528
	v_mul_f32_e32 v25, 0x45800000, v23
	v_cndmask_b32_e32 v30, v23, v25, vcc
	v_pk_mul_f32 v[40:41], v[48:49], v[30:31] op_sel_hi:[1,0]
	v_pk_mul_f32 v[26:27], v[58:59], v[30:31] op_sel_hi:[1,0]
	v_pk_fma_f32 v[40:41], v[16:17], v[40:41], v[50:51]
	s_nop 0
	v_mul_f32_e32 v23, 0xbfb8aa3b, v40
	v_exp_f32_e32 v46, v23
	v_mul_f32_e32 v23, 0xbfb8aa3b, v41
	v_exp_f32_e32 v47, v23
	s_nop 0
	v_pk_add_f32 v[28:29], v[46:47], 1.0 op_sel_hi:[1,0]
	s_nop 0
	v_div_scale_f32 v23, s[0:1], v29, v29, 1.0
	v_rcp_f32_e32 v25, v23
	v_pk_fma_f32 v[46:47], v[10:11], v[26:27], v[14:15]
	v_fma_f32 v27, -v23, v25, 1.0
	v_fmac_f32_e32 v25, v27, v25
	v_div_scale_f32 v27, vcc, 1.0, v29, 1.0
	v_mul_f32_e32 v31, v27, v25
	v_fma_f32 v35, -v23, v31, v27
	v_fmac_f32_e32 v31, v35, v25
	v_div_scale_f32 v35, s[0:1], v28, v28, 1.0
	v_rcp_f32_e32 v37, v35
	v_mul_f32_e32 v26, 0xbfb8aa3b, v46
	v_fma_f32 v23, -v23, v31, v27
	v_mul_f32_e32 v27, 0xbfb8aa3b, v47
	v_exp_f32_e32 v26, v26
	v_div_fmas_f32 v23, v23, v25, v31
	v_exp_f32_e32 v27, v27
	v_div_fixup_f32 v29, v23, v29, 1.0
	v_fma_f32 v23, -v35, v37, 1.0
	v_fmac_f32_e32 v37, v23, v37
	v_div_scale_f32 v23, vcc, 1.0, v28, 1.0
	v_mul_f32_e32 v25, v23, v37
	v_fma_f32 v31, -v35, v25, v23
	v_pk_add_f32 v[48:49], v[26:27], 1.0 op_sel_hi:[1,0]
	v_fmac_f32_e32 v25, v31, v37
	v_div_scale_f32 v31, s[0:1], v49, v49, 1.0
	v_fma_f32 v23, -v35, v25, v23
	v_rcp_f32_e32 v35, v31
	v_div_fmas_f32 v23, v23, v37, v25
	v_div_fixup_f32 v28, v23, v28, 1.0
	v_pk_mul_f32 v[26:27], v[40:41], v[28:29]
	v_fma_f32 v23, -v31, v35, 1.0
	v_fmac_f32_e32 v35, v23, v35
	v_div_scale_f32 v23, vcc, 1.0, v49, 1.0
	v_mul_f32_e32 v25, v23, v35
	v_fma_f32 v28, -v31, v25, v23
	v_fmac_f32_e32 v25, v28, v35
	v_div_scale_f32 v28, s[0:1], v48, v48, 1.0
	v_fma_f32 v23, -v31, v25, v23
	v_rcp_f32_e32 v31, v28
	v_div_fmas_f32 v23, v23, v35, v25
	v_div_fixup_f32 v29, v23, v49, 1.0
	v_fma_f32 v23, -v28, v31, 1.0
	v_fmac_f32_e32 v31, v23, v31
	v_div_scale_f32 v23, vcc, 1.0, v48, 1.0
	v_mul_f32_e32 v25, v23, v31
	v_fma_f32 v35, -v28, v25, v23
	v_fmac_f32_e32 v25, v35, v31
	v_pk_mul_f32 v[40:41], v[44:45], v[30:31] op_sel_hi:[1,0]
	v_fma_f32 v23, -v28, v25, v23
	v_pk_fma_f32 v[40:41], v[8:9], v[40:41], v[12:13]
	v_div_fmas_f32 v23, v23, v31, v25
	v_mul_f32_e32 v25, 0xbfb8aa3b, v40
	v_exp_f32_e32 v44, v25
	v_mul_f32_e32 v25, 0xbfb8aa3b, v41
	v_exp_f32_e32 v45, v25
	v_pk_mul_f32 v[30:31], v[42:43], v[30:31] op_sel_hi:[1,0]
	v_div_fixup_f32 v28, v23, v48, 1.0
	v_pk_fma_f32 v[30:31], v[2:3], v[30:31], v[6:7]
	v_pk_add_f32 v[42:43], v[44:45], 1.0 op_sel_hi:[1,0]
	v_mul_f32_e32 v35, 0xbfb8aa3b, v30
	v_div_scale_f32 v23, s[0:1], v43, v43, 1.0
	v_rcp_f32_e32 v25, v23
	v_exp_f32_e32 v44, v35
	v_pk_mul_f32 v[28:29], v[46:47], v[28:29]
	v_fma_f32 v35, -v23, v25, 1.0
	v_fmac_f32_e32 v25, v35, v25
	v_div_scale_f32 v35, vcc, 1.0, v43, 1.0
	v_mul_f32_e32 v37, v35, v25
	v_fma_f32 v39, -v23, v37, v35
	v_fmac_f32_e32 v37, v39, v25
	v_fma_f32 v23, -v23, v37, v35
	v_div_scale_f32 v35, s[0:1], v42, v42, 1.0
	v_rcp_f32_e32 v39, v35
	v_div_fmas_f32 v23, v23, v25, v37
	v_mul_f32_e32 v37, 0xbfb8aa3b, v31
	v_div_fixup_f32 v43, v23, v43, 1.0
	v_fma_f32 v23, -v35, v39, 1.0
	v_exp_f32_e32 v45, v37
	v_fmac_f32_e32 v39, v23, v39
	v_div_scale_f32 v23, vcc, 1.0, v42, 1.0
	v_mul_f32_e32 v25, v23, v39
	v_fma_f32 v37, -v35, v25, v23
	v_fmac_f32_e32 v25, v37, v39
	v_pk_add_f32 v[44:45], v[44:45], 1.0 op_sel_hi:[1,0]
	v_fma_f32 v23, -v35, v25, v23
	v_div_scale_f32 v35, s[0:1], v45, v45, 1.0
	v_rcp_f32_e32 v37, v35
	v_div_fmas_f32 v23, v23, v39, v25
	v_div_fixup_f32 v42, v23, v42, 1.0
	v_pk_mul_f32 v[40:41], v[40:41], v[42:43]
	v_fma_f32 v23, -v35, v37, 1.0
	v_fmac_f32_e32 v37, v23, v37
	v_div_scale_f32 v23, vcc, 1.0, v45, 1.0
	v_mul_f32_e32 v25, v23, v37
	v_fma_f32 v39, -v35, v25, v23
	v_fmac_f32_e32 v25, v39, v37
	v_fma_f32 v23, -v35, v25, v23
	v_div_scale_f32 v35, s[0:1], v44, v44, 1.0
	v_rcp_f32_e32 v39, v35
	v_div_fmas_f32 v23, v23, v37, v25
	v_div_fixup_f32 v43, v23, v45, 1.0
	v_fma_f32 v23, -v35, v39, 1.0
	v_fmac_f32_e32 v39, v23, v39
	v_div_scale_f32 v23, vcc, 1.0, v44, 1.0
	v_mul_f32_e32 v25, v23, v39
	v_fma_f32 v37, -v35, v25, v23
	v_fmac_f32_e32 v25, v37, v39
	v_fma_f32 v23, -v35, v25, v23
	v_div_fmas_f32 v23, v23, v39, v25
	v_div_fixup_f32 v42, v23, v44, 1.0
	v_pk_mul_f32 v[30:31], v[30:31], v[42:43]
	v_bfe_u32 v37, v28, 16, 1
	v_bfe_u32 v25, v30, 16, 1
	v_add3_u32 v25, v30, v25, s61
	v_bfe_u32 v30, v40, 16, 1
	v_add3_u32 v37, v28, v37, s61
	v_bfe_u32 v28, v26, 16, 1
	v_add3_u32 v30, v40, v30, s61
	v_add3_u32 v26, v26, v28, s61
	v_lshrrev_b32_e32 v28, 16, v30
	v_mul_f32_e32 v30, 0x4b800000, v22
	v_cmp_gt_f32_e32 vcc, s67, v22
	v_bfe_u32 v23, v31, 16, 1
	v_bfe_u32 v35, v29, 16, 1
	v_cndmask_b32_e32 v22, v22, v30, vcc
	v_rsq_f32_e32 v22, v22
	v_add3_u32 v23, v31, v23, s61
	v_bfe_u32 v31, v41, 16, 1
	v_add3_u32 v35, v29, v35, s61
	v_bfe_u32 v29, v27, 16, 1
	v_add3_u32 v31, v41, v31, s61
	v_add3_u32 v27, v27, v29, s61
	v_lshrrev_b32_e32 v29, 16, v31
	v_and_or_b32 v29, v23, s65, v29
	v_mul_f32_e32 v23, 0x45800000, v22
	v_cndmask_b32_e32 v22, v22, v23, vcc
	v_pk_mul_f32 v[20:21], v[20:21], v[22:23] op_sel_hi:[1,0]
	v_pk_mul_f32 v[18:19], v[18:19], v[22:23] op_sel_hi:[1,0]
	v_pk_fma_f32 v[16:17], v[16:17], v[20:21], v[50:51]
	v_and_or_b32 v28, v25, s65, v28
	v_mul_f32_e32 v20, 0xbfb8aa3b, v16
	v_mul_f32_e32 v21, 0xbfb8aa3b, v17
	v_exp_f32_e32 v20, v20
	v_exp_f32_e32 v21, v21
	v_pk_fma_f32 v[14:15], v[10:11], v[18:19], v[14:15]
	v_lshrrev_b32_e32 v26, 16, v26
	v_lshrrev_b32_e32 v27, 16, v27
	v_pk_add_f32 v[20:21], v[20:21], 1.0 op_sel_hi:[1,0]
	v_and_or_b32 v27, v35, s65, v27
	v_div_scale_f32 v23, s[0:1], v21, v21, 1.0
	v_rcp_f32_e32 v25, v23
	v_and_or_b32 v26, v37, s65, v26
	ds_write_b128 v24, v[26:29] offset:1056
	v_mul_f32_e32 v10, 0xbfb8aa3b, v14
	v_fma_f32 v11, -v23, v25, 1.0
	v_fmac_f32_e32 v25, v11, v25
	v_div_scale_f32 v11, vcc, 1.0, v21, 1.0
	v_mul_f32_e32 v18, v11, v25
	v_fma_f32 v19, -v23, v18, v11
	v_fmac_f32_e32 v18, v19, v25
	v_fma_f32 v11, -v23, v18, v11
	v_div_scale_f32 v23, s[0:1], v20, v20, 1.0
	v_rcp_f32_e32 v28, v23
	v_div_fmas_f32 v11, v11, v25, v18
	v_div_fixup_f32 v19, v11, v21, 1.0
	v_exp_f32_e32 v10, v10
	v_fma_f32 v11, -v23, v28, 1.0
	v_fmac_f32_e32 v28, v11, v28
	v_mul_f32_e32 v11, 0xbfb8aa3b, v15
	v_exp_f32_e32 v11, v11
	v_div_scale_f32 v18, vcc, 1.0, v20, 1.0
	v_mul_f32_e32 v21, v18, v28
	v_fma_f32 v25, -v23, v21, v18
	v_fmac_f32_e32 v21, v25, v28
	v_pk_add_f32 v[26:27], v[10:11], 1.0 op_sel_hi:[1,0]
	v_fma_f32 v18, -v23, v21, v18
	v_div_scale_f32 v23, s[0:1], v27, v27, 1.0
	v_rcp_f32_e32 v25, v23
	v_div_fmas_f32 v10, v18, v28, v21
	v_div_fixup_f32 v18, v10, v20, 1.0
	v_pk_mul_f32 v[10:11], v[16:17], v[18:19]
	v_fma_f32 v16, -v23, v25, 1.0
	v_fmac_f32_e32 v25, v16, v25
	v_div_scale_f32 v16, vcc, 1.0, v27, 1.0
	v_mul_f32_e32 v17, v16, v25
	v_fma_f32 v18, -v23, v17, v16
	v_fmac_f32_e32 v17, v18, v25
	v_div_scale_f32 v18, s[0:1], v26, v26, 1.0
	v_rcp_f32_e32 v19, v18
	v_fma_f32 v16, -v23, v17, v16
	v_div_fmas_f32 v16, v16, v25, v17
	v_div_fixup_f32 v17, v16, v27, 1.0
	v_fma_f32 v16, -v18, v19, 1.0
	v_pk_mul_f32 v[4:5], v[4:5], v[22:23] op_sel_hi:[1,0]
	v_fmac_f32_e32 v19, v16, v19
	v_div_scale_f32 v16, vcc, 1.0, v26, 1.0
	v_pk_fma_f32 v[4:5], v[8:9], v[4:5], v[12:13]
	v_mul_f32_e32 v20, v16, v19
	v_mul_f32_e32 v8, 0xbfb8aa3b, v4
	v_mul_f32_e32 v9, 0xbfb8aa3b, v5
	v_fma_f32 v21, -v18, v20, v16
	v_exp_f32_e32 v8, v8
	v_exp_f32_e32 v9, v9
	v_fmac_f32_e32 v20, v21, v19
	v_fma_f32 v16, -v18, v20, v16
	v_div_fmas_f32 v16, v16, v19, v20
	v_div_fixup_f32 v16, v16, v26, 1.0
	v_pk_add_f32 v[8:9], v[8:9], 1.0 op_sel_hi:[1,0]
	v_pk_mul_f32 v[12:13], v[14:15], v[16:17]
	v_div_scale_f32 v14, s[0:1], v9, v9, 1.0
	v_rcp_f32_e32 v15, v14
	v_pk_mul_f32 v[0:1], v[0:1], v[22:23] op_sel_hi:[1,0]
	s_nop 0
	v_pk_fma_f32 v[0:1], v[2:3], v[0:1], v[6:7]
	v_fma_f32 v3, -v14, v15, 1.0
	v_fmac_f32_e32 v15, v3, v15
	v_div_scale_f32 v3, vcc, 1.0, v9, 1.0
	v_mul_f32_e32 v6, v3, v15
	v_fma_f32 v7, -v14, v6, v3
	v_fmac_f32_e32 v6, v7, v15
	v_fma_f32 v3, -v14, v6, v3
	v_div_scale_f32 v14, s[0:1], v8, v8, 1.0
	v_rcp_f32_e32 v16, v14
	v_div_fmas_f32 v3, v3, v15, v6
	v_div_fixup_f32 v7, v3, v9, 1.0
	v_mul_f32_e32 v2, 0xbfb8aa3b, v0
	v_fma_f32 v3, -v14, v16, 1.0
	v_fmac_f32_e32 v16, v3, v16
	v_mul_f32_e32 v3, 0xbfb8aa3b, v1
	v_exp_f32_e32 v2, v2
	v_exp_f32_e32 v3, v3
	v_div_scale_f32 v6, vcc, 1.0, v8, 1.0
	v_mul_f32_e32 v9, v6, v16
	v_fma_f32 v15, -v14, v9, v6
	v_fmac_f32_e32 v9, v15, v16
	v_pk_add_f32 v[2:3], v[2:3], 1.0 op_sel_hi:[1,0]
	v_fma_f32 v6, -v14, v9, v6
	v_div_scale_f32 v14, s[0:1], v3, v3, 1.0
	v_rcp_f32_e32 v15, v14
	v_div_fmas_f32 v6, v6, v16, v9
	v_div_fixup_f32 v6, v6, v8, 1.0
	v_pk_mul_f32 v[4:5], v[4:5], v[6:7]
	v_fma_f32 v6, -v14, v15, 1.0
	v_fmac_f32_e32 v15, v6, v15
	v_div_scale_f32 v6, vcc, 1.0, v3, 1.0
	v_mul_f32_e32 v7, v6, v15
	v_fma_f32 v8, -v14, v7, v6
	v_fmac_f32_e32 v7, v8, v15
	v_div_scale_f32 v8, s[0:1], v2, v2, 1.0
	v_rcp_f32_e32 v9, v8
	v_fma_f32 v6, -v14, v7, v6
	v_div_fmas_f32 v6, v6, v15, v7
	v_div_fixup_f32 v3, v6, v3, 1.0
	v_fma_f32 v6, -v8, v9, 1.0
	v_fmac_f32_e32 v9, v6, v9
	v_div_scale_f32 v6, vcc, 1.0, v2, 1.0
	v_mul_f32_e32 v7, v6, v9
	v_fma_f32 v14, -v8, v7, v6
	v_fmac_f32_e32 v7, v14, v9
	v_fma_f32 v6, -v8, v7, v6
	v_div_fmas_f32 v6, v6, v9, v7
	v_div_fixup_f32 v2, v6, v2, 1.0
	v_pk_mul_f32 v[0:1], v[0:1], v[2:3]
	v_bfe_u32 v8, v4, 16, 1
	v_bfe_u32 v2, v1, 16, 1
	v_bfe_u32 v3, v0, 16, 1
	v_add3_u32 v0, v0, v3, s61
	v_add3_u32 v1, v1, v2, s61
	v_bfe_u32 v9, v5, 16, 1
	v_add3_u32 v5, v5, v9, s61
	v_add3_u32 v4, v4, v8, s61
	v_lshrrev_b32_e32 v2, 16, v4
	v_lshrrev_b32_e32 v3, 16, v5
	v_and_or_b32 v3, v1, s65, v3
	v_and_or_b32 v2, v0, s65, v2
	v_cvt_pk_bf16_f32 v1, v11, v13
	v_cvt_pk_bf16_f32 v0, v10, v12
	ds_write_b128 v24, v[0:3] offset:1584
	v_mov_b32_e32 v0, v117
	s_waitcnt lgkmcnt(0)
	s_barrier
	s_nop 0
	v_mbcnt_lo_u32_b32 v0, -1, v0
	v_mbcnt_hi_u32_b32 v2, -1, v0
	v_and_b32_e32 v12, 31, v2
	v_and_or_b32 v0, v32, s68, v12
	v_ashrrev_i32_e32 v1, 31, v0
	v_ashrrev_i32_e32 v2, 2, v2
	v_lshlrev_b64 v[0:1], 9, v[0:1]
	v_and_b32_e32 v8, -8, v2
	v_lshl_add_u64 v[0:1], s[8:9], 0, v[0:1]
	v_ashrrev_i32_e32 v9, 31, v8
	v_lshl_add_u64 v[10:11], v[8:9], 1, v[0:1]
	v_add_co_u32_e32 v0, vcc, s69, v10
	v_lshl_add_u64 v[62:63], v[10:11], 0, s[36:37]
	s_nop 0
	v_addc_co_u32_e32 v1, vcc, 0, v11, vcc
	global_load_dwordx4 v[0:3], v[0:1], off
	v_add_co_u32_e32 v60, vcc, s70, v10
	global_load_dwordx4 v[40:43], v[62:63], off offset:32
	s_nop 0
	v_addc_co_u32_e32 v61, vcc, 0, v11, vcc
	global_load_dwordx4 v[4:7], v[60:61], off
	v_lshlrev_b32_e32 v8, 1, v8
	v_mad_u32_u24 v35, v12, s62, v8
	ds_read_b128 v[8:11], v35
	ds_read_b128 v[44:47], v35 offset:32
	s_waitcnt vmcnt(0) lgkmcnt(0)
	v_mfma_f32_32x32x16_bf16 v[16:31], v[8:11], v[0:3], 0
	global_load_dwordx4 v[48:51], v[60:61], off offset:32
	global_load_dwordx4 v[52:55], v[62:63], off offset:64
	v_mfma_f32_32x32x16_bf16 v[16:31], v[44:47], v[40:43], v[16:31]
	global_load_dwordx4 v[40:43], v[60:61], off offset:64
	v_mfma_f32_32x32x16_bf16 v[0:15], v[8:11], v[4:7], 0
	s_waitcnt vmcnt(0) lgkmcnt(0)
	v_mfma_f32_32x32x16_bf16 v[0:15], v[44:47], v[48:51], v[0:15]
	ds_read_b128 v[44:47], v35 offset:64
	ds_read_b128 v[48:51], v35 offset:96
	s_waitcnt lgkmcnt(1)
	v_mfma_f32_32x32x16_bf16 v[0:15], v[44:47], v[40:43], v[0:15]
	global_load_dwordx4 v[40:43], v[62:63], off offset:96
	v_mfma_f32_32x32x16_bf16 v[16:31], v[44:47], v[52:55], v[16:31]
	s_waitcnt vmcnt(0) lgkmcnt(0)
	v_mfma_f32_32x32x16_bf16 v[16:31], v[48:51], v[40:43], v[16:31]
	global_load_dwordx4 v[40:43], v[60:61], off offset:96
	s_waitcnt vmcnt(0) lgkmcnt(0)
	v_mfma_f32_32x32x16_bf16 v[0:15], v[48:51], v[40:43], v[0:15]
	global_load_dwordx4 v[40:43], v[62:63], off offset:128
	global_load_dwordx4 v[44:47], v[60:61], off offset:128
	ds_read_b128 v[48:51], v35 offset:128
	ds_read_b128 v[56:59], v35 offset:160
	global_load_dwordx4 v[52:55], v[62:63], off offset:160
	s_waitcnt vmcnt(0) lgkmcnt(0)
	v_mfma_f32_32x32x16_bf16 v[16:31], v[48:51], v[40:43], v[16:31]
	global_load_dwordx4 v[40:43], v[60:61], off offset:160
	v_mfma_f32_32x32x16_bf16 v[0:15], v[48:51], v[44:47], v[0:15]
	global_load_dwordx4 v[44:47], v[62:63], off offset:192
	global_load_dwordx4 v[48:51], v[60:61], off offset:192
	v_mfma_f32_32x32x16_bf16 v[16:31], v[56:59], v[52:55], v[16:31]
	ds_read_b128 v[52:55], v35 offset:192
	s_waitcnt vmcnt(0) lgkmcnt(0)
	v_mfma_f32_32x32x16_bf16 v[0:15], v[56:59], v[40:43], v[0:15]
	global_load_dwordx4 v[40:43], v[62:63], off offset:224
	ds_read_b128 v[56:59], v35 offset:224
	v_mfma_f32_32x32x16_bf16 v[16:31], v[52:55], v[44:47], v[16:31]
	global_load_dwordx4 v[44:47], v[60:61], off offset:224
	v_mfma_f32_32x32x16_bf16 v[0:15], v[52:55], v[48:51], v[0:15]
	s_waitcnt vmcnt(0) lgkmcnt(0)
	v_mfma_f32_32x32x16_bf16 v[16:31], v[56:59], v[40:43], v[16:31]
	v_mfma_f32_32x32x16_bf16 v[0:15], v[56:59], v[44:47], v[0:15]
	global_load_dwordx4 v[40:43], v[62:63], off offset:256
	global_load_dwordx4 v[44:47], v[60:61], off offset:256
	ds_read_b128 v[48:51], v35 offset:256
	ds_read_b128 v[56:59], v35 offset:288
	global_load_dwordx4 v[52:55], v[62:63], off offset:288
	s_waitcnt vmcnt(0) lgkmcnt(0)
	v_mfma_f32_32x32x16_bf16 v[16:31], v[48:51], v[40:43], v[16:31]
	global_load_dwordx4 v[40:43], v[60:61], off offset:288
	v_mfma_f32_32x32x16_bf16 v[0:15], v[48:51], v[44:47], v[0:15]
	global_load_dwordx4 v[44:47], v[62:63], off offset:320
	global_load_dwordx4 v[48:51], v[60:61], off offset:320
	v_mfma_f32_32x32x16_bf16 v[16:31], v[56:59], v[52:55], v[16:31]
	ds_read_b128 v[52:55], v35 offset:320
	s_waitcnt vmcnt(0) lgkmcnt(0)
	v_mfma_f32_32x32x16_bf16 v[0:15], v[56:59], v[40:43], v[0:15]
	global_load_dwordx4 v[40:43], v[62:63], off offset:352
	ds_read_b128 v[56:59], v35 offset:352
	v_mfma_f32_32x32x16_bf16 v[16:31], v[52:55], v[44:47], v[16:31]
	global_load_dwordx4 v[44:47], v[60:61], off offset:352
	v_mfma_f32_32x32x16_bf16 v[0:15], v[52:55], v[48:51], v[0:15]
	s_waitcnt vmcnt(0) lgkmcnt(0)
	v_mfma_f32_32x32x16_bf16 v[16:31], v[56:59], v[40:43], v[16:31]
	v_mfma_f32_32x32x16_bf16 v[0:15], v[56:59], v[44:47], v[0:15]
	global_load_dwordx4 v[40:43], v[62:63], off offset:384
	global_load_dwordx4 v[44:47], v[60:61], off offset:384
	ds_read_b128 v[48:51], v35 offset:384
	ds_read_b128 v[56:59], v35 offset:416
	global_load_dwordx4 v[52:55], v[62:63], off offset:416
	s_waitcnt vmcnt(0) lgkmcnt(0)
	v_mfma_f32_32x32x16_bf16 v[16:31], v[48:51], v[40:43], v[16:31]
	global_load_dwordx4 v[40:43], v[60:61], off offset:416
	v_mfma_f32_32x32x16_bf16 v[0:15], v[48:51], v[44:47], v[0:15]
	global_load_dwordx4 v[44:47], v[62:63], off offset:448
	global_load_dwordx4 v[48:51], v[60:61], off offset:448
	v_mfma_f32_32x32x16_bf16 v[16:31], v[56:59], v[52:55], v[16:31]
	ds_read_b128 v[52:55], v35 offset:448
	s_waitcnt vmcnt(0) lgkmcnt(0)
	v_mfma_f32_32x32x16_bf16 v[0:15], v[56:59], v[40:43], v[0:15]
	global_load_dwordx4 v[40:43], v[62:63], off offset:480
	ds_read_b128 v[56:59], v35 offset:480
	v_mfma_f32_32x32x16_bf16 v[16:31], v[52:55], v[44:47], v[16:31]
	global_load_dwordx4 v[44:47], v[60:61], off offset:480
	v_mfma_f32_32x32x16_bf16 v[0:15], v[52:55], v[48:51], v[0:15]
	s_waitcnt vmcnt(0) lgkmcnt(0)
	v_mfma_f32_32x32x16_bf16 v[16:31], v[56:59], v[40:43], v[16:31]
	v_mfma_f32_32x32x16_bf16 v[0:15], v[56:59], v[44:47], v[0:15]
	v_lshrrev_b32_e32 v35, 3, v32
	v_and_b32_e32 v35, 4, v35
	v_mul_u32_u24_e32 v35, 0x108, v35
	v_and_b32_e32 v37, 0x7fffffdf, v32
	s_nop 6
	v_bfe_u32 v39, v16, 16, 1
	v_lshlrev_b32_e32 v35, 1, v35
	v_add3_u32 v16, v16, v39, s61
	v_lshl_add_u32 v35, v37, 1, v35
	ds_write_b16_d16_hi v35, v16 offset:16896
	v_bfe_u32 v16, v17, 16, 1
	v_add3_u32 v16, v17, v16, s61
	ds_write_b16_d16_hi v35, v16 offset:17424
	v_bfe_u32 v16, v18, 16, 1
	v_add3_u32 v16, v18, v16, s61
	ds_write_b16_d16_hi v35, v16 offset:17952
	v_bfe_u32 v16, v19, 16, 1
	v_add3_u32 v16, v19, v16, s61
	ds_write_b16_d16_hi v35, v16 offset:18480
	v_bfe_u32 v16, v20, 16, 1
	v_add3_u32 v16, v20, v16, s61
	ds_write_b16_d16_hi v35, v16 offset:21120
	v_bfe_u32 v16, v21, 16, 1
	v_add3_u32 v16, v21, v16, s61
	ds_write_b16_d16_hi v35, v16 offset:21648
	v_bfe_u32 v16, v22, 16, 1
	v_add3_u32 v16, v22, v16, s61
	ds_write_b16_d16_hi v35, v16 offset:22176
	v_bfe_u32 v16, v23, 16, 1
	v_add3_u32 v16, v23, v16, s61
	ds_write_b16_d16_hi v35, v16 offset:22704
	v_bfe_u32 v16, v24, 16, 1
	v_add3_u32 v16, v24, v16, s61
	ds_write_b16_d16_hi v35, v16 offset:25344
	v_bfe_u32 v16, v25, 16, 1
	v_add3_u32 v16, v25, v16, s61
	ds_write_b16_d16_hi v35, v16 offset:25872
	v_bfe_u32 v16, v26, 16, 1
	v_add3_u32 v16, v26, v16, s61
	ds_write_b16_d16_hi v35, v16 offset:26400
	v_bfe_u32 v16, v27, 16, 1
	v_add3_u32 v16, v27, v16, s61
	ds_write_b16_d16_hi v35, v16 offset:26928
	v_bfe_u32 v16, v28, 16, 1
	v_add3_u32 v16, v28, v16, s61
	ds_write_b16_d16_hi v35, v16 offset:29568
	v_bfe_u32 v16, v29, 16, 1
	v_add3_u32 v16, v29, v16, s61
	ds_write_b16_d16_hi v35, v16 offset:30096
	v_bfe_u32 v16, v30, 16, 1
	v_add3_u32 v16, v30, v16, s61
	ds_write_b16_d16_hi v35, v16 offset:30624
	v_bfe_u32 v16, v31, 16, 1
	v_add3_u32 v16, v31, v16, s61
	ds_write_b16_d16_hi v35, v16 offset:31152
	v_bfe_u32 v16, v0, 16, 1
	v_add3_u32 v0, v0, v16, s61
	ds_write_b16_d16_hi v35, v0 offset:16960
	v_bfe_u32 v0, v1, 16, 1
	v_add3_u32 v0, v1, v0, s61
	ds_write_b16_d16_hi v35, v0 offset:17488
	v_bfe_u32 v0, v2, 16, 1
	v_add3_u32 v0, v2, v0, s61
	ds_write_b16_d16_hi v35, v0 offset:18016
	v_bfe_u32 v0, v3, 16, 1
	v_add3_u32 v0, v3, v0, s61
	ds_write_b16_d16_hi v35, v0 offset:18544
	v_bfe_u32 v0, v4, 16, 1
	v_add3_u32 v0, v4, v0, s61
	ds_write_b16_d16_hi v35, v0 offset:21184
	v_bfe_u32 v0, v5, 16, 1
	v_add3_u32 v0, v5, v0, s61
	ds_write_b16_d16_hi v35, v0 offset:21712
	v_bfe_u32 v0, v6, 16, 1
	v_add3_u32 v0, v6, v0, s61
	ds_write_b16_d16_hi v35, v0 offset:22240
	v_bfe_u32 v0, v7, 16, 1
	v_add3_u32 v0, v7, v0, s61
	ds_write_b16_d16_hi v35, v0 offset:22768
	v_bfe_u32 v0, v8, 16, 1
	v_add3_u32 v0, v8, v0, s61
	ds_write_b16_d16_hi v35, v0 offset:25408
	v_bfe_u32 v0, v9, 16, 1
	v_add3_u32 v0, v9, v0, s61
	ds_write_b16_d16_hi v35, v0 offset:25936
	v_bfe_u32 v0, v10, 16, 1
	v_add3_u32 v0, v10, v0, s61
	ds_write_b16_d16_hi v35, v0 offset:26464
	v_bfe_u32 v0, v11, 16, 1
	v_add3_u32 v0, v11, v0, s61
	ds_write_b16_d16_hi v35, v0 offset:26992
	v_bfe_u32 v0, v12, 16, 1
	v_add3_u32 v0, v12, v0, s61
	ds_write_b16_d16_hi v35, v0 offset:29632
	v_bfe_u32 v0, v13, 16, 1
	v_add3_u32 v0, v13, v0, s61
	ds_write_b16_d16_hi v35, v0 offset:30160
	v_bfe_u32 v0, v14, 16, 1
	v_add3_u32 v0, v14, v0, s61
	ds_write_b16_d16_hi v35, v0 offset:30688
	v_bfe_u32 v0, v15, 16, 1
	v_add3_u32 v0, v15, v0, s61
	v_lshlrev_b32_e32 v116, 1, v38
	ds_write_b16_d16_hi v35, v0 offset:31216
	v_lshl_add_u64 v[0:1], s[8:9], 0, v[116:117]
	v_lshl_add_u64 v[4:5], v[0:1], 0, s[38:39]
	v_mad_u64_u32 v[0:1], s[0:1], v33, s62, v[36:37]
	s_waitcnt lgkmcnt(0)
	s_barrier
	ds_read_b128 v[0:3], v0 offset:16896
	v_add_u32_e32 v6, s55, v33
	v_ashrrev_i32_e32 v7, 31, v6
	v_lshlrev_b64 v[6:7], 11, v[6:7]
	v_lshl_add_u64 v[6:7], v[4:5], 0, v[6:7]
	s_waitcnt lgkmcnt(0)
	global_store_dwordx4 v[6:7], v[0:3], off
	s_nop 1
	v_add_u32_e32 v0, 0x100, v32
	v_ashrrev_i32_e32 v6, 5, v0
	v_mad_u64_u32 v[0:1], s[0:1], v6, s62, v[36:37]
	ds_read_b128 v[0:3], v0 offset:16896
	v_add_u32_e32 v6, s55, v6
	v_ashrrev_i32_e32 v7, 31, v6
	v_lshlrev_b64 v[6:7], 11, v[6:7]
	v_lshl_add_u64 v[6:7], v[4:5], 0, v[6:7]
	s_waitcnt lgkmcnt(0)
	global_store_dwordx4 v[6:7], v[0:3], off
	v_ashrrev_i32_e32 v6, 5, v34
	s_nop 0
	v_mad_u64_u32 v[0:1], s[0:1], v6, s62, v[36:37]
	ds_read_b128 v[0:3], v0 offset:16896
	v_add_u32_e32 v6, s55, v6
	v_ashrrev_i32_e32 v7, 31, v6
	v_lshlrev_b64 v[6:7], 11, v[6:7]
	v_lshl_add_u64 v[6:7], v[4:5], 0, v[6:7]
	s_waitcnt lgkmcnt(0)
	global_store_dwordx4 v[6:7], v[0:3], off
	s_nop 1
	v_add_u32_e32 v0, 0x300, v32
	v_ashrrev_i32_e32 v6, 5, v0
	v_mad_u64_u32 v[0:1], s[0:1], v6, s62, v[36:37]
	ds_read_b128 v[0:3], v0 offset:16896
	v_add_u32_e32 v6, s55, v6
	v_ashrrev_i32_e32 v7, 31, v6
	v_lshlrev_b64 v[6:7], 11, v[6:7]
	v_lshl_add_u64 v[4:5], v[4:5], 0, v[6:7]
	s_waitcnt lgkmcnt(0)
	global_store_dwordx4 v[4:5], v[0:3], off
